# gemm_lds_read_wait_taken_before_cluster_barrier
# baseline (speedup 1.0000x reference)
.LBB0_150:
	ds_read_b128 v[152:155], v148
	ds_read_b128 v[156:159], v148 offset:1024
	ds_read_b128 v[160:163], v148 offset:2048
	ds_read_b128 v[164:167], v148 offset:3072
	s_add_u32 s40, s38, 0xfffc0080
	s_addc_u32 s41, s39, -1
	s_cmp_eq_u32 s75, 12
	s_cselect_b32 s43, s13, s41
	s_cselect_b32 s42, s37, s40
	s_cselect_b32 s41, s9, s74
	s_cselect_b32 s40, s72, s73
	v_lshl_add_u64 v[200:201], s[38:39], 0, v[136:137]
	s_add_i32 m0, s51, 0xc000
	ds_read_b128 v[168:171], v149
	ds_read_b128 v[172:175], v149 offset:1024
	ds_read_b128 v[176:179], v149 offset:2048
	ds_read_b128 v[180:183], v149 offset:3072
	ds_read_b128 v[184:187], v149 offset:4096
	ds_read_b128 v[188:191], v149 offset:5120
	ds_read_b128 v[192:195], v149 offset:6144
	ds_read_b128 v[196:199], v149 offset:7168
	global_load_lds_dwordx4 v[200:201], off
	v_lshl_add_u64 v[200:201], s[38:39], 0, v[138:139]
	s_add_i32 m0, s51, 0xe000
	s_nop 0
	global_load_lds_dwordx4 v[200:201], off
	s_waitcnt lgkmcnt(8)
	s_waitcnt lgkmcnt(0)
	s_setprio 1
	s_barrier
	v_mfma_f32_16x16x32_bf16 v[124:127], v[152:155], v[168:171], v[124:127]
	v_mfma_f32_16x16x32_bf16 v[120:123], v[160:163], v[168:171], v[120:123]
	v_mfma_f32_16x16x32_bf16 v[116:119], v[152:155], v[176:179], v[116:119]
	v_mfma_f32_16x16x32_bf16 v[112:115], v[160:163], v[176:179], v[112:115]
	v_mfma_f32_16x16x32_bf16 v[108:111], v[152:155], v[184:187], v[108:111]
	v_mfma_f32_16x16x32_bf16 v[104:107], v[160:163], v[184:187], v[104:107]
	v_mfma_f32_16x16x32_bf16 v[100:103], v[152:155], v[192:195], v[100:103]
	v_mfma_f32_16x16x32_bf16 v[96:99], v[160:163], v[192:195], v[96:99]
	v_mfma_f32_16x16x32_bf16 v[124:127], v[156:159], v[172:175], v[124:127]
	v_mfma_f32_16x16x32_bf16 v[120:123], v[164:167], v[172:175], v[120:123]
	v_mfma_f32_16x16x32_bf16 v[116:119], v[156:159], v[180:183], v[116:119]
	v_mfma_f32_16x16x32_bf16 v[112:115], v[164:167], v[180:183], v[112:115]
	v_mfma_f32_16x16x32_bf16 v[108:111], v[156:159], v[188:191], v[108:111]
	v_mfma_f32_16x16x32_bf16 v[104:107], v[164:167], v[188:191], v[104:107]
	v_mfma_f32_16x16x32_bf16 v[100:103], v[156:159], v[196:199], v[100:103]
	v_mfma_f32_16x16x32_bf16 v[96:99], v[164:167], v[196:199], v[96:99]
	s_setprio 0
	s_barrier
	s_add_i32 s76, s69, s48
	v_lshl_add_u64 v[208:209], s[40:41], 0, v[132:133]
	s_mov_b32 m0, s76
	ds_read_b128 v[200:203], v150
	ds_read_b128 v[204:207], v150 offset:1024
	ds_read_b128 v[212:215], v150 offset:2048
	ds_read_b128 v[216:219], v150 offset:3072
	global_load_lds_dwordx4 v[208:209], off
	v_lshl_add_u64 v[220:221], s[40:41], 0, v[128:129]
	s_add_i32 m0, s76, 0x2000
	s_nop 0
	global_load_lds_dwordx4 v[220:221], off
	s_waitcnt lgkmcnt(0)
	s_setprio 1
	s_barrier
	v_mfma_f32_16x16x32_bf16 v[76:79], v[200:203], v[168:171], v[76:79]
	v_mfma_f32_16x16x32_bf16 v[72:75], v[212:215], v[168:171], v[72:75]
	v_mfma_f32_16x16x32_bf16 v[60:63], v[200:203], v[176:179], v[60:63]
	v_mfma_f32_16x16x32_bf16 v[56:59], v[212:215], v[176:179], v[56:59]
	v_mfma_f32_16x16x32_bf16 v[44:47], v[200:203], v[184:187], v[44:47]
	v_mfma_f32_16x16x32_bf16 v[40:43], v[212:215], v[184:187], v[40:43]
	v_mfma_f32_16x16x32_bf16 v[36:39], v[200:203], v[192:195], v[36:39]
	v_mfma_f32_16x16x32_bf16 v[32:35], v[212:215], v[192:195], v[32:35]
	v_mfma_f32_16x16x32_bf16 v[76:79], v[204:207], v[172:175], v[76:79]
	v_mfma_f32_16x16x32_bf16 v[72:75], v[216:219], v[172:175], v[72:75]
	v_mfma_f32_16x16x32_bf16 v[60:63], v[204:207], v[180:183], v[60:63]
	v_mfma_f32_16x16x32_bf16 v[56:59], v[216:219], v[180:183], v[56:59]
	v_mfma_f32_16x16x32_bf16 v[44:47], v[204:207], v[188:191], v[44:47]
	v_mfma_f32_16x16x32_bf16 v[40:43], v[216:219], v[188:191], v[40:43]
	v_mfma_f32_16x16x32_bf16 v[36:39], v[204:207], v[196:199], v[36:39]
	v_mfma_f32_16x16x32_bf16 v[32:35], v[216:219], v[196:199], v[32:35]
	s_setprio 0
	s_mov_b32 m0, s51
	v_lshl_add_u64 v[222:223], s[42:43], 0, v[134:135]
	s_barrier
	ds_read_b128 v[168:171], v149 offset:16384
	ds_read_b128 v[172:175], v149 offset:17408
	ds_read_b128 v[176:179], v149 offset:18432
	ds_read_b128 v[180:183], v149 offset:19456
	ds_read_b128 v[184:187], v149 offset:20480
	ds_read_b128 v[188:191], v149 offset:21504
	ds_read_b128 v[192:195], v149 offset:22528
	ds_read_b128 v[196:199], v149 offset:23552
	global_load_lds_dwordx4 v[222:223], off
	v_lshl_add_u64 v[224:225], s[42:43], 0, v[130:131]
	s_mov_b32 m0, s54
	s_nop 0
	global_load_lds_dwordx4 v[224:225], off
	s_waitcnt lgkmcnt(0)
	s_setprio 1
	s_barrier
	v_mfma_f32_16x16x32_bf16 v[92:95], v[152:155], v[168:171], v[92:95]
	v_mfma_f32_16x16x32_bf16 v[88:91], v[160:163], v[168:171], v[88:91]
	v_mfma_f32_16x16x32_bf16 v[84:87], v[152:155], v[176:179], v[84:87]
	v_mfma_f32_16x16x32_bf16 v[80:83], v[160:163], v[176:179], v[80:83]
	v_mfma_f32_16x16x32_bf16 v[68:71], v[152:155], v[184:187], v[68:71]
	v_mfma_f32_16x16x32_bf16 v[64:67], v[160:163], v[184:187], v[64:67]
	v_mfma_f32_16x16x32_bf16 v[52:55], v[152:155], v[192:195], v[52:55]
	v_mfma_f32_16x16x32_bf16 v[48:51], v[160:163], v[192:195], v[48:51]
	v_mfma_f32_16x16x32_bf16 v[92:95], v[156:159], v[172:175], v[92:95]
	v_mfma_f32_16x16x32_bf16 v[88:91], v[164:167], v[172:175], v[88:91]
	v_mfma_f32_16x16x32_bf16 v[84:87], v[156:159], v[180:183], v[84:87]
	v_mfma_f32_16x16x32_bf16 v[80:83], v[164:167], v[180:183], v[80:83]
	v_mfma_f32_16x16x32_bf16 v[68:71], v[156:159], v[188:191], v[68:71]
	v_mfma_f32_16x16x32_bf16 v[64:67], v[164:167], v[188:191], v[64:67]
	v_mfma_f32_16x16x32_bf16 v[52:55], v[156:159], v[196:199], v[52:55]
	v_mfma_f32_16x16x32_bf16 v[48:51], v[164:167], v[196:199], v[48:51]
	s_setprio 0
	s_barrier
	s_add_u32 s76, s40, 0x40000
	s_addc_u32 s77, s41, 0
	s_add_i32 s78, s70, s48
	v_lshl_add_u64 v[152:153], s[76:77], 0, v[132:133]
	s_mov_b32 m0, s78
	s_nop 0
	global_load_lds_dwordx4 v[152:153], off
	v_lshl_add_u64 v[152:153], s[76:77], 0, v[128:129]
	s_add_i32 m0, s78, 0x2000
	s_nop 0
	global_load_lds_dwordx4 v[152:153], off
	s_waitcnt vmcnt(6)
	s_setprio 1
	s_barrier
	v_mfma_f32_16x16x32_bf16 v[28:31], v[200:203], v[168:171], v[28:31]
	v_mfma_f32_16x16x32_bf16 v[24:27], v[212:215], v[168:171], v[24:27]
	v_mfma_f32_16x16x32_bf16 v[20:23], v[200:203], v[176:179], v[20:23]
	v_mfma_f32_16x16x32_bf16 v[16:19], v[212:215], v[176:179], v[16:19]
	v_mfma_f32_16x16x32_bf16 v[12:15], v[200:203], v[184:187], v[12:15]
	v_mfma_f32_16x16x32_bf16 v[8:11], v[212:215], v[184:187], v[8:11]
	v_mfma_f32_16x16x32_bf16 v[4:7], v[200:203], v[192:195], v[4:7]
	v_mfma_f32_16x16x32_bf16 v[0:3], v[212:215], v[192:195], v[0:3]
	v_mfma_f32_16x16x32_bf16 v[28:31], v[204:207], v[172:175], v[28:31]
	v_mfma_f32_16x16x32_bf16 v[24:27], v[216:219], v[172:175], v[24:27]
	v_mfma_f32_16x16x32_bf16 v[20:23], v[204:207], v[180:183], v[20:23]
	v_mfma_f32_16x16x32_bf16 v[16:19], v[216:219], v[180:183], v[16:19]
	v_mfma_f32_16x16x32_bf16 v[12:15], v[204:207], v[188:191], v[12:15]
	v_mfma_f32_16x16x32_bf16 v[8:11], v[216:219], v[188:191], v[8:11]
	v_mfma_f32_16x16x32_bf16 v[4:7], v[204:207], v[196:199], v[4:7]
	v_mfma_f32_16x16x32_bf16 v[0:3], v[216:219], v[196:199], v[0:3]
	s_setprio 0
	s_add_i32 s76, 0, 0x18000
	v_add_u32_e32 v151, s76, v146
	s_barrier
	ds_read_b128 v[152:155], v151
	ds_read_b128 v[156:159], v151 offset:1024
	ds_read_b128 v[160:163], v151 offset:2048
	ds_read_b128 v[164:167], v151 offset:3072
	s_add_u32 s42, s42, 0x40000
	s_addc_u32 s43, s43, 0
	s_mov_b32 m0, s55
	v_lshl_add_u64 v[200:201], s[42:43], 0, v[134:135]
	ds_read_b128 v[168:171], v149 offset:32768
	ds_read_b128 v[172:175], v149 offset:33792
	ds_read_b128 v[176:179], v149 offset:34816
	ds_read_b128 v[180:183], v149 offset:35840
	ds_read_b128 v[184:187], v149 offset:36864
	ds_read_b128 v[188:191], v149 offset:37888
	ds_read_b128 v[192:195], v149 offset:38912
	ds_read_b128 v[196:199], v149 offset:39936
	global_load_lds_dwordx4 v[200:201], off
	v_lshl_add_u64 v[200:201], s[42:43], 0, v[130:131]
	s_mov_b32 m0, s62
	s_nop 0
	global_load_lds_dwordx4 v[200:201], off
	s_waitcnt lgkmcnt(8)
	s_waitcnt lgkmcnt(0)
	s_setprio 1
	s_barrier
	v_mfma_f32_16x16x32_bf16 v[124:127], v[152:155], v[168:171], v[124:127]
	v_mfma_f32_16x16x32_bf16 v[120:123], v[160:163], v[168:171], v[120:123]
	v_mfma_f32_16x16x32_bf16 v[116:119], v[152:155], v[176:179], v[116:119]
	v_mfma_f32_16x16x32_bf16 v[112:115], v[160:163], v[176:179], v[112:115]
	v_mfma_f32_16x16x32_bf16 v[108:111], v[152:155], v[184:187], v[108:111]
	v_mfma_f32_16x16x32_bf16 v[104:107], v[160:163], v[184:187], v[104:107]
	v_mfma_f32_16x16x32_bf16 v[100:103], v[152:155], v[192:195], v[100:103]
	v_mfma_f32_16x16x32_bf16 v[96:99], v[160:163], v[192:195], v[96:99]
	v_mfma_f32_16x16x32_bf16 v[124:127], v[156:159], v[172:175], v[124:127]
	v_mfma_f32_16x16x32_bf16 v[120:123], v[164:167], v[172:175], v[120:123]
	v_mfma_f32_16x16x32_bf16 v[116:119], v[156:159], v[180:183], v[116:119]
	v_mfma_f32_16x16x32_bf16 v[112:115], v[164:167], v[180:183], v[112:115]
	v_mfma_f32_16x16x32_bf16 v[108:111], v[156:159], v[188:191], v[108:111]
	v_mfma_f32_16x16x32_bf16 v[104:107], v[164:167], v[188:191], v[104:107]
	v_mfma_f32_16x16x32_bf16 v[100:103], v[156:159], v[196:199], v[100:103]
	v_mfma_f32_16x16x32_bf16 v[96:99], v[164:167], v[196:199], v[96:99]
	s_setprio 0
	s_barrier
	s_add_i32 s42, 0, 0x1c000
	s_add_i32 s43, s76, s48
	v_add_u32_e32 v151, s42, v146
	v_lshl_add_u64 v[208:209], v[208:209], 0, s[0:1]
	s_mov_b32 m0, s43
	ds_read_b128 v[200:203], v151
	ds_read_b128 v[204:207], v151 offset:1024
	ds_read_b128 v[212:215], v151 offset:2048
	ds_read_b128 v[216:219], v151 offset:3072
	global_load_lds_dwordx4 v[208:209], off
	v_lshl_add_u64 v[208:209], v[220:221], 0, s[0:1]
	s_add_i32 m0, s43, 0x2000
	s_nop 0
	global_load_lds_dwordx4 v[208:209], off
	s_waitcnt lgkmcnt(0)
	s_setprio 1
	s_barrier
	v_mfma_f32_16x16x32_bf16 v[76:79], v[200:203], v[168:171], v[76:79]
	v_mfma_f32_16x16x32_bf16 v[72:75], v[212:215], v[168:171], v[72:75]
	v_mfma_f32_16x16x32_bf16 v[60:63], v[200:203], v[176:179], v[60:63]
	v_mfma_f32_16x16x32_bf16 v[56:59], v[212:215], v[176:179], v[56:59]
	v_mfma_f32_16x16x32_bf16 v[44:47], v[200:203], v[184:187], v[44:47]
	v_mfma_f32_16x16x32_bf16 v[40:43], v[212:215], v[184:187], v[40:43]
	v_mfma_f32_16x16x32_bf16 v[36:39], v[200:203], v[192:195], v[36:39]
	v_mfma_f32_16x16x32_bf16 v[32:35], v[212:215], v[192:195], v[32:35]
	v_mfma_f32_16x16x32_bf16 v[76:79], v[204:207], v[172:175], v[76:79]
	v_mfma_f32_16x16x32_bf16 v[72:75], v[216:219], v[172:175], v[72:75]
	v_mfma_f32_16x16x32_bf16 v[60:63], v[204:207], v[180:183], v[60:63]
	v_mfma_f32_16x16x32_bf16 v[56:59], v[216:219], v[180:183], v[56:59]
	v_mfma_f32_16x16x32_bf16 v[44:47], v[204:207], v[188:191], v[44:47]
	v_mfma_f32_16x16x32_bf16 v[40:43], v[216:219], v[188:191], v[40:43]
	v_mfma_f32_16x16x32_bf16 v[36:39], v[204:207], v[196:199], v[36:39]
	v_mfma_f32_16x16x32_bf16 v[32:35], v[216:219], v[196:199], v[32:35]
	s_setprio 0
	s_mov_b32 m0, s63
	v_lshl_add_u64 v[208:209], v[222:223], 0, s[0:1]
	s_barrier
	ds_read_b128 v[168:171], v149 offset:49152
	ds_read_b128 v[172:175], v149 offset:50176
	ds_read_b128 v[176:179], v149 offset:51200
	ds_read_b128 v[180:183], v149 offset:52224
	ds_read_b128 v[184:187], v149 offset:53248
	ds_read_b128 v[188:191], v149 offset:54272
	ds_read_b128 v[192:195], v149 offset:55296
	ds_read_b128 v[196:199], v149 offset:56320
	global_load_lds_dwordx4 v[208:209], off
	v_lshl_add_u64 v[208:209], v[224:225], 0, s[0:1]
	s_mov_b32 m0, s64
	s_nop 0
	global_load_lds_dwordx4 v[208:209], off
	s_waitcnt lgkmcnt(0)
	s_setprio 1
	s_barrier
	v_mfma_f32_16x16x32_bf16 v[92:95], v[152:155], v[168:171], v[92:95]
	v_mfma_f32_16x16x32_bf16 v[88:91], v[160:163], v[168:171], v[88:91]
	v_mfma_f32_16x16x32_bf16 v[84:87], v[152:155], v[176:179], v[84:87]
	v_mfma_f32_16x16x32_bf16 v[80:83], v[160:163], v[176:179], v[80:83]
	v_mfma_f32_16x16x32_bf16 v[68:71], v[152:155], v[184:187], v[68:71]
	v_mfma_f32_16x16x32_bf16 v[64:67], v[160:163], v[184:187], v[64:67]
	v_mfma_f32_16x16x32_bf16 v[52:55], v[152:155], v[192:195], v[52:55]
	v_mfma_f32_16x16x32_bf16 v[48:51], v[160:163], v[192:195], v[48:51]
	v_mfma_f32_16x16x32_bf16 v[92:95], v[156:159], v[172:175], v[92:95]
	v_mfma_f32_16x16x32_bf16 v[88:91], v[164:167], v[172:175], v[88:91]
	v_mfma_f32_16x16x32_bf16 v[84:87], v[156:159], v[180:183], v[84:87]
	v_mfma_f32_16x16x32_bf16 v[80:83], v[164:167], v[180:183], v[80:83]
	v_mfma_f32_16x16x32_bf16 v[68:71], v[156:159], v[188:191], v[68:71]
	v_mfma_f32_16x16x32_bf16 v[64:67], v[164:167], v[188:191], v[64:67]
	v_mfma_f32_16x16x32_bf16 v[52:55], v[156:159], v[196:199], v[52:55]
	v_mfma_f32_16x16x32_bf16 v[48:51], v[164:167], v[196:199], v[48:51]
	s_setprio 0
	s_barrier
	s_add_u32 s40, s40, 0x40080
	s_addc_u32 s41, s41, 0
	s_add_i32 s42, s42, s48
	v_lshl_add_u64 v[152:153], s[40:41], 0, v[132:133]
	s_mov_b32 m0, s42
	s_nop 0
	global_load_lds_dwordx4 v[152:153], off
	v_lshl_add_u64 v[152:153], s[40:41], 0, v[128:129]
	s_add_i32 m0, s42, 0x2000
	s_nop 0
	global_load_lds_dwordx4 v[152:153], off
	s_waitcnt vmcnt(6)
	s_setprio 1
	s_barrier
	v_mfma_f32_16x16x32_bf16 v[28:31], v[200:203], v[168:171], v[28:31]
	v_mfma_f32_16x16x32_bf16 v[24:27], v[212:215], v[168:171], v[24:27]
	v_mfma_f32_16x16x32_bf16 v[20:23], v[200:203], v[176:179], v[20:23]
	v_mfma_f32_16x16x32_bf16 v[16:19], v[212:215], v[176:179], v[16:19]
	v_mfma_f32_16x16x32_bf16 v[12:15], v[200:203], v[184:187], v[12:15]
	v_mfma_f32_16x16x32_bf16 v[8:11], v[212:215], v[184:187], v[8:11]
	v_mfma_f32_16x16x32_bf16 v[4:7], v[200:203], v[192:195], v[4:7]
	v_mfma_f32_16x16x32_bf16 v[0:3], v[212:215], v[192:195], v[0:3]
	v_mfma_f32_16x16x32_bf16 v[28:31], v[204:207], v[172:175], v[28:31]
	v_mfma_f32_16x16x32_bf16 v[24:27], v[216:219], v[172:175], v[24:27]
	v_mfma_f32_16x16x32_bf16 v[20:23], v[204:207], v[180:183], v[20:23]
	v_mfma_f32_16x16x32_bf16 v[16:19], v[216:219], v[180:183], v[16:19]
	v_mfma_f32_16x16x32_bf16 v[12:15], v[204:207], v[188:191], v[12:15]
	v_mfma_f32_16x16x32_bf16 v[8:11], v[216:219], v[188:191], v[8:11]
	v_mfma_f32_16x16x32_bf16 v[4:7], v[204:207], v[196:199], v[4:7]
	v_mfma_f32_16x16x32_bf16 v[0:3], v[216:219], v[196:199], v[0:3]
	s_setprio 0
	s_add_i32 s75, s75, 2
	s_add_u32 s38, s38, 0x100
	s_addc_u32 s39, s39, 0
	s_add_u32 s73, s73, 0x100
	s_addc_u32 s74, s74, 0
	s_cmp_gt_u32 s75, 13
	s_barrier
	s_cbranch_scc0 .LBB0_150
	v_lshl_add_u32 v151, s36, 8, v144
	s_cmp_gt_i32 s71, 11
	s_mov_b64 s[36:37], -1
	s_cbranch_scc0 .LBB0_155
	s_and_saveexec_b64 s[36:37], s[2:3]
	s_cbranch_execz .LBB0_154
	v_lshl_or_b32 v152, v151, 8, v147
	v_readlane_b32 s38, v253, 59
	v_readlane_b32 s39, v253, 60
	v_or_b32_e32 v153, 0x1000, v152
	s_nop 3
	global_store_dwordx4 v153, v[116:119], s[38:39] nt
	v_or_b32_e32 v153, 0x2000, v152
	global_store_dwordx4 v153, v[108:111], s[38:39] nt
	v_or_b32_e32 v153, 0x3000, v152
	global_store_dwordx4 v153, v[100:103], s[38:39] nt
	v_add_u32_e32 v153, 0x8000, v152
	global_store_dwordx4 v153, v[92:95], s[38:39] nt
	v_add_u32_e32 v153, 0x9000, v152
	global_store_dwordx4 v153, v[84:87], s[38:39] nt
	v_add_u32_e32 v153, 0xa000, v152
	global_store_dwordx4 v153, v[68:71], s[38:39] nt
	v_add_u32_e32 v153, 0xb000, v152
	global_store_dwordx4 v153, v[52:55], s[38:39] nt
	v_or_b32_e32 v153, 16, v152
	global_store_dwordx4 v153, v[120:123], s[38:39] nt
	v_or_b32_e32 v153, 0x1010, v152
	global_store_dwordx4 v153, v[112:115], s[38:39] nt
	v_or_b32_e32 v153, 0x2010, v152
	global_store_dwordx4 v153, v[104:107], s[38:39] nt
	v_or_b32_e32 v153, 0x3010, v152
	global_store_dwordx4 v153, v[96:99], s[38:39] nt
	v_add_u32_e32 v153, 0x8010, v152
	global_store_dwordx4 v153, v[88:91], s[38:39] nt
	v_add_u32_e32 v153, 0x9010, v152
	global_store_dwordx4 v152, v[124:127], s[38:39] nt
	global_store_dwordx4 v153, v[80:83], s[38:39] nt
	v_add_u32_e32 v153, 0xa010, v152
	v_add_u32_e32 v152, 0xb010, v152
	global_store_dwordx4 v153, v[64:67], s[38:39] nt
	global_store_dwordx4 v152, v[48:51], s[38:39] nt

.LBB0_177:
	ds_read_b128 v[152:155], v149
	ds_read_b128 v[156:159], v149 offset:1024
	ds_read_b128 v[160:163], v149 offset:2048
	ds_read_b128 v[164:167], v149 offset:3072
	s_add_u32 s36, s34, 0xfffc0080
	s_addc_u32 s37, s35, -1
	s_cmp_eq_u32 s68, 12
	s_cselect_b32 s39, s9, s37
	s_cselect_b32 s38, s64, s36
	s_cselect_b32 s37, s3, s67
	s_cselect_b32 s36, s65, s66
	v_lshl_add_u64 v[144:145], s[34:35], 0, v[136:137]
	s_add_i32 m0, s13, 0xc000
	ds_read_b128 v[168:171], v150
	ds_read_b128 v[172:175], v150 offset:1024
	ds_read_b128 v[176:179], v150 offset:2048
	ds_read_b128 v[180:183], v150 offset:3072
	ds_read_b128 v[184:187], v150 offset:4096
	ds_read_b128 v[188:191], v150 offset:5120
	ds_read_b128 v[192:195], v150 offset:6144
	ds_read_b128 v[196:199], v150 offset:7168
	global_load_lds_dwordx4 v[144:145], off
	v_lshl_add_u64 v[144:145], s[34:35], 0, v[138:139]
	s_add_i32 m0, s13, 0xe000
	s_nop 0
	global_load_lds_dwordx4 v[144:145], off
	s_waitcnt lgkmcnt(8)
	s_waitcnt lgkmcnt(0)
	s_setprio 1
	s_barrier
	v_mfma_f32_16x16x32_bf16 v[124:127], v[152:155], v[168:171], v[124:127]
	v_mfma_f32_16x16x32_bf16 v[120:123], v[160:163], v[168:171], v[120:123]
	v_mfma_f32_16x16x32_bf16 v[112:115], v[152:155], v[176:179], v[112:115]
	v_mfma_f32_16x16x32_bf16 v[104:107], v[160:163], v[176:179], v[104:107]
	v_mfma_f32_16x16x32_bf16 v[96:99], v[152:155], v[184:187], v[96:99]
	v_mfma_f32_16x16x32_bf16 v[88:91], v[160:163], v[184:187], v[88:91]
	v_mfma_f32_16x16x32_bf16 v[80:83], v[152:155], v[192:195], v[80:83]
	v_mfma_f32_16x16x32_bf16 v[72:75], v[160:163], v[192:195], v[72:75]
	v_mfma_f32_16x16x32_bf16 v[124:127], v[156:159], v[172:175], v[124:127]
	v_mfma_f32_16x16x32_bf16 v[120:123], v[164:167], v[172:175], v[120:123]
	v_mfma_f32_16x16x32_bf16 v[112:115], v[156:159], v[180:183], v[112:115]
	v_mfma_f32_16x16x32_bf16 v[104:107], v[164:167], v[180:183], v[104:107]
	v_mfma_f32_16x16x32_bf16 v[96:99], v[156:159], v[188:191], v[96:99]
	v_mfma_f32_16x16x32_bf16 v[88:91], v[164:167], v[188:191], v[88:91]
	v_mfma_f32_16x16x32_bf16 v[80:83], v[156:159], v[196:199], v[80:83]
	v_mfma_f32_16x16x32_bf16 v[72:75], v[164:167], v[196:199], v[72:75]
	s_setprio 0
	s_barrier
	s_add_i32 s69, s55, s42
	v_lshl_add_u64 v[144:145], s[36:37], 0, v[130:131]
	s_mov_b32 m0, s69
	ds_read_b128 v[200:203], v151
	ds_read_b128 v[204:207], v151 offset:1024
	ds_read_b128 v[212:215], v151 offset:2048
	ds_read_b128 v[216:219], v151 offset:3072
	global_load_lds_dwordx4 v[144:145], off
	v_lshl_add_u64 v[208:209], s[36:37], 0, v[134:135]
	s_add_i32 m0, s69, 0x2000
	s_nop 0
	global_load_lds_dwordx4 v[208:209], off
	s_waitcnt lgkmcnt(0)
	s_setprio 1
	s_barrier
	v_mfma_f32_16x16x32_bf16 v[116:119], v[200:203], v[168:171], v[116:119]
	v_mfma_f32_16x16x32_bf16 v[108:111], v[212:215], v[168:171], v[108:111]
	v_mfma_f32_16x16x32_bf16 v[100:103], v[200:203], v[176:179], v[100:103]
	v_mfma_f32_16x16x32_bf16 v[92:95], v[212:215], v[176:179], v[92:95]
	v_mfma_f32_16x16x32_bf16 v[84:87], v[200:203], v[184:187], v[84:87]
	v_mfma_f32_16x16x32_bf16 v[76:79], v[212:215], v[184:187], v[76:79]
	v_mfma_f32_16x16x32_bf16 v[68:71], v[200:203], v[192:195], v[68:71]
	v_mfma_f32_16x16x32_bf16 v[64:67], v[212:215], v[192:195], v[64:67]
	v_mfma_f32_16x16x32_bf16 v[116:119], v[204:207], v[172:175], v[116:119]
	v_mfma_f32_16x16x32_bf16 v[108:111], v[216:219], v[172:175], v[108:111]
	v_mfma_f32_16x16x32_bf16 v[100:103], v[204:207], v[180:183], v[100:103]
	v_mfma_f32_16x16x32_bf16 v[92:95], v[216:219], v[180:183], v[92:95]
	v_mfma_f32_16x16x32_bf16 v[84:87], v[204:207], v[188:191], v[84:87]
	v_mfma_f32_16x16x32_bf16 v[76:79], v[216:219], v[188:191], v[76:79]
	v_mfma_f32_16x16x32_bf16 v[68:71], v[204:207], v[196:199], v[68:71]
	v_mfma_f32_16x16x32_bf16 v[64:67], v[216:219], v[196:199], v[64:67]
	s_setprio 0
	s_mov_b32 m0, s13
	v_lshl_add_u64 v[220:221], s[38:39], 0, v[128:129]
	s_barrier
	ds_read_b128 v[168:171], v150 offset:16384
	ds_read_b128 v[172:175], v150 offset:17408
	ds_read_b128 v[176:179], v150 offset:18432
	ds_read_b128 v[180:183], v150 offset:19456
	ds_read_b128 v[184:187], v150 offset:20480
	ds_read_b128 v[188:191], v150 offset:21504
	ds_read_b128 v[192:195], v150 offset:22528
	ds_read_b128 v[196:199], v150 offset:23552
	global_load_lds_dwordx4 v[220:221], off
	v_lshl_add_u64 v[222:223], s[38:39], 0, v[132:133]
	s_mov_b32 m0, s43
	s_nop 0
	global_load_lds_dwordx4 v[222:223], off
	s_waitcnt lgkmcnt(0)
	s_setprio 1
	s_barrier
	v_mfma_f32_16x16x32_bf16 v[60:63], v[152:155], v[168:171], v[60:63]
	v_mfma_f32_16x16x32_bf16 v[56:59], v[160:163], v[168:171], v[56:59]
	v_mfma_f32_16x16x32_bf16 v[52:55], v[152:155], v[176:179], v[52:55]
	v_mfma_f32_16x16x32_bf16 v[44:47], v[160:163], v[176:179], v[44:47]
	v_mfma_f32_16x16x32_bf16 v[36:39], v[152:155], v[184:187], v[36:39]
	v_mfma_f32_16x16x32_bf16 v[28:31], v[160:163], v[184:187], v[28:31]
	v_mfma_f32_16x16x32_bf16 v[20:23], v[152:155], v[192:195], v[20:23]
	v_mfma_f32_16x16x32_bf16 v[12:15], v[160:163], v[192:195], v[12:15]
	v_mfma_f32_16x16x32_bf16 v[60:63], v[156:159], v[172:175], v[60:63]
	v_mfma_f32_16x16x32_bf16 v[56:59], v[164:167], v[172:175], v[56:59]
	v_mfma_f32_16x16x32_bf16 v[52:55], v[156:159], v[180:183], v[52:55]
	v_mfma_f32_16x16x32_bf16 v[44:47], v[164:167], v[180:183], v[44:47]
	v_mfma_f32_16x16x32_bf16 v[36:39], v[156:159], v[188:191], v[36:39]
	v_mfma_f32_16x16x32_bf16 v[28:31], v[164:167], v[188:191], v[28:31]
	v_mfma_f32_16x16x32_bf16 v[20:23], v[156:159], v[196:199], v[20:23]
	v_mfma_f32_16x16x32_bf16 v[12:15], v[164:167], v[196:199], v[12:15]
	s_setprio 0
	s_barrier
	s_add_u32 s70, s36, 0x40000
	s_addc_u32 s71, s37, 0
	s_add_i32 s69, s62, s42
	v_lshl_add_u64 v[152:153], s[70:71], 0, v[130:131]
	s_mov_b32 m0, s69
	s_nop 0
	global_load_lds_dwordx4 v[152:153], off
	v_lshl_add_u64 v[152:153], s[70:71], 0, v[134:135]
	s_add_i32 m0, s69, 0x2000
	s_nop 0
	global_load_lds_dwordx4 v[152:153], off
	s_waitcnt vmcnt(6)
	s_setprio 1
	s_barrier
	v_mfma_f32_16x16x32_bf16 v[48:51], v[200:203], v[168:171], v[48:51]
	v_mfma_f32_16x16x32_bf16 v[40:43], v[212:215], v[168:171], v[40:43]
	v_mfma_f32_16x16x32_bf16 v[32:35], v[200:203], v[176:179], v[32:35]
	v_mfma_f32_16x16x32_bf16 v[24:27], v[212:215], v[176:179], v[24:27]
	v_mfma_f32_16x16x32_bf16 v[16:19], v[200:203], v[184:187], v[16:19]
	v_mfma_f32_16x16x32_bf16 v[8:11], v[212:215], v[184:187], v[8:11]
	v_mfma_f32_16x16x32_bf16 v[4:7], v[200:203], v[192:195], v[4:7]
	v_mfma_f32_16x16x32_bf16 v[0:3], v[212:215], v[192:195], v[0:3]
	v_mfma_f32_16x16x32_bf16 v[48:51], v[204:207], v[172:175], v[48:51]
	v_mfma_f32_16x16x32_bf16 v[40:43], v[216:219], v[172:175], v[40:43]
	v_mfma_f32_16x16x32_bf16 v[32:35], v[204:207], v[180:183], v[32:35]
	v_mfma_f32_16x16x32_bf16 v[24:27], v[216:219], v[180:183], v[24:27]
	v_mfma_f32_16x16x32_bf16 v[16:19], v[204:207], v[188:191], v[16:19]
	v_mfma_f32_16x16x32_bf16 v[8:11], v[216:219], v[188:191], v[8:11]
	v_mfma_f32_16x16x32_bf16 v[4:7], v[204:207], v[196:199], v[4:7]
	v_mfma_f32_16x16x32_bf16 v[0:3], v[216:219], v[196:199], v[0:3]
	s_setprio 0
	s_add_i32 s69, 0, 0x18000
	v_add_u32_e32 v164, s69, v147
	s_barrier
	ds_read_b128 v[152:155], v164
	ds_read_b128 v[156:159], v164 offset:1024
	ds_read_b128 v[160:163], v164 offset:2048
	ds_read_b128 v[164:167], v164 offset:3072
	s_add_u32 s38, s38, 0x40000
	s_addc_u32 s39, s39, 0
	s_mov_b32 m0, s48
	v_lshl_add_u64 v[200:201], s[38:39], 0, v[128:129]
	ds_read_b128 v[168:171], v150 offset:32768
	ds_read_b128 v[172:175], v150 offset:33792
	ds_read_b128 v[176:179], v150 offset:34816
	ds_read_b128 v[180:183], v150 offset:35840
	ds_read_b128 v[184:187], v150 offset:36864
	ds_read_b128 v[188:191], v150 offset:37888
	ds_read_b128 v[192:195], v150 offset:38912
	ds_read_b128 v[196:199], v150 offset:39936
	global_load_lds_dwordx4 v[200:201], off
	v_lshl_add_u64 v[200:201], s[38:39], 0, v[132:133]
	s_mov_b32 m0, s49
	s_nop 0
	global_load_lds_dwordx4 v[200:201], off
	s_waitcnt lgkmcnt(8)
	s_waitcnt lgkmcnt(0)
	s_setprio 1
	s_barrier
	v_mfma_f32_16x16x32_bf16 v[124:127], v[152:155], v[168:171], v[124:127]
	v_mfma_f32_16x16x32_bf16 v[120:123], v[160:163], v[168:171], v[120:123]
	v_mfma_f32_16x16x32_bf16 v[112:115], v[152:155], v[176:179], v[112:115]
	v_mfma_f32_16x16x32_bf16 v[104:107], v[160:163], v[176:179], v[104:107]
	v_mfma_f32_16x16x32_bf16 v[96:99], v[152:155], v[184:187], v[96:99]
	v_mfma_f32_16x16x32_bf16 v[88:91], v[160:163], v[184:187], v[88:91]
	v_mfma_f32_16x16x32_bf16 v[80:83], v[152:155], v[192:195], v[80:83]
	v_mfma_f32_16x16x32_bf16 v[72:75], v[160:163], v[192:195], v[72:75]
	v_mfma_f32_16x16x32_bf16 v[124:127], v[156:159], v[172:175], v[124:127]
	v_mfma_f32_16x16x32_bf16 v[120:123], v[164:167], v[172:175], v[120:123]
	v_mfma_f32_16x16x32_bf16 v[112:115], v[156:159], v[180:183], v[112:115]
	v_mfma_f32_16x16x32_bf16 v[104:107], v[164:167], v[180:183], v[104:107]
	v_mfma_f32_16x16x32_bf16 v[96:99], v[156:159], v[188:191], v[96:99]
	v_mfma_f32_16x16x32_bf16 v[88:91], v[164:167], v[188:191], v[88:91]
	v_mfma_f32_16x16x32_bf16 v[80:83], v[156:159], v[196:199], v[80:83]
	v_mfma_f32_16x16x32_bf16 v[72:75], v[164:167], v[196:199], v[72:75]
	s_setprio 0
	s_barrier
	s_add_i32 s38, 0, 0x1c000
	s_add_i32 s39, s69, s42
	v_add_u32_e32 v211, s38, v147
	v_lshl_add_u64 v[144:145], v[144:145], 0, s[0:1]
	s_mov_b32 m0, s39
	ds_read_b128 v[200:203], v211
	ds_read_b128 v[204:207], v211 offset:1024
	ds_read_b128 v[212:215], v211 offset:2048
	ds_read_b128 v[216:219], v211 offset:3072
	global_load_lds_dwordx4 v[144:145], off
	v_lshl_add_u64 v[144:145], v[208:209], 0, s[0:1]
	s_add_i32 m0, s39, 0x2000
	s_nop 0
	global_load_lds_dwordx4 v[144:145], off
	s_waitcnt lgkmcnt(0)
	s_setprio 1
	s_barrier
	v_mfma_f32_16x16x32_bf16 v[116:119], v[200:203], v[168:171], v[116:119]
	v_mfma_f32_16x16x32_bf16 v[108:111], v[212:215], v[168:171], v[108:111]
	v_mfma_f32_16x16x32_bf16 v[100:103], v[200:203], v[176:179], v[100:103]
	v_mfma_f32_16x16x32_bf16 v[92:95], v[212:215], v[176:179], v[92:95]
	v_mfma_f32_16x16x32_bf16 v[84:87], v[200:203], v[184:187], v[84:87]
	v_mfma_f32_16x16x32_bf16 v[76:79], v[212:215], v[184:187], v[76:79]
	v_mfma_f32_16x16x32_bf16 v[68:71], v[200:203], v[192:195], v[68:71]
	v_mfma_f32_16x16x32_bf16 v[64:67], v[212:215], v[192:195], v[64:67]
	v_mfma_f32_16x16x32_bf16 v[116:119], v[204:207], v[172:175], v[116:119]
	v_mfma_f32_16x16x32_bf16 v[108:111], v[216:219], v[172:175], v[108:111]
	v_mfma_f32_16x16x32_bf16 v[100:103], v[204:207], v[180:183], v[100:103]
	v_mfma_f32_16x16x32_bf16 v[92:95], v[216:219], v[180:183], v[92:95]
	v_mfma_f32_16x16x32_bf16 v[84:87], v[204:207], v[188:191], v[84:87]
	v_mfma_f32_16x16x32_bf16 v[76:79], v[216:219], v[188:191], v[76:79]
	v_mfma_f32_16x16x32_bf16 v[68:71], v[204:207], v[196:199], v[68:71]
	v_mfma_f32_16x16x32_bf16 v[64:67], v[216:219], v[196:199], v[64:67]
	s_setprio 0
	s_mov_b32 m0, s51
	v_lshl_add_u64 v[144:145], v[220:221], 0, s[0:1]
	s_barrier
	ds_read_b128 v[168:171], v150 offset:49152
	ds_read_b128 v[172:175], v150 offset:50176
	ds_read_b128 v[176:179], v150 offset:51200
	ds_read_b128 v[180:183], v150 offset:52224
	ds_read_b128 v[184:187], v150 offset:53248
	ds_read_b128 v[188:191], v150 offset:54272
	ds_read_b128 v[192:195], v150 offset:55296
	ds_read_b128 v[196:199], v150 offset:56320
	global_load_lds_dwordx4 v[144:145], off
	v_lshl_add_u64 v[144:145], v[222:223], 0, s[0:1]
	s_mov_b32 m0, s54
	s_nop 0
	global_load_lds_dwordx4 v[144:145], off
	s_waitcnt lgkmcnt(0)
	s_setprio 1
	s_barrier
	v_mfma_f32_16x16x32_bf16 v[60:63], v[152:155], v[168:171], v[60:63]
	v_mfma_f32_16x16x32_bf16 v[56:59], v[160:163], v[168:171], v[56:59]
	v_mfma_f32_16x16x32_bf16 v[52:55], v[152:155], v[176:179], v[52:55]
	v_mfma_f32_16x16x32_bf16 v[44:47], v[160:163], v[176:179], v[44:47]
	v_mfma_f32_16x16x32_bf16 v[36:39], v[152:155], v[184:187], v[36:39]
	v_mfma_f32_16x16x32_bf16 v[28:31], v[160:163], v[184:187], v[28:31]
	v_mfma_f32_16x16x32_bf16 v[20:23], v[152:155], v[192:195], v[20:23]
	v_mfma_f32_16x16x32_bf16 v[12:15], v[160:163], v[192:195], v[12:15]
	v_mfma_f32_16x16x32_bf16 v[60:63], v[156:159], v[172:175], v[60:63]
	v_mfma_f32_16x16x32_bf16 v[56:59], v[164:167], v[172:175], v[56:59]
	v_mfma_f32_16x16x32_bf16 v[52:55], v[156:159], v[180:183], v[52:55]
	v_mfma_f32_16x16x32_bf16 v[44:47], v[164:167], v[180:183], v[44:47]
	v_mfma_f32_16x16x32_bf16 v[36:39], v[156:159], v[188:191], v[36:39]
	v_mfma_f32_16x16x32_bf16 v[28:31], v[164:167], v[188:191], v[28:31]
	v_mfma_f32_16x16x32_bf16 v[20:23], v[156:159], v[196:199], v[20:23]
	v_mfma_f32_16x16x32_bf16 v[12:15], v[164:167], v[196:199], v[12:15]
	s_setprio 0
	s_barrier
	s_add_u32 s36, s36, 0x40080
	s_addc_u32 s37, s37, 0
	s_add_i32 s38, s38, s42
	v_lshl_add_u64 v[144:145], s[36:37], 0, v[130:131]
	s_mov_b32 m0, s38
	s_nop 0
	global_load_lds_dwordx4 v[144:145], off
	v_lshl_add_u64 v[144:145], s[36:37], 0, v[134:135]
	s_add_i32 m0, s38, 0x2000
	s_nop 0
	global_load_lds_dwordx4 v[144:145], off
	s_waitcnt vmcnt(6)
	s_setprio 1
	s_barrier
	v_mfma_f32_16x16x32_bf16 v[48:51], v[200:203], v[168:171], v[48:51]
	v_mfma_f32_16x16x32_bf16 v[40:43], v[212:215], v[168:171], v[40:43]
	v_mfma_f32_16x16x32_bf16 v[32:35], v[200:203], v[176:179], v[32:35]
	v_mfma_f32_16x16x32_bf16 v[24:27], v[212:215], v[176:179], v[24:27]
	v_mfma_f32_16x16x32_bf16 v[16:19], v[200:203], v[184:187], v[16:19]
	v_mfma_f32_16x16x32_bf16 v[8:11], v[212:215], v[184:187], v[8:11]
	v_mfma_f32_16x16x32_bf16 v[4:7], v[200:203], v[192:195], v[4:7]
	v_mfma_f32_16x16x32_bf16 v[0:3], v[212:215], v[192:195], v[0:3]
	v_mfma_f32_16x16x32_bf16 v[48:51], v[204:207], v[172:175], v[48:51]
	v_mfma_f32_16x16x32_bf16 v[40:43], v[216:219], v[172:175], v[40:43]
	v_mfma_f32_16x16x32_bf16 v[32:35], v[204:207], v[180:183], v[32:35]
	v_mfma_f32_16x16x32_bf16 v[24:27], v[216:219], v[180:183], v[24:27]
	v_mfma_f32_16x16x32_bf16 v[16:19], v[204:207], v[188:191], v[16:19]
	v_mfma_f32_16x16x32_bf16 v[8:11], v[216:219], v[188:191], v[8:11]
	v_mfma_f32_16x16x32_bf16 v[4:7], v[204:207], v[196:199], v[4:7]
	v_mfma_f32_16x16x32_bf16 v[0:3], v[216:219], v[196:199], v[0:3]
	s_setprio 0
	s_add_i32 s68, s68, 2
	s_add_u32 s34, s34, 0x100
	s_addc_u32 s35, s35, 0
	s_add_u32 s66, s66, 0x100
	s_addc_u32 s67, s67, 0
	s_cmp_gt_u32 s68, 13
	s_barrier
	s_cbranch_scc0 .LBB0_177
	v_lshl_add_u32 v152, s12, 8, v146
	v_ashrrev_i32_e32 v153, 31, v152
	v_lshl_or_b32 v144, s63, 8, v148
	v_readlane_b32 s34, v253, 61
	v_ashrrev_i32_e32 v145, 31, v144
	v_lshlrev_b64 v[154:155], 17, v[152:153]
	v_readlane_b32 s35, v253, 62
	v_lshlrev_b64 v[156:157], 1, v[144:145]
	v_cvt_pk_bf16_f32 v124, v124, v125
	v_cvt_pk_bf16_f32 v125, v126, v127
	v_cvt_pk_bf16_f32 v126, v120, v121
	s_nop 0
	v_lshl_add_u64 v[154:155], s[34:35], 0, v[154:155]
	v_lshl_add_u64 v[144:145], v[154:155], 0, v[156:157]
	v_cvt_pk_bf16_f32 v127, v122, v123
	global_store_dwordx4 v[144:145], v[124:127], off nt
	v_cvt_pk_bf16_f32 v116, v116, v117
	v_cvt_pk_bf16_f32 v117, v118, v119
	v_cvt_pk_bf16_f32 v118, v108, v109
	v_or_b32_e32 v108, 16, v152
	v_ashrrev_i32_e32 v109, 31, v108
	v_lshlrev_b64 v[108:109], 17, v[108:109]
	v_lshl_add_u64 v[108:109], s[34:35], 0, v[108:109]
	v_cvt_pk_bf16_f32 v119, v110, v111
	global_store_dwordx4 v[144:145], v[116:119], off offset:256 nt
	s_mov_b32 s3, 0x1000000
	s_mov_b32 s63, s2
	v_lshl_add_u64 v[116:117], v[108:109], 0, v[156:157]
	v_cvt_pk_bf16_f32 v108, v112, v113
	v_cvt_pk_bf16_f32 v109, v114, v115
	v_cvt_pk_bf16_f32 v110, v104, v105
	v_cvt_pk_bf16_f32 v111, v106, v107
	global_store_dwordx4 v[116:117], v[108:111], off nt
	v_cvt_pk_bf16_f32 v100, v100, v101
	v_cvt_pk_bf16_f32 v101, v102, v103
	v_cvt_pk_bf16_f32 v102, v92, v93
	v_or_b32_e32 v92, 32, v152
	v_ashrrev_i32_e32 v93, 31, v92
	v_lshlrev_b64 v[92:93], 17, v[92:93]
	v_lshl_add_u64 v[92:93], s[34:35], 0, v[92:93]
	v_cvt_pk_bf16_f32 v103, v94, v95
	global_store_dwordx4 v[116:117], v[100:103], off offset:256 nt
	s_mov_b32 s12, s8
	s_mov_b64 s[36:37], s[30:31]
	v_lshl_add_u64 v[100:101], v[92:93], 0, v[156:157]
	v_cvt_pk_bf16_f32 v92, v96, v97
	v_cvt_pk_bf16_f32 v93, v98, v99
	v_cvt_pk_bf16_f32 v94, v88, v89
	v_cvt_pk_bf16_f32 v95, v90, v91
	global_store_dwordx4 v[100:101], v[92:95], off nt
	v_cvt_pk_bf16_f32 v84, v84, v85
	v_cvt_pk_bf16_f32 v85, v86, v87
	v_cvt_pk_bf16_f32 v86, v76, v77
	v_or_b32_e32 v76, 48, v152
	v_ashrrev_i32_e32 v77, 31, v76
	v_lshlrev_b64 v[76:77], 17, v[76:77]
	v_lshl_add_u64 v[76:77], s[34:35], 0, v[76:77]
	v_cvt_pk_bf16_f32 v87, v78, v79
	global_store_dwordx4 v[100:101], v[84:87], off offset:256 nt
	s_mov_b64 s[34:35], 0x1000000
	s_nop 0
	v_lshl_add_u64 v[84:85], v[76:77], 0, v[156:157]
	v_cvt_pk_bf16_f32 v76, v80, v81
	v_cvt_pk_bf16_f32 v77, v82, v83
	v_cvt_pk_bf16_f32 v78, v72, v73
	v_cvt_pk_bf16_f32 v79, v74, v75
	global_store_dwordx4 v[84:85], v[76:79], off nt
	v_cvt_pk_bf16_f32 v68, v68, v69
	v_cvt_pk_bf16_f32 v69, v70, v71
	v_cvt_pk_bf16_f32 v70, v64, v65
	v_cvt_pk_bf16_f32 v71, v66, v67
	global_store_dwordx4 v[84:85], v[68:71], off offset:256 nt
	v_cvt_pk_bf16_f32 v60, v60, v61
	v_cvt_pk_bf16_f32 v61, v62, v63
	v_cvt_pk_bf16_f32 v62, v56, v57
	v_add_co_u32_e32 v56, vcc, s3, v144
	v_lshl_add_u64 v[64:65], v[144:145], 0, s[34:35]
	s_nop 0
	v_addc_co_u32_e32 v57, vcc, 0, v145, vcc
	s_mov_b32 s3, 0x1200000
	v_cvt_pk_bf16_f32 v63, v58, v59
	global_store_dwordx4 v[56:57], v[60:63], off nt
	v_cvt_pk_bf16_f32 v48, v48, v49
	v_cvt_pk_bf16_f32 v49, v50, v51
	v_cvt_pk_bf16_f32 v50, v40, v41
	v_cvt_pk_bf16_f32 v51, v42, v43
	global_store_dwordx4 v[64:65], v[48:51], off offset:256 nt
	s_mov_b64 s[34:35], 0x1200000
	v_cvt_pk_bf16_f32 v40, v52, v53
	v_cvt_pk_bf16_f32 v41, v54, v55
	v_cvt_pk_bf16_f32 v42, v44, v45
	v_add_co_u32_e32 v44, vcc, s3, v144
	v_lshl_add_u64 v[48:49], v[144:145], 0, s[34:35]
	s_nop 0
	v_addc_co_u32_e32 v45, vcc, 0, v145, vcc
	s_mov_b32 s3, 0x1400000
	v_cvt_pk_bf16_f32 v43, v46, v47
	global_store_dwordx4 v[44:45], v[40:43], off nt
	v_cvt_pk_bf16_f32 v32, v32, v33
	v_cvt_pk_bf16_f32 v33, v34, v35
	v_cvt_pk_bf16_f32 v34, v24, v25
	v_cvt_pk_bf16_f32 v35, v26, v27
	global_store_dwordx4 v[48:49], v[32:35], off offset:256 nt
	s_mov_b64 s[34:35], 0x1400000
	v_cvt_pk_bf16_f32 v24, v36, v37
	v_cvt_pk_bf16_f32 v25, v38, v39
	v_cvt_pk_bf16_f32 v26, v28, v29
	v_add_co_u32_e32 v28, vcc, s3, v144
	v_lshl_add_u64 v[32:33], v[144:145], 0, s[34:35]
	s_nop 0
	v_addc_co_u32_e32 v29, vcc, 0, v145, vcc
	s_mov_b32 s3, 0x1600000
	v_cvt_pk_bf16_f32 v27, v30, v31
	global_store_dwordx4 v[28:29], v[24:27], off nt
	v_cvt_pk_bf16_f32 v16, v16, v17
	v_cvt_pk_bf16_f32 v17, v18, v19
	v_cvt_pk_bf16_f32 v18, v8, v9
	v_cvt_pk_bf16_f32 v19, v10, v11
	global_store_dwordx4 v[32:33], v[16:19], off offset:256 nt
	v_cvt_pk_bf16_f32 v8, v20, v21
	v_cvt_pk_bf16_f32 v9, v22, v23
	v_cvt_pk_bf16_f32 v10, v12, v13
	v_add_co_u32_e32 v12, vcc, s3, v144
	s_mov_b64 s[34:35], 0x1600000
	s_nop 0
	v_addc_co_u32_e32 v13, vcc, 0, v145, vcc
	v_lshl_add_u64 v[16:17], v[144:145], 0, s[34:35]
	s_and_b64 vcc, exec, s[4:5]
	s_mov_b64 s[34:35], s[14:15]
	v_cvt_pk_bf16_f32 v11, v14, v15
	global_store_dwordx4 v[12:13], v[8:11], off nt
	v_cvt_pk_bf16_f32 v4, v4, v5
	v_cvt_pk_bf16_f32 v5, v6, v7
	v_cvt_pk_bf16_f32 v6, v0, v1
	v_cvt_pk_bf16_f32 v7, v2, v3
	global_store_dwordx4 v[16:17], v[4:7], off offset:256 nt
	s_cbranch_vccz .LBB0_170
	s_waitcnt vmcnt(0)
	s_cmpk_gt_u32 s40, 0xff
	s_cbranch_scc1 .LBB0_181
	s_barrier

.LBB0_200:
	s_add_u32 s48, s42, 0xfffc0080
	s_addc_u32 s49, s43, -1
	s_add_i32 s81, 0, 0x10000
	v_add_u32_e32 v140, s81, v144
	ds_read_b128 v[148:151], v140
	ds_read_b128 v[152:155], v140 offset:1024
	ds_read_b128 v[156:159], v140 offset:2048
	ds_read_b128 v[160:163], v140 offset:3072
	s_cmp_eq_u32 s80, 12
	s_cselect_b32 s51, s35, s49
	s_cselect_b32 s50, s76, s48
	s_cselect_b32 s49, s31, s79
	s_cselect_b32 s48, s77, s78
	v_lshl_add_u64 v[140:141], s[42:43], 0, v[136:137]
	s_add_i32 m0, s37, 0xc000
	ds_read_b128 v[164:167], v146
	ds_read_b128 v[168:171], v146 offset:1024
	ds_read_b128 v[172:175], v146 offset:2048
	ds_read_b128 v[176:179], v146 offset:3072
	ds_read_b128 v[180:183], v146 offset:4096
	ds_read_b128 v[184:187], v146 offset:5120
	ds_read_b128 v[188:191], v146 offset:6144
	ds_read_b128 v[192:195], v146 offset:7168
	global_load_lds_dwordx4 v[140:141], off
	v_lshl_add_u64 v[140:141], s[42:43], 0, v[138:139]
	s_add_i32 m0, s37, 0xe000
	s_nop 0
	global_load_lds_dwordx4 v[140:141], off
	s_waitcnt lgkmcnt(8)
	s_waitcnt lgkmcnt(0)
	s_setprio 1
	s_barrier
	v_mfma_f32_16x16x32_bf16 v[124:127], v[148:151], v[164:167], v[124:127]
	v_mfma_f32_16x16x32_bf16 v[120:123], v[156:159], v[164:167], v[120:123]
	v_mfma_f32_16x16x32_bf16 v[116:119], v[148:151], v[172:175], v[116:119]
	v_mfma_f32_16x16x32_bf16 v[108:111], v[156:159], v[172:175], v[108:111]
	v_mfma_f32_16x16x32_bf16 v[100:103], v[148:151], v[180:183], v[100:103]
	v_mfma_f32_16x16x32_bf16 v[92:95], v[156:159], v[180:183], v[92:95]
	v_mfma_f32_16x16x32_bf16 v[84:87], v[148:151], v[188:191], v[84:87]
	v_mfma_f32_16x16x32_bf16 v[76:79], v[156:159], v[188:191], v[76:79]
	v_mfma_f32_16x16x32_bf16 v[124:127], v[152:155], v[168:171], v[124:127]
	v_mfma_f32_16x16x32_bf16 v[120:123], v[160:163], v[168:171], v[120:123]
	v_mfma_f32_16x16x32_bf16 v[116:119], v[152:155], v[176:179], v[116:119]
	v_mfma_f32_16x16x32_bf16 v[108:111], v[160:163], v[176:179], v[108:111]
	v_mfma_f32_16x16x32_bf16 v[100:103], v[152:155], v[184:187], v[100:103]
	v_mfma_f32_16x16x32_bf16 v[92:95], v[160:163], v[184:187], v[92:95]
	v_mfma_f32_16x16x32_bf16 v[84:87], v[152:155], v[192:195], v[84:87]
	v_mfma_f32_16x16x32_bf16 v[76:79], v[160:163], v[192:195], v[76:79]
	s_setprio 0
	s_barrier
	s_add_i32 s84, 0, 0x14000
	v_add_u32_e32 v140, s84, v144
	s_add_i32 s81, s81, s69
	ds_read_b128 v[196:199], v140
	ds_read_b128 v[200:203], v140 offset:1024
	ds_read_b128 v[204:207], v140 offset:2048
	ds_read_b128 v[212:215], v140 offset:3072
	v_lshl_add_u64 v[140:141], s[48:49], 0, v[128:129]
	s_mov_b32 m0, s81
	v_lshl_add_u64 v[208:209], s[48:49], 0, v[134:135]
	global_load_lds_dwordx4 v[140:141], off
	s_add_i32 m0, s81, 0x2000
	s_nop 0
	global_load_lds_dwordx4 v[208:209], off
	s_waitcnt lgkmcnt(0)
	s_setprio 1
	s_barrier
	v_mfma_f32_16x16x32_bf16 v[112:115], v[196:199], v[164:167], v[112:115]
	v_mfma_f32_16x16x32_bf16 v[104:107], v[204:207], v[164:167], v[104:107]
	v_mfma_f32_16x16x32_bf16 v[96:99], v[196:199], v[172:175], v[96:99]
	v_mfma_f32_16x16x32_bf16 v[88:91], v[204:207], v[172:175], v[88:91]
	v_mfma_f32_16x16x32_bf16 v[80:83], v[196:199], v[180:183], v[80:83]
	v_mfma_f32_16x16x32_bf16 v[72:75], v[204:207], v[180:183], v[72:75]
	v_mfma_f32_16x16x32_bf16 v[68:71], v[196:199], v[188:191], v[68:71]
	v_mfma_f32_16x16x32_bf16 v[64:67], v[204:207], v[188:191], v[64:67]
	v_mfma_f32_16x16x32_bf16 v[112:115], v[200:203], v[168:171], v[112:115]
	v_mfma_f32_16x16x32_bf16 v[104:107], v[212:215], v[168:171], v[104:107]
	v_mfma_f32_16x16x32_bf16 v[96:99], v[200:203], v[176:179], v[96:99]
	v_mfma_f32_16x16x32_bf16 v[88:91], v[212:215], v[176:179], v[88:91]
	v_mfma_f32_16x16x32_bf16 v[80:83], v[200:203], v[184:187], v[80:83]
	v_mfma_f32_16x16x32_bf16 v[72:75], v[212:215], v[184:187], v[72:75]
	v_mfma_f32_16x16x32_bf16 v[68:71], v[200:203], v[192:195], v[68:71]
	v_mfma_f32_16x16x32_bf16 v[64:67], v[212:215], v[192:195], v[64:67]
	s_setprio 0
	s_mov_b32 m0, s37
	v_lshl_add_u64 v[216:217], s[50:51], 0, v[130:131]
	s_barrier
	ds_read_b128 v[164:167], v146 offset:16384
	ds_read_b128 v[168:171], v146 offset:17408
	ds_read_b128 v[172:175], v146 offset:18432
	ds_read_b128 v[176:179], v146 offset:19456
	ds_read_b128 v[180:183], v146 offset:20480
	ds_read_b128 v[184:187], v146 offset:21504
	ds_read_b128 v[188:191], v146 offset:22528
	ds_read_b128 v[192:195], v146 offset:23552
	global_load_lds_dwordx4 v[216:217], off
	v_lshl_add_u64 v[218:219], s[50:51], 0, v[132:133]
	s_mov_b32 m0, s70
	s_nop 0
	global_load_lds_dwordx4 v[218:219], off
	s_waitcnt lgkmcnt(0)
	s_setprio 1
	s_barrier
	v_mfma_f32_16x16x32_bf16 v[60:63], v[148:151], v[164:167], v[60:63]
	v_mfma_f32_16x16x32_bf16 v[56:59], v[156:159], v[164:167], v[56:59]
	v_mfma_f32_16x16x32_bf16 v[52:55], v[148:151], v[172:175], v[52:55]
	v_mfma_f32_16x16x32_bf16 v[44:47], v[156:159], v[172:175], v[44:47]
	v_mfma_f32_16x16x32_bf16 v[36:39], v[148:151], v[180:183], v[36:39]
	v_mfma_f32_16x16x32_bf16 v[28:31], v[156:159], v[180:183], v[28:31]
	v_mfma_f32_16x16x32_bf16 v[20:23], v[148:151], v[188:191], v[20:23]
	v_mfma_f32_16x16x32_bf16 v[12:15], v[156:159], v[188:191], v[12:15]
	v_mfma_f32_16x16x32_bf16 v[60:63], v[152:155], v[168:171], v[60:63]
	v_mfma_f32_16x16x32_bf16 v[56:59], v[160:163], v[168:171], v[56:59]
	v_mfma_f32_16x16x32_bf16 v[52:55], v[152:155], v[176:179], v[52:55]
	v_mfma_f32_16x16x32_bf16 v[44:47], v[160:163], v[176:179], v[44:47]
	v_mfma_f32_16x16x32_bf16 v[36:39], v[152:155], v[184:187], v[36:39]
	v_mfma_f32_16x16x32_bf16 v[28:31], v[160:163], v[184:187], v[28:31]
	v_mfma_f32_16x16x32_bf16 v[20:23], v[152:155], v[192:195], v[20:23]
	v_mfma_f32_16x16x32_bf16 v[12:15], v[160:163], v[192:195], v[12:15]
	s_setprio 0
	s_barrier
	s_add_u32 s82, s48, 0x40000
	s_addc_u32 s83, s49, 0
	s_add_i32 s81, s84, s69
	v_lshl_add_u64 v[148:149], s[82:83], 0, v[128:129]
	s_mov_b32 m0, s81
	s_nop 0
	global_load_lds_dwordx4 v[148:149], off
	v_lshl_add_u64 v[148:149], s[82:83], 0, v[134:135]
	s_add_i32 m0, s81, 0x2000
	s_nop 0
	global_load_lds_dwordx4 v[148:149], off
	s_waitcnt vmcnt(6)
	s_setprio 1
	s_barrier
	v_mfma_f32_16x16x32_bf16 v[48:51], v[196:199], v[164:167], v[48:51]
	v_mfma_f32_16x16x32_bf16 v[40:43], v[204:207], v[164:167], v[40:43]
	v_mfma_f32_16x16x32_bf16 v[32:35], v[196:199], v[172:175], v[32:35]
	v_mfma_f32_16x16x32_bf16 v[24:27], v[204:207], v[172:175], v[24:27]
	v_mfma_f32_16x16x32_bf16 v[16:19], v[196:199], v[180:183], v[16:19]
	v_mfma_f32_16x16x32_bf16 v[8:11], v[204:207], v[180:183], v[8:11]
	v_mfma_f32_16x16x32_bf16 v[4:7], v[196:199], v[188:191], v[4:7]
	v_mfma_f32_16x16x32_bf16 v[0:3], v[204:207], v[188:191], v[0:3]
	v_mfma_f32_16x16x32_bf16 v[48:51], v[200:203], v[168:171], v[48:51]
	v_mfma_f32_16x16x32_bf16 v[40:43], v[212:215], v[168:171], v[40:43]
	v_mfma_f32_16x16x32_bf16 v[32:35], v[200:203], v[176:179], v[32:35]
	v_mfma_f32_16x16x32_bf16 v[24:27], v[212:215], v[176:179], v[24:27]
	v_mfma_f32_16x16x32_bf16 v[16:19], v[200:203], v[184:187], v[16:19]
	v_mfma_f32_16x16x32_bf16 v[8:11], v[212:215], v[184:187], v[8:11]
	v_mfma_f32_16x16x32_bf16 v[4:7], v[200:203], v[192:195], v[4:7]
	v_mfma_f32_16x16x32_bf16 v[0:3], v[212:215], v[192:195], v[0:3]
	s_setprio 0
	s_add_i32 s81, 0, 0x18000
	v_add_u32_e32 v147, s81, v144
	s_barrier
	ds_read_b128 v[148:151], v147
	ds_read_b128 v[152:155], v147 offset:1024
	ds_read_b128 v[156:159], v147 offset:2048
	ds_read_b128 v[160:163], v147 offset:3072
	s_add_u32 s50, s50, 0x40000
	s_addc_u32 s51, s51, 0
	s_mov_b32 m0, s71
	v_lshl_add_u64 v[196:197], s[50:51], 0, v[130:131]
	ds_read_b128 v[164:167], v146 offset:32768
	ds_read_b128 v[168:171], v146 offset:33792
	ds_read_b128 v[172:175], v146 offset:34816
	ds_read_b128 v[176:179], v146 offset:35840
	ds_read_b128 v[180:183], v146 offset:36864
	ds_read_b128 v[184:187], v146 offset:37888
	ds_read_b128 v[188:191], v146 offset:38912
	ds_read_b128 v[192:195], v146 offset:39936
	global_load_lds_dwordx4 v[196:197], off
	v_lshl_add_u64 v[196:197], s[50:51], 0, v[132:133]
	s_mov_b32 m0, s72
	s_nop 0
	global_load_lds_dwordx4 v[196:197], off
	s_waitcnt lgkmcnt(8)
	s_waitcnt lgkmcnt(0)
	s_setprio 1
	s_barrier
	v_mfma_f32_16x16x32_bf16 v[124:127], v[148:151], v[164:167], v[124:127]
	v_mfma_f32_16x16x32_bf16 v[120:123], v[156:159], v[164:167], v[120:123]
	v_mfma_f32_16x16x32_bf16 v[116:119], v[148:151], v[172:175], v[116:119]
	v_mfma_f32_16x16x32_bf16 v[108:111], v[156:159], v[172:175], v[108:111]
	v_mfma_f32_16x16x32_bf16 v[100:103], v[148:151], v[180:183], v[100:103]
	v_mfma_f32_16x16x32_bf16 v[92:95], v[156:159], v[180:183], v[92:95]
	v_mfma_f32_16x16x32_bf16 v[84:87], v[148:151], v[188:191], v[84:87]
	v_mfma_f32_16x16x32_bf16 v[76:79], v[156:159], v[188:191], v[76:79]
	v_mfma_f32_16x16x32_bf16 v[124:127], v[152:155], v[168:171], v[124:127]
	v_mfma_f32_16x16x32_bf16 v[120:123], v[160:163], v[168:171], v[120:123]
	v_mfma_f32_16x16x32_bf16 v[116:119], v[152:155], v[176:179], v[116:119]
	v_mfma_f32_16x16x32_bf16 v[108:111], v[160:163], v[176:179], v[108:111]
	v_mfma_f32_16x16x32_bf16 v[100:103], v[152:155], v[184:187], v[100:103]
	v_mfma_f32_16x16x32_bf16 v[92:95], v[160:163], v[184:187], v[92:95]
	v_mfma_f32_16x16x32_bf16 v[84:87], v[152:155], v[192:195], v[84:87]
	v_mfma_f32_16x16x32_bf16 v[76:79], v[160:163], v[192:195], v[76:79]
	s_setprio 0
	s_barrier
	s_add_i32 s50, 0, 0x1c000
	s_add_i32 s51, s81, s69
	v_add_u32_e32 v147, s50, v144
	v_lshl_add_u64 v[140:141], v[140:141], 0, s[2:3]
	s_mov_b32 m0, s51
	ds_read_b128 v[196:199], v147
	ds_read_b128 v[200:203], v147 offset:1024
	ds_read_b128 v[204:207], v147 offset:2048
	ds_read_b128 v[212:215], v147 offset:3072
	global_load_lds_dwordx4 v[140:141], off
	v_lshl_add_u64 v[140:141], v[208:209], 0, s[2:3]
	s_add_i32 m0, s51, 0x2000
	s_nop 0
	global_load_lds_dwordx4 v[140:141], off
	s_waitcnt lgkmcnt(0)
	s_setprio 1
	s_barrier
	v_mfma_f32_16x16x32_bf16 v[112:115], v[196:199], v[164:167], v[112:115]
	v_mfma_f32_16x16x32_bf16 v[104:107], v[204:207], v[164:167], v[104:107]
	v_mfma_f32_16x16x32_bf16 v[96:99], v[196:199], v[172:175], v[96:99]
	v_mfma_f32_16x16x32_bf16 v[88:91], v[204:207], v[172:175], v[88:91]
	v_mfma_f32_16x16x32_bf16 v[80:83], v[196:199], v[180:183], v[80:83]
	v_mfma_f32_16x16x32_bf16 v[72:75], v[204:207], v[180:183], v[72:75]
	v_mfma_f32_16x16x32_bf16 v[68:71], v[196:199], v[188:191], v[68:71]
	v_mfma_f32_16x16x32_bf16 v[64:67], v[204:207], v[188:191], v[64:67]
	v_mfma_f32_16x16x32_bf16 v[112:115], v[200:203], v[168:171], v[112:115]
	v_mfma_f32_16x16x32_bf16 v[104:107], v[212:215], v[168:171], v[104:107]
	v_mfma_f32_16x16x32_bf16 v[96:99], v[200:203], v[176:179], v[96:99]
	v_mfma_f32_16x16x32_bf16 v[88:91], v[212:215], v[176:179], v[88:91]
	v_mfma_f32_16x16x32_bf16 v[80:83], v[200:203], v[184:187], v[80:83]
	v_mfma_f32_16x16x32_bf16 v[72:75], v[212:215], v[184:187], v[72:75]
	v_mfma_f32_16x16x32_bf16 v[68:71], v[200:203], v[192:195], v[68:71]
	v_mfma_f32_16x16x32_bf16 v[64:67], v[212:215], v[192:195], v[64:67]
	s_setprio 0
	s_mov_b32 m0, s0
	v_lshl_add_u64 v[140:141], v[216:217], 0, s[2:3]
	s_barrier
	ds_read_b128 v[164:167], v146 offset:49152
	ds_read_b128 v[168:171], v146 offset:50176
	ds_read_b128 v[172:175], v146 offset:51200
	ds_read_b128 v[176:179], v146 offset:52224
	ds_read_b128 v[180:183], v146 offset:53248
	ds_read_b128 v[184:187], v146 offset:54272
	ds_read_b128 v[188:191], v146 offset:55296
	ds_read_b128 v[192:195], v146 offset:56320
	global_load_lds_dwordx4 v[140:141], off
	v_lshl_add_u64 v[140:141], v[218:219], 0, s[2:3]
	s_mov_b32 m0, s73
	s_nop 0
	global_load_lds_dwordx4 v[140:141], off
	s_waitcnt lgkmcnt(0)
	s_setprio 1
	s_barrier
	v_mfma_f32_16x16x32_bf16 v[60:63], v[148:151], v[164:167], v[60:63]
	v_mfma_f32_16x16x32_bf16 v[56:59], v[156:159], v[164:167], v[56:59]
	v_mfma_f32_16x16x32_bf16 v[52:55], v[148:151], v[172:175], v[52:55]
	v_mfma_f32_16x16x32_bf16 v[44:47], v[156:159], v[172:175], v[44:47]
	v_mfma_f32_16x16x32_bf16 v[36:39], v[148:151], v[180:183], v[36:39]
	v_mfma_f32_16x16x32_bf16 v[28:31], v[156:159], v[180:183], v[28:31]
	v_mfma_f32_16x16x32_bf16 v[20:23], v[148:151], v[188:191], v[20:23]
	v_mfma_f32_16x16x32_bf16 v[12:15], v[156:159], v[188:191], v[12:15]
	v_mfma_f32_16x16x32_bf16 v[60:63], v[152:155], v[168:171], v[60:63]
	v_mfma_f32_16x16x32_bf16 v[56:59], v[160:163], v[168:171], v[56:59]
	v_mfma_f32_16x16x32_bf16 v[52:55], v[152:155], v[176:179], v[52:55]
	v_mfma_f32_16x16x32_bf16 v[44:47], v[160:163], v[176:179], v[44:47]
	v_mfma_f32_16x16x32_bf16 v[36:39], v[152:155], v[184:187], v[36:39]
	v_mfma_f32_16x16x32_bf16 v[28:31], v[160:163], v[184:187], v[28:31]
	v_mfma_f32_16x16x32_bf16 v[20:23], v[152:155], v[192:195], v[20:23]
	v_mfma_f32_16x16x32_bf16 v[12:15], v[160:163], v[192:195], v[12:15]
	s_setprio 0
	s_barrier
	s_add_u32 s48, s48, 0x40080
	s_addc_u32 s49, s49, 0
	s_add_i32 s50, s50, s69
	v_lshl_add_u64 v[140:141], s[48:49], 0, v[128:129]
	s_mov_b32 m0, s50
	s_nop 0
	global_load_lds_dwordx4 v[140:141], off
	v_lshl_add_u64 v[140:141], s[48:49], 0, v[134:135]
	s_add_i32 m0, s50, 0x2000
	s_nop 0
	global_load_lds_dwordx4 v[140:141], off
	s_waitcnt vmcnt(6)
	s_setprio 1
	s_barrier
	v_mfma_f32_16x16x32_bf16 v[48:51], v[196:199], v[164:167], v[48:51]
	v_mfma_f32_16x16x32_bf16 v[40:43], v[204:207], v[164:167], v[40:43]
	v_mfma_f32_16x16x32_bf16 v[32:35], v[196:199], v[172:175], v[32:35]
	v_mfma_f32_16x16x32_bf16 v[24:27], v[204:207], v[172:175], v[24:27]
	v_mfma_f32_16x16x32_bf16 v[16:19], v[196:199], v[180:183], v[16:19]
	v_mfma_f32_16x16x32_bf16 v[8:11], v[204:207], v[180:183], v[8:11]
	v_mfma_f32_16x16x32_bf16 v[4:7], v[196:199], v[188:191], v[4:7]
	v_mfma_f32_16x16x32_bf16 v[0:3], v[204:207], v[188:191], v[0:3]
	v_mfma_f32_16x16x32_bf16 v[48:51], v[200:203], v[168:171], v[48:51]
	v_mfma_f32_16x16x32_bf16 v[40:43], v[212:215], v[168:171], v[40:43]
	v_mfma_f32_16x16x32_bf16 v[32:35], v[200:203], v[176:179], v[32:35]
	v_mfma_f32_16x16x32_bf16 v[24:27], v[212:215], v[176:179], v[24:27]
	v_mfma_f32_16x16x32_bf16 v[16:19], v[200:203], v[184:187], v[16:19]
	v_mfma_f32_16x16x32_bf16 v[8:11], v[212:215], v[184:187], v[8:11]
	v_mfma_f32_16x16x32_bf16 v[4:7], v[200:203], v[192:195], v[4:7]
	v_mfma_f32_16x16x32_bf16 v[0:3], v[212:215], v[192:195], v[0:3]
	s_setprio 0
	s_add_i32 s80, s80, 2
	s_add_u32 s42, s42, 0x100
	s_addc_u32 s43, s43, 0
	s_add_u32 s78, s78, 0x100
	s_addc_u32 s79, s79, 0
	s_cmp_gt_u32 s80, 13
	s_barrier
	s_cbranch_scc0 .LBB0_200
	v_lshl_add_u32 v148, s36, 8, v143
	v_ashrrev_i32_e32 v149, 31, v148
	v_lshl_or_b32 v140, s75, 8, v145
	v_ashrrev_i32_e32 v141, 31, v140
	v_lshlrev_b64 v[150:151], 10, v[148:149]
	v_lshl_add_u64 v[150:151], s[14:15], 0, v[150:151]
	v_lshlrev_b64 v[152:153], 1, v[140:141]
	v_lshl_add_u64 v[140:141], v[150:151], 0, v[152:153]
	v_cvt_pk_bf16_f32 v124, v124, v125
	v_cvt_pk_bf16_f32 v125, v126, v127
	v_cvt_pk_bf16_f32 v126, v120, v121
	v_cvt_pk_bf16_f32 v127, v122, v123
	global_store_dwordx4 v[140:141], v[124:127], off nt
	v_cvt_pk_bf16_f32 v112, v112, v113
	v_cvt_pk_bf16_f32 v113, v114, v115
	v_cvt_pk_bf16_f32 v114, v104, v105
	v_or_b32_e32 v104, 16, v148
	v_ashrrev_i32_e32 v105, 31, v104
	v_lshlrev_b64 v[104:105], 10, v[104:105]
	v_lshl_add_u64 v[104:105], s[14:15], 0, v[104:105]
	v_cvt_pk_bf16_f32 v115, v106, v107
	global_store_dwordx4 v[140:141], v[112:115], off offset:256 nt
	s_mov_b32 s31, 0x20000
	s_mov_b64 s[42:43], 0x20000
	v_lshl_add_u64 v[112:113], v[104:105], 0, v[152:153]
	v_cvt_pk_bf16_f32 v104, v116, v117
	v_cvt_pk_bf16_f32 v105, v118, v119
	v_cvt_pk_bf16_f32 v106, v108, v109
	v_cvt_pk_bf16_f32 v107, v110, v111
	global_store_dwordx4 v[112:113], v[104:107], off nt
	v_cvt_pk_bf16_f32 v96, v96, v97
	v_cvt_pk_bf16_f32 v97, v98, v99
	v_cvt_pk_bf16_f32 v98, v88, v89
	v_or_b32_e32 v88, 32, v148
	v_ashrrev_i32_e32 v89, 31, v88
	v_lshlrev_b64 v[88:89], 10, v[88:89]
	v_lshl_add_u64 v[88:89], s[14:15], 0, v[88:89]
	v_cvt_pk_bf16_f32 v99, v90, v91
	global_store_dwordx4 v[112:113], v[96:99], off offset:256 nt
	s_mov_b32 s75, s30
	s_mov_b32 s36, s34
	v_lshl_add_u64 v[96:97], v[88:89], 0, v[152:153]
	v_cvt_pk_bf16_f32 v88, v100, v101
	v_cvt_pk_bf16_f32 v89, v102, v103
	v_cvt_pk_bf16_f32 v90, v92, v93
	v_cvt_pk_bf16_f32 v91, v94, v95
	global_store_dwordx4 v[96:97], v[88:91], off nt
	v_cvt_pk_bf16_f32 v80, v80, v81
	v_cvt_pk_bf16_f32 v81, v82, v83
	v_cvt_pk_bf16_f32 v82, v72, v73
	v_or_b32_e32 v72, 48, v148
	v_ashrrev_i32_e32 v73, 31, v72
	v_lshlrev_b64 v[72:73], 10, v[72:73]
	v_lshl_add_u64 v[72:73], s[14:15], 0, v[72:73]
	v_cvt_pk_bf16_f32 v83, v74, v75
	global_store_dwordx4 v[96:97], v[80:83], off offset:256 nt
	s_mov_b64 s[48:49], s[40:41]
	s_nop 0
	v_lshl_add_u64 v[80:81], v[72:73], 0, v[152:153]
	v_cvt_pk_bf16_f32 v72, v84, v85
	v_cvt_pk_bf16_f32 v73, v86, v87
	v_cvt_pk_bf16_f32 v74, v76, v77
	v_cvt_pk_bf16_f32 v75, v78, v79
	global_store_dwordx4 v[80:81], v[72:75], off nt
	v_cvt_pk_bf16_f32 v68, v68, v69
	v_cvt_pk_bf16_f32 v69, v70, v71
	v_cvt_pk_bf16_f32 v70, v64, v65
	v_cvt_pk_bf16_f32 v71, v66, v67
	global_store_dwordx4 v[80:81], v[68:71], off offset:256 nt
	v_cvt_pk_bf16_f32 v60, v60, v61
	v_cvt_pk_bf16_f32 v61, v62, v63
	v_cvt_pk_bf16_f32 v62, v56, v57
	v_add_co_u32_e32 v56, vcc, s31, v140
	v_lshl_add_u64 v[64:65], v[140:141], 0, s[42:43]
	s_nop 0
	v_addc_co_u32_e32 v57, vcc, 0, v141, vcc
	s_mov_b32 s31, 0x24000
	v_cvt_pk_bf16_f32 v63, v58, v59
	global_store_dwordx4 v[56:57], v[60:63], off nt
	v_cvt_pk_bf16_f32 v48, v48, v49
	v_cvt_pk_bf16_f32 v49, v50, v51
	v_cvt_pk_bf16_f32 v50, v40, v41
	v_cvt_pk_bf16_f32 v51, v42, v43
	global_store_dwordx4 v[64:65], v[48:51], off offset:256 nt
	s_mov_b64 s[42:43], 0x24000
	v_cvt_pk_bf16_f32 v40, v52, v53
	v_cvt_pk_bf16_f32 v41, v54, v55
	v_cvt_pk_bf16_f32 v42, v44, v45
	v_add_co_u32_e32 v44, vcc, s31, v140
	v_lshl_add_u64 v[48:49], v[140:141], 0, s[42:43]
	s_nop 0
	v_addc_co_u32_e32 v45, vcc, 0, v141, vcc
	s_mov_b32 s31, 0x28000
	v_cvt_pk_bf16_f32 v43, v46, v47
	global_store_dwordx4 v[44:45], v[40:43], off nt
	v_cvt_pk_bf16_f32 v32, v32, v33
	v_cvt_pk_bf16_f32 v33, v34, v35
	v_cvt_pk_bf16_f32 v34, v24, v25
	v_cvt_pk_bf16_f32 v35, v26, v27
	global_store_dwordx4 v[48:49], v[32:35], off offset:256 nt
	s_mov_b64 s[42:43], 0x28000
	v_cvt_pk_bf16_f32 v24, v36, v37
	v_cvt_pk_bf16_f32 v25, v38, v39
	v_cvt_pk_bf16_f32 v26, v28, v29
	v_add_co_u32_e32 v28, vcc, s31, v140
	v_lshl_add_u64 v[32:33], v[140:141], 0, s[42:43]
	s_nop 0
	v_addc_co_u32_e32 v29, vcc, 0, v141, vcc
	s_mov_b32 s31, 0x2c000
	v_cvt_pk_bf16_f32 v27, v30, v31
	global_store_dwordx4 v[28:29], v[24:27], off nt
	v_cvt_pk_bf16_f32 v16, v16, v17
	v_cvt_pk_bf16_f32 v17, v18, v19
	v_cvt_pk_bf16_f32 v18, v8, v9
	v_cvt_pk_bf16_f32 v19, v10, v11
	global_store_dwordx4 v[32:33], v[16:19], off offset:256 nt
	v_cvt_pk_bf16_f32 v8, v20, v21
	v_cvt_pk_bf16_f32 v9, v22, v23
	v_cvt_pk_bf16_f32 v10, v12, v13
	v_add_co_u32_e32 v12, vcc, s31, v140
	s_mov_b64 s[42:43], 0x2c000
	s_nop 0
	v_addc_co_u32_e32 v13, vcc, 0, v141, vcc
	v_lshl_add_u64 v[16:17], v[140:141], 0, s[42:43]
	s_and_b64 vcc, exec, s[28:29]
	s_mov_b64 s[42:43], s[38:39]
	v_cvt_pk_bf16_f32 v11, v14, v15
	global_store_dwordx4 v[12:13], v[8:11], off nt
	v_cvt_pk_bf16_f32 v4, v4, v5
	v_cvt_pk_bf16_f32 v5, v6, v7
	v_cvt_pk_bf16_f32 v6, v0, v1
	v_cvt_pk_bf16_f32 v7, v2, v3
	global_store_dwordx4 v[16:17], v[4:7], off offset:256 nt
	s_cbranch_vccz .LBB0_193
	s_waitcnt vmcnt(0)
	s_cmpk_gt_u32 s65, 0xff
	s_cbranch_scc1 .LBB0_204
	s_barrier

.LBB0_220:
	s_add_u32 s40, s38, 0xfffc0080
	s_addc_u32 s41, s39, -1
	s_add_i32 s76, 0, 0x10000
	v_add_u32_e32 v140, s76, v144
	ds_read_b128 v[148:151], v140
	ds_read_b128 v[152:155], v140 offset:1024
	ds_read_b128 v[156:159], v140 offset:2048
	ds_read_b128 v[160:163], v140 offset:3072
	s_cmp_eq_u32 s75, 12
	s_cselect_b32 s43, s29, s41
	s_cselect_b32 s42, s71, s40
	s_cselect_b32 s41, s15, s74
	s_cselect_b32 s40, s72, s73
	v_lshl_add_u64 v[140:141], s[38:39], 0, v[136:137]
	s_add_i32 m0, s31, 0xc000
	ds_read_b128 v[164:167], v146
	ds_read_b128 v[168:171], v146 offset:1024
	ds_read_b128 v[172:175], v146 offset:2048
	ds_read_b128 v[176:179], v146 offset:3072
	ds_read_b128 v[180:183], v146 offset:4096
	ds_read_b128 v[184:187], v146 offset:5120
	ds_read_b128 v[188:191], v146 offset:6144
	ds_read_b128 v[192:195], v146 offset:7168
	global_load_lds_dwordx4 v[140:141], off
	v_lshl_add_u64 v[140:141], s[38:39], 0, v[138:139]
	s_add_i32 m0, s31, 0xe000
	s_nop 0
	global_load_lds_dwordx4 v[140:141], off
	s_waitcnt lgkmcnt(8)
	s_waitcnt lgkmcnt(0)
	s_setprio 1
	s_barrier
	v_mfma_f32_16x16x32_bf16 v[124:127], v[148:151], v[164:167], v[124:127]
	v_mfma_f32_16x16x32_bf16 v[120:123], v[156:159], v[164:167], v[120:123]
	v_mfma_f32_16x16x32_bf16 v[116:119], v[148:151], v[172:175], v[116:119]
	v_mfma_f32_16x16x32_bf16 v[108:111], v[156:159], v[172:175], v[108:111]
	v_mfma_f32_16x16x32_bf16 v[100:103], v[148:151], v[180:183], v[100:103]
	v_mfma_f32_16x16x32_bf16 v[92:95], v[156:159], v[180:183], v[92:95]
	v_mfma_f32_16x16x32_bf16 v[84:87], v[148:151], v[188:191], v[84:87]
	v_mfma_f32_16x16x32_bf16 v[76:79], v[156:159], v[188:191], v[76:79]
	v_mfma_f32_16x16x32_bf16 v[124:127], v[152:155], v[168:171], v[124:127]
	v_mfma_f32_16x16x32_bf16 v[120:123], v[160:163], v[168:171], v[120:123]
	v_mfma_f32_16x16x32_bf16 v[116:119], v[152:155], v[176:179], v[116:119]
	v_mfma_f32_16x16x32_bf16 v[108:111], v[160:163], v[176:179], v[108:111]
	v_mfma_f32_16x16x32_bf16 v[100:103], v[152:155], v[184:187], v[100:103]
	v_mfma_f32_16x16x32_bf16 v[92:95], v[160:163], v[184:187], v[92:95]
	v_mfma_f32_16x16x32_bf16 v[84:87], v[152:155], v[192:195], v[84:87]
	v_mfma_f32_16x16x32_bf16 v[76:79], v[160:163], v[192:195], v[76:79]
	s_setprio 0
	s_barrier
	s_add_i32 s78, 0, 0x14000
	v_add_u32_e32 v140, s78, v144
	s_add_i32 s76, s76, s64
	ds_read_b128 v[196:199], v140
	ds_read_b128 v[200:203], v140 offset:1024
	ds_read_b128 v[204:207], v140 offset:2048
	ds_read_b128 v[212:215], v140 offset:3072
	v_lshl_add_u64 v[140:141], s[40:41], 0, v[128:129]
	s_mov_b32 m0, s76
	v_lshl_add_u64 v[208:209], s[40:41], 0, v[134:135]
	global_load_lds_dwordx4 v[140:141], off
	s_add_i32 m0, s76, 0x2000
	s_nop 0
	global_load_lds_dwordx4 v[208:209], off
	s_waitcnt lgkmcnt(0)
	s_setprio 1
	s_barrier
	v_mfma_f32_16x16x32_bf16 v[112:115], v[196:199], v[164:167], v[112:115]
	v_mfma_f32_16x16x32_bf16 v[104:107], v[204:207], v[164:167], v[104:107]
	v_mfma_f32_16x16x32_bf16 v[96:99], v[196:199], v[172:175], v[96:99]
	v_mfma_f32_16x16x32_bf16 v[88:91], v[204:207], v[172:175], v[88:91]
	v_mfma_f32_16x16x32_bf16 v[80:83], v[196:199], v[180:183], v[80:83]
	v_mfma_f32_16x16x32_bf16 v[72:75], v[204:207], v[180:183], v[72:75]
	v_mfma_f32_16x16x32_bf16 v[68:71], v[196:199], v[188:191], v[68:71]
	v_mfma_f32_16x16x32_bf16 v[64:67], v[204:207], v[188:191], v[64:67]
	v_mfma_f32_16x16x32_bf16 v[112:115], v[200:203], v[168:171], v[112:115]
	v_mfma_f32_16x16x32_bf16 v[104:107], v[212:215], v[168:171], v[104:107]
	v_mfma_f32_16x16x32_bf16 v[96:99], v[200:203], v[176:179], v[96:99]
	v_mfma_f32_16x16x32_bf16 v[88:91], v[212:215], v[176:179], v[88:91]
	v_mfma_f32_16x16x32_bf16 v[80:83], v[200:203], v[184:187], v[80:83]
	v_mfma_f32_16x16x32_bf16 v[72:75], v[212:215], v[184:187], v[72:75]
	v_mfma_f32_16x16x32_bf16 v[68:71], v[200:203], v[192:195], v[68:71]
	v_mfma_f32_16x16x32_bf16 v[64:67], v[212:215], v[192:195], v[64:67]
	s_setprio 0
	s_mov_b32 m0, s31
	v_lshl_add_u64 v[216:217], s[42:43], 0, v[130:131]
	s_barrier
	ds_read_b128 v[164:167], v146 offset:16384
	ds_read_b128 v[168:171], v146 offset:17408
	ds_read_b128 v[172:175], v146 offset:18432
	ds_read_b128 v[176:179], v146 offset:19456
	ds_read_b128 v[180:183], v146 offset:20480
	ds_read_b128 v[184:187], v146 offset:21504
	ds_read_b128 v[188:191], v146 offset:22528
	ds_read_b128 v[192:195], v146 offset:23552
	global_load_lds_dwordx4 v[216:217], off
	v_lshl_add_u64 v[218:219], s[42:43], 0, v[132:133]
	s_mov_b32 m0, s65
	s_nop 0
	global_load_lds_dwordx4 v[218:219], off
	s_waitcnt lgkmcnt(0)
	s_setprio 1
	s_barrier
	v_mfma_f32_16x16x32_bf16 v[60:63], v[148:151], v[164:167], v[60:63]
	v_mfma_f32_16x16x32_bf16 v[56:59], v[156:159], v[164:167], v[56:59]
	v_mfma_f32_16x16x32_bf16 v[52:55], v[148:151], v[172:175], v[52:55]
	v_mfma_f32_16x16x32_bf16 v[44:47], v[156:159], v[172:175], v[44:47]
	v_mfma_f32_16x16x32_bf16 v[36:39], v[148:151], v[180:183], v[36:39]
	v_mfma_f32_16x16x32_bf16 v[28:31], v[156:159], v[180:183], v[28:31]
	v_mfma_f32_16x16x32_bf16 v[20:23], v[148:151], v[188:191], v[20:23]
	v_mfma_f32_16x16x32_bf16 v[12:15], v[156:159], v[188:191], v[12:15]
	v_mfma_f32_16x16x32_bf16 v[60:63], v[152:155], v[168:171], v[60:63]
	v_mfma_f32_16x16x32_bf16 v[56:59], v[160:163], v[168:171], v[56:59]
	v_mfma_f32_16x16x32_bf16 v[52:55], v[152:155], v[176:179], v[52:55]
	v_mfma_f32_16x16x32_bf16 v[44:47], v[160:163], v[176:179], v[44:47]
	v_mfma_f32_16x16x32_bf16 v[36:39], v[152:155], v[184:187], v[36:39]
	v_mfma_f32_16x16x32_bf16 v[28:31], v[160:163], v[184:187], v[28:31]
	v_mfma_f32_16x16x32_bf16 v[20:23], v[152:155], v[192:195], v[20:23]
	v_mfma_f32_16x16x32_bf16 v[12:15], v[160:163], v[192:195], v[12:15]
	s_setprio 0
	s_barrier
	s_add_u32 s76, s40, 0x40000
	s_addc_u32 s77, s41, 0
	s_add_i32 s78, s78, s64
	v_lshl_add_u64 v[148:149], s[76:77], 0, v[128:129]
	s_mov_b32 m0, s78
	s_nop 0
	global_load_lds_dwordx4 v[148:149], off
	v_lshl_add_u64 v[148:149], s[76:77], 0, v[134:135]
	s_add_i32 m0, s78, 0x2000
	s_nop 0
	global_load_lds_dwordx4 v[148:149], off
	s_waitcnt vmcnt(6)
	s_setprio 1
	s_barrier
	v_mfma_f32_16x16x32_bf16 v[48:51], v[196:199], v[164:167], v[48:51]
	v_mfma_f32_16x16x32_bf16 v[40:43], v[204:207], v[164:167], v[40:43]
	v_mfma_f32_16x16x32_bf16 v[32:35], v[196:199], v[172:175], v[32:35]
	v_mfma_f32_16x16x32_bf16 v[24:27], v[204:207], v[172:175], v[24:27]
	v_mfma_f32_16x16x32_bf16 v[16:19], v[196:199], v[180:183], v[16:19]
	v_mfma_f32_16x16x32_bf16 v[8:11], v[204:207], v[180:183], v[8:11]
	v_mfma_f32_16x16x32_bf16 v[4:7], v[196:199], v[188:191], v[4:7]
	v_mfma_f32_16x16x32_bf16 v[0:3], v[204:207], v[188:191], v[0:3]
	v_mfma_f32_16x16x32_bf16 v[48:51], v[200:203], v[168:171], v[48:51]
	v_mfma_f32_16x16x32_bf16 v[40:43], v[212:215], v[168:171], v[40:43]
	v_mfma_f32_16x16x32_bf16 v[32:35], v[200:203], v[176:179], v[32:35]
	v_mfma_f32_16x16x32_bf16 v[24:27], v[212:215], v[176:179], v[24:27]
	v_mfma_f32_16x16x32_bf16 v[16:19], v[200:203], v[184:187], v[16:19]
	v_mfma_f32_16x16x32_bf16 v[8:11], v[212:215], v[184:187], v[8:11]
	v_mfma_f32_16x16x32_bf16 v[4:7], v[200:203], v[192:195], v[4:7]
	v_mfma_f32_16x16x32_bf16 v[0:3], v[212:215], v[192:195], v[0:3]
	s_setprio 0
	s_add_i32 s76, 0, 0x18000
	v_add_u32_e32 v147, s76, v144
	s_barrier
	ds_read_b128 v[148:151], v147
	ds_read_b128 v[152:155], v147 offset:1024
	ds_read_b128 v[156:159], v147 offset:2048
	ds_read_b128 v[160:163], v147 offset:3072
	s_add_u32 s42, s42, 0x40000
	s_addc_u32 s43, s43, 0
	s_mov_b32 m0, s66
	v_lshl_add_u64 v[196:197], s[42:43], 0, v[130:131]
	ds_read_b128 v[164:167], v146 offset:32768
	ds_read_b128 v[168:171], v146 offset:33792
	ds_read_b128 v[172:175], v146 offset:34816
	ds_read_b128 v[176:179], v146 offset:35840
	ds_read_b128 v[180:183], v146 offset:36864
	ds_read_b128 v[184:187], v146 offset:37888
	ds_read_b128 v[188:191], v146 offset:38912
	ds_read_b128 v[192:195], v146 offset:39936
	global_load_lds_dwordx4 v[196:197], off
	v_lshl_add_u64 v[196:197], s[42:43], 0, v[132:133]
	s_mov_b32 m0, s67
	s_nop 0
	global_load_lds_dwordx4 v[196:197], off
	s_waitcnt lgkmcnt(8)
	s_waitcnt lgkmcnt(0)
	s_setprio 1
	s_barrier
	v_mfma_f32_16x16x32_bf16 v[124:127], v[148:151], v[164:167], v[124:127]
	v_mfma_f32_16x16x32_bf16 v[120:123], v[156:159], v[164:167], v[120:123]
	v_mfma_f32_16x16x32_bf16 v[116:119], v[148:151], v[172:175], v[116:119]
	v_mfma_f32_16x16x32_bf16 v[108:111], v[156:159], v[172:175], v[108:111]
	v_mfma_f32_16x16x32_bf16 v[100:103], v[148:151], v[180:183], v[100:103]
	v_mfma_f32_16x16x32_bf16 v[92:95], v[156:159], v[180:183], v[92:95]
	v_mfma_f32_16x16x32_bf16 v[84:87], v[148:151], v[188:191], v[84:87]
	v_mfma_f32_16x16x32_bf16 v[76:79], v[156:159], v[188:191], v[76:79]
	v_mfma_f32_16x16x32_bf16 v[124:127], v[152:155], v[168:171], v[124:127]
	v_mfma_f32_16x16x32_bf16 v[120:123], v[160:163], v[168:171], v[120:123]
	v_mfma_f32_16x16x32_bf16 v[116:119], v[152:155], v[176:179], v[116:119]
	v_mfma_f32_16x16x32_bf16 v[108:111], v[160:163], v[176:179], v[108:111]
	v_mfma_f32_16x16x32_bf16 v[100:103], v[152:155], v[184:187], v[100:103]
	v_mfma_f32_16x16x32_bf16 v[92:95], v[160:163], v[184:187], v[92:95]
	v_mfma_f32_16x16x32_bf16 v[84:87], v[152:155], v[192:195], v[84:87]
	v_mfma_f32_16x16x32_bf16 v[76:79], v[160:163], v[192:195], v[76:79]
	s_setprio 0
	s_barrier
	s_add_i32 s42, 0, 0x1c000
	s_add_i32 s43, s76, s64
	v_add_u32_e32 v147, s42, v144
	v_lshl_add_u64 v[140:141], v[140:141], 0, s[2:3]
	s_mov_b32 m0, s43
	ds_read_b128 v[196:199], v147
	ds_read_b128 v[200:203], v147 offset:1024
	ds_read_b128 v[204:207], v147 offset:2048
	ds_read_b128 v[212:215], v147 offset:3072
	global_load_lds_dwordx4 v[140:141], off
	v_lshl_add_u64 v[140:141], v[208:209], 0, s[2:3]
	s_add_i32 m0, s43, 0x2000
	s_nop 0
	global_load_lds_dwordx4 v[140:141], off
	s_waitcnt lgkmcnt(0)
	s_setprio 1
	s_barrier
	v_mfma_f32_16x16x32_bf16 v[112:115], v[196:199], v[164:167], v[112:115]
	v_mfma_f32_16x16x32_bf16 v[104:107], v[204:207], v[164:167], v[104:107]
	v_mfma_f32_16x16x32_bf16 v[96:99], v[196:199], v[172:175], v[96:99]
	v_mfma_f32_16x16x32_bf16 v[88:91], v[204:207], v[172:175], v[88:91]
	v_mfma_f32_16x16x32_bf16 v[80:83], v[196:199], v[180:183], v[80:83]
	v_mfma_f32_16x16x32_bf16 v[72:75], v[204:207], v[180:183], v[72:75]
	v_mfma_f32_16x16x32_bf16 v[68:71], v[196:199], v[188:191], v[68:71]
	v_mfma_f32_16x16x32_bf16 v[64:67], v[204:207], v[188:191], v[64:67]
	v_mfma_f32_16x16x32_bf16 v[112:115], v[200:203], v[168:171], v[112:115]
	v_mfma_f32_16x16x32_bf16 v[104:107], v[212:215], v[168:171], v[104:107]
	v_mfma_f32_16x16x32_bf16 v[96:99], v[200:203], v[176:179], v[96:99]
	v_mfma_f32_16x16x32_bf16 v[88:91], v[212:215], v[176:179], v[88:91]
	v_mfma_f32_16x16x32_bf16 v[80:83], v[200:203], v[184:187], v[80:83]
	v_mfma_f32_16x16x32_bf16 v[72:75], v[212:215], v[184:187], v[72:75]
	v_mfma_f32_16x16x32_bf16 v[68:71], v[200:203], v[192:195], v[68:71]
	v_mfma_f32_16x16x32_bf16 v[64:67], v[212:215], v[192:195], v[64:67]
	s_setprio 0
	s_mov_b32 m0, s0
	v_lshl_add_u64 v[140:141], v[216:217], 0, s[2:3]
	s_barrier
	ds_read_b128 v[164:167], v146 offset:49152
	ds_read_b128 v[168:171], v146 offset:50176
	ds_read_b128 v[172:175], v146 offset:51200
	ds_read_b128 v[176:179], v146 offset:52224
	ds_read_b128 v[180:183], v146 offset:53248
	ds_read_b128 v[184:187], v146 offset:54272
	ds_read_b128 v[188:191], v146 offset:55296
	ds_read_b128 v[192:195], v146 offset:56320
	global_load_lds_dwordx4 v[140:141], off
	v_lshl_add_u64 v[140:141], v[218:219], 0, s[2:3]
	s_mov_b32 m0, s68
	s_nop 0
	global_load_lds_dwordx4 v[140:141], off
	s_waitcnt lgkmcnt(0)
	s_setprio 1
	s_barrier
	v_mfma_f32_16x16x32_bf16 v[60:63], v[148:151], v[164:167], v[60:63]
	v_mfma_f32_16x16x32_bf16 v[56:59], v[156:159], v[164:167], v[56:59]
	v_mfma_f32_16x16x32_bf16 v[52:55], v[148:151], v[172:175], v[52:55]
	v_mfma_f32_16x16x32_bf16 v[44:47], v[156:159], v[172:175], v[44:47]
	v_mfma_f32_16x16x32_bf16 v[36:39], v[148:151], v[180:183], v[36:39]
	v_mfma_f32_16x16x32_bf16 v[28:31], v[156:159], v[180:183], v[28:31]
	v_mfma_f32_16x16x32_bf16 v[20:23], v[148:151], v[188:191], v[20:23]
	v_mfma_f32_16x16x32_bf16 v[12:15], v[156:159], v[188:191], v[12:15]
	v_mfma_f32_16x16x32_bf16 v[60:63], v[152:155], v[168:171], v[60:63]
	v_mfma_f32_16x16x32_bf16 v[56:59], v[160:163], v[168:171], v[56:59]
	v_mfma_f32_16x16x32_bf16 v[52:55], v[152:155], v[176:179], v[52:55]
	v_mfma_f32_16x16x32_bf16 v[44:47], v[160:163], v[176:179], v[44:47]
	v_mfma_f32_16x16x32_bf16 v[36:39], v[152:155], v[184:187], v[36:39]
	v_mfma_f32_16x16x32_bf16 v[28:31], v[160:163], v[184:187], v[28:31]
	v_mfma_f32_16x16x32_bf16 v[20:23], v[152:155], v[192:195], v[20:23]
	v_mfma_f32_16x16x32_bf16 v[12:15], v[160:163], v[192:195], v[12:15]
	s_setprio 0
	s_barrier
	s_add_u32 s40, s40, 0x40080
	s_addc_u32 s41, s41, 0
	s_add_i32 s42, s42, s64
	v_lshl_add_u64 v[140:141], s[40:41], 0, v[128:129]
	s_mov_b32 m0, s42
	s_nop 0
	global_load_lds_dwordx4 v[140:141], off
	v_lshl_add_u64 v[140:141], s[40:41], 0, v[134:135]
	s_add_i32 m0, s42, 0x2000
	s_nop 0
	global_load_lds_dwordx4 v[140:141], off
	s_waitcnt vmcnt(6)
	s_setprio 1
	s_barrier
	v_mfma_f32_16x16x32_bf16 v[48:51], v[196:199], v[164:167], v[48:51]
	v_mfma_f32_16x16x32_bf16 v[40:43], v[204:207], v[164:167], v[40:43]
	v_mfma_f32_16x16x32_bf16 v[32:35], v[196:199], v[172:175], v[32:35]
	v_mfma_f32_16x16x32_bf16 v[24:27], v[204:207], v[172:175], v[24:27]
	v_mfma_f32_16x16x32_bf16 v[16:19], v[196:199], v[180:183], v[16:19]
	v_mfma_f32_16x16x32_bf16 v[8:11], v[204:207], v[180:183], v[8:11]
	v_mfma_f32_16x16x32_bf16 v[4:7], v[196:199], v[188:191], v[4:7]
	v_mfma_f32_16x16x32_bf16 v[0:3], v[204:207], v[188:191], v[0:3]
	v_mfma_f32_16x16x32_bf16 v[48:51], v[200:203], v[168:171], v[48:51]
	v_mfma_f32_16x16x32_bf16 v[40:43], v[212:215], v[168:171], v[40:43]
	v_mfma_f32_16x16x32_bf16 v[32:35], v[200:203], v[176:179], v[32:35]
	v_mfma_f32_16x16x32_bf16 v[24:27], v[212:215], v[176:179], v[24:27]
	v_mfma_f32_16x16x32_bf16 v[16:19], v[200:203], v[184:187], v[16:19]
	v_mfma_f32_16x16x32_bf16 v[8:11], v[212:215], v[184:187], v[8:11]
	v_mfma_f32_16x16x32_bf16 v[4:7], v[200:203], v[192:195], v[4:7]
	v_mfma_f32_16x16x32_bf16 v[0:3], v[212:215], v[192:195], v[0:3]
	s_setprio 0
	s_add_i32 s75, s75, 2
	s_add_u32 s38, s38, 0x100
	s_addc_u32 s39, s39, 0
	s_add_u32 s73, s73, 0x100
	s_addc_u32 s74, s74, 0
	s_cmp_gt_u32 s75, 13
	s_barrier
	s_cbranch_scc0 .LBB0_220
	v_lshl_add_u32 v148, s30, 8, v143
	v_ashrrev_i32_e32 v149, 31, v148
	v_lshl_or_b32 v140, s70, 8, v145
	v_ashrrev_i32_e32 v141, 31, v140
	v_lshlrev_b64 v[150:151], 13, v[148:149]
	v_lshl_add_u64 v[150:151], s[8:9], 0, v[150:151]
	v_lshlrev_b64 v[152:153], 1, v[140:141]
	v_lshl_add_u64 v[140:141], v[150:151], 0, v[152:153]
	v_cvt_pk_bf16_f32 v124, v124, v125
	v_cvt_pk_bf16_f32 v125, v126, v127
	v_cvt_pk_bf16_f32 v126, v120, v121
	v_cvt_pk_bf16_f32 v127, v122, v123
	global_store_dwordx4 v[140:141], v[124:127], off nt
	v_cvt_pk_bf16_f32 v112, v112, v113
	v_cvt_pk_bf16_f32 v113, v114, v115
	v_cvt_pk_bf16_f32 v114, v104, v105
	v_or_b32_e32 v104, 16, v148
	v_ashrrev_i32_e32 v105, 31, v104
	v_lshlrev_b64 v[104:105], 13, v[104:105]
	v_lshl_add_u64 v[104:105], s[8:9], 0, v[104:105]
	v_cvt_pk_bf16_f32 v115, v106, v107
	global_store_dwordx4 v[140:141], v[112:115], off offset:256 nt
	s_mov_b32 s15, 0x100000
	s_mov_b64 s[38:39], 0x100000
	v_lshl_add_u64 v[112:113], v[104:105], 0, v[152:153]
	v_cvt_pk_bf16_f32 v104, v116, v117
	v_cvt_pk_bf16_f32 v105, v118, v119
	v_cvt_pk_bf16_f32 v106, v108, v109
	v_cvt_pk_bf16_f32 v107, v110, v111
	global_store_dwordx4 v[112:113], v[104:107], off nt
	v_cvt_pk_bf16_f32 v96, v96, v97
	v_cvt_pk_bf16_f32 v97, v98, v99
	v_cvt_pk_bf16_f32 v98, v88, v89
	v_or_b32_e32 v88, 32, v148
	v_ashrrev_i32_e32 v89, 31, v88
	v_lshlrev_b64 v[88:89], 13, v[88:89]
	v_lshl_add_u64 v[88:89], s[8:9], 0, v[88:89]
	v_cvt_pk_bf16_f32 v99, v90, v91
	global_store_dwordx4 v[112:113], v[96:99], off offset:256 nt
	s_mov_b32 s70, s14
	s_mov_b32 s30, s28
	v_lshl_add_u64 v[96:97], v[88:89], 0, v[152:153]
	v_cvt_pk_bf16_f32 v88, v100, v101
	v_cvt_pk_bf16_f32 v89, v102, v103
	v_cvt_pk_bf16_f32 v90, v92, v93
	v_cvt_pk_bf16_f32 v91, v94, v95
	global_store_dwordx4 v[96:97], v[88:91], off nt
	v_cvt_pk_bf16_f32 v80, v80, v81
	v_cvt_pk_bf16_f32 v81, v82, v83
	v_cvt_pk_bf16_f32 v82, v72, v73
	v_or_b32_e32 v72, 48, v148
	v_ashrrev_i32_e32 v73, 31, v72
	v_lshlrev_b64 v[72:73], 13, v[72:73]
	v_lshl_add_u64 v[72:73], s[8:9], 0, v[72:73]
	v_cvt_pk_bf16_f32 v83, v74, v75
	global_store_dwordx4 v[96:97], v[80:83], off offset:256 nt
	s_mov_b64 s[40:41], s[36:37]
	s_nop 0
	v_lshl_add_u64 v[80:81], v[72:73], 0, v[152:153]
	v_cvt_pk_bf16_f32 v72, v84, v85
	v_cvt_pk_bf16_f32 v73, v86, v87
	v_cvt_pk_bf16_f32 v74, v76, v77
	v_cvt_pk_bf16_f32 v75, v78, v79
	global_store_dwordx4 v[80:81], v[72:75], off nt
	v_cvt_pk_bf16_f32 v68, v68, v69
	v_cvt_pk_bf16_f32 v69, v70, v71
	v_cvt_pk_bf16_f32 v70, v64, v65
	v_cvt_pk_bf16_f32 v71, v66, v67
	global_store_dwordx4 v[80:81], v[68:71], off offset:256 nt
	v_cvt_pk_bf16_f32 v60, v60, v61
	v_cvt_pk_bf16_f32 v61, v62, v63
	v_cvt_pk_bf16_f32 v62, v56, v57
	v_add_co_u32_e32 v56, vcc, s15, v140
	v_lshl_add_u64 v[64:65], v[140:141], 0, s[38:39]
	s_nop 0
	v_addc_co_u32_e32 v57, vcc, 0, v141, vcc
	s_mov_b32 s15, 0x120000
	v_cvt_pk_bf16_f32 v63, v58, v59
	global_store_dwordx4 v[56:57], v[60:63], off nt
	v_cvt_pk_bf16_f32 v48, v48, v49
	v_cvt_pk_bf16_f32 v49, v50, v51
	v_cvt_pk_bf16_f32 v50, v40, v41
	v_cvt_pk_bf16_f32 v51, v42, v43
	global_store_dwordx4 v[64:65], v[48:51], off offset:256 nt
	s_mov_b64 s[38:39], 0x120000
	v_cvt_pk_bf16_f32 v40, v52, v53
	v_cvt_pk_bf16_f32 v41, v54, v55
	v_cvt_pk_bf16_f32 v42, v44, v45
	v_add_co_u32_e32 v44, vcc, s15, v140
	v_lshl_add_u64 v[48:49], v[140:141], 0, s[38:39]
	s_nop 0
	v_addc_co_u32_e32 v45, vcc, 0, v141, vcc
	s_mov_b32 s15, 0x140000
	v_cvt_pk_bf16_f32 v43, v46, v47
	global_store_dwordx4 v[44:45], v[40:43], off nt
	v_cvt_pk_bf16_f32 v32, v32, v33
	v_cvt_pk_bf16_f32 v33, v34, v35
	v_cvt_pk_bf16_f32 v34, v24, v25
	v_cvt_pk_bf16_f32 v35, v26, v27
	global_store_dwordx4 v[48:49], v[32:35], off offset:256 nt
	s_mov_b64 s[38:39], 0x140000
	v_cvt_pk_bf16_f32 v24, v36, v37
	v_cvt_pk_bf16_f32 v25, v38, v39
	v_cvt_pk_bf16_f32 v26, v28, v29
	v_add_co_u32_e32 v28, vcc, s15, v140
	v_lshl_add_u64 v[32:33], v[140:141], 0, s[38:39]
	s_nop 0
	v_addc_co_u32_e32 v29, vcc, 0, v141, vcc
	s_mov_b32 s15, 0x160000
	v_cvt_pk_bf16_f32 v27, v30, v31
	global_store_dwordx4 v[28:29], v[24:27], off nt
	v_cvt_pk_bf16_f32 v16, v16, v17
	v_cvt_pk_bf16_f32 v17, v18, v19
	v_cvt_pk_bf16_f32 v18, v8, v9
	v_cvt_pk_bf16_f32 v19, v10, v11
	global_store_dwordx4 v[32:33], v[16:19], off offset:256 nt
	v_cvt_pk_bf16_f32 v8, v20, v21
	v_cvt_pk_bf16_f32 v9, v22, v23
	v_cvt_pk_bf16_f32 v10, v12, v13
	v_add_co_u32_e32 v12, vcc, s15, v140
	s_mov_b64 s[38:39], 0x160000
	s_nop 0
	v_addc_co_u32_e32 v13, vcc, 0, v141, vcc
	v_lshl_add_u64 v[16:17], v[140:141], 0, s[38:39]
	s_and_b64 vcc, exec, s[12:13]
	s_mov_b64 s[38:39], s[34:35]
	v_cvt_pk_bf16_f32 v11, v14, v15
	global_store_dwordx4 v[12:13], v[8:11], off nt
	v_cvt_pk_bf16_f32 v4, v4, v5
	v_cvt_pk_bf16_f32 v5, v6, v7
	v_cvt_pk_bf16_f32 v6, v0, v1
	v_cvt_pk_bf16_f32 v7, v2, v3
	global_store_dwordx4 v[16:17], v[4:7], off offset:256 nt
	s_cbranch_vccz .LBB0_213
	s_waitcnt vmcnt(0)
	s_cmpk_gt_u32 s49, 0xff
	s_cbranch_scc1 .LBB0_183
	s_barrier
	s_branch .LBB0_183

.LBB0_262:
	ds_read_b128 v[128:131], v157
	ds_read_b128 v[132:135], v157 offset:1024
	ds_read_b128 v[160:163], v157 offset:2048
	ds_read_b128 v[164:167], v157 offset:3072
	s_add_u32 s34, s30, 0xfffc0080
	s_addc_u32 s35, s31, -1
	s_cmp_eq_u32 s59, 28
	s_cselect_b32 s37, s1, s35
	s_cselect_b32 s36, s2, s34
	s_cselect_b32 s35, s13, s58
	s_cselect_b32 s34, s15, s55
	v_lshl_add_u64 v[152:153], s[30:31], 0, v[148:149]
	s_add_i32 m0, s40, 0xc000
	ds_read_b128 v[168:171], v158
	ds_read_b128 v[172:175], v158 offset:1024
	ds_read_b128 v[176:179], v158 offset:2048
	ds_read_b128 v[180:183], v158 offset:3072
	ds_read_b128 v[184:187], v158 offset:4096
	ds_read_b128 v[188:191], v158 offset:5120
	ds_read_b128 v[192:195], v158 offset:6144
	ds_read_b128 v[196:199], v158 offset:7168
	global_load_lds_dwordx4 v[152:153], off
	v_lshl_add_u64 v[152:153], s[30:31], 0, v[150:151]
	s_add_i32 m0, s40, 0xe000
	s_nop 0
	global_load_lds_dwordx4 v[152:153], off
	s_waitcnt lgkmcnt(8)
	s_waitcnt lgkmcnt(0)
	s_setprio 1
	s_barrier
	v_mfma_f32_16x16x32_bf16 v[124:127], v[128:131], v[168:171], v[124:127]
	v_mfma_f32_16x16x32_bf16 v[100:103], v[160:163], v[168:171], v[100:103]
	v_mfma_f32_16x16x32_bf16 v[116:119], v[128:131], v[176:179], v[116:119]
	v_mfma_f32_16x16x32_bf16 v[96:99], v[160:163], v[176:179], v[96:99]
	v_mfma_f32_16x16x32_bf16 v[92:95], v[128:131], v[184:187], v[92:95]
	v_mfma_f32_16x16x32_bf16 v[72:75], v[160:163], v[184:187], v[72:75]
	v_mfma_f32_16x16x32_bf16 v[84:87], v[128:131], v[192:195], v[84:87]
	v_mfma_f32_16x16x32_bf16 v[60:63], v[160:163], v[192:195], v[60:63]
	v_mfma_f32_16x16x32_bf16 v[124:127], v[132:135], v[172:175], v[124:127]
	v_mfma_f32_16x16x32_bf16 v[100:103], v[164:167], v[172:175], v[100:103]
	v_mfma_f32_16x16x32_bf16 v[116:119], v[132:135], v[180:183], v[116:119]
	v_mfma_f32_16x16x32_bf16 v[96:99], v[164:167], v[180:183], v[96:99]
	v_mfma_f32_16x16x32_bf16 v[92:95], v[132:135], v[188:191], v[92:95]
	v_mfma_f32_16x16x32_bf16 v[72:75], v[164:167], v[188:191], v[72:75]
	v_mfma_f32_16x16x32_bf16 v[84:87], v[132:135], v[196:199], v[84:87]
	v_mfma_f32_16x16x32_bf16 v[60:63], v[164:167], v[196:199], v[60:63]
	s_setprio 0
	s_barrier
	s_add_i32 s60, s51, s39
	v_lshl_add_u64 v[152:153], s[34:35], 0, v[138:139]
	s_mov_b32 m0, s60
	ds_read_b128 v[200:203], v159
	ds_read_b128 v[204:207], v159 offset:1024
	ds_read_b128 v[212:215], v159 offset:2048
	ds_read_b128 v[216:219], v159 offset:3072
	global_load_lds_dwordx4 v[152:153], off
	v_lshl_add_u64 v[208:209], s[34:35], 0, v[142:143]
	s_add_i32 m0, s60, 0x2000
	s_nop 0
	global_load_lds_dwordx4 v[208:209], off
	s_waitcnt lgkmcnt(0)
	s_setprio 1
	s_barrier
	v_mfma_f32_16x16x32_bf16 v[120:123], v[200:203], v[168:171], v[120:123]
	v_mfma_f32_16x16x32_bf16 v[108:111], v[212:215], v[168:171], v[108:111]
	v_mfma_f32_16x16x32_bf16 v[112:115], v[200:203], v[176:179], v[112:115]
	v_mfma_f32_16x16x32_bf16 v[104:107], v[212:215], v[176:179], v[104:107]
	v_mfma_f32_16x16x32_bf16 v[88:91], v[200:203], v[184:187], v[88:91]
	v_mfma_f32_16x16x32_bf16 v[80:83], v[212:215], v[184:187], v[80:83]
	v_mfma_f32_16x16x32_bf16 v[76:79], v[200:203], v[192:195], v[76:79]
	v_mfma_f32_16x16x32_bf16 v[68:71], v[212:215], v[192:195], v[68:71]
	v_mfma_f32_16x16x32_bf16 v[120:123], v[204:207], v[172:175], v[120:123]
	v_mfma_f32_16x16x32_bf16 v[108:111], v[216:219], v[172:175], v[108:111]
	v_mfma_f32_16x16x32_bf16 v[112:115], v[204:207], v[180:183], v[112:115]
	v_mfma_f32_16x16x32_bf16 v[104:107], v[216:219], v[180:183], v[104:107]
	v_mfma_f32_16x16x32_bf16 v[88:91], v[204:207], v[188:191], v[88:91]
	v_mfma_f32_16x16x32_bf16 v[80:83], v[216:219], v[188:191], v[80:83]
	v_mfma_f32_16x16x32_bf16 v[76:79], v[204:207], v[196:199], v[76:79]
	v_mfma_f32_16x16x32_bf16 v[68:71], v[216:219], v[196:199], v[68:71]
	s_setprio 0
	s_mov_b32 m0, s40
	v_lshl_add_u64 v[220:221], s[36:37], 0, v[136:137]
	s_barrier
	ds_read_b128 v[168:171], v158 offset:16384
	ds_read_b128 v[172:175], v158 offset:17408
	ds_read_b128 v[176:179], v158 offset:18432
	ds_read_b128 v[180:183], v158 offset:19456
	ds_read_b128 v[184:187], v158 offset:20480
	ds_read_b128 v[188:191], v158 offset:21504
	ds_read_b128 v[192:195], v158 offset:22528
	ds_read_b128 v[196:199], v158 offset:23552
	global_load_lds_dwordx4 v[220:221], off
	v_lshl_add_u64 v[222:223], s[36:37], 0, v[140:141]
	s_mov_b32 m0, s41
	s_nop 0
	global_load_lds_dwordx4 v[222:223], off
	s_waitcnt lgkmcnt(0)
	s_setprio 1
	s_barrier
	v_mfma_f32_16x16x32_bf16 v[64:67], v[128:131], v[168:171], v[64:67]
	v_mfma_f32_16x16x32_bf16 v[48:51], v[160:163], v[168:171], v[48:51]
	v_mfma_f32_16x16x32_bf16 v[44:47], v[128:131], v[176:179], v[44:47]
	v_mfma_f32_16x16x32_bf16 v[32:35], v[160:163], v[176:179], v[32:35]
	v_mfma_f32_16x16x32_bf16 v[28:31], v[128:131], v[184:187], v[28:31]
	v_mfma_f32_16x16x32_bf16 v[16:19], v[160:163], v[184:187], v[16:19]
	v_mfma_f32_16x16x32_bf16 v[12:15], v[128:131], v[192:195], v[12:15]
	v_mfma_f32_16x16x32_bf16 v[0:3], v[160:163], v[192:195], v[0:3]
	v_mfma_f32_16x16x32_bf16 v[64:67], v[132:135], v[172:175], v[64:67]
	v_mfma_f32_16x16x32_bf16 v[48:51], v[164:167], v[172:175], v[48:51]
	v_mfma_f32_16x16x32_bf16 v[44:47], v[132:135], v[180:183], v[44:47]
	v_mfma_f32_16x16x32_bf16 v[32:35], v[164:167], v[180:183], v[32:35]
	v_mfma_f32_16x16x32_bf16 v[28:31], v[132:135], v[188:191], v[28:31]
	v_mfma_f32_16x16x32_bf16 v[16:19], v[164:167], v[188:191], v[16:19]
	v_mfma_f32_16x16x32_bf16 v[12:15], v[132:135], v[196:199], v[12:15]
	v_mfma_f32_16x16x32_bf16 v[0:3], v[164:167], v[196:199], v[0:3]
	s_setprio 0
	s_barrier
	s_add_u32 s60, s34, 0x80000
	s_addc_u32 s61, s35, 0
	s_add_i32 s62, s53, s39
	v_lshl_add_u64 v[128:129], s[60:61], 0, v[138:139]
	s_mov_b32 m0, s62
	s_nop 0
	global_load_lds_dwordx4 v[128:129], off
	v_lshl_add_u64 v[128:129], s[60:61], 0, v[142:143]
	s_add_i32 m0, s62, 0x2000
	s_nop 0
	global_load_lds_dwordx4 v[128:129], off
	s_waitcnt vmcnt(6)
	s_setprio 1
	s_barrier
	v_mfma_f32_16x16x32_bf16 v[56:59], v[200:203], v[168:171], v[56:59]
	v_mfma_f32_16x16x32_bf16 v[52:55], v[212:215], v[168:171], v[52:55]
	v_mfma_f32_16x16x32_bf16 v[40:43], v[200:203], v[176:179], v[40:43]
	v_mfma_f32_16x16x32_bf16 v[36:39], v[212:215], v[176:179], v[36:39]
	v_mfma_f32_16x16x32_bf16 v[24:27], v[200:203], v[184:187], v[24:27]
	v_mfma_f32_16x16x32_bf16 v[20:23], v[212:215], v[184:187], v[20:23]
	v_mfma_f32_16x16x32_bf16 v[8:11], v[200:203], v[192:195], v[8:11]
	v_mfma_f32_16x16x32_bf16 v[4:7], v[212:215], v[192:195], v[4:7]
	v_mfma_f32_16x16x32_bf16 v[56:59], v[204:207], v[172:175], v[56:59]
	v_mfma_f32_16x16x32_bf16 v[52:55], v[216:219], v[172:175], v[52:55]
	v_mfma_f32_16x16x32_bf16 v[40:43], v[204:207], v[180:183], v[40:43]
	v_mfma_f32_16x16x32_bf16 v[36:39], v[216:219], v[180:183], v[36:39]
	v_mfma_f32_16x16x32_bf16 v[24:27], v[204:207], v[188:191], v[24:27]
	v_mfma_f32_16x16x32_bf16 v[20:23], v[216:219], v[188:191], v[20:23]
	v_mfma_f32_16x16x32_bf16 v[8:11], v[204:207], v[196:199], v[8:11]
	v_mfma_f32_16x16x32_bf16 v[4:7], v[216:219], v[196:199], v[4:7]
	s_setprio 0
	s_add_i32 s60, 0, 0x18000
	v_add_u32_e32 v164, s60, v156
	s_barrier
	ds_read_b128 v[128:131], v164
	ds_read_b128 v[132:135], v164 offset:1024
	ds_read_b128 v[160:163], v164 offset:2048
	ds_read_b128 v[164:167], v164 offset:3072
	s_add_u32 s36, s36, 0x40000
	s_addc_u32 s37, s37, 0
	s_mov_b32 m0, s42
	v_lshl_add_u64 v[200:201], s[36:37], 0, v[136:137]
	ds_read_b128 v[168:171], v158 offset:32768
	ds_read_b128 v[172:175], v158 offset:33792
	ds_read_b128 v[176:179], v158 offset:34816
	ds_read_b128 v[180:183], v158 offset:35840
	ds_read_b128 v[184:187], v158 offset:36864
	ds_read_b128 v[188:191], v158 offset:37888
	ds_read_b128 v[192:195], v158 offset:38912
	ds_read_b128 v[196:199], v158 offset:39936
	global_load_lds_dwordx4 v[200:201], off
	v_lshl_add_u64 v[200:201], s[36:37], 0, v[140:141]
	s_mov_b32 m0, s43
	s_nop 0
	global_load_lds_dwordx4 v[200:201], off
	s_waitcnt lgkmcnt(8)
	s_waitcnt lgkmcnt(0)
	s_setprio 1
	s_barrier
	v_mfma_f32_16x16x32_bf16 v[124:127], v[128:131], v[168:171], v[124:127]
	v_mfma_f32_16x16x32_bf16 v[100:103], v[160:163], v[168:171], v[100:103]
	v_mfma_f32_16x16x32_bf16 v[116:119], v[128:131], v[176:179], v[116:119]
	v_mfma_f32_16x16x32_bf16 v[96:99], v[160:163], v[176:179], v[96:99]
	v_mfma_f32_16x16x32_bf16 v[92:95], v[128:131], v[184:187], v[92:95]
	v_mfma_f32_16x16x32_bf16 v[72:75], v[160:163], v[184:187], v[72:75]
	v_mfma_f32_16x16x32_bf16 v[84:87], v[128:131], v[192:195], v[84:87]
	v_mfma_f32_16x16x32_bf16 v[60:63], v[160:163], v[192:195], v[60:63]
	v_mfma_f32_16x16x32_bf16 v[124:127], v[132:135], v[172:175], v[124:127]
	v_mfma_f32_16x16x32_bf16 v[100:103], v[164:167], v[172:175], v[100:103]
	v_mfma_f32_16x16x32_bf16 v[116:119], v[132:135], v[180:183], v[116:119]
	v_mfma_f32_16x16x32_bf16 v[96:99], v[164:167], v[180:183], v[96:99]
	v_mfma_f32_16x16x32_bf16 v[92:95], v[132:135], v[188:191], v[92:95]
	v_mfma_f32_16x16x32_bf16 v[72:75], v[164:167], v[188:191], v[72:75]
	v_mfma_f32_16x16x32_bf16 v[84:87], v[132:135], v[196:199], v[84:87]
	v_mfma_f32_16x16x32_bf16 v[60:63], v[164:167], v[196:199], v[60:63]
	s_setprio 0
	s_barrier
	s_add_i32 s36, 0, 0x1c000
	s_add_i32 s37, s60, s39
	v_add_u32_e32 v211, s36, v156
	v_lshl_add_u64 v[152:153], v[152:153], 0, s[4:5]
	s_mov_b32 m0, s37
	ds_read_b128 v[200:203], v211
	ds_read_b128 v[204:207], v211 offset:1024
	ds_read_b128 v[212:215], v211 offset:2048
	ds_read_b128 v[216:219], v211 offset:3072
	global_load_lds_dwordx4 v[152:153], off
	v_lshl_add_u64 v[152:153], v[208:209], 0, s[4:5]
	s_add_i32 m0, s37, 0x2000
	s_nop 0
	global_load_lds_dwordx4 v[152:153], off
	s_waitcnt lgkmcnt(0)
	s_setprio 1
	s_barrier
	v_mfma_f32_16x16x32_bf16 v[120:123], v[200:203], v[168:171], v[120:123]
	v_mfma_f32_16x16x32_bf16 v[108:111], v[212:215], v[168:171], v[108:111]
	v_mfma_f32_16x16x32_bf16 v[112:115], v[200:203], v[176:179], v[112:115]
	v_mfma_f32_16x16x32_bf16 v[104:107], v[212:215], v[176:179], v[104:107]
	v_mfma_f32_16x16x32_bf16 v[88:91], v[200:203], v[184:187], v[88:91]
	v_mfma_f32_16x16x32_bf16 v[80:83], v[212:215], v[184:187], v[80:83]
	v_mfma_f32_16x16x32_bf16 v[76:79], v[200:203], v[192:195], v[76:79]
	v_mfma_f32_16x16x32_bf16 v[68:71], v[212:215], v[192:195], v[68:71]
	v_mfma_f32_16x16x32_bf16 v[120:123], v[204:207], v[172:175], v[120:123]
	v_mfma_f32_16x16x32_bf16 v[108:111], v[216:219], v[172:175], v[108:111]
	v_mfma_f32_16x16x32_bf16 v[112:115], v[204:207], v[180:183], v[112:115]
	v_mfma_f32_16x16x32_bf16 v[104:107], v[216:219], v[180:183], v[104:107]
	v_mfma_f32_16x16x32_bf16 v[88:91], v[204:207], v[188:191], v[88:91]
	v_mfma_f32_16x16x32_bf16 v[80:83], v[216:219], v[188:191], v[80:83]
	v_mfma_f32_16x16x32_bf16 v[76:79], v[204:207], v[196:199], v[76:79]
	v_mfma_f32_16x16x32_bf16 v[68:71], v[216:219], v[196:199], v[68:71]
	s_setprio 0
	s_mov_b32 m0, s48
	v_lshl_add_u64 v[152:153], v[220:221], 0, s[4:5]
	s_barrier
	ds_read_b128 v[168:171], v158 offset:49152
	ds_read_b128 v[172:175], v158 offset:50176
	ds_read_b128 v[176:179], v158 offset:51200
	ds_read_b128 v[180:183], v158 offset:52224
	ds_read_b128 v[184:187], v158 offset:53248
	ds_read_b128 v[188:191], v158 offset:54272
	ds_read_b128 v[192:195], v158 offset:55296
	ds_read_b128 v[196:199], v158 offset:56320
	global_load_lds_dwordx4 v[152:153], off
	v_lshl_add_u64 v[152:153], v[222:223], 0, s[4:5]
	s_mov_b32 m0, s49
	s_nop 0
	global_load_lds_dwordx4 v[152:153], off
	s_waitcnt lgkmcnt(0)
	s_setprio 1
	s_barrier
	v_mfma_f32_16x16x32_bf16 v[64:67], v[128:131], v[168:171], v[64:67]
	v_mfma_f32_16x16x32_bf16 v[48:51], v[160:163], v[168:171], v[48:51]
	v_mfma_f32_16x16x32_bf16 v[44:47], v[128:131], v[176:179], v[44:47]
	v_mfma_f32_16x16x32_bf16 v[32:35], v[160:163], v[176:179], v[32:35]
	v_mfma_f32_16x16x32_bf16 v[28:31], v[128:131], v[184:187], v[28:31]
	v_mfma_f32_16x16x32_bf16 v[16:19], v[160:163], v[184:187], v[16:19]
	v_mfma_f32_16x16x32_bf16 v[12:15], v[128:131], v[192:195], v[12:15]
	v_mfma_f32_16x16x32_bf16 v[0:3], v[160:163], v[192:195], v[0:3]
	v_mfma_f32_16x16x32_bf16 v[64:67], v[132:135], v[172:175], v[64:67]
	v_mfma_f32_16x16x32_bf16 v[48:51], v[164:167], v[172:175], v[48:51]
	v_mfma_f32_16x16x32_bf16 v[44:47], v[132:135], v[180:183], v[44:47]
	v_mfma_f32_16x16x32_bf16 v[32:35], v[164:167], v[180:183], v[32:35]
	v_mfma_f32_16x16x32_bf16 v[28:31], v[132:135], v[188:191], v[28:31]
	v_mfma_f32_16x16x32_bf16 v[16:19], v[164:167], v[188:191], v[16:19]
	v_mfma_f32_16x16x32_bf16 v[12:15], v[132:135], v[196:199], v[12:15]
	v_mfma_f32_16x16x32_bf16 v[0:3], v[164:167], v[196:199], v[0:3]
	s_setprio 0
	s_barrier
	s_add_u32 s34, s34, 0x80080
	s_addc_u32 s35, s35, 0
	s_add_i32 s36, s36, s39
	v_lshl_add_u64 v[128:129], s[34:35], 0, v[138:139]
	s_mov_b32 m0, s36
	s_nop 0
	global_load_lds_dwordx4 v[128:129], off
	v_lshl_add_u64 v[128:129], s[34:35], 0, v[142:143]
	s_add_i32 m0, s36, 0x2000
	s_nop 0
	global_load_lds_dwordx4 v[128:129], off
	s_waitcnt vmcnt(6)
	s_setprio 1
	s_barrier
	v_mfma_f32_16x16x32_bf16 v[56:59], v[200:203], v[168:171], v[56:59]
	v_mfma_f32_16x16x32_bf16 v[52:55], v[212:215], v[168:171], v[52:55]
	v_mfma_f32_16x16x32_bf16 v[40:43], v[200:203], v[176:179], v[40:43]
	v_mfma_f32_16x16x32_bf16 v[36:39], v[212:215], v[176:179], v[36:39]
	v_mfma_f32_16x16x32_bf16 v[24:27], v[200:203], v[184:187], v[24:27]
	v_mfma_f32_16x16x32_bf16 v[20:23], v[212:215], v[184:187], v[20:23]
	v_mfma_f32_16x16x32_bf16 v[8:11], v[200:203], v[192:195], v[8:11]
	v_mfma_f32_16x16x32_bf16 v[4:7], v[212:215], v[192:195], v[4:7]
	v_mfma_f32_16x16x32_bf16 v[56:59], v[204:207], v[172:175], v[56:59]
	v_mfma_f32_16x16x32_bf16 v[52:55], v[216:219], v[172:175], v[52:55]
	v_mfma_f32_16x16x32_bf16 v[40:43], v[204:207], v[180:183], v[40:43]
	v_mfma_f32_16x16x32_bf16 v[36:39], v[216:219], v[180:183], v[36:39]
	v_mfma_f32_16x16x32_bf16 v[24:27], v[204:207], v[188:191], v[24:27]
	v_mfma_f32_16x16x32_bf16 v[20:23], v[216:219], v[188:191], v[20:23]
	v_mfma_f32_16x16x32_bf16 v[8:11], v[204:207], v[196:199], v[8:11]
	v_mfma_f32_16x16x32_bf16 v[4:7], v[216:219], v[196:199], v[4:7]
	s_setprio 0
	s_add_i32 s59, s59, 2
	s_add_u32 s30, s30, 0x100
	s_addc_u32 s31, s31, 0
	s_add_u32 s55, s55, 0x100
	s_addc_u32 s58, s58, 0
	s_cmp_gt_u32 s59, 29
	s_barrier
	s_cbranch_scc0 .LBB0_262
	s_cmp_gt_i32 s0, 31
	s_cselect_b64 vcc, -1, 0
	s_and_b64 s[30:31], vcc, exec
	s_cselect_b32 s2, 0x200, 0
	v_lshl_add_u64 v[128:129], v[144:145], 0, s[2:3]
	global_load_dwordx4 v[132:135], v[128:129], off
	s_nop 0
	global_load_dwordx4 v[128:131], v[128:129], off offset:16
	v_cndmask_b32_e32 v121, v125, v121, vcc
	v_cndmask_b32_e32 v120, v124, v120, vcc
	v_cndmask_b32_e32 v101, v101, v109, vcc
	v_cndmask_b32_e32 v100, v100, v108, vcc
	v_cndmask_b32_e32 v123, v127, v123, vcc
	v_cndmask_b32_e32 v122, v126, v122, vcc
	v_cndmask_b32_e32 v103, v103, v111, vcc
	v_cndmask_b32_e32 v102, v102, v110, vcc
	v_cndmask_b32_e32 v111, v119, v115, vcc
	v_cndmask_b32_e32 v110, v118, v114, vcc
	v_cndmask_b32_e32 v99, v99, v107, vcc
	v_cndmask_b32_e32 v98, v98, v106, vcc
	v_cndmask_b32_e32 v109, v117, v113, vcc
	v_cndmask_b32_e32 v108, v116, v112, vcc
	v_cndmask_b32_e32 v89, v93, v89, vcc
	v_cndmask_b32_e32 v88, v92, v88, vcc
	v_cndmask_b32_e32 v73, v73, v81, vcc
	v_cndmask_b32_e32 v72, v72, v80, vcc
	v_cndmask_b32_e32 v105, v97, v105, vcc
	v_cndmask_b32_e32 v104, v96, v104, vcc
	v_cndmask_b32_e32 v74, v74, v82, vcc
	v_lshl_add_u32 v152, s0, 8, v155
	v_ashrrev_i32_e32 v153, 31, v152
	v_lshlrev_b64 v[162:163], 8, v[152:153]
	v_cndmask_b32_e32 v75, v75, v83, vcc
	v_lshl_add_u64 v[96:97], v[146:147], 0, v[162:163]
	v_cndmask_b32_e32 v91, v95, v91, vcc
	v_cndmask_b32_e32 v90, v94, v90, vcc
	v_or_b32_e32 v160, 16, v152
	v_ashrrev_i32_e32 v161, 31, v160
	v_lshlrev_b64 v[106:107], 8, v[160:161]
	v_cndmask_b32_e32 v61, v61, v69, vcc
	v_cndmask_b32_e32 v60, v60, v68, vcc
	v_cndmask_b32_e32 v57, v65, v57, vcc
	v_cndmask_b32_e32 v56, v64, v56, vcc
	v_cndmask_b32_e32 v49, v49, v53, vcc
	v_cndmask_b32_e32 v48, v48, v52, vcc
	v_cndmask_b32_e32 v62, v62, v70, vcc
	v_cndmask_b32_e32 v50, v50, v54, vcc
	v_cndmask_b32_e32 v41, v45, v41, vcc
	v_cndmask_b32_e32 v40, v44, v40, vcc
	v_cndmask_b32_e32 v33, v33, v37, vcc
	v_cndmask_b32_e32 v32, v32, v36, vcc
	v_cndmask_b32_e32 v25, v29, v25, vcc
	v_cndmask_b32_e32 v24, v28, v24, vcc
	v_cndmask_b32_e32 v17, v17, v21, vcc
	v_cndmask_b32_e32 v16, v16, v20, vcc
	v_cndmask_b32_e32 v34, v34, v38, vcc
	v_cndmask_b32_e32 v18, v18, v22, vcc
	v_cndmask_b32_e32 v9, v13, v9, vcc
	v_cndmask_b32_e32 v8, v12, v8, vcc
	v_cndmask_b32_e32 v1, v1, v5, vcc
	v_cndmask_b32_e32 v0, v0, v4, vcc
	v_cndmask_b32_e32 v63, v63, v71, vcc
	v_cndmask_b32_e32 v51, v51, v55, vcc
	v_cndmask_b32_e32 v2, v2, v6, vcc
	v_cndmask_b32_e32 v35, v35, v39, vcc
	v_cndmask_b32_e32 v59, v67, v59, vcc
	v_cndmask_b32_e32 v58, v66, v58, vcc
	v_cndmask_b32_e32 v19, v19, v23, vcc
	v_cndmask_b32_e32 v43, v47, v43, vcc
	v_cndmask_b32_e32 v42, v46, v42, vcc
	v_cndmask_b32_e32 v3, v3, v7, vcc
	v_cndmask_b32_e32 v27, v31, v27, vcc
	v_cndmask_b32_e32 v26, v30, v26, vcc
	v_cndmask_b32_e32 v11, v15, v11, vcc
	v_cndmask_b32_e32 v10, v14, v10, vcc
	s_mov_b32 s0, 0x9000
	s_mov_b64 s[34:35], s[28:29]
	s_mov_b64 s[30:31], s[26:27]
	s_waitcnt vmcnt(0)
	v_pk_add_f32 v[114:115], v[120:121], v[132:133]
	v_pk_add_f32 v[100:101], v[100:101], v[128:129]
	v_pk_add_f32 v[112:113], v[122:123], v[134:135]
	v_pk_add_f32 v[102:103], v[102:103], v[130:131]
	v_pk_add_f32 v[116:117], v[98:99], v[130:131]
	v_mul_f32_e32 v98, 0xbfb8aa3b, v114
	v_mul_f32_e32 v99, 0xbfb8aa3b, v100
	v_mul_f32_e32 v118, 0xbfb8aa3b, v115
	v_mul_f32_e32 v119, 0xbfb8aa3b, v101
	v_mul_f32_e32 v120, 0xbfb8aa3b, v112
	v_mul_f32_e32 v121, 0xbfb8aa3b, v102
	v_mul_f32_e32 v122, 0xbfb8aa3b, v113
	v_mul_f32_e32 v123, 0xbfb8aa3b, v103
	v_exp_f32_e32 v98, v98
	v_exp_f32_e32 v99, v99
	v_exp_f32_e32 v118, v118
	v_exp_f32_e32 v119, v119
	v_exp_f32_e32 v120, v120
	v_exp_f32_e32 v121, v121
	v_exp_f32_e32 v122, v122
	v_exp_f32_e32 v123, v123
	v_pk_add_f32 v[88:89], v[88:89], v[132:133]
	v_pk_add_f32 v[72:73], v[72:73], v[128:129]
	v_add_f32_e32 v98, 1.0, v98
	v_add_f32_e32 v99, 1.0, v99
	v_add_f32_e32 v118, 1.0, v118
	v_add_f32_e32 v119, 1.0, v119
	v_mul_f32_e32 v80, 0xbfb8aa3b, v88
	v_mul_f32_e32 v81, 0xbfb8aa3b, v72
	v_mul_f32_e32 v82, 0xbfb8aa3b, v89
	v_pk_add_f32 v[104:105], v[104:105], v[128:129]
	v_add_f32_e32 v120, 1.0, v120
	v_add_f32_e32 v121, 1.0, v121
	v_add_f32_e32 v122, 1.0, v122
	v_add_f32_e32 v123, 1.0, v123
	v_rcp_f32_e32 v98, v98
	v_rcp_f32_e32 v99, v99
	v_rcp_f32_e32 v118, v118
	v_rcp_f32_e32 v119, v119
	v_exp_f32_e32 v80, v80
	v_exp_f32_e32 v81, v81
	v_exp_f32_e32 v82, v82
	v_mul_f32_e32 v127, 0xbfb8aa3b, v105
	v_rcp_f32_e32 v120, v120
	v_rcp_f32_e32 v121, v121
	v_rcp_f32_e32 v122, v122
	v_rcp_f32_e32 v123, v123
	v_exp_f32_e32 v127, v127
	v_mul_f32_e32 v98, v114, v98
	v_mul_f32_e32 v100, v100, v99
	v_mul_f32_e32 v99, v115, v118
	v_mul_f32_e32 v101, v101, v119
	v_add_f32_e32 v80, 1.0, v80
	v_add_f32_e32 v81, 1.0, v81
	v_add_f32_e32 v82, 1.0, v82
	v_mul_f32_e32 v83, 0xbfb8aa3b, v73
	v_pk_add_f32 v[110:111], v[110:111], v[134:135]
	v_mul_f32_e32 v112, v112, v120
	v_mul_f32_e32 v102, v102, v121
	v_mul_f32_e32 v113, v113, v122
	v_mul_f32_e32 v103, v103, v123
	v_cvt_pk_bf16_f32 v98, v98, v99
	v_cvt_pk_bf16_f32 v99, v112, v113
	v_cvt_pk_bf16_f32 v100, v100, v101
	v_cvt_pk_bf16_f32 v101, v102, v103
	v_rcp_f32_e32 v80, v80
	v_rcp_f32_e32 v81, v81
	v_rcp_f32_e32 v82, v82
	v_exp_f32_e32 v83, v83
	global_store_dwordx4 v[96:97], v[98:101], off
	v_pk_add_f32 v[90:91], v[90:91], v[134:135]
	v_pk_add_f32 v[74:75], v[74:75], v[130:131]
	v_add_f32_e32 v99, 1.0, v127
	v_mul_f32_e32 v100, 0xbfb8aa3b, v110
	v_mul_f32_e32 v101, 0xbfb8aa3b, v116
	v_rcp_f32_e32 v99, v99
	v_exp_f32_e32 v100, v100
	v_exp_f32_e32 v101, v101
	v_pk_add_f32 v[108:109], v[108:109], v[132:133]
	v_mul_f32_e32 v88, v88, v80
	v_mul_f32_e32 v92, v72, v81
	v_mul_f32_e32 v72, v89, v82
	v_add_f32_e32 v80, 1.0, v83
	v_mul_f32_e32 v81, 0xbfb8aa3b, v90
	v_mul_f32_e32 v82, 0xbfb8aa3b, v74
	v_mul_f32_e32 v126, 0xbfb8aa3b, v109
	v_rcp_f32_e32 v80, v80
	v_exp_f32_e32 v81, v81
	v_exp_f32_e32 v82, v82
	v_mul_f32_e32 v124, 0xbfb8aa3b, v108
	v_exp_f32_e32 v126, v126
	v_mul_f32_e32 v105, v105, v99
	v_add_f32_e32 v99, 1.0, v100
	v_add_f32_e32 v100, 1.0, v101
	v_mul_f32_e32 v101, 0xbfb8aa3b, v111
	v_mul_f32_e32 v102, 0xbfb8aa3b, v117
	v_mul_f32_e32 v125, 0xbfb8aa3b, v104
	v_exp_f32_e32 v124, v124
	v_exp_f32_e32 v101, v101
	v_exp_f32_e32 v102, v102
	v_exp_f32_e32 v125, v125
	v_mul_f32_e32 v83, v73, v80
	v_add_f32_e32 v73, 1.0, v81
	v_add_f32_e32 v80, 1.0, v82
	v_mul_f32_e32 v81, 0xbfb8aa3b, v91
	v_mul_f32_e32 v82, 0xbfb8aa3b, v75
	v_add_f32_e32 v126, 1.0, v126
	v_exp_f32_e32 v81, v81
	v_exp_f32_e32 v82, v82
	v_add_f32_e32 v124, 1.0, v124
	v_rcp_f32_e32 v126, v126
	v_add_f32_e32 v101, 1.0, v101
	v_add_f32_e32 v102, 1.0, v102
	v_add_f32_e32 v125, 1.0, v125
	v_rcp_f32_e32 v124, v124
	v_rcp_f32_e32 v99, v99
	v_rcp_f32_e32 v100, v100
	v_rcp_f32_e32 v101, v101
	v_rcp_f32_e32 v102, v102
	v_rcp_f32_e32 v125, v125
	v_add_f32_e32 v81, 1.0, v81
	v_add_f32_e32 v82, 1.0, v82
	v_mul_f32_e32 v98, v109, v126
	v_rcp_f32_e32 v73, v73
	v_rcp_f32_e32 v80, v80
	v_rcp_f32_e32 v81, v81
	v_rcp_f32_e32 v82, v82
	v_mul_f32_e32 v108, v108, v124
	v_mul_f32_e32 v99, v110, v99
	v_mul_f32_e32 v109, v116, v100
	v_mul_f32_e32 v100, v111, v101
	v_mul_f32_e32 v101, v117, v102
	v_lshl_add_u64 v[102:103], v[146:147], 0, v[106:107]
	v_cvt_pk_bf16_f32 v98, v108, v98
	v_mul_f32_e32 v104, v104, v125
	v_cvt_pk_bf16_f32 v99, v99, v100
	v_cvt_pk_bf16_f32 v100, v104, v105
	v_cvt_pk_bf16_f32 v101, v109, v101
	global_store_dwordx4 v[102:103], v[98:101], off
	v_mul_f32_e32 v73, v90, v73
	v_mul_f32_e32 v89, v74, v80
	v_or_b32_e32 v98, 32, v152
	v_ashrrev_i32_e32 v99, 31, v98
	v_lshlrev_b64 v[98:99], 8, v[98:99]
	v_mul_f32_e32 v74, v91, v81
	v_mul_f32_e32 v75, v75, v82
	v_lshl_add_u64 v[80:81], v[146:147], 0, v[98:99]
	v_cvt_pk_bf16_f32 v72, v88, v72
	v_cvt_pk_bf16_f32 v73, v73, v74
	v_cvt_pk_bf16_f32 v74, v92, v83
	v_cvt_pk_bf16_f32 v75, v89, v75
	global_store_dwordx4 v[80:81], v[72:75], off
	v_pk_add_f32 v[60:61], v[60:61], v[128:129]
	v_pk_add_f32 v[56:57], v[56:57], v[132:133]
	v_cndmask_b32_e32 v75, v85, v77, vcc
	v_cndmask_b32_e32 v74, v84, v76, vcc
	v_pk_add_f32 v[74:75], v[74:75], v[132:133]
	v_mul_f32_e32 v69, 0xbfb8aa3b, v60
	v_mul_f32_e32 v68, 0xbfb8aa3b, v74
	v_mul_f32_e32 v70, 0xbfb8aa3b, v75
	v_pk_add_f32 v[48:49], v[48:49], v[128:129]
	v_exp_f32_e32 v68, v68
	v_exp_f32_e32 v69, v69
	v_exp_f32_e32 v70, v70
	v_mul_f32_e32 v52, 0xbfb8aa3b, v56
	v_mul_f32_e32 v53, 0xbfb8aa3b, v48
	v_mul_f32_e32 v54, 0xbfb8aa3b, v57
	v_exp_f32_e32 v52, v52
	v_exp_f32_e32 v53, v53
	v_exp_f32_e32 v54, v54
	v_pk_add_f32 v[40:41], v[40:41], v[132:133]
	v_pk_add_f32 v[32:33], v[32:33], v[128:129]
	v_mul_f32_e32 v36, 0xbfb8aa3b, v40
	v_mul_f32_e32 v37, 0xbfb8aa3b, v32
	v_mul_f32_e32 v38, 0xbfb8aa3b, v41
	v_pk_add_f32 v[24:25], v[24:25], v[132:133]
	v_pk_add_f32 v[16:17], v[16:17], v[128:129]
	v_exp_f32_e32 v36, v36
	v_exp_f32_e32 v37, v37
	v_exp_f32_e32 v38, v38
	v_mul_f32_e32 v20, 0xbfb8aa3b, v24
	v_mul_f32_e32 v21, 0xbfb8aa3b, v16
	v_mul_f32_e32 v22, 0xbfb8aa3b, v25
	v_add_f32_e32 v68, 1.0, v68
	v_add_f32_e32 v69, 1.0, v69
	v_add_f32_e32 v70, 1.0, v70
	v_mul_f32_e32 v71, 0xbfb8aa3b, v61
	v_exp_f32_e32 v20, v20
	v_exp_f32_e32 v21, v21
	v_exp_f32_e32 v22, v22
	v_pk_add_f32 v[8:9], v[8:9], v[132:133]
	v_pk_add_f32 v[0:1], v[0:1], v[128:129]
	v_rcp_f32_e32 v68, v68
	v_rcp_f32_e32 v69, v69
	v_rcp_f32_e32 v70, v70
	v_exp_f32_e32 v71, v71
	v_add_f32_e32 v52, 1.0, v52
	v_add_f32_e32 v53, 1.0, v53
	v_add_f32_e32 v54, 1.0, v54
	v_mul_f32_e32 v55, 0xbfb8aa3b, v49
	v_mul_f32_e32 v4, 0xbfb8aa3b, v8
	v_mul_f32_e32 v5, 0xbfb8aa3b, v0
	v_mul_f32_e32 v6, 0xbfb8aa3b, v9
	v_rcp_f32_e32 v52, v52
	v_rcp_f32_e32 v53, v53
	v_rcp_f32_e32 v54, v54
	v_exp_f32_e32 v55, v55
	v_exp_f32_e32 v4, v4
	v_exp_f32_e32 v5, v5
	v_exp_f32_e32 v6, v6
	v_cndmask_b32_e32 v77, v87, v79, vcc
	v_cndmask_b32_e32 v76, v86, v78, vcc
	v_add_f32_e32 v36, 1.0, v36
	v_add_f32_e32 v37, 1.0, v37
	v_add_f32_e32 v38, 1.0, v38
	v_mul_f32_e32 v39, 0xbfb8aa3b, v33
	v_pk_add_f32 v[76:77], v[76:77], v[134:135]
	v_pk_add_f32 v[62:63], v[62:63], v[130:131]
	v_rcp_f32_e32 v36, v36
	v_rcp_f32_e32 v37, v37
	v_rcp_f32_e32 v38, v38
	v_exp_f32_e32 v39, v39
	v_add_f32_e32 v20, 1.0, v20
	v_add_f32_e32 v21, 1.0, v21
	v_add_f32_e32 v22, 1.0, v22
	v_mul_f32_e32 v23, 0xbfb8aa3b, v17
	v_mul_f32_e32 v74, v74, v68
	v_mul_f32_e32 v78, v60, v69
	v_mul_f32_e32 v60, v75, v70
	v_add_f32_e32 v68, 1.0, v71
	v_mul_f32_e32 v69, 0xbfb8aa3b, v76
	v_mul_f32_e32 v70, 0xbfb8aa3b, v62
	v_pk_add_f32 v[58:59], v[58:59], v[134:135]
	v_pk_add_f32 v[50:51], v[50:51], v[130:131]
	v_rcp_f32_e32 v20, v20
	v_rcp_f32_e32 v21, v21
	v_rcp_f32_e32 v22, v22
	v_exp_f32_e32 v23, v23
	v_rcp_f32_e32 v68, v68
	v_exp_f32_e32 v69, v69
	v_exp_f32_e32 v70, v70
	v_mul_f32_e32 v52, v56, v52
	v_mul_f32_e32 v53, v48, v53
	v_mul_f32_e32 v48, v57, v54
	v_add_f32_e32 v54, 1.0, v55
	v_mul_f32_e32 v55, 0xbfb8aa3b, v58
	v_mul_f32_e32 v56, 0xbfb8aa3b, v50
	v_add_f32_e32 v4, 1.0, v4
	v_add_f32_e32 v5, 1.0, v5
	v_add_f32_e32 v6, 1.0, v6
	v_mul_f32_e32 v7, 0xbfb8aa3b, v1
	v_rcp_f32_e32 v54, v54
	v_exp_f32_e32 v55, v55
	v_exp_f32_e32 v56, v56
	v_pk_add_f32 v[42:43], v[42:43], v[134:135]
	v_pk_add_f32 v[34:35], v[34:35], v[130:131]
	v_rcp_f32_e32 v4, v4
	v_rcp_f32_e32 v5, v5
	v_rcp_f32_e32 v6, v6
	v_exp_f32_e32 v7, v7
	v_mul_f32_e32 v36, v40, v36
	v_mul_f32_e32 v37, v32, v37
	v_mul_f32_e32 v32, v41, v38
	v_add_f32_e32 v38, 1.0, v39
	v_mul_f32_e32 v39, 0xbfb8aa3b, v42
	v_mul_f32_e32 v40, 0xbfb8aa3b, v34
	v_pk_add_f32 v[26:27], v[26:27], v[134:135]
	v_pk_add_f32 v[18:19], v[18:19], v[130:131]
	v_rcp_f32_e32 v38, v38
	v_exp_f32_e32 v39, v39
	v_exp_f32_e32 v40, v40
	v_mul_f32_e32 v20, v24, v20
	v_mul_f32_e32 v21, v16, v21
	v_mul_f32_e32 v16, v25, v22
	v_add_f32_e32 v22, 1.0, v23
	v_mul_f32_e32 v23, 0xbfb8aa3b, v26
	v_mul_f32_e32 v24, 0xbfb8aa3b, v18
	v_mul_f32_e32 v71, v61, v68
	v_add_f32_e32 v61, 1.0, v69
	v_add_f32_e32 v68, 1.0, v70
	v_mul_f32_e32 v69, 0xbfb8aa3b, v77
	v_mul_f32_e32 v70, 0xbfb8aa3b, v63
	v_rcp_f32_e32 v22, v22
	v_exp_f32_e32 v23, v23
	v_exp_f32_e32 v24, v24
	v_pk_add_f32 v[10:11], v[10:11], v[134:135]
	v_pk_add_f32 v[2:3], v[2:3], v[130:131]
	v_exp_f32_e32 v69, v69
	v_exp_f32_e32 v70, v70
	v_mul_f32_e32 v54, v49, v54
	v_add_f32_e32 v49, 1.0, v55
	v_add_f32_e32 v55, 1.0, v56
	v_mul_f32_e32 v56, 0xbfb8aa3b, v59
	v_mul_f32_e32 v4, v8, v4
	v_mul_f32_e32 v5, v0, v5
	v_mul_f32_e32 v0, v9, v6
	v_add_f32_e32 v6, 1.0, v7
	v_mul_f32_e32 v7, 0xbfb8aa3b, v10
	v_mul_f32_e32 v8, 0xbfb8aa3b, v2
	v_exp_f32_e32 v56, v56
	v_rcp_f32_e32 v6, v6
	v_exp_f32_e32 v7, v7
	v_exp_f32_e32 v8, v8
	v_mul_f32_e32 v57, 0xbfb8aa3b, v51
	v_mul_f32_e32 v38, v33, v38
	v_add_f32_e32 v33, 1.0, v39
	v_add_f32_e32 v39, 1.0, v40
	v_mul_f32_e32 v40, 0xbfb8aa3b, v43
	v_mul_f32_e32 v41, 0xbfb8aa3b, v35
	v_exp_f32_e32 v57, v57
	v_exp_f32_e32 v40, v40
	v_exp_f32_e32 v41, v41
	v_mul_f32_e32 v22, v17, v22
	v_add_f32_e32 v17, 1.0, v23
	v_add_f32_e32 v23, 1.0, v24
	v_mul_f32_e32 v24, 0xbfb8aa3b, v27
	v_add_f32_e32 v69, 1.0, v69
	v_add_f32_e32 v70, 1.0, v70
	v_exp_f32_e32 v24, v24
	v_mul_f32_e32 v25, 0xbfb8aa3b, v19
	v_rcp_f32_e32 v61, v61
	v_rcp_f32_e32 v68, v68
	v_rcp_f32_e32 v69, v69
	v_rcp_f32_e32 v70, v70
	v_add_f32_e32 v56, 1.0, v56
	v_exp_f32_e32 v25, v25
	v_mul_f32_e32 v6, v1, v6
	v_add_f32_e32 v1, 1.0, v7
	v_add_f32_e32 v7, 1.0, v8
	v_mul_f32_e32 v8, 0xbfb8aa3b, v11
	v_or_b32_e32 v72, 48, v152
	v_rcp_f32_e32 v49, v49
	v_rcp_f32_e32 v55, v55
	v_rcp_f32_e32 v56, v56
	v_exp_f32_e32 v8, v8
	v_ashrrev_i32_e32 v73, 31, v72
	v_add_f32_e32 v57, 1.0, v57
	v_add_f32_e32 v40, 1.0, v40
	v_add_f32_e32 v41, 1.0, v41
	v_mul_f32_e32 v9, 0xbfb8aa3b, v3
	v_lshlrev_b64 v[72:73], 8, v[72:73]
	v_rcp_f32_e32 v57, v57
	v_rcp_f32_e32 v33, v33
	v_rcp_f32_e32 v39, v39
	v_rcp_f32_e32 v40, v40
	v_rcp_f32_e32 v41, v41
	v_add_f32_e32 v24, 1.0, v24
	v_exp_f32_e32 v9, v9
	v_mul_f32_e32 v61, v76, v61
	v_mul_f32_e32 v75, v62, v68
	v_mul_f32_e32 v62, v77, v69
	v_mul_f32_e32 v63, v63, v70
	v_lshl_add_u64 v[68:69], v[146:147], 0, v[72:73]
	v_rcp_f32_e32 v17, v17
	v_rcp_f32_e32 v23, v23
	v_rcp_f32_e32 v24, v24
	v_add_f32_e32 v25, 1.0, v25
	v_cvt_pk_bf16_f32 v60, v74, v60
	v_cvt_pk_bf16_f32 v61, v61, v62
	v_cvt_pk_bf16_f32 v62, v78, v71
	v_cvt_pk_bf16_f32 v63, v75, v63
	global_store_dwordx4 v[68:69], v[60:63], off
	v_mul_f32_e32 v49, v58, v49
	v_mul_f32_e32 v55, v50, v55
	v_mul_f32_e32 v50, v59, v56
	v_cvt_pk_bf16_f32 v48, v52, v48
	v_add_co_u32_e64 v52, s[0:1], s0, v96
	v_rcp_f32_e32 v25, v25
	v_add_f32_e32 v8, 1.0, v8
	v_cvt_pk_bf16_f32 v49, v49, v50
	v_cvt_pk_bf16_f32 v50, v53, v54
	v_addc_co_u32_e64 v53, s[0:1], 0, v97, s[0:1]
	v_rcp_f32_e32 v1, v1
	v_rcp_f32_e32 v7, v7
	v_rcp_f32_e32 v8, v8
	v_mul_f32_e32 v51, v51, v57
	v_mul_f32_e32 v33, v42, v33
	v_mul_f32_e32 v39, v34, v39
	v_mul_f32_e32 v34, v43, v40
	v_mul_f32_e32 v35, v35, v41
	s_mov_b32 s0, 0xa000
	v_add_f32_e32 v9, 1.0, v9
	v_cvt_pk_bf16_f32 v51, v55, v51
	global_store_dwordx4 v[52:53], v[48:51], off offset:-4096
	v_cvt_pk_bf16_f32 v32, v36, v32
	v_cvt_pk_bf16_f32 v33, v33, v34
	v_cvt_pk_bf16_f32 v34, v37, v38
	v_cvt_pk_bf16_f32 v35, v39, v35
	global_store_dwordx4 v[52:53], v[32:35], off
	v_mul_f32_e32 v17, v26, v17
	v_mul_f32_e32 v23, v18, v23
	v_mul_f32_e32 v18, v27, v24
	v_cvt_pk_bf16_f32 v16, v20, v16
	v_add_co_u32_e64 v20, s[0:1], s0, v96
	v_rcp_f32_e32 v9, v9
	v_mul_f32_e32 v19, v19, v25
	v_cvt_pk_bf16_f32 v17, v17, v18
	v_cvt_pk_bf16_f32 v18, v21, v22
	v_addc_co_u32_e64 v21, s[0:1], 0, v97, s[0:1]
	v_cvt_pk_bf16_f32 v19, v23, v19
	global_store_dwordx4 v[20:21], v[16:19], off
	v_mul_f32_e32 v1, v10, v1
	v_mul_f32_e32 v7, v2, v7
	v_mul_f32_e32 v2, v11, v8
	v_cvt_pk_bf16_f32 v0, v4, v0
	v_add_co_u32_e32 v4, vcc, 0xb000, v96
	v_cvt_pk_bf16_f32 v1, v1, v2
	v_cvt_pk_bf16_f32 v2, v5, v6
	v_mul_f32_e32 v3, v3, v9
	s_nop 0
	v_addc_co_u32_e32 v5, vcc, 0, v97, vcc
	s_and_b64 vcc, exec, s[8:9]
	s_mov_b32 s0, s14
	v_cvt_pk_bf16_f32 v3, v7, v3
	global_store_dwordx4 v[4:5], v[0:3], off
	s_cbranch_vccz .LBB0_255
	s_waitcnt vmcnt(0)
	s_cmpk_gt_u32 s33, 0xff
	s_cbranch_scc1 .LBB0_266
	s_barrier

.LBB0_654:
	ds_read_b128 v[144:147], v157
	ds_read_b128 v[148:151], v157 offset:1024
	ds_read_b128 v[160:163], v157 offset:2048
	ds_read_b128 v[164:167], v157 offset:3072
	s_add_u32 s24, s22, 0xfffc0080
	s_addc_u32 s25, s23, -1
	s_cmp_eq_u32 s49, 12
	s_cselect_b32 s27, s13, s25
	s_cselect_b32 s26, s19, s24
	s_cselect_b32 s25, s3, s48
	s_cselect_b32 s24, s42, s43
	v_lshl_add_u64 v[152:153], s[22:23], 0, v[136:137]
	s_add_i32 m0, s21, 0xc000
	ds_read_b128 v[168:171], v158
	ds_read_b128 v[176:179], v158 offset:1024
	ds_read_b128 v[180:183], v158 offset:2048
	ds_read_b128 v[184:187], v158 offset:3072
	ds_read_b128 v[188:191], v158 offset:4096
	ds_read_b128 v[192:195], v158 offset:5120
	ds_read_b128 v[196:199], v158 offset:6144
	ds_read_b128 v[200:203], v158 offset:7168
	global_load_lds_dwordx4 v[152:153], off
	v_lshl_add_u64 v[152:153], s[22:23], 0, v[138:139]
	s_add_i32 m0, s21, 0xe000
	s_nop 0
	global_load_lds_dwordx4 v[152:153], off
	s_waitcnt lgkmcnt(8)
	s_waitcnt lgkmcnt(0)
	s_setprio 1
	s_barrier
	v_mfma_f32_16x16x32_bf16 v[124:127], v[144:147], v[168:171], v[124:127]
	v_mfma_f32_16x16x32_bf16 v[120:123], v[160:163], v[168:171], v[120:123]
	v_mfma_f32_16x16x32_bf16 v[116:119], v[144:147], v[180:183], v[116:119]
	v_mfma_f32_16x16x32_bf16 v[112:115], v[160:163], v[180:183], v[112:115]
	v_mfma_f32_16x16x32_bf16 v[96:99], v[144:147], v[188:191], v[96:99]
	v_mfma_f32_16x16x32_bf16 v[88:91], v[160:163], v[188:191], v[88:91]
	v_mfma_f32_16x16x32_bf16 v[80:83], v[144:147], v[196:199], v[80:83]
	v_mfma_f32_16x16x32_bf16 v[72:75], v[160:163], v[196:199], v[72:75]
	v_mfma_f32_16x16x32_bf16 v[124:127], v[148:151], v[176:179], v[124:127]
	v_mfma_f32_16x16x32_bf16 v[120:123], v[164:167], v[176:179], v[120:123]
	v_mfma_f32_16x16x32_bf16 v[116:119], v[148:151], v[184:187], v[116:119]
	v_mfma_f32_16x16x32_bf16 v[112:115], v[164:167], v[184:187], v[112:115]
	v_mfma_f32_16x16x32_bf16 v[96:99], v[148:151], v[192:195], v[96:99]
	v_mfma_f32_16x16x32_bf16 v[88:91], v[164:167], v[192:195], v[88:91]
	v_mfma_f32_16x16x32_bf16 v[80:83], v[148:151], v[200:203], v[80:83]
	v_mfma_f32_16x16x32_bf16 v[72:75], v[164:167], v[200:203], v[72:75]
	s_setprio 0
	s_barrier
	s_add_i32 s50, s40, s29
	v_lshl_add_u64 v[152:153], s[24:25], 0, v[130:131]
	s_mov_b32 m0, s50
	ds_read_b128 v[204:207], v159
	ds_read_b128 v[212:215], v159 offset:1024
	ds_read_b128 v[216:219], v159 offset:2048
	ds_read_b128 v[220:223], v159 offset:3072
	global_load_lds_dwordx4 v[152:153], off
	v_lshl_add_u64 v[172:173], s[24:25], 0, v[134:135]
	s_add_i32 m0, s50, 0x2000
	s_nop 0
	global_load_lds_dwordx4 v[172:173], off
	s_waitcnt lgkmcnt(0)
	s_setprio 1
	s_barrier
	v_mfma_f32_16x16x32_bf16 v[108:111], v[204:207], v[168:171], v[108:111]
	v_mfma_f32_16x16x32_bf16 v[104:107], v[216:219], v[168:171], v[104:107]
	v_mfma_f32_16x16x32_bf16 v[100:103], v[204:207], v[180:183], v[100:103]
	v_mfma_f32_16x16x32_bf16 v[92:95], v[216:219], v[180:183], v[92:95]
	v_mfma_f32_16x16x32_bf16 v[84:87], v[204:207], v[188:191], v[84:87]
	v_mfma_f32_16x16x32_bf16 v[76:79], v[216:219], v[188:191], v[76:79]
	v_mfma_f32_16x16x32_bf16 v[68:71], v[204:207], v[196:199], v[68:71]
	v_mfma_f32_16x16x32_bf16 v[64:67], v[216:219], v[196:199], v[64:67]
	v_mfma_f32_16x16x32_bf16 v[108:111], v[212:215], v[176:179], v[108:111]
	v_mfma_f32_16x16x32_bf16 v[104:107], v[220:223], v[176:179], v[104:107]
	v_mfma_f32_16x16x32_bf16 v[100:103], v[212:215], v[184:187], v[100:103]
	v_mfma_f32_16x16x32_bf16 v[92:95], v[220:223], v[184:187], v[92:95]
	v_mfma_f32_16x16x32_bf16 v[84:87], v[212:215], v[192:195], v[84:87]
	v_mfma_f32_16x16x32_bf16 v[76:79], v[220:223], v[192:195], v[76:79]
	v_mfma_f32_16x16x32_bf16 v[68:71], v[212:215], v[200:203], v[68:71]
	v_mfma_f32_16x16x32_bf16 v[64:67], v[220:223], v[200:203], v[64:67]
	s_setprio 0
	s_mov_b32 m0, s21
	v_lshl_add_u64 v[208:209], s[26:27], 0, v[128:129]
	s_barrier
	ds_read_b128 v[168:171], v158 offset:16384
	ds_read_b128 v[176:179], v158 offset:17408
	ds_read_b128 v[180:183], v158 offset:18432
	ds_read_b128 v[184:187], v158 offset:19456
	ds_read_b128 v[188:191], v158 offset:20480
	ds_read_b128 v[192:195], v158 offset:21504
	ds_read_b128 v[196:199], v158 offset:22528
	ds_read_b128 v[200:203], v158 offset:23552
	global_load_lds_dwordx4 v[208:209], off
	v_lshl_add_u64 v[224:225], s[26:27], 0, v[132:133]
	s_mov_b32 m0, s30
	s_nop 0
	global_load_lds_dwordx4 v[224:225], off
	s_waitcnt lgkmcnt(0)
	s_setprio 1
	s_barrier
	v_mfma_f32_16x16x32_bf16 v[60:63], v[144:147], v[168:171], v[60:63]
	v_mfma_f32_16x16x32_bf16 v[56:59], v[160:163], v[168:171], v[56:59]
	v_mfma_f32_16x16x32_bf16 v[52:55], v[144:147], v[180:183], v[52:55]
	v_mfma_f32_16x16x32_bf16 v[48:51], v[160:163], v[180:183], v[48:51]
	v_mfma_f32_16x16x32_bf16 v[32:35], v[144:147], v[188:191], v[32:35]
	v_mfma_f32_16x16x32_bf16 v[24:27], v[160:163], v[188:191], v[24:27]
	v_mfma_f32_16x16x32_bf16 v[16:19], v[144:147], v[196:199], v[16:19]
	v_mfma_f32_16x16x32_bf16 v[8:11], v[160:163], v[196:199], v[8:11]
	v_mfma_f32_16x16x32_bf16 v[60:63], v[148:151], v[176:179], v[60:63]
	v_mfma_f32_16x16x32_bf16 v[56:59], v[164:167], v[176:179], v[56:59]
	v_mfma_f32_16x16x32_bf16 v[52:55], v[148:151], v[184:187], v[52:55]
	v_mfma_f32_16x16x32_bf16 v[48:51], v[164:167], v[184:187], v[48:51]
	v_mfma_f32_16x16x32_bf16 v[32:35], v[148:151], v[192:195], v[32:35]
	v_mfma_f32_16x16x32_bf16 v[24:27], v[164:167], v[192:195], v[24:27]
	v_mfma_f32_16x16x32_bf16 v[16:19], v[148:151], v[200:203], v[16:19]
	v_mfma_f32_16x16x32_bf16 v[8:11], v[164:167], v[200:203], v[8:11]
	s_setprio 0
	s_barrier
	s_add_u32 s50, s24, 0x40000
	s_addc_u32 s51, s25, 0
	s_add_i32 s52, s41, s29
	v_lshl_add_u64 v[144:145], s[50:51], 0, v[130:131]
	s_mov_b32 m0, s52
	s_nop 0
	global_load_lds_dwordx4 v[144:145], off
	v_lshl_add_u64 v[144:145], s[50:51], 0, v[134:135]
	s_add_i32 m0, s52, 0x2000
	s_nop 0
	global_load_lds_dwordx4 v[144:145], off
	s_waitcnt vmcnt(6)
	s_setprio 1
	s_barrier
	v_mfma_f32_16x16x32_bf16 v[44:47], v[204:207], v[168:171], v[44:47]
	v_mfma_f32_16x16x32_bf16 v[40:43], v[216:219], v[168:171], v[40:43]
	v_mfma_f32_16x16x32_bf16 v[36:39], v[204:207], v[180:183], v[36:39]
	v_mfma_f32_16x16x32_bf16 v[28:31], v[216:219], v[180:183], v[28:31]
	v_mfma_f32_16x16x32_bf16 v[20:23], v[204:207], v[188:191], v[20:23]
	v_mfma_f32_16x16x32_bf16 v[12:15], v[216:219], v[188:191], v[12:15]
	v_mfma_f32_16x16x32_bf16 v[4:7], v[204:207], v[196:199], v[4:7]
	v_mfma_f32_16x16x32_bf16 v[0:3], v[216:219], v[196:199], v[0:3]
	v_mfma_f32_16x16x32_bf16 v[44:47], v[212:215], v[176:179], v[44:47]
	v_mfma_f32_16x16x32_bf16 v[40:43], v[220:223], v[176:179], v[40:43]
	v_mfma_f32_16x16x32_bf16 v[36:39], v[212:215], v[184:187], v[36:39]
	v_mfma_f32_16x16x32_bf16 v[28:31], v[220:223], v[184:187], v[28:31]
	v_mfma_f32_16x16x32_bf16 v[20:23], v[212:215], v[192:195], v[20:23]
	v_mfma_f32_16x16x32_bf16 v[12:15], v[220:223], v[192:195], v[12:15]
	v_mfma_f32_16x16x32_bf16 v[4:7], v[212:215], v[200:203], v[4:7]
	v_mfma_f32_16x16x32_bf16 v[0:3], v[220:223], v[200:203], v[0:3]
	s_setprio 0
	s_add_i32 s50, 0, 0x18000
	v_add_u32_e32 v164, s50, v155
	s_barrier
	ds_read_b128 v[144:147], v164
	ds_read_b128 v[148:151], v164 offset:1024
	ds_read_b128 v[160:163], v164 offset:2048
	ds_read_b128 v[164:167], v164 offset:3072
	s_add_u32 s26, s26, 0x40000
	s_addc_u32 s27, s27, 0
	s_mov_b32 m0, s31
	v_lshl_add_u64 v[204:205], s[26:27], 0, v[128:129]
	ds_read_b128 v[168:171], v158 offset:32768
	ds_read_b128 v[176:179], v158 offset:33792
	ds_read_b128 v[180:183], v158 offset:34816
	ds_read_b128 v[184:187], v158 offset:35840
	ds_read_b128 v[188:191], v158 offset:36864
	ds_read_b128 v[192:195], v158 offset:37888
	ds_read_b128 v[196:199], v158 offset:38912
	ds_read_b128 v[200:203], v158 offset:39936
	global_load_lds_dwordx4 v[204:205], off
	v_lshl_add_u64 v[204:205], s[26:27], 0, v[132:133]
	s_mov_b32 m0, s33
	s_nop 0
	global_load_lds_dwordx4 v[204:205], off
	s_waitcnt lgkmcnt(8)
	s_waitcnt lgkmcnt(0)
	s_setprio 1
	s_barrier
	v_mfma_f32_16x16x32_bf16 v[124:127], v[144:147], v[168:171], v[124:127]
	v_mfma_f32_16x16x32_bf16 v[120:123], v[160:163], v[168:171], v[120:123]
	v_mfma_f32_16x16x32_bf16 v[116:119], v[144:147], v[180:183], v[116:119]
	v_mfma_f32_16x16x32_bf16 v[112:115], v[160:163], v[180:183], v[112:115]
	v_mfma_f32_16x16x32_bf16 v[96:99], v[144:147], v[188:191], v[96:99]
	v_mfma_f32_16x16x32_bf16 v[88:91], v[160:163], v[188:191], v[88:91]
	v_mfma_f32_16x16x32_bf16 v[80:83], v[144:147], v[196:199], v[80:83]
	v_mfma_f32_16x16x32_bf16 v[72:75], v[160:163], v[196:199], v[72:75]
	v_mfma_f32_16x16x32_bf16 v[124:127], v[148:151], v[176:179], v[124:127]
	v_mfma_f32_16x16x32_bf16 v[120:123], v[164:167], v[176:179], v[120:123]
	v_mfma_f32_16x16x32_bf16 v[116:119], v[148:151], v[184:187], v[116:119]
	v_mfma_f32_16x16x32_bf16 v[112:115], v[164:167], v[184:187], v[112:115]
	v_mfma_f32_16x16x32_bf16 v[96:99], v[148:151], v[192:195], v[96:99]
	v_mfma_f32_16x16x32_bf16 v[88:91], v[164:167], v[192:195], v[88:91]
	v_mfma_f32_16x16x32_bf16 v[80:83], v[148:151], v[200:203], v[80:83]
	v_mfma_f32_16x16x32_bf16 v[72:75], v[164:167], v[200:203], v[72:75]
	s_setprio 0
	s_barrier
	s_add_i32 s26, 0, 0x1c000
	s_add_i32 s27, s50, s29
	v_add_u32_e32 v175, s26, v155
	v_lshl_add_u64 v[152:153], v[152:153], 0, s[0:1]
	s_mov_b32 m0, s27
	ds_read_b128 v[204:207], v175
	ds_read_b128 v[212:215], v175 offset:1024
	ds_read_b128 v[216:219], v175 offset:2048
	ds_read_b128 v[220:223], v175 offset:3072
	global_load_lds_dwordx4 v[152:153], off
	v_lshl_add_u64 v[152:153], v[172:173], 0, s[0:1]
	s_add_i32 m0, s27, 0x2000
	s_nop 0
	global_load_lds_dwordx4 v[152:153], off
	s_waitcnt lgkmcnt(0)
	s_setprio 1
	s_barrier
	v_mfma_f32_16x16x32_bf16 v[108:111], v[204:207], v[168:171], v[108:111]
	v_mfma_f32_16x16x32_bf16 v[104:107], v[216:219], v[168:171], v[104:107]
	v_mfma_f32_16x16x32_bf16 v[100:103], v[204:207], v[180:183], v[100:103]
	v_mfma_f32_16x16x32_bf16 v[92:95], v[216:219], v[180:183], v[92:95]
	v_mfma_f32_16x16x32_bf16 v[84:87], v[204:207], v[188:191], v[84:87]
	v_mfma_f32_16x16x32_bf16 v[76:79], v[216:219], v[188:191], v[76:79]
	v_mfma_f32_16x16x32_bf16 v[68:71], v[204:207], v[196:199], v[68:71]
	v_mfma_f32_16x16x32_bf16 v[64:67], v[216:219], v[196:199], v[64:67]
	v_mfma_f32_16x16x32_bf16 v[108:111], v[212:215], v[176:179], v[108:111]
	v_mfma_f32_16x16x32_bf16 v[104:107], v[220:223], v[176:179], v[104:107]
	v_mfma_f32_16x16x32_bf16 v[100:103], v[212:215], v[184:187], v[100:103]
	v_mfma_f32_16x16x32_bf16 v[92:95], v[220:223], v[184:187], v[92:95]
	v_mfma_f32_16x16x32_bf16 v[84:87], v[212:215], v[192:195], v[84:87]
	v_mfma_f32_16x16x32_bf16 v[76:79], v[220:223], v[192:195], v[76:79]
	v_mfma_f32_16x16x32_bf16 v[68:71], v[212:215], v[200:203], v[68:71]
	v_mfma_f32_16x16x32_bf16 v[64:67], v[220:223], v[200:203], v[64:67]
	s_setprio 0
	s_mov_b32 m0, s35
	v_lshl_add_u64 v[152:153], v[208:209], 0, s[0:1]
	s_barrier
	ds_read_b128 v[168:171], v158 offset:49152
	ds_read_b128 v[176:179], v158 offset:50176
	ds_read_b128 v[180:183], v158 offset:51200
	ds_read_b128 v[184:187], v158 offset:52224
	ds_read_b128 v[188:191], v158 offset:53248
	ds_read_b128 v[192:195], v158 offset:54272
	ds_read_b128 v[196:199], v158 offset:55296
	ds_read_b128 v[200:203], v158 offset:56320
	global_load_lds_dwordx4 v[152:153], off
	v_lshl_add_u64 v[152:153], v[224:225], 0, s[0:1]
	s_mov_b32 m0, s36
	s_nop 0
	global_load_lds_dwordx4 v[152:153], off
	s_waitcnt lgkmcnt(0)
	s_setprio 1
	s_barrier
	v_mfma_f32_16x16x32_bf16 v[60:63], v[144:147], v[168:171], v[60:63]
	v_mfma_f32_16x16x32_bf16 v[56:59], v[160:163], v[168:171], v[56:59]
	v_mfma_f32_16x16x32_bf16 v[52:55], v[144:147], v[180:183], v[52:55]
	v_mfma_f32_16x16x32_bf16 v[48:51], v[160:163], v[180:183], v[48:51]
	v_mfma_f32_16x16x32_bf16 v[32:35], v[144:147], v[188:191], v[32:35]
	v_mfma_f32_16x16x32_bf16 v[24:27], v[160:163], v[188:191], v[24:27]
	v_mfma_f32_16x16x32_bf16 v[16:19], v[144:147], v[196:199], v[16:19]
	v_mfma_f32_16x16x32_bf16 v[8:11], v[160:163], v[196:199], v[8:11]
	v_mfma_f32_16x16x32_bf16 v[60:63], v[148:151], v[176:179], v[60:63]
	v_mfma_f32_16x16x32_bf16 v[56:59], v[164:167], v[176:179], v[56:59]
	v_mfma_f32_16x16x32_bf16 v[52:55], v[148:151], v[184:187], v[52:55]
	v_mfma_f32_16x16x32_bf16 v[48:51], v[164:167], v[184:187], v[48:51]
	v_mfma_f32_16x16x32_bf16 v[32:35], v[148:151], v[192:195], v[32:35]
	v_mfma_f32_16x16x32_bf16 v[24:27], v[164:167], v[192:195], v[24:27]
	v_mfma_f32_16x16x32_bf16 v[16:19], v[148:151], v[200:203], v[16:19]
	v_mfma_f32_16x16x32_bf16 v[8:11], v[164:167], v[200:203], v[8:11]
	s_setprio 0
	s_barrier
	s_add_u32 s24, s24, 0x40080
	s_addc_u32 s25, s25, 0
	s_add_i32 s26, s26, s29
	v_lshl_add_u64 v[144:145], s[24:25], 0, v[130:131]
	s_mov_b32 m0, s26
	s_nop 0
	global_load_lds_dwordx4 v[144:145], off
	v_lshl_add_u64 v[144:145], s[24:25], 0, v[134:135]
	s_add_i32 m0, s26, 0x2000
	s_nop 0
	global_load_lds_dwordx4 v[144:145], off
	s_waitcnt vmcnt(6)
	s_setprio 1
	s_barrier
	v_mfma_f32_16x16x32_bf16 v[44:47], v[204:207], v[168:171], v[44:47]
	v_mfma_f32_16x16x32_bf16 v[40:43], v[216:219], v[168:171], v[40:43]
	v_mfma_f32_16x16x32_bf16 v[36:39], v[204:207], v[180:183], v[36:39]
	v_mfma_f32_16x16x32_bf16 v[28:31], v[216:219], v[180:183], v[28:31]
	v_mfma_f32_16x16x32_bf16 v[20:23], v[204:207], v[188:191], v[20:23]
	v_mfma_f32_16x16x32_bf16 v[12:15], v[216:219], v[188:191], v[12:15]
	v_mfma_f32_16x16x32_bf16 v[4:7], v[204:207], v[196:199], v[4:7]
	v_mfma_f32_16x16x32_bf16 v[0:3], v[216:219], v[196:199], v[0:3]
	v_mfma_f32_16x16x32_bf16 v[44:47], v[212:215], v[176:179], v[44:47]
	v_mfma_f32_16x16x32_bf16 v[40:43], v[220:223], v[176:179], v[40:43]
	v_mfma_f32_16x16x32_bf16 v[36:39], v[212:215], v[184:187], v[36:39]
	v_mfma_f32_16x16x32_bf16 v[28:31], v[220:223], v[184:187], v[28:31]
	v_mfma_f32_16x16x32_bf16 v[20:23], v[212:215], v[192:195], v[20:23]
	v_mfma_f32_16x16x32_bf16 v[12:15], v[220:223], v[192:195], v[12:15]
	v_mfma_f32_16x16x32_bf16 v[4:7], v[212:215], v[200:203], v[4:7]
	v_mfma_f32_16x16x32_bf16 v[0:3], v[220:223], v[200:203], v[0:3]
	s_setprio 0
	s_add_i32 s49, s49, 2
	s_add_u32 s22, s22, 0x100
	s_addc_u32 s23, s23, 0
	s_add_u32 s43, s43, 0x100
	s_addc_u32 s48, s48, 0
	s_cmp_gt_u32 s49, 13
	s_barrier
	s_cbranch_scc0 .LBB0_654
	v_lshl_add_u32 v148, s18, 8, v154
	v_lshl_or_b32 v144, s20, 8, v156
	v_readlane_b32 s48, v253, 12
	v_ashrrev_i32_e32 v145, 31, v144
	v_ashrrev_i32_e32 v149, 31, v148
	v_readlane_b32 s49, v253, 13
	v_lshlrev_b64 v[150:151], 12, v[148:149]
	v_or_b32_e32 v172, 16, v148
	v_lshl_add_u64 v[146:147], v[144:145], 2, s[48:49]
	v_lshl_add_u64 v[150:151], v[146:147], 0, v[150:151]
	v_ashrrev_i32_e32 v173, 31, v172
	global_load_dwordx4 v[160:163], v[150:151], off
	global_load_dwordx4 v[164:167], v[150:151], off offset:16
	global_load_dwordx4 v[168:171], v[150:151], off offset:512
	global_load_dwordx4 v[176:179], v[150:151], off offset:528
	v_lshlrev_b64 v[150:151], 12, v[172:173]
	v_or_b32_e32 v152, 32, v148
	v_lshl_add_u64 v[150:151], v[146:147], 0, v[150:151]
	v_ashrrev_i32_e32 v153, 31, v152
	global_load_dwordx4 v[180:183], v[150:151], off
	global_load_dwordx4 v[184:187], v[150:151], off offset:16
	global_load_dwordx4 v[188:191], v[150:151], off offset:512
	global_load_dwordx4 v[192:195], v[150:151], off offset:528
	v_lshlrev_b64 v[150:151], 12, v[152:153]
	v_lshl_add_u64 v[208:209], v[146:147], 0, v[150:151]
	v_or_b32_e32 v150, 48, v148
	global_load_dwordx4 v[196:199], v[208:209], off
	global_load_dwordx4 v[200:203], v[208:209], off offset:16
	v_ashrrev_i32_e32 v151, 31, v150
	v_lshlrev_b64 v[204:205], 11, v[148:149]
	v_lshlrev_b64 v[216:217], 12, v[150:151]
	v_lshl_add_u64 v[218:219], s[10:11], 0, v[204:205]
	global_load_dwordx4 v[204:207], v[208:209], off offset:528
	global_load_dwordx4 v[212:215], v[208:209], off offset:512
	v_lshlrev_b64 v[144:145], 1, v[144:145]
	v_lshl_add_u64 v[208:209], v[146:147], 0, v[216:217]
	v_lshl_add_u64 v[232:233], v[218:219], 0, v[144:145]
	global_load_dwordx4 v[216:219], v[208:209], off offset:16
	global_load_dwordx4 v[220:223], v[208:209], off
	global_load_dwordx4 v[224:227], v[208:209], off offset:528
	global_load_dwordx4 v[228:231], v[208:209], off offset:512
	v_lshlrev_b64 v[172:173], 11, v[172:173]
	v_lshl_add_u64 v[172:173], s[10:11], 0, v[172:173]
	v_lshl_add_u64 v[172:173], v[172:173], 0, v[144:145]
	v_readlane_b32 s50, v253, 14
	v_readlane_b32 s51, v253, 15
	v_readlane_b32 s52, v253, 16
	v_readlane_b32 s53, v253, 17
	v_readlane_b32 s54, v253, 18
	v_readlane_b32 s55, v253, 19
	v_readlane_b32 s56, v253, 20
	v_readlane_b32 s57, v253, 21
	v_readlane_b32 s58, v253, 22
	v_readlane_b32 s59, v253, 23
	v_readlane_b32 s60, v253, 24
	v_readlane_b32 s61, v253, 25
	v_readlane_b32 s62, v253, 26
	v_readlane_b32 s63, v253, 27
	s_waitcnt vmcnt(0)
	v_pk_add_f32 v[126:127], v[126:127], v[162:163]
	v_pk_add_f32 v[124:125], v[124:125], v[160:161]
	v_pk_add_f32 v[160:161], v[122:123], v[166:167]
	v_pk_add_f32 v[162:163], v[120:121], v[164:165]
	v_pk_add_f32 v[164:165], v[110:111], v[170:171]
	v_pk_add_f32 v[166:167], v[108:109], v[168:169]
	v_pk_add_f32 v[168:169], v[106:107], v[178:179]
	v_cvt_pk_bf16_f32 v120, v124, v125
	v_cvt_pk_bf16_f32 v121, v126, v127
	v_cvt_pk_bf16_f32 v122, v162, v163
	v_cvt_pk_bf16_f32 v123, v160, v161
	v_pk_add_f32 v[106:107], v[112:113], v[184:185]
	global_store_dwordx4 v[232:233], v[120:123], off
	v_cvt_pk_bf16_f32 v112, v166, v167
	v_cvt_pk_bf16_f32 v113, v164, v165
	v_pk_add_f32 v[170:171], v[104:105], v[176:177]
	v_pk_add_f32 v[108:109], v[118:119], v[182:183]
	v_pk_add_f32 v[110:111], v[116:117], v[180:181]
	v_pk_add_f32 v[104:105], v[114:115], v[186:187]
	v_cvt_pk_bf16_f32 v114, v170, v171
	v_cvt_pk_bf16_f32 v115, v168, v169
	global_store_dwordx4 v[232:233], v[112:115], off offset:256
	v_mul_f32_e32 v175, v125, v125
	v_mul_f32_e32 v176, v127, v127
	v_cvt_pk_bf16_f32 v112, v110, v111
	v_cvt_pk_bf16_f32 v113, v108, v109
	v_mul_f32_e32 v125, v167, v167
	v_mul_f32_e32 v127, v165, v165
	v_cvt_pk_bf16_f32 v114, v106, v107
	v_cvt_pk_bf16_f32 v115, v104, v105
	global_store_dwordx4 v[172:173], v[112:115], off
	v_mul_f32_e32 v177, v163, v163
	v_mul_f32_e32 v178, v161, v161
	v_pk_add_f32 v[112:113], v[100:101], v[188:189]
	v_pk_add_f32 v[100:101], v[92:93], v[192:193]
	v_pk_add_f32 v[92:93], v[98:99], v[198:199]
	v_lshlrev_b64 v[98:99], 11, v[152:153]
	v_mul_f32_e32 v161, v171, v171
	v_fmac_f32_e32 v175, v124, v124
	v_fmac_f32_e32 v176, v126, v126
	v_fmac_f32_e32 v125, v166, v166
	v_fmac_f32_e32 v127, v164, v164
	v_lshl_add_u64 v[98:99], s[10:11], 0, v[98:99]
	v_mul_f32_e32 v163, v169, v169
	v_fmac_f32_e32 v177, v162, v162
	v_fmac_f32_e32 v161, v170, v170
	v_add_f32_e32 v116, v175, v176
	v_add_f32_e32 v117, v125, v127
	v_lshl_add_u64 v[118:119], v[98:99], 0, v[144:145]
	v_pk_add_f32 v[98:99], v[84:85], v[212:213]
	v_pk_add_f32 v[84:85], v[76:77], v[204:205]
	v_pk_add_f32 v[76:77], v[82:83], v[222:223]
	v_lshlrev_b64 v[82:83], 11, v[150:151]
	v_fmac_f32_e32 v178, v160, v160
	v_fmac_f32_e32 v163, v168, v168
	v_add_f32_e32 v116, v116, v177
	v_add_f32_e32 v117, v117, v161
	v_lshl_add_u64 v[82:83], s[10:11], 0, v[82:83]
	v_add_f32_e32 v116, v178, v116
	v_add_f32_e32 v117, v163, v117
	v_cvt_pk_bf16_f32 v114, v112, v113
	v_lshl_add_u64 v[122:123], v[82:83], 0, v[144:145]
	v_pk_add_f32 v[82:83], v[68:69], v[228:229]
	v_pk_add_f32 v[68:69], v[64:65], v[224:225]
	v_and_b32_e32 v65, 64, v174
	v_add_f32_e32 v120, v116, v117
	v_pk_add_f32 v[102:103], v[102:103], v[190:191]
	v_pk_add_f32 v[94:95], v[94:95], v[194:195]
	v_cvt_pk_bf16_f32 v115, v102, v103
	v_cvt_pk_bf16_f32 v116, v100, v101
	v_pk_add_f32 v[96:97], v[96:97], v[196:197]
	v_cvt_pk_bf16_f32 v117, v94, v95
	global_store_dwordx4 v[172:173], v[114:117], off offset:256
	v_xor_b32_e32 v64, 16, v174
	v_add_u32_e32 v65, 64, v65
	v_cvt_pk_bf16_f32 v114, v96, v97
	v_pk_add_f32 v[90:91], v[90:91], v[202:203]
	v_pk_add_f32 v[88:89], v[88:89], v[200:201]
	v_cvt_pk_bf16_f32 v115, v92, v93
	v_cmp_lt_i32_e32 vcc, v64, v65
	v_cvt_pk_bf16_f32 v116, v88, v89
	v_cvt_pk_bf16_f32 v117, v90, v91
	global_store_dwordx4 v[118:119], v[114:117], off
	v_pk_add_f32 v[86:87], v[86:87], v[214:215]
	v_pk_add_f32 v[78:79], v[78:79], v[206:207]
	v_cvt_pk_bf16_f32 v114, v98, v99
	v_cvt_pk_bf16_f32 v115, v86, v87
	v_cvt_pk_bf16_f32 v116, v84, v85
	v_pk_add_f32 v[80:81], v[80:81], v[220:221]
	v_cvt_pk_bf16_f32 v117, v78, v79
	global_store_dwordx4 v[118:119], v[114:117], off offset:256
	v_cndmask_b32_e32 v64, v174, v64, vcc
	v_pk_add_f32 v[74:75], v[74:75], v[218:219]
	v_cvt_pk_bf16_f32 v114, v80, v81
	v_pk_add_f32 v[72:73], v[72:73], v[216:217]
	v_cvt_pk_bf16_f32 v115, v76, v77
	v_pk_add_f32 v[70:71], v[70:71], v[230:231]
	v_cvt_pk_bf16_f32 v116, v72, v73
	v_cvt_pk_bf16_f32 v117, v74, v75
	global_store_dwordx4 v[122:123], v[114:117], off
	v_pk_add_f32 v[66:67], v[66:67], v[226:227]
	v_cvt_pk_bf16_f32 v118, v82, v83
	v_cvt_pk_bf16_f32 v119, v70, v71
	s_nop 0
	v_lshlrev_b32_e32 v114, 2, v64
	ds_bpermute_b32 v64, v114, v120
	v_xor_b32_e32 v115, 32, v174
	v_cmp_lt_i32_e32 vcc, v115, v65
	s_waitcnt lgkmcnt(0)
	v_add_f32_e32 v116, v120, v64
	v_cndmask_b32_e32 v65, v174, v115, vcc
	v_lshlrev_b32_e32 v115, 2, v65
	ds_bpermute_b32 v117, v115, v116
	v_lshl_add_u64 v[64:65], v[148:149], 2, s[66:67]
	v_cvt_pk_bf16_f32 v120, v68, v69
	v_cvt_pk_bf16_f32 v121, v66, v67
	global_store_dwordx4 v[122:123], v[118:121], off offset:256
	s_and_saveexec_b64 s[18:19], s[6:7]
	s_cbranch_execz .LBB0_657
	s_waitcnt lgkmcnt(0)
	v_add_f32_e32 v116, v116, v117
	global_atomic_add_f32 v[64:65], v116, off

.LBB0_712:
	ds_read_b128 v[144:147], v151
	ds_read_b128 v[156:159], v151 offset:1024
	ds_read_b128 v[160:163], v151 offset:2048
	ds_read_b128 v[164:167], v151 offset:3072
	s_add_u32 s26, s2, 0xfffc0080
	s_addc_u32 s27, s3, -1
	s_cmp_eq_u32 s56, 12
	s_cselect_b32 s29, s21, s27
	s_cselect_b32 s28, s52, s26
	s_cselect_b32 s27, s19, s55
	s_cselect_b32 s26, s53, s54
	v_lshl_add_u64 v[172:173], s[2:3], 0, v[136:137]
	s_add_i32 m0, s34, 0xc000
	ds_read_b128 v[168:171], v152
	ds_read_b128 v[176:179], v152 offset:1024
	ds_read_b128 v[180:183], v152 offset:2048
	ds_read_b128 v[184:187], v152 offset:3072
	ds_read_b128 v[188:191], v152 offset:4096
	ds_read_b128 v[192:195], v152 offset:5120
	ds_read_b128 v[196:199], v152 offset:6144
	ds_read_b128 v[200:203], v152 offset:7168
	global_load_lds_dwordx4 v[172:173], off
	v_lshl_add_u64 v[172:173], s[2:3], 0, v[138:139]
	s_add_i32 m0, s34, 0xe000
	s_nop 0
	global_load_lds_dwordx4 v[172:173], off
	s_waitcnt lgkmcnt(8)
	s_waitcnt lgkmcnt(0)
	s_setprio 1
	s_barrier
	v_mfma_f32_16x16x32_bf16 v[124:127], v[144:147], v[168:171], v[124:127]
	v_mfma_f32_16x16x32_bf16 v[120:123], v[160:163], v[168:171], v[120:123]
	v_mfma_f32_16x16x32_bf16 v[116:119], v[144:147], v[180:183], v[116:119]
	v_mfma_f32_16x16x32_bf16 v[112:115], v[160:163], v[180:183], v[112:115]
	v_mfma_f32_16x16x32_bf16 v[104:107], v[144:147], v[188:191], v[104:107]
	v_mfma_f32_16x16x32_bf16 v[96:99], v[160:163], v[188:191], v[96:99]
	v_mfma_f32_16x16x32_bf16 v[76:79], v[144:147], v[196:199], v[76:79]
	v_mfma_f32_16x16x32_bf16 v[72:75], v[160:163], v[196:199], v[72:75]
	v_mfma_f32_16x16x32_bf16 v[124:127], v[156:159], v[176:179], v[124:127]
	v_mfma_f32_16x16x32_bf16 v[120:123], v[164:167], v[176:179], v[120:123]
	v_mfma_f32_16x16x32_bf16 v[116:119], v[156:159], v[184:187], v[116:119]
	v_mfma_f32_16x16x32_bf16 v[112:115], v[164:167], v[184:187], v[112:115]
	v_mfma_f32_16x16x32_bf16 v[104:107], v[156:159], v[192:195], v[104:107]
	v_mfma_f32_16x16x32_bf16 v[96:99], v[164:167], v[192:195], v[96:99]
	v_mfma_f32_16x16x32_bf16 v[76:79], v[156:159], v[200:203], v[76:79]
	v_mfma_f32_16x16x32_bf16 v[72:75], v[164:167], v[200:203], v[72:75]
	s_setprio 0
	s_barrier
	s_add_i32 s57, s43, s33
	v_lshl_add_u64 v[172:173], s[26:27], 0, v[130:131]
	s_mov_b32 m0, s57
	ds_read_b128 v[204:207], v153
	ds_read_b128 v[212:215], v153 offset:1024
	ds_read_b128 v[216:219], v153 offset:2048
	ds_read_b128 v[220:223], v153 offset:3072
	global_load_lds_dwordx4 v[172:173], off
	v_lshl_add_u64 v[208:209], s[26:27], 0, v[134:135]
	s_add_i32 m0, s57, 0x2000
	s_nop 0
	global_load_lds_dwordx4 v[208:209], off
	s_waitcnt lgkmcnt(0)
	s_setprio 1
	s_barrier
	v_mfma_f32_16x16x32_bf16 v[108:111], v[204:207], v[168:171], v[108:111]
	v_mfma_f32_16x16x32_bf16 v[100:103], v[216:219], v[168:171], v[100:103]
	v_mfma_f32_16x16x32_bf16 v[92:95], v[204:207], v[180:183], v[92:95]
	v_mfma_f32_16x16x32_bf16 v[88:91], v[216:219], v[180:183], v[88:91]
	v_mfma_f32_16x16x32_bf16 v[84:87], v[204:207], v[188:191], v[84:87]
	v_mfma_f32_16x16x32_bf16 v[80:83], v[216:219], v[188:191], v[80:83]
	v_mfma_f32_16x16x32_bf16 v[68:71], v[204:207], v[196:199], v[68:71]
	v_mfma_f32_16x16x32_bf16 v[64:67], v[216:219], v[196:199], v[64:67]
	v_mfma_f32_16x16x32_bf16 v[108:111], v[212:215], v[176:179], v[108:111]
	v_mfma_f32_16x16x32_bf16 v[100:103], v[220:223], v[176:179], v[100:103]
	v_mfma_f32_16x16x32_bf16 v[92:95], v[212:215], v[184:187], v[92:95]
	v_mfma_f32_16x16x32_bf16 v[88:91], v[220:223], v[184:187], v[88:91]
	v_mfma_f32_16x16x32_bf16 v[84:87], v[212:215], v[192:195], v[84:87]
	v_mfma_f32_16x16x32_bf16 v[80:83], v[220:223], v[192:195], v[80:83]
	v_mfma_f32_16x16x32_bf16 v[68:71], v[212:215], v[200:203], v[68:71]
	v_mfma_f32_16x16x32_bf16 v[64:67], v[220:223], v[200:203], v[64:67]
	s_setprio 0
	s_mov_b32 m0, s34
	v_lshl_add_u64 v[224:225], s[28:29], 0, v[128:129]
	s_barrier
	ds_read_b128 v[168:171], v152 offset:16384
	ds_read_b128 v[176:179], v152 offset:17408
	ds_read_b128 v[180:183], v152 offset:18432
	ds_read_b128 v[184:187], v152 offset:19456
	ds_read_b128 v[188:191], v152 offset:20480
	ds_read_b128 v[192:195], v152 offset:21504
	ds_read_b128 v[196:199], v152 offset:22528
	ds_read_b128 v[200:203], v152 offset:23552
	global_load_lds_dwordx4 v[224:225], off
	v_lshl_add_u64 v[226:227], s[28:29], 0, v[132:133]
	s_mov_b32 m0, s35
	s_nop 0
	global_load_lds_dwordx4 v[226:227], off
	s_waitcnt lgkmcnt(0)
	s_setprio 1
	s_barrier
	v_mfma_f32_16x16x32_bf16 v[60:63], v[144:147], v[168:171], v[60:63]
	v_mfma_f32_16x16x32_bf16 v[56:59], v[160:163], v[168:171], v[56:59]
	v_mfma_f32_16x16x32_bf16 v[44:47], v[144:147], v[180:183], v[44:47]
	v_mfma_f32_16x16x32_bf16 v[40:43], v[160:163], v[180:183], v[40:43]
	v_mfma_f32_16x16x32_bf16 v[28:31], v[144:147], v[188:191], v[28:31]
	v_mfma_f32_16x16x32_bf16 v[24:27], v[160:163], v[188:191], v[24:27]
	v_mfma_f32_16x16x32_bf16 v[12:15], v[144:147], v[196:199], v[12:15]
	v_mfma_f32_16x16x32_bf16 v[8:11], v[160:163], v[196:199], v[8:11]
	v_mfma_f32_16x16x32_bf16 v[60:63], v[156:159], v[176:179], v[60:63]
	v_mfma_f32_16x16x32_bf16 v[56:59], v[164:167], v[176:179], v[56:59]
	v_mfma_f32_16x16x32_bf16 v[44:47], v[156:159], v[184:187], v[44:47]
	v_mfma_f32_16x16x32_bf16 v[40:43], v[164:167], v[184:187], v[40:43]
	v_mfma_f32_16x16x32_bf16 v[28:31], v[156:159], v[192:195], v[28:31]
	v_mfma_f32_16x16x32_bf16 v[24:27], v[164:167], v[192:195], v[24:27]
	v_mfma_f32_16x16x32_bf16 v[12:15], v[156:159], v[200:203], v[12:15]
	v_mfma_f32_16x16x32_bf16 v[8:11], v[164:167], v[200:203], v[8:11]
	s_setprio 0
	s_barrier
	s_add_u32 s58, s26, 0x40000
	s_addc_u32 s59, s27, 0
	s_add_i32 s57, s48, s33
	v_lshl_add_u64 v[144:145], s[58:59], 0, v[130:131]
	s_mov_b32 m0, s57
	s_nop 0
	global_load_lds_dwordx4 v[144:145], off
	v_lshl_add_u64 v[144:145], s[58:59], 0, v[134:135]
	s_add_i32 m0, s57, 0x2000
	s_nop 0
	global_load_lds_dwordx4 v[144:145], off
	s_waitcnt vmcnt(6)
	s_setprio 1
	s_barrier
	v_mfma_f32_16x16x32_bf16 v[52:55], v[204:207], v[168:171], v[52:55]
	v_mfma_f32_16x16x32_bf16 v[48:51], v[216:219], v[168:171], v[48:51]
	v_mfma_f32_16x16x32_bf16 v[36:39], v[204:207], v[180:183], v[36:39]
	v_mfma_f32_16x16x32_bf16 v[32:35], v[216:219], v[180:183], v[32:35]
	v_mfma_f32_16x16x32_bf16 v[20:23], v[204:207], v[188:191], v[20:23]
	v_mfma_f32_16x16x32_bf16 v[16:19], v[216:219], v[188:191], v[16:19]
	v_mfma_f32_16x16x32_bf16 v[4:7], v[204:207], v[196:199], v[4:7]
	v_mfma_f32_16x16x32_bf16 v[0:3], v[216:219], v[196:199], v[0:3]
	v_mfma_f32_16x16x32_bf16 v[52:55], v[212:215], v[176:179], v[52:55]
	v_mfma_f32_16x16x32_bf16 v[48:51], v[220:223], v[176:179], v[48:51]
	v_mfma_f32_16x16x32_bf16 v[36:39], v[212:215], v[184:187], v[36:39]
	v_mfma_f32_16x16x32_bf16 v[32:35], v[220:223], v[184:187], v[32:35]
	v_mfma_f32_16x16x32_bf16 v[20:23], v[212:215], v[192:195], v[20:23]
	v_mfma_f32_16x16x32_bf16 v[16:19], v[220:223], v[192:195], v[16:19]
	v_mfma_f32_16x16x32_bf16 v[4:7], v[212:215], v[200:203], v[4:7]
	v_mfma_f32_16x16x32_bf16 v[0:3], v[220:223], v[200:203], v[0:3]
	s_setprio 0
	s_add_i32 s57, 0, 0x18000
	v_add_u32_e32 v155, s57, v149
	s_barrier
	ds_read_b128 v[144:147], v155
	ds_read_b128 v[156:159], v155 offset:1024
	ds_read_b128 v[160:163], v155 offset:2048
	ds_read_b128 v[164:167], v155 offset:3072
	s_add_u32 s28, s28, 0x40000
	s_addc_u32 s29, s29, 0
	s_mov_b32 m0, s36
	v_lshl_add_u64 v[204:205], s[28:29], 0, v[128:129]
	ds_read_b128 v[168:171], v152 offset:32768
	ds_read_b128 v[176:179], v152 offset:33792
	ds_read_b128 v[180:183], v152 offset:34816
	ds_read_b128 v[184:187], v152 offset:35840
	ds_read_b128 v[188:191], v152 offset:36864
	ds_read_b128 v[192:195], v152 offset:37888
	ds_read_b128 v[196:199], v152 offset:38912
	ds_read_b128 v[200:203], v152 offset:39936
	global_load_lds_dwordx4 v[204:205], off
	v_lshl_add_u64 v[204:205], s[28:29], 0, v[132:133]
	s_mov_b32 m0, s37
	s_nop 0
	global_load_lds_dwordx4 v[204:205], off
	s_waitcnt lgkmcnt(8)
	s_waitcnt lgkmcnt(0)
	s_setprio 1
	s_barrier
	v_mfma_f32_16x16x32_bf16 v[124:127], v[144:147], v[168:171], v[124:127]
	v_mfma_f32_16x16x32_bf16 v[120:123], v[160:163], v[168:171], v[120:123]
	v_mfma_f32_16x16x32_bf16 v[116:119], v[144:147], v[180:183], v[116:119]
	v_mfma_f32_16x16x32_bf16 v[112:115], v[160:163], v[180:183], v[112:115]
	v_mfma_f32_16x16x32_bf16 v[104:107], v[144:147], v[188:191], v[104:107]
	v_mfma_f32_16x16x32_bf16 v[96:99], v[160:163], v[188:191], v[96:99]
	v_mfma_f32_16x16x32_bf16 v[76:79], v[144:147], v[196:199], v[76:79]
	v_mfma_f32_16x16x32_bf16 v[72:75], v[160:163], v[196:199], v[72:75]
	v_mfma_f32_16x16x32_bf16 v[124:127], v[156:159], v[176:179], v[124:127]
	v_mfma_f32_16x16x32_bf16 v[120:123], v[164:167], v[176:179], v[120:123]
	v_mfma_f32_16x16x32_bf16 v[116:119], v[156:159], v[184:187], v[116:119]
	v_mfma_f32_16x16x32_bf16 v[112:115], v[164:167], v[184:187], v[112:115]
	v_mfma_f32_16x16x32_bf16 v[104:107], v[156:159], v[192:195], v[104:107]
	v_mfma_f32_16x16x32_bf16 v[96:99], v[164:167], v[192:195], v[96:99]
	v_mfma_f32_16x16x32_bf16 v[76:79], v[156:159], v[200:203], v[76:79]
	v_mfma_f32_16x16x32_bf16 v[72:75], v[164:167], v[200:203], v[72:75]
	s_setprio 0
	s_barrier
	s_add_i32 s28, 0, 0x1c000
	s_add_i32 s29, s57, s33
	v_add_u32_e32 v155, s28, v149
	v_lshl_add_u64 v[172:173], v[172:173], 0, s[8:9]
	s_mov_b32 m0, s29
	ds_read_b128 v[204:207], v155
	ds_read_b128 v[212:215], v155 offset:1024
	ds_read_b128 v[216:219], v155 offset:2048
	ds_read_b128 v[220:223], v155 offset:3072
	global_load_lds_dwordx4 v[172:173], off
	v_lshl_add_u64 v[172:173], v[208:209], 0, s[8:9]
	s_add_i32 m0, s29, 0x2000
	s_nop 0
	global_load_lds_dwordx4 v[172:173], off
	s_waitcnt lgkmcnt(0)
	s_setprio 1
	s_barrier
	v_mfma_f32_16x16x32_bf16 v[108:111], v[204:207], v[168:171], v[108:111]
	v_mfma_f32_16x16x32_bf16 v[100:103], v[216:219], v[168:171], v[100:103]
	v_mfma_f32_16x16x32_bf16 v[92:95], v[204:207], v[180:183], v[92:95]
	v_mfma_f32_16x16x32_bf16 v[88:91], v[216:219], v[180:183], v[88:91]
	v_mfma_f32_16x16x32_bf16 v[84:87], v[204:207], v[188:191], v[84:87]
	v_mfma_f32_16x16x32_bf16 v[80:83], v[216:219], v[188:191], v[80:83]
	v_mfma_f32_16x16x32_bf16 v[68:71], v[204:207], v[196:199], v[68:71]
	v_mfma_f32_16x16x32_bf16 v[64:67], v[216:219], v[196:199], v[64:67]
	v_mfma_f32_16x16x32_bf16 v[108:111], v[212:215], v[176:179], v[108:111]
	v_mfma_f32_16x16x32_bf16 v[100:103], v[220:223], v[176:179], v[100:103]
	v_mfma_f32_16x16x32_bf16 v[92:95], v[212:215], v[184:187], v[92:95]
	v_mfma_f32_16x16x32_bf16 v[88:91], v[220:223], v[184:187], v[88:91]
	v_mfma_f32_16x16x32_bf16 v[84:87], v[212:215], v[192:195], v[84:87]
	v_mfma_f32_16x16x32_bf16 v[80:83], v[220:223], v[192:195], v[80:83]
	v_mfma_f32_16x16x32_bf16 v[68:71], v[212:215], v[200:203], v[68:71]
	v_mfma_f32_16x16x32_bf16 v[64:67], v[220:223], v[200:203], v[64:67]
	s_setprio 0
	s_mov_b32 m0, s39
	v_lshl_add_u64 v[172:173], v[224:225], 0, s[8:9]
	s_barrier
	ds_read_b128 v[168:171], v152 offset:49152
	ds_read_b128 v[176:179], v152 offset:50176
	ds_read_b128 v[180:183], v152 offset:51200
	ds_read_b128 v[184:187], v152 offset:52224
	ds_read_b128 v[188:191], v152 offset:53248
	ds_read_b128 v[192:195], v152 offset:54272
	ds_read_b128 v[196:199], v152 offset:55296
	ds_read_b128 v[200:203], v152 offset:56320
	global_load_lds_dwordx4 v[172:173], off
	v_lshl_add_u64 v[172:173], v[226:227], 0, s[8:9]
	s_mov_b32 m0, s40
	s_nop 0
	global_load_lds_dwordx4 v[172:173], off
	s_waitcnt lgkmcnt(0)
	s_setprio 1
	s_barrier
	v_mfma_f32_16x16x32_bf16 v[60:63], v[144:147], v[168:171], v[60:63]
	v_mfma_f32_16x16x32_bf16 v[56:59], v[160:163], v[168:171], v[56:59]
	v_mfma_f32_16x16x32_bf16 v[44:47], v[144:147], v[180:183], v[44:47]
	v_mfma_f32_16x16x32_bf16 v[40:43], v[160:163], v[180:183], v[40:43]
	v_mfma_f32_16x16x32_bf16 v[28:31], v[144:147], v[188:191], v[28:31]
	v_mfma_f32_16x16x32_bf16 v[24:27], v[160:163], v[188:191], v[24:27]
	v_mfma_f32_16x16x32_bf16 v[12:15], v[144:147], v[196:199], v[12:15]
	v_mfma_f32_16x16x32_bf16 v[8:11], v[160:163], v[196:199], v[8:11]
	v_mfma_f32_16x16x32_bf16 v[60:63], v[156:159], v[176:179], v[60:63]
	v_mfma_f32_16x16x32_bf16 v[56:59], v[164:167], v[176:179], v[56:59]
	v_mfma_f32_16x16x32_bf16 v[44:47], v[156:159], v[184:187], v[44:47]
	v_mfma_f32_16x16x32_bf16 v[40:43], v[164:167], v[184:187], v[40:43]
	v_mfma_f32_16x16x32_bf16 v[28:31], v[156:159], v[192:195], v[28:31]
	v_mfma_f32_16x16x32_bf16 v[24:27], v[164:167], v[192:195], v[24:27]
	v_mfma_f32_16x16x32_bf16 v[12:15], v[156:159], v[200:203], v[12:15]
	v_mfma_f32_16x16x32_bf16 v[8:11], v[164:167], v[200:203], v[8:11]
	s_setprio 0
	s_barrier
	s_add_u32 s26, s26, 0x40080
	s_addc_u32 s27, s27, 0
	s_add_i32 s28, s28, s33
	v_lshl_add_u64 v[144:145], s[26:27], 0, v[130:131]
	s_mov_b32 m0, s28
	s_nop 0
	global_load_lds_dwordx4 v[144:145], off
	v_lshl_add_u64 v[144:145], s[26:27], 0, v[134:135]
	s_add_i32 m0, s28, 0x2000
	s_nop 0
	global_load_lds_dwordx4 v[144:145], off
	s_waitcnt vmcnt(6)
	s_setprio 1
	s_barrier
	v_mfma_f32_16x16x32_bf16 v[52:55], v[204:207], v[168:171], v[52:55]
	v_mfma_f32_16x16x32_bf16 v[48:51], v[216:219], v[168:171], v[48:51]
	v_mfma_f32_16x16x32_bf16 v[36:39], v[204:207], v[180:183], v[36:39]
	v_mfma_f32_16x16x32_bf16 v[32:35], v[216:219], v[180:183], v[32:35]
	v_mfma_f32_16x16x32_bf16 v[20:23], v[204:207], v[188:191], v[20:23]
	v_mfma_f32_16x16x32_bf16 v[16:19], v[216:219], v[188:191], v[16:19]
	v_mfma_f32_16x16x32_bf16 v[4:7], v[204:207], v[196:199], v[4:7]
	v_mfma_f32_16x16x32_bf16 v[0:3], v[216:219], v[196:199], v[0:3]
	v_mfma_f32_16x16x32_bf16 v[52:55], v[212:215], v[176:179], v[52:55]
	v_mfma_f32_16x16x32_bf16 v[48:51], v[220:223], v[176:179], v[48:51]
	v_mfma_f32_16x16x32_bf16 v[36:39], v[212:215], v[184:187], v[36:39]
	v_mfma_f32_16x16x32_bf16 v[32:35], v[220:223], v[184:187], v[32:35]
	v_mfma_f32_16x16x32_bf16 v[20:23], v[212:215], v[192:195], v[20:23]
	v_mfma_f32_16x16x32_bf16 v[16:19], v[220:223], v[192:195], v[16:19]
	v_mfma_f32_16x16x32_bf16 v[4:7], v[212:215], v[200:203], v[4:7]
	v_mfma_f32_16x16x32_bf16 v[0:3], v[220:223], v[200:203], v[0:3]
	s_setprio 0
	s_add_i32 s56, s56, 2
	s_add_u32 s2, s2, 0x100
	s_addc_u32 s3, s3, 0
	s_add_u32 s54, s54, 0x100
	s_addc_u32 s55, s55, 0
	s_cmp_gt_u32 s56, 13
	s_barrier
	s_cbranch_scc0 .LBB0_712
	v_lshl_add_u32 v146, s0, 8, v148
	v_ashrrev_i32_e32 v147, 31, v146
	v_lshl_add_u64 v[144:145], v[146:147], 2, s[66:67]
	global_load_dword v155, v[144:145], off
	global_load_dword v164, v[144:145], off offset:64
	global_load_dword v165, v[144:145], off offset:128
	global_load_dword v166, v[144:145], off offset:192
	global_load_dword v167, v[144:145], off offset:512
	global_load_dword v168, v[144:145], off offset:576
	global_load_dword v169, v[144:145], off offset:640
	global_load_dword v170, v[144:145], off offset:704
	v_lshl_or_b32 v144, s1, 8, v150
	v_ashrrev_i32_e32 v145, 31, v144
	v_lshlrev_b64 v[160:161], 10, v[146:147]
	v_lshlrev_b64 v[162:163], 1, v[144:145]
	v_lshl_add_u64 v[144:145], s[92:93], 0, v[160:161]
	v_or_b32_e32 v156, 16, v146
	v_ashrrev_i32_e32 v157, 31, v156
	v_or_b32_e32 v158, 32, v146
	v_lshlrev_b64 v[156:157], 10, v[156:157]
	v_lshl_add_u64 v[144:145], v[144:145], 0, v[162:163]
	v_ashrrev_i32_e32 v159, 31, v158
	v_lshl_add_u64 v[156:157], s[92:93], 0, v[156:157]
	v_lshlrev_b64 v[158:159], 10, v[158:159]
	v_lshl_add_u64 v[156:157], v[156:157], 0, v[162:163]
	v_lshl_add_u64 v[158:159], s[92:93], 0, v[158:159]
	v_lshl_add_u64 v[158:159], v[158:159], 0, v[162:163]
	s_mov_b64 s[26:27], s[24:25]
	s_waitcnt vmcnt(0)
	v_fmamk_f32 v147, v155, 0x3a800000, v154
	v_fmamk_f32 v155, v164, 0x3a800000, v154
	v_fmamk_f32 v160, v165, 0x3a800000, v154
	v_mul_f32_e32 v161, 0x4b800000, v147
	v_mul_f32_e32 v164, 0x4b800000, v155
	v_cmp_gt_f32_e32 vcc, s49, v147
	v_cmp_gt_f32_e64 s[0:1], s49, v155
	v_mul_f32_e32 v165, 0x4b800000, v160
	v_cndmask_b32_e32 v147, v147, v161, vcc
	v_cndmask_b32_e64 v155, v155, v164, s[0:1]
	v_cmp_gt_f32_e64 s[2:3], s49, v160
	v_rsq_f32_e32 v147, v147
	v_rsq_f32_e32 v155, v155
	v_cndmask_b32_e64 v160, v160, v165, s[2:3]
	v_rsq_f32_e32 v160, v160
	v_mul_f32_e32 v161, 0x45800000, v147
	v_mul_f32_e32 v164, 0x45800000, v155
	v_cndmask_b32_e32 v147, v147, v161, vcc
	v_mul_f32_e32 v165, 0x45800000, v160
	v_cndmask_b32_e64 v155, v155, v164, s[0:1]
	v_cndmask_b32_e64 v161, v160, v165, s[2:3]
	v_mul_f32_e32 v160, 0x3e0293ee, v147
	v_mul_f32_e32 v164, 0x3e0293ee, v155
	v_fmamk_f32 v171, v166, 0x3a800000, v154
	v_mul_f32_e32 v166, 0x3e0293ee, v161
	v_pk_mul_f32 v[126:127], v[126:127], v[160:161] op_sel_hi:[1,0]
	v_pk_mul_f32 v[124:125], v[124:125], v[160:161] op_sel_hi:[1,0]
	v_pk_mul_f32 v[122:123], v[122:123], v[160:161] op_sel_hi:[1,0]
	v_pk_mul_f32 v[120:121], v[120:121], v[160:161] op_sel_hi:[1,0]
	v_pk_mul_f32 v[110:111], v[110:111], v[160:161] op_sel_hi:[1,0]
	v_pk_mul_f32 v[108:109], v[108:109], v[160:161] op_sel_hi:[1,0]
	v_pk_mul_f32 v[102:103], v[102:103], v[160:161] op_sel_hi:[1,0]
	v_pk_mul_f32 v[100:101], v[100:101], v[160:161] op_sel_hi:[1,0]
	v_pk_mul_f32 v[118:119], v[118:119], v[164:165] op_sel_hi:[1,0]
	v_pk_mul_f32 v[116:117], v[116:117], v[164:165] op_sel_hi:[1,0]
	v_pk_mul_f32 v[114:115], v[114:115], v[164:165] op_sel_hi:[1,0]
	v_pk_mul_f32 v[112:113], v[112:113], v[164:165] op_sel_hi:[1,0]
	v_pk_mul_f32 v[94:95], v[94:95], v[164:165] op_sel_hi:[1,0]
	v_pk_mul_f32 v[92:93], v[92:93], v[164:165] op_sel_hi:[1,0]
	v_pk_mul_f32 v[160:161], v[90:91], v[164:165] op_sel_hi:[1,0]
	v_pk_mul_f32 v[164:165], v[88:89], v[164:165] op_sel_hi:[1,0]
	v_cvt_pk_bf16_f32 v88, v124, v125
	v_cvt_pk_bf16_f32 v89, v126, v127
	v_cvt_pk_bf16_f32 v90, v120, v121
	v_cvt_pk_bf16_f32 v91, v122, v123
	global_store_dwordx4 v[144:145], v[88:91], off
	v_fmamk_f32 v167, v167, 0x3a800000, v154
	v_pk_mul_f32 v[106:107], v[106:107], v[166:167] op_sel_hi:[1,0]
	v_cvt_pk_bf16_f32 v88, v108, v109
	v_cvt_pk_bf16_f32 v89, v110, v111
	v_cvt_pk_bf16_f32 v90, v100, v101
	v_cvt_pk_bf16_f32 v91, v102, v103
	global_store_dwordx4 v[144:145], v[88:91], off offset:256
	v_pk_mul_f32 v[104:105], v[104:105], v[166:167] op_sel_hi:[1,0]
	v_pk_mul_f32 v[98:99], v[98:99], v[166:167] op_sel_hi:[1,0]
	v_cvt_pk_bf16_f32 v88, v116, v117
	v_cvt_pk_bf16_f32 v89, v118, v119
	v_cvt_pk_bf16_f32 v90, v112, v113
	v_cvt_pk_bf16_f32 v91, v114, v115
	global_store_dwordx4 v[156:157], v[88:91], off
	v_pk_mul_f32 v[96:97], v[96:97], v[166:167] op_sel_hi:[1,0]
	v_pk_mul_f32 v[86:87], v[86:87], v[166:167] op_sel_hi:[1,0]
	v_cvt_pk_bf16_f32 v88, v92, v93
	v_cvt_pk_bf16_f32 v89, v94, v95
	v_cvt_pk_bf16_f32 v90, v164, v165
	v_cvt_pk_bf16_f32 v91, v160, v161
	global_store_dwordx4 v[156:157], v[88:91], off offset:256
	v_pk_mul_f32 v[84:85], v[84:85], v[166:167] op_sel_hi:[1,0]
	v_cmp_gt_f32_e32 vcc, s49, v171
	v_cvt_pk_bf16_f32 v88, v104, v105
	v_cvt_pk_bf16_f32 v89, v106, v107
	v_cvt_pk_bf16_f32 v90, v96, v97
	v_cvt_pk_bf16_f32 v91, v98, v99
	global_store_dwordx4 v[158:159], v[88:91], off
	s_mov_b64 s[0:1], 0x20000
	v_fmamk_f32 v168, v168, 0x3a800000, v154
	v_pk_mul_f32 v[88:89], v[82:83], v[166:167] op_sel_hi:[1,0]
	v_pk_mul_f32 v[82:83], v[80:81], v[166:167] op_sel_hi:[1,0]
	v_cvt_pk_bf16_f32 v80, v84, v85
	v_cvt_pk_bf16_f32 v81, v86, v87
	v_fmamk_f32 v169, v169, 0x3a800000, v154
	v_cvt_pk_bf16_f32 v82, v82, v83
	v_cvt_pk_bf16_f32 v83, v88, v89
	global_store_dwordx4 v[158:159], v[80:83], off offset:256
	v_fmamk_f32 v170, v170, 0x3a800000, v154
	s_mov_b64 s[2:3], s[22:23]
	v_mul_f32_e32 v82, 0x4b800000, v171
	v_cndmask_b32_e32 v82, v171, v82, vcc
	v_rsq_f32_e32 v82, v82
	v_or_b32_e32 v80, 48, v146
	v_ashrrev_i32_e32 v81, 31, v80
	v_lshlrev_b64 v[80:81], 10, v[80:81]
	v_mul_f32_e32 v83, 0x45800000, v82
	v_cndmask_b32_e32 v82, v82, v83, vcc
	v_lshl_add_u64 v[80:81], s[92:93], 0, v[80:81]
	v_mul_f32_e32 v82, 0x3e0293ee, v82
	v_lshl_add_u64 v[80:81], v[80:81], 0, v[162:163]
	v_pk_mul_f32 v[78:79], v[78:79], v[82:83] op_sel_hi:[1,0]
	v_pk_mul_f32 v[76:77], v[76:77], v[82:83] op_sel_hi:[1,0]
	v_pk_mul_f32 v[84:85], v[74:75], v[82:83] op_sel_hi:[1,0]
	v_pk_mul_f32 v[74:75], v[72:73], v[82:83] op_sel_hi:[1,0]
	v_cvt_pk_bf16_f32 v72, v76, v77
	v_cvt_pk_bf16_f32 v73, v78, v79
	v_pk_mul_f32 v[70:71], v[70:71], v[82:83] op_sel_hi:[1,0]
	v_cvt_pk_bf16_f32 v74, v74, v75
	v_cvt_pk_bf16_f32 v75, v84, v85
	global_store_dwordx4 v[80:81], v[72:75], off
	v_pk_mul_f32 v[68:69], v[68:69], v[82:83] op_sel_hi:[1,0]
	v_cmp_gt_f32_e32 vcc, s49, v167
	v_pk_mul_f32 v[72:73], v[66:67], v[82:83] op_sel_hi:[1,0]
	v_pk_mul_f32 v[66:67], v[64:65], v[82:83] op_sel_hi:[1,0]
	v_cvt_pk_bf16_f32 v64, v68, v69
	v_cvt_pk_bf16_f32 v65, v70, v71
	s_nop 0
	v_cvt_pk_bf16_f32 v66, v66, v67
	v_mul_f32_e32 v67, 0x4b800000, v167
	v_cndmask_b32_e32 v67, v167, v67, vcc
	v_rsq_f32_e32 v68, v67
	v_cvt_pk_bf16_f32 v67, v72, v73
	global_store_dwordx4 v[80:81], v[64:67], off offset:256
	s_nop 1
	v_mul_f32_e32 v66, 0x45800000, v68
	v_cndmask_b32_e32 v66, v68, v66, vcc
	v_mul_f32_e32 v66, 0x3e0293ee, v66
	v_lshl_add_u64 v[64:65], v[144:145], 0, s[0:1]
	v_pk_mul_f32 v[60:61], v[60:61], v[66:67] op_sel_hi:[1,0]
	s_mov_b32 s0, 0x20000
	v_pk_mul_f32 v[68:69], v[58:59], v[66:67] op_sel_hi:[1,0]
	v_pk_mul_f32 v[58:59], v[56:57], v[66:67] op_sel_hi:[1,0]
	v_cvt_pk_bf16_f32 v56, v60, v61
	v_add_co_u32_e32 v60, vcc, s0, v144
	v_pk_mul_f32 v[62:63], v[62:63], v[66:67] op_sel_hi:[1,0]
	s_nop 0
	v_addc_co_u32_e32 v61, vcc, 0, v145, vcc
	v_cvt_pk_bf16_f32 v57, v62, v63
	v_cvt_pk_bf16_f32 v58, v58, v59
	v_cvt_pk_bf16_f32 v59, v68, v69
	global_store_dwordx4 v[60:61], v[56:59], off
	v_pk_mul_f32 v[54:55], v[54:55], v[66:67] op_sel_hi:[1,0]
	v_pk_mul_f32 v[52:53], v[52:53], v[66:67] op_sel_hi:[1,0]
	v_pk_mul_f32 v[56:57], v[50:51], v[66:67] op_sel_hi:[1,0]
	v_pk_mul_f32 v[50:51], v[48:49], v[66:67] op_sel_hi:[1,0]
	v_cvt_pk_bf16_f32 v48, v52, v53
	v_cvt_pk_bf16_f32 v49, v54, v55
	v_cmp_gt_f32_e32 vcc, s49, v168
	v_cvt_pk_bf16_f32 v50, v50, v51
	v_mul_f32_e32 v51, 0x4b800000, v168
	s_mov_b64 s[0:1], 0x24000
	v_cndmask_b32_e32 v51, v168, v51, vcc
	v_rsq_f32_e32 v52, v51
	v_cvt_pk_bf16_f32 v51, v56, v57
	global_store_dwordx4 v[64:65], v[48:51], off offset:256
	s_nop 1
	v_mul_f32_e32 v50, 0x45800000, v52
	v_cndmask_b32_e32 v50, v52, v50, vcc
	v_mul_f32_e32 v50, 0x3e0293ee, v50
	v_lshl_add_u64 v[48:49], v[144:145], 0, s[0:1]
	v_pk_mul_f32 v[44:45], v[44:45], v[50:51] op_sel_hi:[1,0]
	s_mov_b32 s0, 0x24000
	v_pk_mul_f32 v[52:53], v[42:43], v[50:51] op_sel_hi:[1,0]
	v_pk_mul_f32 v[42:43], v[40:41], v[50:51] op_sel_hi:[1,0]
	v_cvt_pk_bf16_f32 v40, v44, v45
	v_add_co_u32_e32 v44, vcc, s0, v144
	v_pk_mul_f32 v[46:47], v[46:47], v[50:51] op_sel_hi:[1,0]
	s_nop 0
	v_addc_co_u32_e32 v45, vcc, 0, v145, vcc
	v_cvt_pk_bf16_f32 v41, v46, v47
	v_cvt_pk_bf16_f32 v42, v42, v43
	v_cvt_pk_bf16_f32 v43, v52, v53
	global_store_dwordx4 v[44:45], v[40:43], off
	v_pk_mul_f32 v[38:39], v[38:39], v[50:51] op_sel_hi:[1,0]
	v_pk_mul_f32 v[36:37], v[36:37], v[50:51] op_sel_hi:[1,0]
	v_pk_mul_f32 v[40:41], v[34:35], v[50:51] op_sel_hi:[1,0]
	v_pk_mul_f32 v[34:35], v[32:33], v[50:51] op_sel_hi:[1,0]
	v_cvt_pk_bf16_f32 v32, v36, v37
	v_cvt_pk_bf16_f32 v33, v38, v39
	v_cmp_gt_f32_e32 vcc, s49, v169
	v_cvt_pk_bf16_f32 v34, v34, v35
	v_mul_f32_e32 v35, 0x4b800000, v169
	s_mov_b32 s1, s18
	v_cndmask_b32_e32 v35, v169, v35, vcc
	v_rsq_f32_e32 v36, v35
	v_cvt_pk_bf16_f32 v35, v40, v41
	global_store_dwordx4 v[48:49], v[32:35], off offset:256
	s_mov_b32 s0, s20
	s_nop 0
	v_mul_f32_e32 v34, 0x45800000, v36
	v_cndmask_b32_e32 v34, v36, v34, vcc
	v_mul_f32_e32 v34, 0x3e0293ee, v34
	v_pk_mul_f32 v[28:29], v[28:29], v[34:35] op_sel_hi:[1,0]
	v_pk_mul_f32 v[36:37], v[26:27], v[34:35] op_sel_hi:[1,0]
	v_pk_mul_f32 v[26:27], v[24:25], v[34:35] op_sel_hi:[1,0]
	v_cvt_pk_bf16_f32 v24, v28, v29
	v_add_co_u32_e32 v28, vcc, s50, v144
	v_pk_mul_f32 v[30:31], v[30:31], v[34:35] op_sel_hi:[1,0]
	s_nop 0
	v_addc_co_u32_e32 v29, vcc, 0, v145, vcc
	v_cvt_pk_bf16_f32 v25, v30, v31
	v_cvt_pk_bf16_f32 v26, v26, v27
	v_cvt_pk_bf16_f32 v27, v36, v37
	global_store_dwordx4 v[28:29], v[24:27], off
	v_pk_mul_f32 v[22:23], v[22:23], v[34:35] op_sel_hi:[1,0]
	v_pk_mul_f32 v[20:21], v[20:21], v[34:35] op_sel_hi:[1,0]
	v_pk_mul_f32 v[24:25], v[18:19], v[34:35] op_sel_hi:[1,0]
	v_pk_mul_f32 v[18:19], v[16:17], v[34:35] op_sel_hi:[1,0]
	v_cvt_pk_bf16_f32 v16, v20, v21
	v_cvt_pk_bf16_f32 v17, v22, v23
	v_cmp_gt_f32_e32 vcc, s49, v170
	v_cvt_pk_bf16_f32 v18, v18, v19
	v_mul_f32_e32 v19, 0x4b800000, v170
	v_lshl_add_u64 v[32:33], v[144:145], 0, s[12:13]
	v_cndmask_b32_e32 v19, v170, v19, vcc
	v_rsq_f32_e32 v20, v19
	v_cvt_pk_bf16_f32 v19, v24, v25
	global_store_dwordx4 v[32:33], v[16:19], off offset:256
	s_nop 1
	v_mul_f32_e32 v18, 0x45800000, v20
	v_cndmask_b32_e32 v18, v20, v18, vcc
	v_mul_f32_e32 v18, 0x3e0293ee, v18
	v_pk_mul_f32 v[12:13], v[12:13], v[18:19] op_sel_hi:[1,0]
	v_pk_mul_f32 v[20:21], v[10:11], v[18:19] op_sel_hi:[1,0]
	v_pk_mul_f32 v[10:11], v[8:9], v[18:19] op_sel_hi:[1,0]
	v_cvt_pk_bf16_f32 v8, v12, v13
	v_add_co_u32_e32 v12, vcc, s51, v144
	v_pk_mul_f32 v[14:15], v[14:15], v[18:19] op_sel_hi:[1,0]
	s_nop 0
	v_addc_co_u32_e32 v13, vcc, 0, v145, vcc
	v_cvt_pk_bf16_f32 v9, v14, v15
	v_lshl_add_u64 v[16:17], v[144:145], 0, s[16:17]
	v_cvt_pk_bf16_f32 v10, v10, v11
	v_cvt_pk_bf16_f32 v11, v20, v21
	global_store_dwordx4 v[12:13], v[8:11], off
	s_and_b64 vcc, exec, s[6:7]
	v_pk_mul_f32 v[6:7], v[6:7], v[18:19] op_sel_hi:[1,0]
	v_pk_mul_f32 v[8:9], v[2:3], v[18:19] op_sel_hi:[1,0]
	v_pk_mul_f32 v[2:3], v[0:1], v[18:19] op_sel_hi:[1,0]
	v_pk_mul_f32 v[4:5], v[4:5], v[18:19] op_sel_hi:[1,0]
	s_nop 0
	v_cvt_pk_bf16_f32 v0, v4, v5
	v_cvt_pk_bf16_f32 v1, v6, v7
	v_cvt_pk_bf16_f32 v2, v2, v3
	v_cvt_pk_bf16_f32 v3, v8, v9
	global_store_dwordx4 v[16:17], v[0:3], off offset:256
	s_cbranch_vccz .LBB0_705
	s_waitcnt vmcnt(0)
	s_cmpk_gt_u32 s30, 0xff
	s_cbranch_scc1 .LBB0_716
	s_barrier

.LBB0_792:
	ds_read_b128 v[144:147], v178
	ds_read_b128 v[148:151], v178 offset:1024
	ds_read_b128 v[152:155], v178 offset:2048
	ds_read_b128 v[156:159], v178 offset:3072
	s_add_u32 s40, s38, 0xfffe0080
	s_addc_u32 s41, s39, -1
	s_cmp_eq_u32 s63, 4
	s_cselect_b32 s43, s27, s41
	s_cselect_b32 s42, s35, s40
	s_cselect_b32 s41, s25, s62
	s_cselect_b32 s40, s60, s61
	v_lshl_add_u64 v[172:173], s[38:39], 0, v[136:137]
	s_add_i32 m0, s37, 0xc000
	ds_read_b128 v[160:163], v179
	ds_read_b128 v[164:167], v179 offset:1024
	ds_read_b128 v[168:171], v179 offset:2048
	ds_read_b128 v[182:185], v179 offset:3072
	ds_read_b128 v[186:189], v179 offset:4096
	ds_read_b128 v[190:193], v179 offset:5120
	ds_read_b128 v[194:197], v179 offset:6144
	ds_read_b128 v[198:201], v179 offset:7168
	global_load_lds_dwordx4 v[172:173], off
	v_lshl_add_u64 v[172:173], s[38:39], 0, v[138:139]
	s_add_i32 m0, s37, 0xe000
	s_nop 0
	global_load_lds_dwordx4 v[172:173], off
	s_waitcnt lgkmcnt(8)
	s_waitcnt lgkmcnt(0)
	s_setprio 1
	s_barrier
	v_mfma_f32_16x16x32_bf16 v[124:127], v[144:147], v[160:163], v[124:127]
	v_mfma_f32_16x16x32_bf16 v[120:123], v[152:155], v[160:163], v[120:123]
	v_mfma_f32_16x16x32_bf16 v[108:111], v[144:147], v[168:171], v[108:111]
	v_mfma_f32_16x16x32_bf16 v[104:107], v[152:155], v[168:171], v[104:107]
	v_mfma_f32_16x16x32_bf16 v[96:99], v[144:147], v[186:189], v[96:99]
	v_mfma_f32_16x16x32_bf16 v[88:91], v[152:155], v[186:189], v[88:91]
	v_mfma_f32_16x16x32_bf16 v[80:83], v[144:147], v[194:197], v[80:83]
	v_mfma_f32_16x16x32_bf16 v[72:75], v[152:155], v[194:197], v[72:75]
	v_mfma_f32_16x16x32_bf16 v[124:127], v[148:151], v[164:167], v[124:127]
	v_mfma_f32_16x16x32_bf16 v[120:123], v[156:159], v[164:167], v[120:123]
	v_mfma_f32_16x16x32_bf16 v[108:111], v[148:151], v[182:185], v[108:111]
	v_mfma_f32_16x16x32_bf16 v[104:107], v[156:159], v[182:185], v[104:107]
	v_mfma_f32_16x16x32_bf16 v[96:99], v[148:151], v[190:193], v[96:99]
	v_mfma_f32_16x16x32_bf16 v[88:91], v[156:159], v[190:193], v[88:91]
	v_mfma_f32_16x16x32_bf16 v[80:83], v[148:151], v[198:201], v[80:83]
	v_mfma_f32_16x16x32_bf16 v[72:75], v[156:159], v[198:201], v[72:75]
	s_setprio 0
	s_barrier
	s_add_i32 s64, s58, s48
	v_lshl_add_u64 v[172:173], s[40:41], 0, v[130:131]
	s_mov_b32 m0, s64
	ds_read_b128 v[202:205], v180
	ds_read_b128 v[206:209], v180 offset:1024
	ds_read_b128 v[212:215], v180 offset:2048
	ds_read_b128 v[216:219], v180 offset:3072
	global_load_lds_dwordx4 v[172:173], off
	v_lshl_add_u64 v[220:221], s[40:41], 0, v[134:135]
	s_add_i32 m0, s64, 0x2000
	s_nop 0
	global_load_lds_dwordx4 v[220:221], off
	s_waitcnt lgkmcnt(0)
	s_setprio 1
	s_barrier
	v_mfma_f32_16x16x32_bf16 v[116:119], v[202:205], v[160:163], v[116:119]
	v_mfma_f32_16x16x32_bf16 v[112:115], v[212:215], v[160:163], v[112:115]
	v_mfma_f32_16x16x32_bf16 v[100:103], v[202:205], v[168:171], v[100:103]
	v_mfma_f32_16x16x32_bf16 v[92:95], v[212:215], v[168:171], v[92:95]
	v_mfma_f32_16x16x32_bf16 v[84:87], v[202:205], v[186:189], v[84:87]
	v_mfma_f32_16x16x32_bf16 v[76:79], v[212:215], v[186:189], v[76:79]
	v_mfma_f32_16x16x32_bf16 v[68:71], v[202:205], v[194:197], v[68:71]
	v_mfma_f32_16x16x32_bf16 v[64:67], v[212:215], v[194:197], v[64:67]
	v_mfma_f32_16x16x32_bf16 v[116:119], v[206:209], v[164:167], v[116:119]
	v_mfma_f32_16x16x32_bf16 v[112:115], v[216:219], v[164:167], v[112:115]
	v_mfma_f32_16x16x32_bf16 v[100:103], v[206:209], v[182:185], v[100:103]
	v_mfma_f32_16x16x32_bf16 v[92:95], v[216:219], v[182:185], v[92:95]
	v_mfma_f32_16x16x32_bf16 v[84:87], v[206:209], v[190:193], v[84:87]
	v_mfma_f32_16x16x32_bf16 v[76:79], v[216:219], v[190:193], v[76:79]
	v_mfma_f32_16x16x32_bf16 v[68:71], v[206:209], v[198:201], v[68:71]
	v_mfma_f32_16x16x32_bf16 v[64:67], v[216:219], v[198:201], v[64:67]
	s_setprio 0
	s_mov_b32 m0, s37
	v_lshl_add_u64 v[222:223], s[42:43], 0, v[128:129]
	s_barrier
	ds_read_b128 v[160:163], v179 offset:16384
	ds_read_b128 v[164:167], v179 offset:17408
	ds_read_b128 v[168:171], v179 offset:18432
	ds_read_b128 v[182:185], v179 offset:19456
	ds_read_b128 v[186:189], v179 offset:20480
	ds_read_b128 v[190:193], v179 offset:21504
	ds_read_b128 v[194:197], v179 offset:22528
	ds_read_b128 v[198:201], v179 offset:23552
	global_load_lds_dwordx4 v[222:223], off
	v_lshl_add_u64 v[224:225], s[42:43], 0, v[132:133]
	s_mov_b32 m0, s49
	s_nop 0
	global_load_lds_dwordx4 v[224:225], off
	s_waitcnt lgkmcnt(0)
	s_setprio 1
	s_barrier
	v_mfma_f32_16x16x32_bf16 v[60:63], v[144:147], v[160:163], v[60:63]
	v_mfma_f32_16x16x32_bf16 v[56:59], v[152:155], v[160:163], v[56:59]
	v_mfma_f32_16x16x32_bf16 v[44:47], v[144:147], v[168:171], v[44:47]
	v_mfma_f32_16x16x32_bf16 v[40:43], v[152:155], v[168:171], v[40:43]
	v_mfma_f32_16x16x32_bf16 v[32:35], v[144:147], v[186:189], v[32:35]
	v_mfma_f32_16x16x32_bf16 v[24:27], v[152:155], v[186:189], v[24:27]
	v_mfma_f32_16x16x32_bf16 v[16:19], v[144:147], v[194:197], v[16:19]
	v_mfma_f32_16x16x32_bf16 v[8:11], v[152:155], v[194:197], v[8:11]
	v_mfma_f32_16x16x32_bf16 v[60:63], v[148:151], v[164:167], v[60:63]
	v_mfma_f32_16x16x32_bf16 v[56:59], v[156:159], v[164:167], v[56:59]
	v_mfma_f32_16x16x32_bf16 v[44:47], v[148:151], v[182:185], v[44:47]
	v_mfma_f32_16x16x32_bf16 v[40:43], v[156:159], v[182:185], v[40:43]
	v_mfma_f32_16x16x32_bf16 v[32:35], v[148:151], v[190:193], v[32:35]
	v_mfma_f32_16x16x32_bf16 v[24:27], v[156:159], v[190:193], v[24:27]
	v_mfma_f32_16x16x32_bf16 v[16:19], v[148:151], v[198:201], v[16:19]
	v_mfma_f32_16x16x32_bf16 v[8:11], v[156:159], v[198:201], v[8:11]
	s_setprio 0
	s_barrier
	s_add_u32 s64, s40, 0x20000
	s_addc_u32 s65, s41, 0
	s_add_i32 s66, s59, s48
	v_lshl_add_u64 v[144:145], s[64:65], 0, v[130:131]
	s_mov_b32 m0, s66
	s_nop 0
	global_load_lds_dwordx4 v[144:145], off
	v_lshl_add_u64 v[144:145], s[64:65], 0, v[134:135]
	s_add_i32 m0, s66, 0x2000
	s_nop 0
	global_load_lds_dwordx4 v[144:145], off
	s_waitcnt vmcnt(6)
	s_setprio 1
	s_barrier
	v_mfma_f32_16x16x32_bf16 v[52:55], v[202:205], v[160:163], v[52:55]
	v_mfma_f32_16x16x32_bf16 v[48:51], v[212:215], v[160:163], v[48:51]
	v_mfma_f32_16x16x32_bf16 v[36:39], v[202:205], v[168:171], v[36:39]
	v_mfma_f32_16x16x32_bf16 v[28:31], v[212:215], v[168:171], v[28:31]
	v_mfma_f32_16x16x32_bf16 v[20:23], v[202:205], v[186:189], v[20:23]
	v_mfma_f32_16x16x32_bf16 v[12:15], v[212:215], v[186:189], v[12:15]
	v_mfma_f32_16x16x32_bf16 v[4:7], v[202:205], v[194:197], v[4:7]
	v_mfma_f32_16x16x32_bf16 v[0:3], v[212:215], v[194:197], v[0:3]
	v_mfma_f32_16x16x32_bf16 v[52:55], v[206:209], v[164:167], v[52:55]
	v_mfma_f32_16x16x32_bf16 v[48:51], v[216:219], v[164:167], v[48:51]
	v_mfma_f32_16x16x32_bf16 v[36:39], v[206:209], v[182:185], v[36:39]
	v_mfma_f32_16x16x32_bf16 v[28:31], v[216:219], v[182:185], v[28:31]
	v_mfma_f32_16x16x32_bf16 v[20:23], v[206:209], v[190:193], v[20:23]
	v_mfma_f32_16x16x32_bf16 v[12:15], v[216:219], v[190:193], v[12:15]
	v_mfma_f32_16x16x32_bf16 v[4:7], v[206:209], v[198:201], v[4:7]
	v_mfma_f32_16x16x32_bf16 v[0:3], v[216:219], v[198:201], v[0:3]
	s_setprio 0
	s_add_i32 s64, 0, 0x18000
	v_add_u32_e32 v156, s64, v176
	s_barrier
	ds_read_b128 v[144:147], v156
	ds_read_b128 v[148:151], v156 offset:1024
	ds_read_b128 v[152:155], v156 offset:2048
	ds_read_b128 v[156:159], v156 offset:3072
	s_add_u32 s42, s42, 0x20000
	s_addc_u32 s43, s43, 0
	s_mov_b32 m0, s50
	v_lshl_add_u64 v[202:203], s[42:43], 0, v[128:129]
	ds_read_b128 v[160:163], v179 offset:32768
	ds_read_b128 v[164:167], v179 offset:33792
	ds_read_b128 v[168:171], v179 offset:34816
	ds_read_b128 v[182:185], v179 offset:35840
	ds_read_b128 v[186:189], v179 offset:36864
	ds_read_b128 v[190:193], v179 offset:37888
	ds_read_b128 v[194:197], v179 offset:38912
	ds_read_b128 v[198:201], v179 offset:39936
	global_load_lds_dwordx4 v[202:203], off
	v_lshl_add_u64 v[202:203], s[42:43], 0, v[132:133]
	s_mov_b32 m0, s51
	s_nop 0
	global_load_lds_dwordx4 v[202:203], off
	s_waitcnt lgkmcnt(8)
	s_waitcnt lgkmcnt(0)
	s_setprio 1
	s_barrier
	v_mfma_f32_16x16x32_bf16 v[124:127], v[144:147], v[160:163], v[124:127]
	v_mfma_f32_16x16x32_bf16 v[120:123], v[152:155], v[160:163], v[120:123]
	v_mfma_f32_16x16x32_bf16 v[108:111], v[144:147], v[168:171], v[108:111]
	v_mfma_f32_16x16x32_bf16 v[104:107], v[152:155], v[168:171], v[104:107]
	v_mfma_f32_16x16x32_bf16 v[96:99], v[144:147], v[186:189], v[96:99]
	v_mfma_f32_16x16x32_bf16 v[88:91], v[152:155], v[186:189], v[88:91]
	v_mfma_f32_16x16x32_bf16 v[80:83], v[144:147], v[194:197], v[80:83]
	v_mfma_f32_16x16x32_bf16 v[72:75], v[152:155], v[194:197], v[72:75]
	v_mfma_f32_16x16x32_bf16 v[124:127], v[148:151], v[164:167], v[124:127]
	v_mfma_f32_16x16x32_bf16 v[120:123], v[156:159], v[164:167], v[120:123]
	v_mfma_f32_16x16x32_bf16 v[108:111], v[148:151], v[182:185], v[108:111]
	v_mfma_f32_16x16x32_bf16 v[104:107], v[156:159], v[182:185], v[104:107]
	v_mfma_f32_16x16x32_bf16 v[96:99], v[148:151], v[190:193], v[96:99]
	v_mfma_f32_16x16x32_bf16 v[88:91], v[156:159], v[190:193], v[88:91]
	v_mfma_f32_16x16x32_bf16 v[80:83], v[148:151], v[198:201], v[80:83]
	v_mfma_f32_16x16x32_bf16 v[72:75], v[156:159], v[198:201], v[72:75]
	s_setprio 0
	s_barrier
	s_add_i32 s42, 0, 0x1c000
	s_add_i32 s43, s64, s48
	v_add_u32_e32 v181, s42, v176
	v_lshl_add_u64 v[172:173], v[172:173], 0, s[0:1]
	s_mov_b32 m0, s43
	ds_read_b128 v[202:205], v181
	ds_read_b128 v[206:209], v181 offset:1024
	ds_read_b128 v[212:215], v181 offset:2048
	ds_read_b128 v[216:219], v181 offset:3072
	global_load_lds_dwordx4 v[172:173], off
	v_lshl_add_u64 v[172:173], v[220:221], 0, s[0:1]
	s_add_i32 m0, s43, 0x2000
	s_nop 0
	global_load_lds_dwordx4 v[172:173], off
	s_waitcnt lgkmcnt(0)
	s_setprio 1
	s_barrier
	v_mfma_f32_16x16x32_bf16 v[116:119], v[202:205], v[160:163], v[116:119]
	v_mfma_f32_16x16x32_bf16 v[112:115], v[212:215], v[160:163], v[112:115]
	v_mfma_f32_16x16x32_bf16 v[100:103], v[202:205], v[168:171], v[100:103]
	v_mfma_f32_16x16x32_bf16 v[92:95], v[212:215], v[168:171], v[92:95]
	v_mfma_f32_16x16x32_bf16 v[84:87], v[202:205], v[186:189], v[84:87]
	v_mfma_f32_16x16x32_bf16 v[76:79], v[212:215], v[186:189], v[76:79]
	v_mfma_f32_16x16x32_bf16 v[68:71], v[202:205], v[194:197], v[68:71]
	v_mfma_f32_16x16x32_bf16 v[64:67], v[212:215], v[194:197], v[64:67]
	v_mfma_f32_16x16x32_bf16 v[116:119], v[206:209], v[164:167], v[116:119]
	v_mfma_f32_16x16x32_bf16 v[112:115], v[216:219], v[164:167], v[112:115]
	v_mfma_f32_16x16x32_bf16 v[100:103], v[206:209], v[182:185], v[100:103]
	v_mfma_f32_16x16x32_bf16 v[92:95], v[216:219], v[182:185], v[92:95]
	v_mfma_f32_16x16x32_bf16 v[84:87], v[206:209], v[190:193], v[84:87]
	v_mfma_f32_16x16x32_bf16 v[76:79], v[216:219], v[190:193], v[76:79]
	v_mfma_f32_16x16x32_bf16 v[68:71], v[206:209], v[198:201], v[68:71]
	v_mfma_f32_16x16x32_bf16 v[64:67], v[216:219], v[198:201], v[64:67]
	s_setprio 0
	s_mov_b32 m0, s53
	v_lshl_add_u64 v[172:173], v[222:223], 0, s[0:1]
	s_barrier
	ds_read_b128 v[160:163], v179 offset:49152
	ds_read_b128 v[164:167], v179 offset:50176
	ds_read_b128 v[168:171], v179 offset:51200
	ds_read_b128 v[182:185], v179 offset:52224
	ds_read_b128 v[186:189], v179 offset:53248
	ds_read_b128 v[190:193], v179 offset:54272
	ds_read_b128 v[194:197], v179 offset:55296
	ds_read_b128 v[198:201], v179 offset:56320
	global_load_lds_dwordx4 v[172:173], off
	v_lshl_add_u64 v[172:173], v[224:225], 0, s[0:1]
	s_mov_b32 m0, s54
	s_nop 0
	global_load_lds_dwordx4 v[172:173], off
	s_waitcnt lgkmcnt(0)
	s_setprio 1
	s_barrier
	v_mfma_f32_16x16x32_bf16 v[60:63], v[144:147], v[160:163], v[60:63]
	v_mfma_f32_16x16x32_bf16 v[56:59], v[152:155], v[160:163], v[56:59]
	v_mfma_f32_16x16x32_bf16 v[44:47], v[144:147], v[168:171], v[44:47]
	v_mfma_f32_16x16x32_bf16 v[40:43], v[152:155], v[168:171], v[40:43]
	v_mfma_f32_16x16x32_bf16 v[32:35], v[144:147], v[186:189], v[32:35]
	v_mfma_f32_16x16x32_bf16 v[24:27], v[152:155], v[186:189], v[24:27]
	v_mfma_f32_16x16x32_bf16 v[16:19], v[144:147], v[194:197], v[16:19]
	v_mfma_f32_16x16x32_bf16 v[8:11], v[152:155], v[194:197], v[8:11]
	v_mfma_f32_16x16x32_bf16 v[60:63], v[148:151], v[164:167], v[60:63]
	v_mfma_f32_16x16x32_bf16 v[56:59], v[156:159], v[164:167], v[56:59]
	v_mfma_f32_16x16x32_bf16 v[44:47], v[148:151], v[182:185], v[44:47]
	v_mfma_f32_16x16x32_bf16 v[40:43], v[156:159], v[182:185], v[40:43]
	v_mfma_f32_16x16x32_bf16 v[32:35], v[148:151], v[190:193], v[32:35]
	v_mfma_f32_16x16x32_bf16 v[24:27], v[156:159], v[190:193], v[24:27]
	v_mfma_f32_16x16x32_bf16 v[16:19], v[148:151], v[198:201], v[16:19]
	v_mfma_f32_16x16x32_bf16 v[8:11], v[156:159], v[198:201], v[8:11]
	s_setprio 0
	s_barrier
	s_add_u32 s40, s40, 0x20080
	s_addc_u32 s41, s41, 0
	s_add_i32 s42, s42, s48
	v_lshl_add_u64 v[144:145], s[40:41], 0, v[130:131]
	s_mov_b32 m0, s42
	s_nop 0
	global_load_lds_dwordx4 v[144:145], off
	v_lshl_add_u64 v[144:145], s[40:41], 0, v[134:135]
	s_add_i32 m0, s42, 0x2000
	s_nop 0
	global_load_lds_dwordx4 v[144:145], off
	s_waitcnt vmcnt(6)
	s_setprio 1
	s_barrier
	v_mfma_f32_16x16x32_bf16 v[52:55], v[202:205], v[160:163], v[52:55]
	v_mfma_f32_16x16x32_bf16 v[48:51], v[212:215], v[160:163], v[48:51]
	v_mfma_f32_16x16x32_bf16 v[36:39], v[202:205], v[168:171], v[36:39]
	v_mfma_f32_16x16x32_bf16 v[28:31], v[212:215], v[168:171], v[28:31]
	v_mfma_f32_16x16x32_bf16 v[20:23], v[202:205], v[186:189], v[20:23]
	v_mfma_f32_16x16x32_bf16 v[12:15], v[212:215], v[186:189], v[12:15]
	v_mfma_f32_16x16x32_bf16 v[4:7], v[202:205], v[194:197], v[4:7]
	v_mfma_f32_16x16x32_bf16 v[0:3], v[212:215], v[194:197], v[0:3]
	v_mfma_f32_16x16x32_bf16 v[52:55], v[206:209], v[164:167], v[52:55]
	v_mfma_f32_16x16x32_bf16 v[48:51], v[216:219], v[164:167], v[48:51]
	v_mfma_f32_16x16x32_bf16 v[36:39], v[206:209], v[182:185], v[36:39]
	v_mfma_f32_16x16x32_bf16 v[28:31], v[216:219], v[182:185], v[28:31]
	v_mfma_f32_16x16x32_bf16 v[20:23], v[206:209], v[190:193], v[20:23]
	v_mfma_f32_16x16x32_bf16 v[12:15], v[216:219], v[190:193], v[12:15]
	v_mfma_f32_16x16x32_bf16 v[4:7], v[206:209], v[198:201], v[4:7]
	v_mfma_f32_16x16x32_bf16 v[0:3], v[216:219], v[198:201], v[0:3]
	s_setprio 0
	s_add_i32 s63, s63, 2
	s_add_u32 s38, s38, 0x100
	s_addc_u32 s39, s39, 0
	s_add_u32 s61, s61, 0x100
	s_addc_u32 s62, s62, 0
	s_cmp_gt_u32 s63, 5
	s_barrier
	s_cbranch_scc0 .LBB0_792
	v_lshl_or_b32 v144, s36, 8, v177
	v_lshl_add_u32 v150, s34, 8, v175
	v_ashrrev_i32_e32 v145, 31, v144
	v_ashrrev_i32_e32 v151, 31, v150
	v_lshlrev_b64 v[144:145], 1, v[144:145]
	v_lshl_add_u64 v[146:147], s[10:11], 0, v[144:145]
	v_lshlrev_b64 v[148:149], 11, v[150:151]
	v_lshl_add_u64 v[152:153], v[146:147], 0, v[148:149]
	global_load_dwordx4 v[156:159], v[152:153], off
	global_load_dwordx4 v[160:163], v[152:153], off offset:256
	v_or_b32_e32 v152, 16, v150
	v_ashrrev_i32_e32 v153, 31, v152
	v_lshlrev_b64 v[170:171], 11, v[152:153]
	v_lshl_add_u64 v[152:153], v[146:147], 0, v[170:171]
	global_load_dwordx4 v[164:167], v[152:153], off
	global_load_dwordx4 v[182:185], v[152:153], off offset:256
	v_or_b32_e32 v152, 32, v150
	v_ashrrev_i32_e32 v153, 31, v152
	v_lshlrev_b64 v[154:155], 11, v[152:153]
	v_lshl_add_u64 v[152:153], v[146:147], 0, v[154:155]
	global_load_dwordx4 v[186:189], v[152:153], off
	global_load_dwordx4 v[190:193], v[152:153], off offset:256
	v_or_b32_e32 v152, 48, v150
	v_ashrrev_i32_e32 v153, 31, v152
	v_lshlrev_b64 v[152:153], 11, v[152:153]
	v_lshl_add_u64 v[168:169], v[146:147], 0, v[152:153]
	global_load_dwordx4 v[194:197], v[168:169], off
	global_load_dwordx4 v[198:201], v[168:169], off offset:256
	s_waitcnt vmcnt(0)
	v_lshlrev_b32_e32 v202, 16, v156
	v_and_b32_e32 v203, 0xffff0000, v156
	v_lshlrev_b32_e32 v204, 16, v157
	v_and_b32_e32 v205, 0xffff0000, v157
	v_lshlrev_b32_e32 v206, 16, v158
	v_and_b32_e32 v207, 0xffff0000, v158
	v_lshlrev_b32_e32 v208, 16, v159
	v_and_b32_e32 v209, 0xffff0000, v159
	v_pk_add_f32 v[126:127], v[126:127], v[204:205]
	v_pk_add_f32 v[124:125], v[124:125], v[202:203]
	v_lshlrev_b32_e32 v224, 16, v166
	v_and_b32_e32 v225, 0xffff0000, v166
	v_lshlrev_b32_e32 v226, 16, v167
	v_and_b32_e32 v227, 0xffff0000, v167
	v_lshlrev_b32_e32 v212, 16, v160
	v_lshlrev_b32_e32 v166, 16, v194
	v_and_b32_e32 v167, 0xffff0000, v194
	v_lshlrev_b32_e32 v172, 16, v195
	v_and_b32_e32 v173, 0xffff0000, v195
	v_pk_add_f32 v[194:195], v[122:123], v[208:209]
	v_pk_add_f32 v[122:123], v[120:121], v[206:207]
	v_mul_f32_e32 v120, v125, v125
	v_mul_f32_e32 v121, v127, v127
	v_fmac_f32_e32 v120, v124, v124
	v_fmac_f32_e32 v121, v126, v126
	v_add_f32_e32 v120, v120, v121
	v_mul_f32_e32 v121, v123, v123
	v_fmac_f32_e32 v121, v122, v122
	v_add_f32_e32 v120, v121, v120
	v_mul_f32_e32 v121, v195, v195
	v_fmac_f32_e32 v121, v194, v194
	v_and_b32_e32 v213, 0xffff0000, v160
	v_lshlrev_b32_e32 v214, 16, v161
	v_and_b32_e32 v215, 0xffff0000, v161
	v_add_f32_e32 v181, v121, v120
	v_cvt_pk_bf16_f32 v120, v124, v125
	v_lshl_add_u64 v[124:125], s[90:91], 0, v[148:149]
	v_lshlrev_b32_e32 v216, 16, v162
	v_and_b32_e32 v217, 0xffff0000, v162
	v_lshlrev_b32_e32 v218, 16, v163
	v_and_b32_e32 v219, 0xffff0000, v163
	v_cvt_pk_bf16_f32 v121, v126, v127
	v_lshl_add_u64 v[124:125], v[124:125], 0, v[144:145]
	v_pk_add_f32 v[118:119], v[118:119], v[214:215]
	v_pk_add_f32 v[116:117], v[116:117], v[212:213]
	v_cvt_pk_bf16_f32 v122, v122, v123
	v_cvt_pk_bf16_f32 v123, v194, v195
	global_store_dwordx4 v[124:125], v[120:123], off
	v_lshlrev_b32_e32 v220, 16, v164
	v_and_b32_e32 v221, 0xffff0000, v164
	v_pk_add_f32 v[120:121], v[114:115], v[218:219]
	v_pk_add_f32 v[114:115], v[112:113], v[216:217]
	v_mul_f32_e32 v112, v117, v117
	v_mul_f32_e32 v113, v119, v119
	v_fmac_f32_e32 v112, v116, v116
	v_fmac_f32_e32 v113, v118, v118
	v_add_f32_e32 v112, v112, v113
	v_mul_f32_e32 v113, v115, v115
	v_fmac_f32_e32 v113, v114, v114
	v_add_f32_e32 v112, v113, v112
	v_mul_f32_e32 v113, v121, v121
	v_fmac_f32_e32 v113, v120, v120
	v_add_f32_e32 v112, v113, v112
	v_lshlrev_b32_e32 v222, 16, v165
	v_and_b32_e32 v223, 0xffff0000, v165
	v_add_f32_e32 v126, v181, v112
	v_cvt_pk_bf16_f32 v112, v116, v117
	v_cvt_pk_bf16_f32 v113, v118, v119
	v_lshl_add_u64 v[116:117], s[90:91], 0, v[170:171]
	v_lshlrev_b32_e32 v230, 16, v184
	v_and_b32_e32 v231, 0xffff0000, v184
	v_lshlrev_b32_e32 v232, 16, v186
	v_and_b32_e32 v233, 0xffff0000, v186
	v_lshlrev_b32_e32 v186, 16, v187
	v_and_b32_e32 v187, 0xffff0000, v187
	v_cvt_pk_bf16_f32 v114, v114, v115
	v_cvt_pk_bf16_f32 v115, v120, v121
	global_store_dwordx4 v[124:125], v[112:115], off offset:256
	v_pk_add_f32 v[110:111], v[110:111], v[222:223]
	v_pk_add_f32 v[108:109], v[108:109], v[220:221]
	v_lshl_add_u64 v[118:119], v[116:117], 0, v[144:145]
	v_cvt_pk_bf16_f32 v112, v108, v109
	v_cvt_pk_bf16_f32 v113, v110, v111
	v_lshlrev_b32_e32 v228, 16, v182
	v_and_b32_e32 v229, 0xffff0000, v182
	v_lshlrev_b32_e32 v182, 16, v183
	v_and_b32_e32 v183, 0xffff0000, v183
	v_lshlrev_b32_e32 v184, 16, v185
	v_and_b32_e32 v185, 0xffff0000, v185
	v_lshlrev_b32_e32 v238, 16, v192
	v_and_b32_e32 v239, 0xffff0000, v192
	v_pk_add_f32 v[106:107], v[106:107], v[226:227]
	v_pk_add_f32 v[104:105], v[104:105], v[224:225]
	v_lshlrev_b32_e32 v156, 16, v200
	v_cvt_pk_bf16_f32 v114, v104, v105
	v_cvt_pk_bf16_f32 v115, v106, v107
	global_store_dwordx4 v[118:119], v[112:115], off
	v_and_b32_e32 v157, 0xffff0000, v200
	v_pk_add_f32 v[102:103], v[102:103], v[182:183]
	v_pk_add_f32 v[112:113], v[92:93], v[230:231]
	v_pk_add_f32 v[92:93], v[98:99], v[186:187]
	v_lshl_add_u64 v[98:99], s[90:91], 0, v[154:155]
	v_pk_add_f32 v[100:101], v[100:101], v[228:229]
	v_pk_add_f32 v[94:95], v[94:95], v[184:185]
	v_cvt_pk_bf16_f32 v114, v100, v101
	v_cvt_pk_bf16_f32 v115, v102, v103
	v_cvt_pk_bf16_f32 v116, v112, v113
	v_lshlrev_b32_e32 v234, 16, v188
	v_cvt_pk_bf16_f32 v117, v94, v95
	global_store_dwordx4 v[118:119], v[114:117], off offset:256
	v_lshl_add_u64 v[118:119], v[98:99], 0, v[144:145]
	v_pk_add_f32 v[98:99], v[76:77], v[238:239]
	v_pk_add_f32 v[76:77], v[82:83], v[172:173]
	v_lshl_add_u64 v[82:83], s[90:91], 0, v[152:153]
	v_lshl_add_u64 v[122:123], v[82:83], 0, v[144:145]
	v_pk_add_f32 v[82:83], v[64:65], v[156:157]
	v_and_b32_e32 v65, 64, v174
	v_and_b32_e32 v235, 0xffff0000, v188
	v_lshlrev_b32_e32 v188, 16, v189
	v_and_b32_e32 v189, 0xffff0000, v189
	v_lshlrev_b32_e32 v236, 16, v190
	v_and_b32_e32 v237, 0xffff0000, v190
	v_pk_add_f32 v[96:97], v[96:97], v[232:233]
	v_xor_b32_e32 v64, 16, v174
	v_cvt_pk_bf16_f32 v114, v96, v97
	v_add_u32_e32 v65, 64, v65
	v_lshlrev_b32_e32 v190, 16, v191
	v_and_b32_e32 v191, 0xffff0000, v191
	v_lshlrev_b32_e32 v192, 16, v193
	v_and_b32_e32 v193, 0xffff0000, v193
	v_pk_add_f32 v[90:91], v[90:91], v[188:189]
	v_pk_add_f32 v[88:89], v[88:89], v[234:235]
	v_cvt_pk_bf16_f32 v115, v92, v93
	v_pk_add_f32 v[84:85], v[84:85], v[236:237]
	v_cvt_pk_bf16_f32 v116, v88, v89
	v_cvt_pk_bf16_f32 v117, v90, v91
	global_store_dwordx4 v[118:119], v[114:117], off
	v_cmp_lt_i32_e32 vcc, v64, v65
	v_lshlrev_b32_e32 v164, 16, v196
	v_cvt_pk_bf16_f32 v114, v84, v85
	v_and_b32_e32 v165, 0xffff0000, v196
	v_lshlrev_b32_e32 v168, 16, v197
	v_and_b32_e32 v169, 0xffff0000, v197
	v_pk_add_f32 v[86:87], v[86:87], v[190:191]
	v_pk_add_f32 v[78:79], v[78:79], v[192:193]
	v_cvt_pk_bf16_f32 v115, v86, v87
	v_cvt_pk_bf16_f32 v116, v98, v99
	v_pk_add_f32 v[80:81], v[80:81], v[166:167]
	v_cvt_pk_bf16_f32 v117, v78, v79
	global_store_dwordx4 v[118:119], v[114:117], off offset:256
	v_cndmask_b32_e32 v64, v174, v64, vcc
	v_pk_add_f32 v[74:75], v[74:75], v[168:169]
	v_cvt_pk_bf16_f32 v114, v80, v81
	v_pk_add_f32 v[72:73], v[72:73], v[164:165]
	v_cvt_pk_bf16_f32 v115, v76, v77
	v_lshlrev_b32_e32 v158, 16, v198
	v_cvt_pk_bf16_f32 v116, v72, v73
	v_cvt_pk_bf16_f32 v117, v74, v75
	global_store_dwordx4 v[122:123], v[114:117], off
	v_and_b32_e32 v159, 0xffff0000, v198
	v_lshlrev_b32_e32 v162, 16, v199
	v_lshlrev_b32_e32 v114, 2, v64
	ds_bpermute_b32 v64, v114, v126
	v_xor_b32_e32 v115, 32, v174
	v_cmp_lt_i32_e32 vcc, v115, v65
	v_and_b32_e32 v163, 0xffff0000, v199
	v_lshlrev_b32_e32 v160, 16, v201
	v_cndmask_b32_e32 v65, v174, v115, vcc
	v_lshlrev_b32_e32 v115, 2, v65
	s_waitcnt lgkmcnt(0)
	v_add_f32_e32 v116, v126, v64
	ds_bpermute_b32 v117, v115, v116
	v_and_b32_e32 v161, 0xffff0000, v201
	v_pk_add_f32 v[70:71], v[70:71], v[162:163]
	v_pk_add_f32 v[68:69], v[68:69], v[158:159]
	v_pk_add_f32 v[66:67], v[66:67], v[160:161]
	v_lshl_add_u64 v[64:65], v[150:151], 2, s[2:3]
	v_cvt_pk_bf16_f32 v118, v68, v69
	v_cvt_pk_bf16_f32 v119, v70, v71
	v_cvt_pk_bf16_f32 v120, v82, v83
	v_cvt_pk_bf16_f32 v121, v66, v67
	global_store_dwordx4 v[122:123], v[118:121], off offset:256
	s_and_saveexec_b64 s[34:35], s[6:7]
	s_cbranch_execz .LBB0_795
	s_waitcnt lgkmcnt(0)
	v_add_f32_e32 v116, v116, v117
	global_atomic_add_f32 v[64:65], v116, off

.LBB0_850:
	ds_read_b128 v[144:147], v151
	ds_read_b128 v[156:159], v151 offset:1024
	ds_read_b128 v[160:163], v151 offset:2048
	ds_read_b128 v[164:167], v151 offset:3072
	s_add_u32 s36, s34, 0xfffc0080
	s_addc_u32 s37, s35, -1
	s_cmp_eq_u32 s66, 12
	s_cselect_b32 s39, s27, s37
	s_cselect_b32 s38, s62, s36
	s_cselect_b32 s37, s25, s65
	s_cselect_b32 s36, s63, s64
	v_lshl_add_u64 v[172:173], s[34:35], 0, v[136:137]
	s_add_i32 m0, s42, 0xc000
	ds_read_b128 v[168:171], v152
	ds_read_b128 v[176:179], v152 offset:1024
	ds_read_b128 v[180:183], v152 offset:2048
	ds_read_b128 v[184:187], v152 offset:3072
	ds_read_b128 v[188:191], v152 offset:4096
	ds_read_b128 v[192:195], v152 offset:5120
	ds_read_b128 v[196:199], v152 offset:6144
	ds_read_b128 v[200:203], v152 offset:7168
	global_load_lds_dwordx4 v[172:173], off
	v_lshl_add_u64 v[172:173], s[34:35], 0, v[138:139]
	s_add_i32 m0, s42, 0xe000
	s_nop 0
	global_load_lds_dwordx4 v[172:173], off
	s_waitcnt lgkmcnt(8)
	s_waitcnt lgkmcnt(0)
	s_setprio 1
	s_barrier
	v_mfma_f32_16x16x32_bf16 v[124:127], v[144:147], v[168:171], v[124:127]
	v_mfma_f32_16x16x32_bf16 v[120:123], v[160:163], v[168:171], v[120:123]
	v_mfma_f32_16x16x32_bf16 v[116:119], v[144:147], v[180:183], v[116:119]
	v_mfma_f32_16x16x32_bf16 v[112:115], v[160:163], v[180:183], v[112:115]
	v_mfma_f32_16x16x32_bf16 v[92:95], v[144:147], v[188:191], v[92:95]
	v_mfma_f32_16x16x32_bf16 v[88:91], v[160:163], v[188:191], v[88:91]
	v_mfma_f32_16x16x32_bf16 v[76:79], v[144:147], v[196:199], v[76:79]
	v_mfma_f32_16x16x32_bf16 v[72:75], v[160:163], v[196:199], v[72:75]
	v_mfma_f32_16x16x32_bf16 v[124:127], v[156:159], v[176:179], v[124:127]
	v_mfma_f32_16x16x32_bf16 v[120:123], v[164:167], v[176:179], v[120:123]
	v_mfma_f32_16x16x32_bf16 v[116:119], v[156:159], v[184:187], v[116:119]
	v_mfma_f32_16x16x32_bf16 v[112:115], v[164:167], v[184:187], v[112:115]
	v_mfma_f32_16x16x32_bf16 v[92:95], v[156:159], v[192:195], v[92:95]
	v_mfma_f32_16x16x32_bf16 v[88:91], v[164:167], v[192:195], v[88:91]
	v_mfma_f32_16x16x32_bf16 v[76:79], v[156:159], v[200:203], v[76:79]
	v_mfma_f32_16x16x32_bf16 v[72:75], v[164:167], v[200:203], v[72:75]
	s_setprio 0
	s_barrier
	s_add_i32 s67, s55, s41
	v_lshl_add_u64 v[172:173], s[36:37], 0, v[130:131]
	s_mov_b32 m0, s67
	ds_read_b128 v[204:207], v153
	ds_read_b128 v[212:215], v153 offset:1024
	ds_read_b128 v[216:219], v153 offset:2048
	ds_read_b128 v[220:223], v153 offset:3072
	global_load_lds_dwordx4 v[172:173], off
	v_lshl_add_u64 v[208:209], s[36:37], 0, v[134:135]
	s_add_i32 m0, s67, 0x2000
	s_nop 0
	global_load_lds_dwordx4 v[208:209], off
	s_waitcnt lgkmcnt(0)
	s_setprio 1
	s_barrier
	v_mfma_f32_16x16x32_bf16 v[108:111], v[204:207], v[168:171], v[108:111]
	v_mfma_f32_16x16x32_bf16 v[104:107], v[216:219], v[168:171], v[104:107]
	v_mfma_f32_16x16x32_bf16 v[100:103], v[204:207], v[180:183], v[100:103]
	v_mfma_f32_16x16x32_bf16 v[96:99], v[216:219], v[180:183], v[96:99]
	v_mfma_f32_16x16x32_bf16 v[84:87], v[204:207], v[188:191], v[84:87]
	v_mfma_f32_16x16x32_bf16 v[80:83], v[216:219], v[188:191], v[80:83]
	v_mfma_f32_16x16x32_bf16 v[68:71], v[204:207], v[196:199], v[68:71]
	v_mfma_f32_16x16x32_bf16 v[64:67], v[216:219], v[196:199], v[64:67]
	v_mfma_f32_16x16x32_bf16 v[108:111], v[212:215], v[176:179], v[108:111]
	v_mfma_f32_16x16x32_bf16 v[104:107], v[220:223], v[176:179], v[104:107]
	v_mfma_f32_16x16x32_bf16 v[100:103], v[212:215], v[184:187], v[100:103]
	v_mfma_f32_16x16x32_bf16 v[96:99], v[220:223], v[184:187], v[96:99]
	v_mfma_f32_16x16x32_bf16 v[84:87], v[212:215], v[192:195], v[84:87]
	v_mfma_f32_16x16x32_bf16 v[80:83], v[220:223], v[192:195], v[80:83]
	v_mfma_f32_16x16x32_bf16 v[68:71], v[212:215], v[200:203], v[68:71]
	v_mfma_f32_16x16x32_bf16 v[64:67], v[220:223], v[200:203], v[64:67]
	s_setprio 0
	s_mov_b32 m0, s42
	v_lshl_add_u64 v[224:225], s[38:39], 0, v[128:129]
	s_barrier
	ds_read_b128 v[168:171], v152 offset:16384
	ds_read_b128 v[176:179], v152 offset:17408
	ds_read_b128 v[180:183], v152 offset:18432
	ds_read_b128 v[184:187], v152 offset:19456
	ds_read_b128 v[188:191], v152 offset:20480
	ds_read_b128 v[192:195], v152 offset:21504
	ds_read_b128 v[196:199], v152 offset:22528
	ds_read_b128 v[200:203], v152 offset:23552
	global_load_lds_dwordx4 v[224:225], off
	v_lshl_add_u64 v[226:227], s[38:39], 0, v[132:133]
	s_mov_b32 m0, s43
	s_nop 0
	global_load_lds_dwordx4 v[226:227], off
	s_waitcnt lgkmcnt(0)
	s_setprio 1
	s_barrier
	v_mfma_f32_16x16x32_bf16 v[60:63], v[144:147], v[168:171], v[60:63]
	v_mfma_f32_16x16x32_bf16 v[56:59], v[160:163], v[168:171], v[56:59]
	v_mfma_f32_16x16x32_bf16 v[44:47], v[144:147], v[180:183], v[44:47]
	v_mfma_f32_16x16x32_bf16 v[40:43], v[160:163], v[180:183], v[40:43]
	v_mfma_f32_16x16x32_bf16 v[28:31], v[144:147], v[188:191], v[28:31]
	v_mfma_f32_16x16x32_bf16 v[24:27], v[160:163], v[188:191], v[24:27]
	v_mfma_f32_16x16x32_bf16 v[12:15], v[144:147], v[196:199], v[12:15]
	v_mfma_f32_16x16x32_bf16 v[8:11], v[160:163], v[196:199], v[8:11]
	v_mfma_f32_16x16x32_bf16 v[60:63], v[156:159], v[176:179], v[60:63]
	v_mfma_f32_16x16x32_bf16 v[56:59], v[164:167], v[176:179], v[56:59]
	v_mfma_f32_16x16x32_bf16 v[44:47], v[156:159], v[184:187], v[44:47]
	v_mfma_f32_16x16x32_bf16 v[40:43], v[164:167], v[184:187], v[40:43]
	v_mfma_f32_16x16x32_bf16 v[28:31], v[156:159], v[192:195], v[28:31]
	v_mfma_f32_16x16x32_bf16 v[24:27], v[164:167], v[192:195], v[24:27]
	v_mfma_f32_16x16x32_bf16 v[12:15], v[156:159], v[200:203], v[12:15]
	v_mfma_f32_16x16x32_bf16 v[8:11], v[164:167], v[200:203], v[8:11]
	s_setprio 0
	s_barrier
	s_add_u32 s68, s36, 0x40000
	s_addc_u32 s69, s37, 0
	s_add_i32 s67, s56, s41
	v_lshl_add_u64 v[144:145], s[68:69], 0, v[130:131]
	s_mov_b32 m0, s67
	s_nop 0
	global_load_lds_dwordx4 v[144:145], off
	v_lshl_add_u64 v[144:145], s[68:69], 0, v[134:135]
	s_add_i32 m0, s67, 0x2000
	s_nop 0
	global_load_lds_dwordx4 v[144:145], off
	s_waitcnt vmcnt(6)
	s_setprio 1
	s_barrier
	v_mfma_f32_16x16x32_bf16 v[52:55], v[204:207], v[168:171], v[52:55]
	v_mfma_f32_16x16x32_bf16 v[48:51], v[216:219], v[168:171], v[48:51]
	v_mfma_f32_16x16x32_bf16 v[36:39], v[204:207], v[180:183], v[36:39]
	v_mfma_f32_16x16x32_bf16 v[32:35], v[216:219], v[180:183], v[32:35]
	v_mfma_f32_16x16x32_bf16 v[20:23], v[204:207], v[188:191], v[20:23]
	v_mfma_f32_16x16x32_bf16 v[16:19], v[216:219], v[188:191], v[16:19]
	v_mfma_f32_16x16x32_bf16 v[4:7], v[204:207], v[196:199], v[4:7]
	v_mfma_f32_16x16x32_bf16 v[0:3], v[216:219], v[196:199], v[0:3]
	v_mfma_f32_16x16x32_bf16 v[52:55], v[212:215], v[176:179], v[52:55]
	v_mfma_f32_16x16x32_bf16 v[48:51], v[220:223], v[176:179], v[48:51]
	v_mfma_f32_16x16x32_bf16 v[36:39], v[212:215], v[184:187], v[36:39]
	v_mfma_f32_16x16x32_bf16 v[32:35], v[220:223], v[184:187], v[32:35]
	v_mfma_f32_16x16x32_bf16 v[20:23], v[212:215], v[192:195], v[20:23]
	v_mfma_f32_16x16x32_bf16 v[16:19], v[220:223], v[192:195], v[16:19]
	v_mfma_f32_16x16x32_bf16 v[4:7], v[212:215], v[200:203], v[4:7]
	v_mfma_f32_16x16x32_bf16 v[0:3], v[220:223], v[200:203], v[0:3]
	s_setprio 0
	s_add_i32 s67, 0, 0x18000
	v_add_u32_e32 v155, s67, v149
	s_barrier
	ds_read_b128 v[144:147], v155
	ds_read_b128 v[156:159], v155 offset:1024
	ds_read_b128 v[160:163], v155 offset:2048
	ds_read_b128 v[164:167], v155 offset:3072
	s_add_u32 s38, s38, 0x40000
	s_addc_u32 s39, s39, 0
	s_mov_b32 m0, s48
	v_lshl_add_u64 v[204:205], s[38:39], 0, v[128:129]
	ds_read_b128 v[168:171], v152 offset:32768
	ds_read_b128 v[176:179], v152 offset:33792
	ds_read_b128 v[180:183], v152 offset:34816
	ds_read_b128 v[184:187], v152 offset:35840
	ds_read_b128 v[188:191], v152 offset:36864
	ds_read_b128 v[192:195], v152 offset:37888
	ds_read_b128 v[196:199], v152 offset:38912
	ds_read_b128 v[200:203], v152 offset:39936
	global_load_lds_dwordx4 v[204:205], off
	v_lshl_add_u64 v[204:205], s[38:39], 0, v[132:133]
	s_mov_b32 m0, s49
	s_nop 0
	global_load_lds_dwordx4 v[204:205], off
	s_waitcnt lgkmcnt(8)
	s_waitcnt lgkmcnt(0)
	s_setprio 1
	s_barrier
	v_mfma_f32_16x16x32_bf16 v[124:127], v[144:147], v[168:171], v[124:127]
	v_mfma_f32_16x16x32_bf16 v[120:123], v[160:163], v[168:171], v[120:123]
	v_mfma_f32_16x16x32_bf16 v[116:119], v[144:147], v[180:183], v[116:119]
	v_mfma_f32_16x16x32_bf16 v[112:115], v[160:163], v[180:183], v[112:115]
	v_mfma_f32_16x16x32_bf16 v[92:95], v[144:147], v[188:191], v[92:95]
	v_mfma_f32_16x16x32_bf16 v[88:91], v[160:163], v[188:191], v[88:91]
	v_mfma_f32_16x16x32_bf16 v[76:79], v[144:147], v[196:199], v[76:79]
	v_mfma_f32_16x16x32_bf16 v[72:75], v[160:163], v[196:199], v[72:75]
	v_mfma_f32_16x16x32_bf16 v[124:127], v[156:159], v[176:179], v[124:127]
	v_mfma_f32_16x16x32_bf16 v[120:123], v[164:167], v[176:179], v[120:123]
	v_mfma_f32_16x16x32_bf16 v[116:119], v[156:159], v[184:187], v[116:119]
	v_mfma_f32_16x16x32_bf16 v[112:115], v[164:167], v[184:187], v[112:115]
	v_mfma_f32_16x16x32_bf16 v[92:95], v[156:159], v[192:195], v[92:95]
	v_mfma_f32_16x16x32_bf16 v[88:91], v[164:167], v[192:195], v[88:91]
	v_mfma_f32_16x16x32_bf16 v[76:79], v[156:159], v[200:203], v[76:79]
	v_mfma_f32_16x16x32_bf16 v[72:75], v[164:167], v[200:203], v[72:75]
	s_setprio 0
	s_barrier
	s_add_i32 s38, 0, 0x1c000
	s_add_i32 s39, s67, s41
	v_add_u32_e32 v155, s38, v149
	v_lshl_add_u64 v[172:173], v[172:173], 0, s[8:9]
	s_mov_b32 m0, s39
	ds_read_b128 v[204:207], v155
	ds_read_b128 v[212:215], v155 offset:1024
	ds_read_b128 v[216:219], v155 offset:2048
	ds_read_b128 v[220:223], v155 offset:3072
	global_load_lds_dwordx4 v[172:173], off
	v_lshl_add_u64 v[172:173], v[208:209], 0, s[8:9]
	s_add_i32 m0, s39, 0x2000
	s_nop 0
	global_load_lds_dwordx4 v[172:173], off
	s_waitcnt lgkmcnt(0)
	s_setprio 1
	s_barrier
	v_mfma_f32_16x16x32_bf16 v[108:111], v[204:207], v[168:171], v[108:111]
	v_mfma_f32_16x16x32_bf16 v[104:107], v[216:219], v[168:171], v[104:107]
	v_mfma_f32_16x16x32_bf16 v[100:103], v[204:207], v[180:183], v[100:103]
	v_mfma_f32_16x16x32_bf16 v[96:99], v[216:219], v[180:183], v[96:99]
	v_mfma_f32_16x16x32_bf16 v[84:87], v[204:207], v[188:191], v[84:87]
	v_mfma_f32_16x16x32_bf16 v[80:83], v[216:219], v[188:191], v[80:83]
	v_mfma_f32_16x16x32_bf16 v[68:71], v[204:207], v[196:199], v[68:71]
	v_mfma_f32_16x16x32_bf16 v[64:67], v[216:219], v[196:199], v[64:67]
	v_mfma_f32_16x16x32_bf16 v[108:111], v[212:215], v[176:179], v[108:111]
	v_mfma_f32_16x16x32_bf16 v[104:107], v[220:223], v[176:179], v[104:107]
	v_mfma_f32_16x16x32_bf16 v[100:103], v[212:215], v[184:187], v[100:103]
	v_mfma_f32_16x16x32_bf16 v[96:99], v[220:223], v[184:187], v[96:99]
	v_mfma_f32_16x16x32_bf16 v[84:87], v[212:215], v[192:195], v[84:87]
	v_mfma_f32_16x16x32_bf16 v[80:83], v[220:223], v[192:195], v[80:83]
	v_mfma_f32_16x16x32_bf16 v[68:71], v[212:215], v[200:203], v[68:71]
	v_mfma_f32_16x16x32_bf16 v[64:67], v[220:223], v[200:203], v[64:67]
	s_setprio 0
	s_mov_b32 m0, s51
	v_lshl_add_u64 v[172:173], v[224:225], 0, s[8:9]
	s_barrier
	ds_read_b128 v[168:171], v152 offset:49152
	ds_read_b128 v[176:179], v152 offset:50176
	ds_read_b128 v[180:183], v152 offset:51200
	ds_read_b128 v[184:187], v152 offset:52224
	ds_read_b128 v[188:191], v152 offset:53248
	ds_read_b128 v[192:195], v152 offset:54272
	ds_read_b128 v[196:199], v152 offset:55296
	ds_read_b128 v[200:203], v152 offset:56320
	global_load_lds_dwordx4 v[172:173], off
	v_lshl_add_u64 v[172:173], v[226:227], 0, s[8:9]
	s_mov_b32 m0, s52
	s_nop 0
	global_load_lds_dwordx4 v[172:173], off
	s_waitcnt lgkmcnt(0)
	s_setprio 1
	s_barrier
	v_mfma_f32_16x16x32_bf16 v[60:63], v[144:147], v[168:171], v[60:63]
	v_mfma_f32_16x16x32_bf16 v[56:59], v[160:163], v[168:171], v[56:59]
	v_mfma_f32_16x16x32_bf16 v[44:47], v[144:147], v[180:183], v[44:47]
	v_mfma_f32_16x16x32_bf16 v[40:43], v[160:163], v[180:183], v[40:43]
	v_mfma_f32_16x16x32_bf16 v[28:31], v[144:147], v[188:191], v[28:31]
	v_mfma_f32_16x16x32_bf16 v[24:27], v[160:163], v[188:191], v[24:27]
	v_mfma_f32_16x16x32_bf16 v[12:15], v[144:147], v[196:199], v[12:15]
	v_mfma_f32_16x16x32_bf16 v[8:11], v[160:163], v[196:199], v[8:11]
	v_mfma_f32_16x16x32_bf16 v[60:63], v[156:159], v[176:179], v[60:63]
	v_mfma_f32_16x16x32_bf16 v[56:59], v[164:167], v[176:179], v[56:59]
	v_mfma_f32_16x16x32_bf16 v[44:47], v[156:159], v[184:187], v[44:47]
	v_mfma_f32_16x16x32_bf16 v[40:43], v[164:167], v[184:187], v[40:43]
	v_mfma_f32_16x16x32_bf16 v[28:31], v[156:159], v[192:195], v[28:31]
	v_mfma_f32_16x16x32_bf16 v[24:27], v[164:167], v[192:195], v[24:27]
	v_mfma_f32_16x16x32_bf16 v[12:15], v[156:159], v[200:203], v[12:15]
	v_mfma_f32_16x16x32_bf16 v[8:11], v[164:167], v[200:203], v[8:11]
	s_setprio 0
	s_barrier
	s_add_u32 s36, s36, 0x40080
	s_addc_u32 s37, s37, 0
	s_add_i32 s38, s38, s41
	v_lshl_add_u64 v[144:145], s[36:37], 0, v[130:131]
	s_mov_b32 m0, s38
	s_nop 0
	global_load_lds_dwordx4 v[144:145], off
	v_lshl_add_u64 v[144:145], s[36:37], 0, v[134:135]
	s_add_i32 m0, s38, 0x2000
	s_nop 0
	global_load_lds_dwordx4 v[144:145], off
	s_waitcnt vmcnt(6)
	s_setprio 1
	s_barrier
	v_mfma_f32_16x16x32_bf16 v[52:55], v[204:207], v[168:171], v[52:55]
	v_mfma_f32_16x16x32_bf16 v[48:51], v[216:219], v[168:171], v[48:51]
	v_mfma_f32_16x16x32_bf16 v[36:39], v[204:207], v[180:183], v[36:39]
	v_mfma_f32_16x16x32_bf16 v[32:35], v[216:219], v[180:183], v[32:35]
	v_mfma_f32_16x16x32_bf16 v[20:23], v[204:207], v[188:191], v[20:23]
	v_mfma_f32_16x16x32_bf16 v[16:19], v[216:219], v[188:191], v[16:19]
	v_mfma_f32_16x16x32_bf16 v[4:7], v[204:207], v[196:199], v[4:7]
	v_mfma_f32_16x16x32_bf16 v[0:3], v[216:219], v[196:199], v[0:3]
	v_mfma_f32_16x16x32_bf16 v[52:55], v[212:215], v[176:179], v[52:55]
	v_mfma_f32_16x16x32_bf16 v[48:51], v[220:223], v[176:179], v[48:51]
	v_mfma_f32_16x16x32_bf16 v[36:39], v[212:215], v[184:187], v[36:39]
	v_mfma_f32_16x16x32_bf16 v[32:35], v[220:223], v[184:187], v[32:35]
	v_mfma_f32_16x16x32_bf16 v[20:23], v[212:215], v[192:195], v[20:23]
	v_mfma_f32_16x16x32_bf16 v[16:19], v[220:223], v[192:195], v[16:19]
	v_mfma_f32_16x16x32_bf16 v[4:7], v[212:215], v[200:203], v[4:7]
	v_mfma_f32_16x16x32_bf16 v[0:3], v[220:223], v[200:203], v[0:3]
	s_setprio 0
	s_add_i32 s66, s66, 2
	s_add_u32 s34, s34, 0x100
	s_addc_u32 s35, s35, 0
	s_add_u32 s64, s64, 0x100
	s_addc_u32 s65, s65, 0
	s_cmp_gt_u32 s66, 13
	s_barrier
	s_cbranch_scc0 .LBB0_850
	v_lshl_add_u32 v146, s0, 8, v148
	v_ashrrev_i32_e32 v147, 31, v146
	v_lshl_add_u64 v[144:145], v[146:147], 2, s[2:3]
	global_load_dword v155, v[144:145], off
	global_load_dword v162, v[144:145], off offset:64
	global_load_dword v163, v[144:145], off offset:128
	global_load_dword v164, v[144:145], off offset:192
	global_load_dword v165, v[144:145], off offset:512
	global_load_dword v166, v[144:145], off offset:576
	global_load_dword v167, v[144:145], off offset:640
	global_load_dword v168, v[144:145], off offset:704
	v_lshl_or_b32 v144, s1, 8, v150
	v_ashrrev_i32_e32 v145, 31, v144
	v_lshlrev_b64 v[158:159], 13, v[146:147]
	v_lshlrev_b64 v[160:161], 1, v[144:145]
	v_lshl_add_u64 v[144:145], s[92:93], 0, v[158:159]
	v_lshl_add_u64 v[144:145], v[144:145], 0, v[160:161]
	v_or_b32_e32 v156, 16, v146
	v_ashrrev_i32_e32 v157, 31, v156
	v_lshlrev_b64 v[156:157], 13, v[156:157]
	v_lshl_add_u64 v[156:157], s[92:93], 0, v[156:157]
	v_lshl_add_u64 v[156:157], v[156:157], 0, v[160:161]
	s_mov_b64 s[36:37], s[30:31]
	s_mov_b64 s[34:35], s[28:29]
	s_waitcnt vmcnt(0)
	v_fmamk_f32 v147, v155, 0x3a800000, v154
	v_mul_f32_e32 v158, 0x4b800000, v147
	v_cmp_gt_f32_e32 vcc, s57, v147
	v_fmamk_f32 v155, v162, 0x3a800000, v154
	v_mul_f32_e32 v162, 0x4b800000, v155
	v_cndmask_b32_e32 v147, v147, v158, vcc
	v_rsq_f32_e32 v158, v147
	v_cmp_gt_f32_e64 s[0:1], s57, v155
	v_fmamk_f32 v159, v163, 0x3a800000, v154
	v_fmamk_f32 v163, v164, 0x3a800000, v154
	v_cndmask_b32_e64 v155, v155, v162, s[0:1]
	v_rsq_f32_e32 v155, v155
	v_mul_f32_e32 v162, 0x45800000, v158
	v_cndmask_b32_e32 v158, v158, v162, vcc
	v_pk_mul_f32 v[124:125], v[124:125], v[158:159] op_sel_hi:[1,0]
	v_pk_mul_f32 v[104:105], v[104:105], v[158:159] op_sel_hi:[1,0]
	v_fmamk_f32 v164, v165, 0x3a800000, v154
	v_fmamk_f32 v165, v166, 0x3a800000, v154
	v_fmamk_f32 v166, v167, 0x3a800000, v154
	v_mul_f32_e32 v167, 0x45800000, v155
	v_pk_mul_f32 v[126:127], v[126:127], v[158:159] op_sel_hi:[1,0]
	v_pk_mul_f32 v[122:123], v[122:123], v[158:159] op_sel_hi:[1,0]
	v_pk_mul_f32 v[120:121], v[120:121], v[158:159] op_sel_hi:[1,0]
	v_pk_mul_f32 v[108:109], v[108:109], v[158:159] op_sel_hi:[1,0]
	v_pk_mul_f32 v[106:107], v[106:107], v[158:159] op_sel_hi:[1,0]
	v_max_f32_e32 v124, 0, v124
	v_max_f32_e32 v125, 0, v125
	v_max_f32_e32 v104, 0, v104
	v_cndmask_b32_e64 v162, v155, v167, s[0:1]
	v_pk_mul_f32 v[110:111], v[110:111], v[158:159] op_sel_hi:[1,0]
	v_max_f32_e32 v120, 0, v120
	v_max_f32_e32 v121, 0, v121
	v_max_f32_e32 v126, 0, v126
	v_max_f32_e32 v122, 0, v122
	v_max_f32_e32 v127, 0, v127
	v_max_f32_e32 v123, 0, v123
	v_max_f32_e32 v108, 0, v108
	v_max_f32_e32 v109, 0, v109
	v_max_f32_e32 v105, 0, v105
	v_max_f32_e32 v106, 0, v106
	v_max_f32_e32 v107, 0, v107
	v_mul_f32_e32 v124, v124, v124
	v_mul_f32_e32 v125, v125, v125
	v_mul_f32_e32 v155, v104, v104
	v_cvt_pk_bf16_f32 v104, v124, v125
	v_fmamk_f32 v147, v168, 0x3a800000, v154
	v_pk_mul_f32 v[112:113], v[112:113], v[162:163] op_sel_hi:[1,0]
	v_max_f32_e32 v110, 0, v110
	v_max_f32_e32 v111, 0, v111
	v_mul_f32_e32 v120, v120, v120
	v_mul_f32_e32 v121, v121, v121
	v_mul_f32_e32 v126, v126, v126
	v_mul_f32_e32 v122, v122, v122
	v_mul_f32_e32 v127, v127, v127
	v_mul_f32_e32 v123, v123, v123
	v_mul_f32_e32 v108, v108, v108
	v_mul_f32_e32 v109, v109, v109
	v_mul_f32_e32 v158, v105, v105
	v_mul_f32_e32 v167, v106, v106
	v_mul_f32_e32 v168, v107, v107
	v_cvt_pk_bf16_f32 v105, v126, v127
	v_cvt_pk_bf16_f32 v106, v120, v121
	v_cvt_pk_bf16_f32 v107, v122, v123
	global_store_dwordx4 v[144:145], v[104:107], off nt
	v_pk_mul_f32 v[116:117], v[116:117], v[162:163] op_sel_hi:[1,0]
	v_mul_f32_e32 v110, v110, v110
	v_cvt_pk_bf16_f32 v104, v108, v109
	v_mul_f32_e32 v111, v111, v111
	v_cvt_pk_bf16_f32 v105, v110, v111
	v_cvt_pk_bf16_f32 v106, v155, v158
	v_cvt_pk_bf16_f32 v107, v167, v168
	global_store_dwordx4 v[144:145], v[104:107], off offset:256 nt
	v_pk_mul_f32 v[118:119], v[118:119], v[162:163] op_sel_hi:[1,0]
	v_pk_mul_f32 v[114:115], v[114:115], v[162:163] op_sel_hi:[1,0]
	v_max_f32_e32 v104, 0, v112
	v_mul_f32_e32 v106, v104, v104
	v_max_f32_e32 v104, 0, v117
	v_max_f32_e32 v116, 0, v116
	v_max_f32_e32 v107, 0, v113
	v_mul_f32_e32 v104, v104, v104
	v_pk_mul_f32 v[98:99], v[98:99], v[162:163] op_sel_hi:[1,0]
	v_pk_mul_f32 v[96:97], v[96:97], v[162:163] op_sel_hi:[1,0]
	v_mul_f32_e32 v105, v116, v116
	v_mul_f32_e32 v107, v107, v107
	v_max_f32_e32 v108, 0, v118
	v_max_f32_e32 v109, 0, v114
	v_max_f32_e32 v110, 0, v119
	v_max_f32_e32 v111, 0, v115
	v_cvt_pk_bf16_f32 v104, v105, v104
	v_pk_mul_f32 v[102:103], v[102:103], v[162:163] op_sel_hi:[1,0]
	v_pk_mul_f32 v[100:101], v[100:101], v[162:163] op_sel_hi:[1,0]
	v_max_f32_e32 v96, 0, v96
	v_max_f32_e32 v97, 0, v97
	v_max_f32_e32 v98, 0, v98
	v_mul_f32_e32 v108, v108, v108
	v_mul_f32_e32 v109, v109, v109
	v_mul_f32_e32 v110, v110, v110
	v_mul_f32_e32 v111, v111, v111
	v_cvt_pk_bf16_f32 v105, v108, v110
	v_cvt_pk_bf16_f32 v106, v106, v107
	v_cvt_pk_bf16_f32 v107, v109, v111
	global_store_dwordx4 v[156:157], v[104:107], off nt
	v_max_f32_e32 v100, 0, v100
	v_max_f32_e32 v99, 0, v99
	v_mul_f32_e32 v104, v96, v96
	v_max_f32_e32 v96, 0, v101
	v_mul_f32_e32 v101, v97, v97
	v_max_f32_e32 v97, 0, v102
	v_mul_f32_e32 v102, v98, v98
	v_max_f32_e32 v98, 0, v103
	v_mul_f32_e32 v96, v96, v96
	v_mul_f32_e32 v97, v97, v97
	v_mul_f32_e32 v98, v98, v98
	v_mul_f32_e32 v100, v100, v100
	v_mul_f32_e32 v99, v99, v99
	v_cvt_pk_bf16_f32 v96, v100, v96
	v_cvt_pk_bf16_f32 v97, v97, v98
	v_cvt_pk_bf16_f32 v98, v104, v101
	v_cvt_pk_bf16_f32 v99, v102, v99
	global_store_dwordx4 v[156:157], v[96:99], off offset:256 nt
	v_cmp_gt_f32_e32 vcc, s57, v159
	s_mov_b64 s[0:1], 0x100000
	v_mul_f32_e32 v98, 0x4b800000, v159
	v_cndmask_b32_e32 v98, v159, v98, vcc
	v_rsq_f32_e32 v98, v98
	v_or_b32_e32 v96, 32, v146
	v_ashrrev_i32_e32 v97, 31, v96
	v_lshlrev_b64 v[96:97], 13, v[96:97]
	v_mul_f32_e32 v99, 0x45800000, v98
	v_cndmask_b32_e32 v98, v98, v99, vcc
	v_pk_mul_f32 v[88:89], v[88:89], v[98:99] op_sel_hi:[1,0]
	v_pk_mul_f32 v[92:93], v[92:93], v[98:99] op_sel_hi:[1,0]
	v_pk_mul_f32 v[90:91], v[90:91], v[98:99] op_sel_hi:[1,0]
	v_max_f32_e32 v88, 0, v88
	v_pk_mul_f32 v[94:95], v[94:95], v[98:99] op_sel_hi:[1,0]
	v_mul_f32_e32 v99, v88, v88
	v_max_f32_e32 v88, 0, v93
	v_max_f32_e32 v89, 0, v89
	v_max_f32_e32 v90, 0, v90
	v_lshl_add_u64 v[96:97], s[92:93], 0, v[96:97]
	v_max_f32_e32 v92, 0, v92
	v_mul_f32_e32 v88, v88, v88
	v_mul_f32_e32 v93, v89, v89
	v_max_f32_e32 v89, 0, v94
	v_mul_f32_e32 v94, v90, v90
	v_max_f32_e32 v90, 0, v95
	v_max_f32_e32 v91, 0, v91
	v_pk_mul_f32 v[82:83], v[82:83], v[98:99] op_sel_hi:[1,0]
	v_pk_mul_f32 v[80:81], v[80:81], v[98:99] op_sel_hi:[1,0]
	v_lshl_add_u64 v[96:97], v[96:97], 0, v[160:161]
	v_mul_f32_e32 v92, v92, v92
	v_mul_f32_e32 v89, v89, v89
	v_mul_f32_e32 v90, v90, v90
	v_mul_f32_e32 v91, v91, v91
	v_cvt_pk_bf16_f32 v88, v92, v88
	v_pk_mul_f32 v[86:87], v[86:87], v[98:99] op_sel_hi:[1,0]
	v_pk_mul_f32 v[84:85], v[84:85], v[98:99] op_sel_hi:[1,0]
	v_max_f32_e32 v80, 0, v80
	v_max_f32_e32 v81, 0, v81
	v_max_f32_e32 v82, 0, v82
	v_cvt_pk_bf16_f32 v89, v89, v90
	v_cvt_pk_bf16_f32 v90, v99, v93
	v_cvt_pk_bf16_f32 v91, v94, v91
	global_store_dwordx4 v[96:97], v[88:91], off nt
	v_max_f32_e32 v84, 0, v84
	v_max_f32_e32 v83, 0, v83
	v_mul_f32_e32 v88, v80, v80
	v_max_f32_e32 v80, 0, v85
	v_mul_f32_e32 v85, v81, v81
	v_max_f32_e32 v81, 0, v86
	v_mul_f32_e32 v86, v82, v82
	v_max_f32_e32 v82, 0, v87
	v_mul_f32_e32 v80, v80, v80
	v_mul_f32_e32 v81, v81, v81
	v_mul_f32_e32 v82, v82, v82
	v_mul_f32_e32 v84, v84, v84
	v_mul_f32_e32 v83, v83, v83
	v_cvt_pk_bf16_f32 v80, v84, v80
	v_cvt_pk_bf16_f32 v81, v81, v82
	v_cvt_pk_bf16_f32 v82, v88, v85
	v_cvt_pk_bf16_f32 v83, v86, v83
	global_store_dwordx4 v[96:97], v[80:83], off offset:256 nt
	v_cmp_gt_f32_e32 vcc, s57, v163
	s_nop 0
	v_mul_f32_e32 v82, 0x4b800000, v163
	v_cndmask_b32_e32 v82, v163, v82, vcc
	v_rsq_f32_e32 v82, v82
	v_or_b32_e32 v80, 48, v146
	v_ashrrev_i32_e32 v81, 31, v80
	v_lshlrev_b64 v[80:81], 13, v[80:81]
	v_mul_f32_e32 v83, 0x45800000, v82
	v_cndmask_b32_e32 v82, v82, v83, vcc
	v_pk_mul_f32 v[72:73], v[72:73], v[82:83] op_sel_hi:[1,0]
	v_pk_mul_f32 v[76:77], v[76:77], v[82:83] op_sel_hi:[1,0]
	v_pk_mul_f32 v[74:75], v[74:75], v[82:83] op_sel_hi:[1,0]
	v_max_f32_e32 v72, 0, v72
	v_pk_mul_f32 v[78:79], v[78:79], v[82:83] op_sel_hi:[1,0]
	v_mul_f32_e32 v83, v72, v72
	v_max_f32_e32 v72, 0, v77
	v_max_f32_e32 v73, 0, v73
	v_max_f32_e32 v74, 0, v74
	v_lshl_add_u64 v[80:81], s[92:93], 0, v[80:81]
	v_max_f32_e32 v76, 0, v76
	v_mul_f32_e32 v72, v72, v72
	v_mul_f32_e32 v77, v73, v73
	v_max_f32_e32 v73, 0, v78
	v_mul_f32_e32 v78, v74, v74
	v_max_f32_e32 v74, 0, v79
	v_max_f32_e32 v75, 0, v75
	v_pk_mul_f32 v[64:65], v[64:65], v[82:83] op_sel_hi:[1,0]
	v_lshl_add_u64 v[80:81], v[80:81], 0, v[160:161]
	v_mul_f32_e32 v76, v76, v76
	v_mul_f32_e32 v73, v73, v73
	v_mul_f32_e32 v74, v74, v74
	v_mul_f32_e32 v75, v75, v75
	v_cvt_pk_bf16_f32 v72, v76, v72
	v_pk_mul_f32 v[68:69], v[68:69], v[82:83] op_sel_hi:[1,0]
	v_max_f32_e32 v64, 0, v64
	v_cvt_pk_bf16_f32 v73, v73, v74
	v_cvt_pk_bf16_f32 v74, v83, v77
	v_cvt_pk_bf16_f32 v75, v78, v75
	global_store_dwordx4 v[80:81], v[72:75], off nt
	v_max_f32_e32 v68, 0, v68
	v_mul_f32_e32 v68, v68, v68
	v_mul_f32_e32 v72, v64, v64
	v_max_f32_e32 v64, 0, v69
	v_mul_f32_e32 v64, v64, v64
	v_cvt_pk_bf16_f32 v64, v68, v64
	v_mul_f32_e32 v68, 0x4b800000, v164
	v_cmp_gt_f32_e32 vcc, s57, v164
	v_pk_mul_f32 v[66:67], v[66:67], v[82:83] op_sel_hi:[1,0]
	v_pk_mul_f32 v[70:71], v[70:71], v[82:83] op_sel_hi:[1,0]
	v_cndmask_b32_e32 v68, v164, v68, vcc
	v_max_f32_e32 v65, 0, v65
	v_max_f32_e32 v66, 0, v66
	v_rsq_f32_e32 v68, v68
	v_mul_f32_e32 v69, v65, v65
	v_max_f32_e32 v65, 0, v70
	v_mul_f32_e32 v70, v66, v66
	v_max_f32_e32 v66, 0, v71
	v_mul_f32_e32 v65, v65, v65
	v_max_f32_e32 v67, 0, v67
	v_mul_f32_e32 v66, v66, v66
	v_mul_f32_e32 v67, v67, v67
	v_cvt_pk_bf16_f32 v65, v65, v66
	v_cvt_pk_bf16_f32 v66, v72, v69
	v_cvt_pk_bf16_f32 v67, v70, v67
	global_store_dwordx4 v[80:81], v[64:67], off offset:256 nt
	s_nop 1
	v_mul_f32_e32 v66, 0x45800000, v68
	v_cndmask_b32_e32 v66, v68, v66, vcc
	v_pk_mul_f32 v[56:57], v[56:57], v[66:67] op_sel_hi:[1,0]
	v_pk_mul_f32 v[60:61], v[60:61], v[66:67] op_sel_hi:[1,0]
	v_pk_mul_f32 v[58:59], v[58:59], v[66:67] op_sel_hi:[1,0]
	v_max_f32_e32 v56, 0, v56
	v_pk_mul_f32 v[62:63], v[62:63], v[66:67] op_sel_hi:[1,0]
	v_max_f32_e32 v60, 0, v60
	v_mul_f32_e32 v67, v56, v56
	v_max_f32_e32 v56, 0, v61
	v_max_f32_e32 v57, 0, v57
	v_max_f32_e32 v58, 0, v58
	v_mul_f32_e32 v60, v60, v60
	v_mul_f32_e32 v56, v56, v56
	v_mul_f32_e32 v61, v57, v57
	v_max_f32_e32 v57, 0, v62
	v_mul_f32_e32 v62, v58, v58
	v_max_f32_e32 v58, 0, v63
	v_mul_f32_e32 v57, v57, v57
	v_max_f32_e32 v59, 0, v59
	v_mul_f32_e32 v58, v58, v58
	v_cvt_pk_bf16_f32 v56, v60, v56
	v_add_co_u32_e32 v60, vcc, s58, v144
	v_pk_mul_f32 v[48:49], v[48:49], v[66:67] op_sel_hi:[1,0]
	v_mul_f32_e32 v59, v59, v59
	v_cvt_pk_bf16_f32 v57, v57, v58
	v_cvt_pk_bf16_f32 v58, v67, v61
	v_addc_co_u32_e32 v61, vcc, 0, v145, vcc
	v_pk_mul_f32 v[52:53], v[52:53], v[66:67] op_sel_hi:[1,0]
	v_max_f32_e32 v48, 0, v48
	v_cvt_pk_bf16_f32 v59, v62, v59
	global_store_dwordx4 v[60:61], v[56:59], off nt
	v_max_f32_e32 v52, 0, v52
	v_mul_f32_e32 v52, v52, v52
	v_mul_f32_e32 v56, v48, v48
	v_max_f32_e32 v48, 0, v53
	v_mul_f32_e32 v48, v48, v48
	v_cvt_pk_bf16_f32 v48, v52, v48
	v_mul_f32_e32 v52, 0x4b800000, v165
	v_cmp_gt_f32_e32 vcc, s57, v165
	v_pk_mul_f32 v[50:51], v[50:51], v[66:67] op_sel_hi:[1,0]
	v_pk_mul_f32 v[54:55], v[54:55], v[66:67] op_sel_hi:[1,0]
	v_cndmask_b32_e32 v52, v165, v52, vcc
	v_max_f32_e32 v49, 0, v49
	v_max_f32_e32 v50, 0, v50
	v_rsq_f32_e32 v52, v52
	v_mul_f32_e32 v53, v49, v49
	v_max_f32_e32 v49, 0, v54
	v_mul_f32_e32 v54, v50, v50
	v_max_f32_e32 v50, 0, v55
	v_mul_f32_e32 v49, v49, v49
	v_max_f32_e32 v51, 0, v51
	v_mul_f32_e32 v50, v50, v50
	v_lshl_add_u64 v[64:65], v[144:145], 0, s[0:1]
	v_mul_f32_e32 v51, v51, v51
	v_cvt_pk_bf16_f32 v49, v49, v50
	v_cvt_pk_bf16_f32 v50, v56, v53
	v_cvt_pk_bf16_f32 v51, v54, v51
	global_store_dwordx4 v[64:65], v[48:51], off offset:256 nt
	s_mov_b32 s1, s24
	s_mov_b32 s0, s26
	v_mul_f32_e32 v50, 0x45800000, v52
	v_cndmask_b32_e32 v50, v52, v50, vcc
	v_pk_mul_f32 v[40:41], v[40:41], v[50:51] op_sel_hi:[1,0]
	v_pk_mul_f32 v[44:45], v[44:45], v[50:51] op_sel_hi:[1,0]
	v_pk_mul_f32 v[42:43], v[42:43], v[50:51] op_sel_hi:[1,0]
	v_max_f32_e32 v40, 0, v40
	v_pk_mul_f32 v[46:47], v[46:47], v[50:51] op_sel_hi:[1,0]
	v_max_f32_e32 v44, 0, v44
	v_mul_f32_e32 v51, v40, v40
	v_max_f32_e32 v40, 0, v45
	v_max_f32_e32 v41, 0, v41
	v_max_f32_e32 v42, 0, v42
	v_mul_f32_e32 v44, v44, v44
	v_mul_f32_e32 v40, v40, v40
	v_mul_f32_e32 v45, v41, v41
	v_max_f32_e32 v41, 0, v46
	v_mul_f32_e32 v46, v42, v42
	v_max_f32_e32 v42, 0, v47
	v_mul_f32_e32 v41, v41, v41
	v_max_f32_e32 v43, 0, v43
	v_mul_f32_e32 v42, v42, v42
	v_cvt_pk_bf16_f32 v40, v44, v40
	v_add_co_u32_e32 v44, vcc, s59, v144
	v_pk_mul_f32 v[32:33], v[32:33], v[50:51] op_sel_hi:[1,0]
	v_mul_f32_e32 v43, v43, v43
	v_cvt_pk_bf16_f32 v41, v41, v42
	v_cvt_pk_bf16_f32 v42, v51, v45
	v_addc_co_u32_e32 v45, vcc, 0, v145, vcc
	v_pk_mul_f32 v[36:37], v[36:37], v[50:51] op_sel_hi:[1,0]
	v_max_f32_e32 v32, 0, v32
	v_cvt_pk_bf16_f32 v43, v46, v43
	global_store_dwordx4 v[44:45], v[40:43], off nt
	v_max_f32_e32 v36, 0, v36
	v_mul_f32_e32 v36, v36, v36
	v_mul_f32_e32 v40, v32, v32
	v_max_f32_e32 v32, 0, v37
	v_mul_f32_e32 v32, v32, v32
	v_cvt_pk_bf16_f32 v32, v36, v32
	v_mul_f32_e32 v36, 0x4b800000, v166
	v_cmp_gt_f32_e32 vcc, s57, v166
	v_pk_mul_f32 v[34:35], v[34:35], v[50:51] op_sel_hi:[1,0]
	v_pk_mul_f32 v[38:39], v[38:39], v[50:51] op_sel_hi:[1,0]
	v_cndmask_b32_e32 v36, v166, v36, vcc
	v_max_f32_e32 v33, 0, v33
	v_max_f32_e32 v34, 0, v34
	v_rsq_f32_e32 v36, v36
	v_mul_f32_e32 v37, v33, v33
	v_max_f32_e32 v33, 0, v38
	v_mul_f32_e32 v38, v34, v34
	v_max_f32_e32 v34, 0, v39
	v_mul_f32_e32 v33, v33, v33
	v_max_f32_e32 v35, 0, v35
	v_mul_f32_e32 v34, v34, v34
	v_lshl_add_u64 v[48:49], v[144:145], 0, s[18:19]
	v_mul_f32_e32 v35, v35, v35
	v_cvt_pk_bf16_f32 v33, v33, v34
	v_cvt_pk_bf16_f32 v34, v40, v37
	v_cvt_pk_bf16_f32 v35, v38, v35
	global_store_dwordx4 v[48:49], v[32:35], off offset:256 nt
	s_nop 1
	v_mul_f32_e32 v34, 0x45800000, v36
	v_cndmask_b32_e32 v34, v36, v34, vcc
	v_pk_mul_f32 v[24:25], v[24:25], v[34:35] op_sel_hi:[1,0]
	v_pk_mul_f32 v[28:29], v[28:29], v[34:35] op_sel_hi:[1,0]
	v_pk_mul_f32 v[26:27], v[26:27], v[34:35] op_sel_hi:[1,0]
	v_max_f32_e32 v24, 0, v24
	v_pk_mul_f32 v[30:31], v[30:31], v[34:35] op_sel_hi:[1,0]
	v_max_f32_e32 v28, 0, v28
	v_mul_f32_e32 v35, v24, v24
	v_max_f32_e32 v24, 0, v29
	v_max_f32_e32 v25, 0, v25
	v_max_f32_e32 v26, 0, v26
	v_mul_f32_e32 v28, v28, v28
	v_mul_f32_e32 v24, v24, v24
	v_mul_f32_e32 v29, v25, v25
	v_max_f32_e32 v25, 0, v30
	v_mul_f32_e32 v30, v26, v26
	v_max_f32_e32 v26, 0, v31
	v_mul_f32_e32 v25, v25, v25
	v_max_f32_e32 v27, 0, v27
	v_mul_f32_e32 v26, v26, v26
	v_cvt_pk_bf16_f32 v24, v28, v24
	v_add_co_u32_e32 v28, vcc, s60, v144
	v_pk_mul_f32 v[16:17], v[16:17], v[34:35] op_sel_hi:[1,0]
	v_mul_f32_e32 v27, v27, v27
	v_cvt_pk_bf16_f32 v25, v25, v26
	v_cvt_pk_bf16_f32 v26, v35, v29
	v_addc_co_u32_e32 v29, vcc, 0, v145, vcc
	v_pk_mul_f32 v[20:21], v[20:21], v[34:35] op_sel_hi:[1,0]
	v_max_f32_e32 v16, 0, v16
	v_cvt_pk_bf16_f32 v27, v30, v27
	global_store_dwordx4 v[28:29], v[24:27], off nt
	v_max_f32_e32 v20, 0, v20
	v_mul_f32_e32 v20, v20, v20
	v_mul_f32_e32 v24, v16, v16
	v_max_f32_e32 v16, 0, v21
	v_mul_f32_e32 v16, v16, v16
	v_cvt_pk_bf16_f32 v16, v20, v16
	v_mul_f32_e32 v20, 0x4b800000, v147
	v_cmp_gt_f32_e32 vcc, s57, v147
	v_pk_mul_f32 v[18:19], v[18:19], v[34:35] op_sel_hi:[1,0]
	v_pk_mul_f32 v[22:23], v[22:23], v[34:35] op_sel_hi:[1,0]
	v_cndmask_b32_e32 v20, v147, v20, vcc
	v_max_f32_e32 v17, 0, v17
	v_max_f32_e32 v18, 0, v18
	v_rsq_f32_e32 v20, v20
	v_mul_f32_e32 v21, v17, v17
	v_max_f32_e32 v17, 0, v22
	v_mul_f32_e32 v22, v18, v18
	v_max_f32_e32 v18, 0, v23
	v_mul_f32_e32 v17, v17, v17
	v_max_f32_e32 v19, 0, v19
	v_mul_f32_e32 v18, v18, v18
	v_lshl_add_u64 v[32:33], v[144:145], 0, s[20:21]
	v_mul_f32_e32 v19, v19, v19
	v_cvt_pk_bf16_f32 v17, v17, v18
	v_cvt_pk_bf16_f32 v18, v24, v21
	v_cvt_pk_bf16_f32 v19, v22, v19
	global_store_dwordx4 v[32:33], v[16:19], off offset:256 nt
	s_nop 1
	v_mul_f32_e32 v18, 0x45800000, v20
	v_cndmask_b32_e32 v18, v20, v18, vcc
	v_pk_mul_f32 v[8:9], v[8:9], v[18:19] op_sel_hi:[1,0]
	v_pk_mul_f32 v[12:13], v[12:13], v[18:19] op_sel_hi:[1,0]
	v_pk_mul_f32 v[10:11], v[10:11], v[18:19] op_sel_hi:[1,0]
	v_max_f32_e32 v8, 0, v8
	v_pk_mul_f32 v[14:15], v[14:15], v[18:19] op_sel_hi:[1,0]
	v_max_f32_e32 v12, 0, v12
	v_mul_f32_e32 v19, v8, v8
	v_max_f32_e32 v8, 0, v13
	v_max_f32_e32 v9, 0, v9
	v_max_f32_e32 v10, 0, v10
	v_mul_f32_e32 v12, v12, v12
	v_mul_f32_e32 v8, v8, v8
	v_mul_f32_e32 v13, v9, v9
	v_max_f32_e32 v9, 0, v14
	v_mul_f32_e32 v14, v10, v10
	v_max_f32_e32 v10, 0, v15
	v_mul_f32_e32 v9, v9, v9
	v_max_f32_e32 v11, 0, v11
	v_mul_f32_e32 v10, v10, v10
	v_cvt_pk_bf16_f32 v8, v12, v8
	v_add_co_u32_e32 v12, vcc, s61, v144
	v_pk_mul_f32 v[2:3], v[2:3], v[18:19] op_sel_hi:[1,0]
	v_pk_mul_f32 v[0:1], v[0:1], v[18:19] op_sel_hi:[1,0]
	v_mul_f32_e32 v11, v11, v11
	v_cvt_pk_bf16_f32 v9, v9, v10
	v_cvt_pk_bf16_f32 v10, v19, v13
	v_addc_co_u32_e32 v13, vcc, 0, v145, vcc
	v_pk_mul_f32 v[6:7], v[6:7], v[18:19] op_sel_hi:[1,0]
	v_pk_mul_f32 v[4:5], v[4:5], v[18:19] op_sel_hi:[1,0]
	v_max_f32_e32 v0, 0, v0
	v_max_f32_e32 v1, 0, v1
	v_max_f32_e32 v2, 0, v2
	v_cvt_pk_bf16_f32 v11, v14, v11
	global_store_dwordx4 v[12:13], v[8:11], off nt
	v_max_f32_e32 v3, 0, v3
	v_lshl_add_u64 v[16:17], v[144:145], 0, s[22:23]
	v_mul_f32_e32 v8, v0, v0
	v_max_f32_e32 v0, 0, v5
	v_mul_f32_e32 v5, v1, v1
	v_max_f32_e32 v1, 0, v6
	v_mul_f32_e32 v6, v2, v2
	v_max_f32_e32 v2, 0, v7
	v_max_f32_e32 v4, 0, v4
	v_mul_f32_e32 v0, v0, v0
	v_mul_f32_e32 v1, v1, v1
	v_mul_f32_e32 v2, v2, v2
	v_mul_f32_e32 v3, v3, v3
	s_and_b64 vcc, exec, s[6:7]
	v_mul_f32_e32 v4, v4, v4
	v_cvt_pk_bf16_f32 v0, v4, v0
	v_cvt_pk_bf16_f32 v1, v1, v2
	v_cvt_pk_bf16_f32 v2, v8, v5
	v_cvt_pk_bf16_f32 v3, v6, v3
	global_store_dwordx4 v[16:17], v[0:3], off offset:256 nt
	s_cbranch_vccz .LBB0_843
	s_waitcnt vmcnt(0)
	s_cmpk_gt_u32 s33, 0xff
	s_cbranch_scc1 .LBB0_854
	s_barrier

.LBB0_896:
	ds_read_b128 v[144:147], v178
	ds_read_b128 v[148:151], v178 offset:1024
	ds_read_b128 v[152:155], v178 offset:2048
	ds_read_b128 v[156:159], v178 offset:3072
	s_add_u32 s42, s40, 0xfff00080
	s_addc_u32 s43, s41, -1
	s_cmp_eq_u32 s65, 60
	s_cselect_b32 s49, s29, s43
	s_cselect_b32 s48, s37, s42
	s_cselect_b32 s43, s27, s64
	s_cselect_b32 s42, s62, s63
	v_lshl_add_u64 v[172:173], s[40:41], 0, v[136:137]
	s_add_i32 m0, s39, 0xc000
	ds_read_b128 v[160:163], v179
	ds_read_b128 v[164:167], v179 offset:1024
	ds_read_b128 v[168:171], v179 offset:2048
	ds_read_b128 v[182:185], v179 offset:3072
	ds_read_b128 v[186:189], v179 offset:4096
	ds_read_b128 v[190:193], v179 offset:5120
	ds_read_b128 v[194:197], v179 offset:6144
	ds_read_b128 v[198:201], v179 offset:7168
	global_load_lds_dwordx4 v[172:173], off
	v_lshl_add_u64 v[172:173], s[40:41], 0, v[138:139]
	s_add_i32 m0, s39, 0xe000
	s_nop 0
	global_load_lds_dwordx4 v[172:173], off
	s_waitcnt lgkmcnt(8)
	s_waitcnt lgkmcnt(0)
	s_setprio 1
	s_barrier
	v_mfma_f32_16x16x32_bf16 v[124:127], v[144:147], v[160:163], v[124:127]
	v_mfma_f32_16x16x32_bf16 v[120:123], v[152:155], v[160:163], v[120:123]
	v_mfma_f32_16x16x32_bf16 v[108:111], v[144:147], v[168:171], v[108:111]
	v_mfma_f32_16x16x32_bf16 v[104:107], v[152:155], v[168:171], v[104:107]
	v_mfma_f32_16x16x32_bf16 v[96:99], v[144:147], v[186:189], v[96:99]
	v_mfma_f32_16x16x32_bf16 v[88:91], v[152:155], v[186:189], v[88:91]
	v_mfma_f32_16x16x32_bf16 v[80:83], v[144:147], v[194:197], v[80:83]
	v_mfma_f32_16x16x32_bf16 v[72:75], v[152:155], v[194:197], v[72:75]
	v_mfma_f32_16x16x32_bf16 v[124:127], v[148:151], v[164:167], v[124:127]
	v_mfma_f32_16x16x32_bf16 v[120:123], v[156:159], v[164:167], v[120:123]
	v_mfma_f32_16x16x32_bf16 v[108:111], v[148:151], v[182:185], v[108:111]
	v_mfma_f32_16x16x32_bf16 v[104:107], v[156:159], v[182:185], v[104:107]
	v_mfma_f32_16x16x32_bf16 v[96:99], v[148:151], v[190:193], v[96:99]
	v_mfma_f32_16x16x32_bf16 v[88:91], v[156:159], v[190:193], v[88:91]
	v_mfma_f32_16x16x32_bf16 v[80:83], v[148:151], v[198:201], v[80:83]
	v_mfma_f32_16x16x32_bf16 v[72:75], v[156:159], v[198:201], v[72:75]
	s_setprio 0
	s_barrier
	s_add_i32 s66, s60, s50
	v_lshl_add_u64 v[172:173], s[42:43], 0, v[130:131]
	s_mov_b32 m0, s66
	ds_read_b128 v[202:205], v180
	ds_read_b128 v[206:209], v180 offset:1024
	ds_read_b128 v[212:215], v180 offset:2048
	ds_read_b128 v[216:219], v180 offset:3072
	global_load_lds_dwordx4 v[172:173], off
	v_lshl_add_u64 v[220:221], s[42:43], 0, v[134:135]
	s_add_i32 m0, s66, 0x2000
	s_nop 0
	global_load_lds_dwordx4 v[220:221], off
	s_waitcnt lgkmcnt(0)
	s_setprio 1
	s_barrier
	v_mfma_f32_16x16x32_bf16 v[116:119], v[202:205], v[160:163], v[116:119]
	v_mfma_f32_16x16x32_bf16 v[112:115], v[212:215], v[160:163], v[112:115]
	v_mfma_f32_16x16x32_bf16 v[100:103], v[202:205], v[168:171], v[100:103]
	v_mfma_f32_16x16x32_bf16 v[92:95], v[212:215], v[168:171], v[92:95]
	v_mfma_f32_16x16x32_bf16 v[84:87], v[202:205], v[186:189], v[84:87]
	v_mfma_f32_16x16x32_bf16 v[76:79], v[212:215], v[186:189], v[76:79]
	v_mfma_f32_16x16x32_bf16 v[68:71], v[202:205], v[194:197], v[68:71]
	v_mfma_f32_16x16x32_bf16 v[64:67], v[212:215], v[194:197], v[64:67]
	v_mfma_f32_16x16x32_bf16 v[116:119], v[206:209], v[164:167], v[116:119]
	v_mfma_f32_16x16x32_bf16 v[112:115], v[216:219], v[164:167], v[112:115]
	v_mfma_f32_16x16x32_bf16 v[100:103], v[206:209], v[182:185], v[100:103]
	v_mfma_f32_16x16x32_bf16 v[92:95], v[216:219], v[182:185], v[92:95]
	v_mfma_f32_16x16x32_bf16 v[84:87], v[206:209], v[190:193], v[84:87]
	v_mfma_f32_16x16x32_bf16 v[76:79], v[216:219], v[190:193], v[76:79]
	v_mfma_f32_16x16x32_bf16 v[68:71], v[206:209], v[198:201], v[68:71]
	v_mfma_f32_16x16x32_bf16 v[64:67], v[216:219], v[198:201], v[64:67]
	s_setprio 0
	s_mov_b32 m0, s39
	v_lshl_add_u64 v[222:223], s[48:49], 0, v[128:129]
	s_barrier
	ds_read_b128 v[160:163], v179 offset:16384
	ds_read_b128 v[164:167], v179 offset:17408
	ds_read_b128 v[168:171], v179 offset:18432
	ds_read_b128 v[182:185], v179 offset:19456
	ds_read_b128 v[186:189], v179 offset:20480
	ds_read_b128 v[190:193], v179 offset:21504
	ds_read_b128 v[194:197], v179 offset:22528
	ds_read_b128 v[198:201], v179 offset:23552
	global_load_lds_dwordx4 v[222:223], off
	v_lshl_add_u64 v[224:225], s[48:49], 0, v[132:133]
	s_mov_b32 m0, s51
	s_nop 0
	global_load_lds_dwordx4 v[224:225], off
	s_waitcnt lgkmcnt(0)
	s_setprio 1
	s_barrier
	v_mfma_f32_16x16x32_bf16 v[60:63], v[144:147], v[160:163], v[60:63]
	v_mfma_f32_16x16x32_bf16 v[56:59], v[152:155], v[160:163], v[56:59]
	v_mfma_f32_16x16x32_bf16 v[44:47], v[144:147], v[168:171], v[44:47]
	v_mfma_f32_16x16x32_bf16 v[40:43], v[152:155], v[168:171], v[40:43]
	v_mfma_f32_16x16x32_bf16 v[32:35], v[144:147], v[186:189], v[32:35]
	v_mfma_f32_16x16x32_bf16 v[24:27], v[152:155], v[186:189], v[24:27]
	v_mfma_f32_16x16x32_bf16 v[16:19], v[144:147], v[194:197], v[16:19]
	v_mfma_f32_16x16x32_bf16 v[8:11], v[152:155], v[194:197], v[8:11]
	v_mfma_f32_16x16x32_bf16 v[60:63], v[148:151], v[164:167], v[60:63]
	v_mfma_f32_16x16x32_bf16 v[56:59], v[156:159], v[164:167], v[56:59]
	v_mfma_f32_16x16x32_bf16 v[44:47], v[148:151], v[182:185], v[44:47]
	v_mfma_f32_16x16x32_bf16 v[40:43], v[156:159], v[182:185], v[40:43]
	v_mfma_f32_16x16x32_bf16 v[32:35], v[148:151], v[190:193], v[32:35]
	v_mfma_f32_16x16x32_bf16 v[24:27], v[156:159], v[190:193], v[24:27]
	v_mfma_f32_16x16x32_bf16 v[16:19], v[148:151], v[198:201], v[16:19]
	v_mfma_f32_16x16x32_bf16 v[8:11], v[156:159], v[198:201], v[8:11]
	s_setprio 0
	s_barrier
	s_add_u32 s66, s42, 0x100000
	s_addc_u32 s67, s43, 0
	s_add_i32 s68, s61, s50
	v_lshl_add_u64 v[144:145], s[66:67], 0, v[130:131]
	s_mov_b32 m0, s68
	s_nop 0
	global_load_lds_dwordx4 v[144:145], off
	v_lshl_add_u64 v[144:145], s[66:67], 0, v[134:135]
	s_add_i32 m0, s68, 0x2000
	s_nop 0
	global_load_lds_dwordx4 v[144:145], off
	s_waitcnt vmcnt(6)
	s_setprio 1
	s_barrier
	v_mfma_f32_16x16x32_bf16 v[52:55], v[202:205], v[160:163], v[52:55]
	v_mfma_f32_16x16x32_bf16 v[48:51], v[212:215], v[160:163], v[48:51]
	v_mfma_f32_16x16x32_bf16 v[36:39], v[202:205], v[168:171], v[36:39]
	v_mfma_f32_16x16x32_bf16 v[28:31], v[212:215], v[168:171], v[28:31]
	v_mfma_f32_16x16x32_bf16 v[20:23], v[202:205], v[186:189], v[20:23]
	v_mfma_f32_16x16x32_bf16 v[12:15], v[212:215], v[186:189], v[12:15]
	v_mfma_f32_16x16x32_bf16 v[4:7], v[202:205], v[194:197], v[4:7]
	v_mfma_f32_16x16x32_bf16 v[0:3], v[212:215], v[194:197], v[0:3]
	v_mfma_f32_16x16x32_bf16 v[52:55], v[206:209], v[164:167], v[52:55]
	v_mfma_f32_16x16x32_bf16 v[48:51], v[216:219], v[164:167], v[48:51]
	v_mfma_f32_16x16x32_bf16 v[36:39], v[206:209], v[182:185], v[36:39]
	v_mfma_f32_16x16x32_bf16 v[28:31], v[216:219], v[182:185], v[28:31]
	v_mfma_f32_16x16x32_bf16 v[20:23], v[206:209], v[190:193], v[20:23]
	v_mfma_f32_16x16x32_bf16 v[12:15], v[216:219], v[190:193], v[12:15]
	v_mfma_f32_16x16x32_bf16 v[4:7], v[206:209], v[198:201], v[4:7]
	v_mfma_f32_16x16x32_bf16 v[0:3], v[216:219], v[198:201], v[0:3]
	s_setprio 0
	s_add_i32 s66, 0, 0x18000
	v_add_u32_e32 v156, s66, v176
	s_barrier
	ds_read_b128 v[144:147], v156
	ds_read_b128 v[148:151], v156 offset:1024
	ds_read_b128 v[152:155], v156 offset:2048
	ds_read_b128 v[156:159], v156 offset:3072
	s_add_u32 s48, s48, 0x100000
	s_addc_u32 s49, s49, 0
	s_mov_b32 m0, s52
	v_lshl_add_u64 v[202:203], s[48:49], 0, v[128:129]
	ds_read_b128 v[160:163], v179 offset:32768
	ds_read_b128 v[164:167], v179 offset:33792
	ds_read_b128 v[168:171], v179 offset:34816
	ds_read_b128 v[182:185], v179 offset:35840
	ds_read_b128 v[186:189], v179 offset:36864
	ds_read_b128 v[190:193], v179 offset:37888
	ds_read_b128 v[194:197], v179 offset:38912
	ds_read_b128 v[198:201], v179 offset:39936
	global_load_lds_dwordx4 v[202:203], off
	v_lshl_add_u64 v[202:203], s[48:49], 0, v[132:133]
	s_mov_b32 m0, s53
	s_nop 0
	global_load_lds_dwordx4 v[202:203], off
	s_waitcnt lgkmcnt(8)
	s_waitcnt lgkmcnt(0)
	s_setprio 1
	s_barrier
	v_mfma_f32_16x16x32_bf16 v[124:127], v[144:147], v[160:163], v[124:127]
	v_mfma_f32_16x16x32_bf16 v[120:123], v[152:155], v[160:163], v[120:123]
	v_mfma_f32_16x16x32_bf16 v[108:111], v[144:147], v[168:171], v[108:111]
	v_mfma_f32_16x16x32_bf16 v[104:107], v[152:155], v[168:171], v[104:107]
	v_mfma_f32_16x16x32_bf16 v[96:99], v[144:147], v[186:189], v[96:99]
	v_mfma_f32_16x16x32_bf16 v[88:91], v[152:155], v[186:189], v[88:91]
	v_mfma_f32_16x16x32_bf16 v[80:83], v[144:147], v[194:197], v[80:83]
	v_mfma_f32_16x16x32_bf16 v[72:75], v[152:155], v[194:197], v[72:75]
	v_mfma_f32_16x16x32_bf16 v[124:127], v[148:151], v[164:167], v[124:127]
	v_mfma_f32_16x16x32_bf16 v[120:123], v[156:159], v[164:167], v[120:123]
	v_mfma_f32_16x16x32_bf16 v[108:111], v[148:151], v[182:185], v[108:111]
	v_mfma_f32_16x16x32_bf16 v[104:107], v[156:159], v[182:185], v[104:107]
	v_mfma_f32_16x16x32_bf16 v[96:99], v[148:151], v[190:193], v[96:99]
	v_mfma_f32_16x16x32_bf16 v[88:91], v[156:159], v[190:193], v[88:91]
	v_mfma_f32_16x16x32_bf16 v[80:83], v[148:151], v[198:201], v[80:83]
	v_mfma_f32_16x16x32_bf16 v[72:75], v[156:159], v[198:201], v[72:75]
	s_setprio 0
	s_barrier
	s_add_i32 s48, 0, 0x1c000
	s_add_i32 s49, s66, s50
	v_add_u32_e32 v181, s48, v176
	v_lshl_add_u64 v[172:173], v[172:173], 0, s[0:1]
	s_mov_b32 m0, s49
	ds_read_b128 v[202:205], v181
	ds_read_b128 v[206:209], v181 offset:1024
	ds_read_b128 v[212:215], v181 offset:2048
	ds_read_b128 v[216:219], v181 offset:3072
	global_load_lds_dwordx4 v[172:173], off
	v_lshl_add_u64 v[172:173], v[220:221], 0, s[0:1]
	s_add_i32 m0, s49, 0x2000
	s_nop 0
	global_load_lds_dwordx4 v[172:173], off
	s_waitcnt lgkmcnt(0)
	s_setprio 1
	s_barrier
	v_mfma_f32_16x16x32_bf16 v[116:119], v[202:205], v[160:163], v[116:119]
	v_mfma_f32_16x16x32_bf16 v[112:115], v[212:215], v[160:163], v[112:115]
	v_mfma_f32_16x16x32_bf16 v[100:103], v[202:205], v[168:171], v[100:103]
	v_mfma_f32_16x16x32_bf16 v[92:95], v[212:215], v[168:171], v[92:95]
	v_mfma_f32_16x16x32_bf16 v[84:87], v[202:205], v[186:189], v[84:87]
	v_mfma_f32_16x16x32_bf16 v[76:79], v[212:215], v[186:189], v[76:79]
	v_mfma_f32_16x16x32_bf16 v[68:71], v[202:205], v[194:197], v[68:71]
	v_mfma_f32_16x16x32_bf16 v[64:67], v[212:215], v[194:197], v[64:67]
	v_mfma_f32_16x16x32_bf16 v[116:119], v[206:209], v[164:167], v[116:119]
	v_mfma_f32_16x16x32_bf16 v[112:115], v[216:219], v[164:167], v[112:115]
	v_mfma_f32_16x16x32_bf16 v[100:103], v[206:209], v[182:185], v[100:103]
	v_mfma_f32_16x16x32_bf16 v[92:95], v[216:219], v[182:185], v[92:95]
	v_mfma_f32_16x16x32_bf16 v[84:87], v[206:209], v[190:193], v[84:87]
	v_mfma_f32_16x16x32_bf16 v[76:79], v[216:219], v[190:193], v[76:79]
	v_mfma_f32_16x16x32_bf16 v[68:71], v[206:209], v[198:201], v[68:71]
	v_mfma_f32_16x16x32_bf16 v[64:67], v[216:219], v[198:201], v[64:67]
	s_setprio 0
	s_mov_b32 m0, s55
	v_lshl_add_u64 v[172:173], v[222:223], 0, s[0:1]
	s_barrier
	ds_read_b128 v[160:163], v179 offset:49152
	ds_read_b128 v[164:167], v179 offset:50176
	ds_read_b128 v[168:171], v179 offset:51200
	ds_read_b128 v[182:185], v179 offset:52224
	ds_read_b128 v[186:189], v179 offset:53248
	ds_read_b128 v[190:193], v179 offset:54272
	ds_read_b128 v[194:197], v179 offset:55296
	ds_read_b128 v[198:201], v179 offset:56320
	global_load_lds_dwordx4 v[172:173], off
	v_lshl_add_u64 v[172:173], v[224:225], 0, s[0:1]
	s_mov_b32 m0, s56
	s_nop 0
	global_load_lds_dwordx4 v[172:173], off
	s_waitcnt lgkmcnt(0)
	s_setprio 1
	s_barrier
	v_mfma_f32_16x16x32_bf16 v[60:63], v[144:147], v[160:163], v[60:63]
	v_mfma_f32_16x16x32_bf16 v[56:59], v[152:155], v[160:163], v[56:59]
	v_mfma_f32_16x16x32_bf16 v[44:47], v[144:147], v[168:171], v[44:47]
	v_mfma_f32_16x16x32_bf16 v[40:43], v[152:155], v[168:171], v[40:43]
	v_mfma_f32_16x16x32_bf16 v[32:35], v[144:147], v[186:189], v[32:35]
	v_mfma_f32_16x16x32_bf16 v[24:27], v[152:155], v[186:189], v[24:27]
	v_mfma_f32_16x16x32_bf16 v[16:19], v[144:147], v[194:197], v[16:19]
	v_mfma_f32_16x16x32_bf16 v[8:11], v[152:155], v[194:197], v[8:11]
	v_mfma_f32_16x16x32_bf16 v[60:63], v[148:151], v[164:167], v[60:63]
	v_mfma_f32_16x16x32_bf16 v[56:59], v[156:159], v[164:167], v[56:59]
	v_mfma_f32_16x16x32_bf16 v[44:47], v[148:151], v[182:185], v[44:47]
	v_mfma_f32_16x16x32_bf16 v[40:43], v[156:159], v[182:185], v[40:43]
	v_mfma_f32_16x16x32_bf16 v[32:35], v[148:151], v[190:193], v[32:35]
	v_mfma_f32_16x16x32_bf16 v[24:27], v[156:159], v[190:193], v[24:27]
	v_mfma_f32_16x16x32_bf16 v[16:19], v[148:151], v[198:201], v[16:19]
	v_mfma_f32_16x16x32_bf16 v[8:11], v[156:159], v[198:201], v[8:11]
	s_setprio 0
	s_barrier
	s_add_u32 s42, s42, 0x100080
	s_addc_u32 s43, s43, 0
	s_add_i32 s48, s48, s50
	v_lshl_add_u64 v[144:145], s[42:43], 0, v[130:131]
	s_mov_b32 m0, s48
	s_nop 0
	global_load_lds_dwordx4 v[144:145], off
	v_lshl_add_u64 v[144:145], s[42:43], 0, v[134:135]
	s_add_i32 m0, s48, 0x2000
	s_nop 0
	global_load_lds_dwordx4 v[144:145], off
	s_waitcnt vmcnt(6)
	s_setprio 1
	s_barrier
	v_mfma_f32_16x16x32_bf16 v[52:55], v[202:205], v[160:163], v[52:55]
	v_mfma_f32_16x16x32_bf16 v[48:51], v[212:215], v[160:163], v[48:51]
	v_mfma_f32_16x16x32_bf16 v[36:39], v[202:205], v[168:171], v[36:39]
	v_mfma_f32_16x16x32_bf16 v[28:31], v[212:215], v[168:171], v[28:31]
	v_mfma_f32_16x16x32_bf16 v[20:23], v[202:205], v[186:189], v[20:23]
	v_mfma_f32_16x16x32_bf16 v[12:15], v[212:215], v[186:189], v[12:15]
	v_mfma_f32_16x16x32_bf16 v[4:7], v[202:205], v[194:197], v[4:7]
	v_mfma_f32_16x16x32_bf16 v[0:3], v[212:215], v[194:197], v[0:3]
	v_mfma_f32_16x16x32_bf16 v[52:55], v[206:209], v[164:167], v[52:55]
	v_mfma_f32_16x16x32_bf16 v[48:51], v[216:219], v[164:167], v[48:51]
	v_mfma_f32_16x16x32_bf16 v[36:39], v[206:209], v[182:185], v[36:39]
	v_mfma_f32_16x16x32_bf16 v[28:31], v[216:219], v[182:185], v[28:31]
	v_mfma_f32_16x16x32_bf16 v[20:23], v[206:209], v[190:193], v[20:23]
	v_mfma_f32_16x16x32_bf16 v[12:15], v[216:219], v[190:193], v[12:15]
	v_mfma_f32_16x16x32_bf16 v[4:7], v[206:209], v[198:201], v[4:7]
	v_mfma_f32_16x16x32_bf16 v[0:3], v[216:219], v[198:201], v[0:3]
	s_setprio 0
	s_add_i32 s65, s65, 2
	s_add_u32 s40, s40, 0x100
	s_addc_u32 s41, s41, 0
	s_add_u32 s63, s63, 0x100
	s_addc_u32 s64, s64, 0
	s_cmp_gt_u32 s65, 61
	s_barrier
	s_cbranch_scc0 .LBB0_896
	v_lshl_or_b32 v144, s38, 8, v177
	v_lshl_add_u32 v150, s36, 8, v175
	v_ashrrev_i32_e32 v145, 31, v144
	v_ashrrev_i32_e32 v151, 31, v150
	v_lshlrev_b64 v[144:145], 1, v[144:145]
	v_lshl_add_u64 v[146:147], s[90:91], 0, v[144:145]
	v_lshlrev_b64 v[148:149], 11, v[150:151]
	v_lshl_add_u64 v[152:153], v[146:147], 0, v[148:149]
	global_load_dwordx4 v[156:159], v[152:153], off
	global_load_dwordx4 v[160:163], v[152:153], off offset:256
	v_or_b32_e32 v152, 16, v150
	v_ashrrev_i32_e32 v153, 31, v152
	v_lshlrev_b64 v[170:171], 11, v[152:153]
	v_lshl_add_u64 v[152:153], v[146:147], 0, v[170:171]
	global_load_dwordx4 v[164:167], v[152:153], off
	global_load_dwordx4 v[182:185], v[152:153], off offset:256
	v_or_b32_e32 v152, 32, v150
	v_ashrrev_i32_e32 v153, 31, v152
	v_lshlrev_b64 v[154:155], 11, v[152:153]
	v_lshl_add_u64 v[152:153], v[146:147], 0, v[154:155]
	global_load_dwordx4 v[186:189], v[152:153], off
	global_load_dwordx4 v[190:193], v[152:153], off offset:256
	v_or_b32_e32 v152, 48, v150
	v_ashrrev_i32_e32 v153, 31, v152
	v_lshlrev_b64 v[152:153], 11, v[152:153]
	v_lshl_add_u64 v[168:169], v[146:147], 0, v[152:153]
	global_load_dwordx4 v[194:197], v[168:169], off
	global_load_dwordx4 v[198:201], v[168:169], off offset:256
	s_waitcnt vmcnt(0)
	v_lshlrev_b32_e32 v202, 16, v156
	v_and_b32_e32 v203, 0xffff0000, v156
	v_lshlrev_b32_e32 v204, 16, v157
	v_and_b32_e32 v205, 0xffff0000, v157
	v_lshlrev_b32_e32 v206, 16, v158
	v_and_b32_e32 v207, 0xffff0000, v158
	v_lshlrev_b32_e32 v208, 16, v159
	v_and_b32_e32 v209, 0xffff0000, v159
	v_pk_add_f32 v[126:127], v[126:127], v[204:205]
	v_pk_add_f32 v[124:125], v[124:125], v[202:203]
	v_lshlrev_b32_e32 v224, 16, v166
	v_and_b32_e32 v225, 0xffff0000, v166
	v_lshlrev_b32_e32 v226, 16, v167
	v_and_b32_e32 v227, 0xffff0000, v167
	v_lshlrev_b32_e32 v212, 16, v160
	v_lshlrev_b32_e32 v166, 16, v194
	v_and_b32_e32 v167, 0xffff0000, v194
	v_lshlrev_b32_e32 v172, 16, v195
	v_and_b32_e32 v173, 0xffff0000, v195
	v_pk_add_f32 v[194:195], v[122:123], v[208:209]
	v_pk_add_f32 v[122:123], v[120:121], v[206:207]
	v_mul_f32_e32 v120, v125, v125
	v_mul_f32_e32 v121, v127, v127
	v_fmac_f32_e32 v120, v124, v124
	v_fmac_f32_e32 v121, v126, v126
	v_add_f32_e32 v120, v120, v121
	v_mul_f32_e32 v121, v123, v123
	v_fmac_f32_e32 v121, v122, v122
	v_add_f32_e32 v120, v121, v120
	v_mul_f32_e32 v121, v195, v195
	v_fmac_f32_e32 v121, v194, v194
	v_and_b32_e32 v213, 0xffff0000, v160
	v_lshlrev_b32_e32 v214, 16, v161
	v_and_b32_e32 v215, 0xffff0000, v161
	v_add_f32_e32 v181, v121, v120
	v_cvt_pk_bf16_f32 v120, v124, v125
	v_lshl_add_u64 v[124:125], s[10:11], 0, v[148:149]
	v_lshlrev_b32_e32 v216, 16, v162
	v_and_b32_e32 v217, 0xffff0000, v162
	v_lshlrev_b32_e32 v218, 16, v163
	v_and_b32_e32 v219, 0xffff0000, v163
	v_cvt_pk_bf16_f32 v121, v126, v127
	v_lshl_add_u64 v[124:125], v[124:125], 0, v[144:145]
	v_pk_add_f32 v[118:119], v[118:119], v[214:215]
	v_pk_add_f32 v[116:117], v[116:117], v[212:213]
	v_cvt_pk_bf16_f32 v122, v122, v123
	v_cvt_pk_bf16_f32 v123, v194, v195
	global_store_dwordx4 v[124:125], v[120:123], off
	v_lshlrev_b32_e32 v220, 16, v164
	v_and_b32_e32 v221, 0xffff0000, v164
	v_pk_add_f32 v[120:121], v[114:115], v[218:219]
	v_pk_add_f32 v[114:115], v[112:113], v[216:217]
	v_mul_f32_e32 v112, v117, v117
	v_mul_f32_e32 v113, v119, v119
	v_fmac_f32_e32 v112, v116, v116
	v_fmac_f32_e32 v113, v118, v118
	v_add_f32_e32 v112, v112, v113
	v_mul_f32_e32 v113, v115, v115
	v_fmac_f32_e32 v113, v114, v114
	v_add_f32_e32 v112, v113, v112
	v_mul_f32_e32 v113, v121, v121
	v_fmac_f32_e32 v113, v120, v120
	v_add_f32_e32 v112, v113, v112
	v_lshlrev_b32_e32 v222, 16, v165
	v_and_b32_e32 v223, 0xffff0000, v165
	v_add_f32_e32 v126, v181, v112
	v_cvt_pk_bf16_f32 v112, v116, v117
	v_cvt_pk_bf16_f32 v113, v118, v119
	v_lshl_add_u64 v[116:117], s[10:11], 0, v[170:171]
	v_lshlrev_b32_e32 v230, 16, v184
	v_and_b32_e32 v231, 0xffff0000, v184
	v_lshlrev_b32_e32 v232, 16, v186
	v_and_b32_e32 v233, 0xffff0000, v186
	v_lshlrev_b32_e32 v186, 16, v187
	v_and_b32_e32 v187, 0xffff0000, v187
	v_cvt_pk_bf16_f32 v114, v114, v115
	v_cvt_pk_bf16_f32 v115, v120, v121
	global_store_dwordx4 v[124:125], v[112:115], off offset:256
	v_pk_add_f32 v[110:111], v[110:111], v[222:223]
	v_pk_add_f32 v[108:109], v[108:109], v[220:221]
	v_lshl_add_u64 v[118:119], v[116:117], 0, v[144:145]
	v_cvt_pk_bf16_f32 v112, v108, v109
	v_cvt_pk_bf16_f32 v113, v110, v111
	v_lshlrev_b32_e32 v228, 16, v182
	v_and_b32_e32 v229, 0xffff0000, v182
	v_lshlrev_b32_e32 v182, 16, v183
	v_and_b32_e32 v183, 0xffff0000, v183
	v_lshlrev_b32_e32 v184, 16, v185
	v_and_b32_e32 v185, 0xffff0000, v185
	v_lshlrev_b32_e32 v238, 16, v192
	v_and_b32_e32 v239, 0xffff0000, v192
	v_pk_add_f32 v[106:107], v[106:107], v[226:227]
	v_pk_add_f32 v[104:105], v[104:105], v[224:225]
	v_lshlrev_b32_e32 v156, 16, v200
	v_cvt_pk_bf16_f32 v114, v104, v105
	v_cvt_pk_bf16_f32 v115, v106, v107
	global_store_dwordx4 v[118:119], v[112:115], off
	v_and_b32_e32 v157, 0xffff0000, v200
	v_pk_add_f32 v[102:103], v[102:103], v[182:183]
	v_pk_add_f32 v[112:113], v[92:93], v[230:231]
	v_pk_add_f32 v[92:93], v[98:99], v[186:187]
	v_lshl_add_u64 v[98:99], s[10:11], 0, v[154:155]
	v_pk_add_f32 v[100:101], v[100:101], v[228:229]
	v_pk_add_f32 v[94:95], v[94:95], v[184:185]
	v_cvt_pk_bf16_f32 v114, v100, v101
	v_cvt_pk_bf16_f32 v115, v102, v103
	v_cvt_pk_bf16_f32 v116, v112, v113
	v_lshlrev_b32_e32 v234, 16, v188
	v_cvt_pk_bf16_f32 v117, v94, v95
	global_store_dwordx4 v[118:119], v[114:117], off offset:256
	v_lshl_add_u64 v[118:119], v[98:99], 0, v[144:145]
	v_pk_add_f32 v[98:99], v[76:77], v[238:239]
	v_pk_add_f32 v[76:77], v[82:83], v[172:173]
	v_lshl_add_u64 v[82:83], s[10:11], 0, v[152:153]
	v_lshl_add_u64 v[122:123], v[82:83], 0, v[144:145]
	v_pk_add_f32 v[82:83], v[64:65], v[156:157]
	v_and_b32_e32 v65, 64, v174
	v_and_b32_e32 v235, 0xffff0000, v188
	v_lshlrev_b32_e32 v188, 16, v189
	v_and_b32_e32 v189, 0xffff0000, v189
	v_lshlrev_b32_e32 v236, 16, v190
	v_and_b32_e32 v237, 0xffff0000, v190
	v_pk_add_f32 v[96:97], v[96:97], v[232:233]
	v_xor_b32_e32 v64, 16, v174
	v_cvt_pk_bf16_f32 v114, v96, v97
	v_add_u32_e32 v65, 64, v65
	v_lshlrev_b32_e32 v190, 16, v191
	v_and_b32_e32 v191, 0xffff0000, v191
	v_lshlrev_b32_e32 v192, 16, v193
	v_and_b32_e32 v193, 0xffff0000, v193
	v_pk_add_f32 v[90:91], v[90:91], v[188:189]
	v_pk_add_f32 v[88:89], v[88:89], v[234:235]
	v_cvt_pk_bf16_f32 v115, v92, v93
	v_pk_add_f32 v[84:85], v[84:85], v[236:237]
	v_cvt_pk_bf16_f32 v116, v88, v89
	v_cvt_pk_bf16_f32 v117, v90, v91
	global_store_dwordx4 v[118:119], v[114:117], off
	v_cmp_lt_i32_e32 vcc, v64, v65
	v_lshlrev_b32_e32 v164, 16, v196
	v_cvt_pk_bf16_f32 v114, v84, v85
	v_and_b32_e32 v165, 0xffff0000, v196
	v_lshlrev_b32_e32 v168, 16, v197
	v_and_b32_e32 v169, 0xffff0000, v197
	v_pk_add_f32 v[86:87], v[86:87], v[190:191]
	v_pk_add_f32 v[78:79], v[78:79], v[192:193]
	v_cvt_pk_bf16_f32 v115, v86, v87
	v_cvt_pk_bf16_f32 v116, v98, v99
	v_pk_add_f32 v[80:81], v[80:81], v[166:167]
	v_cvt_pk_bf16_f32 v117, v78, v79
	global_store_dwordx4 v[118:119], v[114:117], off offset:256
	v_cndmask_b32_e32 v64, v174, v64, vcc
	v_pk_add_f32 v[74:75], v[74:75], v[168:169]
	v_cvt_pk_bf16_f32 v114, v80, v81
	v_pk_add_f32 v[72:73], v[72:73], v[164:165]
	v_cvt_pk_bf16_f32 v115, v76, v77
	v_lshlrev_b32_e32 v158, 16, v198
	v_cvt_pk_bf16_f32 v116, v72, v73
	v_cvt_pk_bf16_f32 v117, v74, v75
	global_store_dwordx4 v[122:123], v[114:117], off
	v_and_b32_e32 v159, 0xffff0000, v198
	v_lshlrev_b32_e32 v162, 16, v199
	v_lshlrev_b32_e32 v114, 2, v64
	ds_bpermute_b32 v64, v114, v126
	v_xor_b32_e32 v115, 32, v174
	v_cmp_lt_i32_e32 vcc, v115, v65
	v_and_b32_e32 v163, 0xffff0000, v199
	v_lshlrev_b32_e32 v160, 16, v201
	v_cndmask_b32_e32 v65, v174, v115, vcc
	v_lshlrev_b32_e32 v115, 2, v65
	s_waitcnt lgkmcnt(0)
	v_add_f32_e32 v116, v126, v64
	ds_bpermute_b32 v117, v115, v116
	v_and_b32_e32 v161, 0xffff0000, v201
	v_pk_add_f32 v[70:71], v[70:71], v[162:163]
	v_pk_add_f32 v[68:69], v[68:69], v[158:159]
	v_pk_add_f32 v[66:67], v[66:67], v[160:161]
	v_lshl_add_u64 v[64:65], v[150:151], 2, s[18:19]
	v_cvt_pk_bf16_f32 v118, v68, v69
	v_cvt_pk_bf16_f32 v119, v70, v71
	v_cvt_pk_bf16_f32 v120, v82, v83
	v_cvt_pk_bf16_f32 v121, v66, v67
	global_store_dwordx4 v[122:123], v[118:121], off offset:256
	s_and_saveexec_b64 s[36:37], s[6:7]
	s_cbranch_execz .LBB0_899
	s_waitcnt lgkmcnt(0)
	v_add_f32_e32 v116, v116, v117
	global_atomic_add_f32 v[64:65], v116, off

.LBB0_946:
	ds_read_b128 v[144:147], v153
	ds_read_b128 v[158:161], v153 offset:1024
	ds_read_b128 v[162:165], v153 offset:2048
	ds_read_b128 v[166:169], v153 offset:3072
	s_add_u32 s28, s2, 0xfffc0080
	s_addc_u32 s29, s3, -1
	s_cmp_eq_u32 s58, 12
	s_cselect_b32 s31, s23, s29
	s_cselect_b32 s30, s54, s28
	s_cselect_b32 s29, s21, s57
	s_cselect_b32 s28, s55, s56
	v_lshl_add_u64 v[148:149], s[2:3], 0, v[136:137]
	s_add_i32 m0, s37, 0xc000
	ds_read_b128 v[170:173], v154
	ds_read_b128 v[176:179], v154 offset:1024
	ds_read_b128 v[180:183], v154 offset:2048
	ds_read_b128 v[184:187], v154 offset:3072
	ds_read_b128 v[188:191], v154 offset:4096
	ds_read_b128 v[192:195], v154 offset:5120
	ds_read_b128 v[196:199], v154 offset:6144
	ds_read_b128 v[200:203], v154 offset:7168
	global_load_lds_dwordx4 v[148:149], off
	v_lshl_add_u64 v[148:149], s[2:3], 0, v[138:139]
	s_add_i32 m0, s37, 0xe000
	s_nop 0
	global_load_lds_dwordx4 v[148:149], off
	s_waitcnt lgkmcnt(8)
	s_waitcnt lgkmcnt(0)
	s_setprio 1
	s_barrier
	v_mfma_f32_16x16x32_bf16 v[124:127], v[144:147], v[170:173], v[124:127]
	v_mfma_f32_16x16x32_bf16 v[120:123], v[162:165], v[170:173], v[120:123]
	v_mfma_f32_16x16x32_bf16 v[116:119], v[144:147], v[180:183], v[116:119]
	v_mfma_f32_16x16x32_bf16 v[112:115], v[162:165], v[180:183], v[112:115]
	v_mfma_f32_16x16x32_bf16 v[104:107], v[144:147], v[188:191], v[104:107]
	v_mfma_f32_16x16x32_bf16 v[96:99], v[162:165], v[188:191], v[96:99]
	v_mfma_f32_16x16x32_bf16 v[76:79], v[144:147], v[196:199], v[76:79]
	v_mfma_f32_16x16x32_bf16 v[72:75], v[162:165], v[196:199], v[72:75]
	v_mfma_f32_16x16x32_bf16 v[124:127], v[158:161], v[176:179], v[124:127]
	v_mfma_f32_16x16x32_bf16 v[120:123], v[166:169], v[176:179], v[120:123]
	v_mfma_f32_16x16x32_bf16 v[116:119], v[158:161], v[184:187], v[116:119]
	v_mfma_f32_16x16x32_bf16 v[112:115], v[166:169], v[184:187], v[112:115]
	v_mfma_f32_16x16x32_bf16 v[104:107], v[158:161], v[192:195], v[104:107]
	v_mfma_f32_16x16x32_bf16 v[96:99], v[166:169], v[192:195], v[96:99]
	v_mfma_f32_16x16x32_bf16 v[76:79], v[158:161], v[200:203], v[76:79]
	v_mfma_f32_16x16x32_bf16 v[72:75], v[166:169], v[200:203], v[72:75]
	s_setprio 0
	s_barrier
	s_add_i32 s59, s50, s34
	v_lshl_add_u64 v[148:149], s[28:29], 0, v[132:133]
	s_mov_b32 m0, s59
	ds_read_b128 v[204:207], v155
	ds_read_b128 v[212:215], v155 offset:1024
	ds_read_b128 v[216:219], v155 offset:2048
	ds_read_b128 v[220:223], v155 offset:3072
	global_load_lds_dwordx4 v[148:149], off
	v_lshl_add_u64 v[208:209], s[28:29], 0, v[128:129]
	s_add_i32 m0, s59, 0x2000
	s_nop 0
	global_load_lds_dwordx4 v[208:209], off
	s_waitcnt lgkmcnt(0)
	s_setprio 1
	s_barrier
	v_mfma_f32_16x16x32_bf16 v[108:111], v[204:207], v[170:173], v[108:111]
	v_mfma_f32_16x16x32_bf16 v[100:103], v[216:219], v[170:173], v[100:103]
	v_mfma_f32_16x16x32_bf16 v[92:95], v[204:207], v[180:183], v[92:95]
	v_mfma_f32_16x16x32_bf16 v[88:91], v[216:219], v[180:183], v[88:91]
	v_mfma_f32_16x16x32_bf16 v[84:87], v[204:207], v[188:191], v[84:87]
	v_mfma_f32_16x16x32_bf16 v[80:83], v[216:219], v[188:191], v[80:83]
	v_mfma_f32_16x16x32_bf16 v[68:71], v[204:207], v[196:199], v[68:71]
	v_mfma_f32_16x16x32_bf16 v[64:67], v[216:219], v[196:199], v[64:67]
	v_mfma_f32_16x16x32_bf16 v[108:111], v[212:215], v[176:179], v[108:111]
	v_mfma_f32_16x16x32_bf16 v[100:103], v[220:223], v[176:179], v[100:103]
	v_mfma_f32_16x16x32_bf16 v[92:95], v[212:215], v[184:187], v[92:95]
	v_mfma_f32_16x16x32_bf16 v[88:91], v[220:223], v[184:187], v[88:91]
	v_mfma_f32_16x16x32_bf16 v[84:87], v[212:215], v[192:195], v[84:87]
	v_mfma_f32_16x16x32_bf16 v[80:83], v[220:223], v[192:195], v[80:83]
	v_mfma_f32_16x16x32_bf16 v[68:71], v[212:215], v[200:203], v[68:71]
	v_mfma_f32_16x16x32_bf16 v[64:67], v[220:223], v[200:203], v[64:67]
	s_setprio 0
	s_mov_b32 m0, s37
	v_lshl_add_u64 v[224:225], s[30:31], 0, v[134:135]
	s_barrier
	ds_read_b128 v[170:173], v154 offset:16384
	ds_read_b128 v[176:179], v154 offset:17408
	ds_read_b128 v[180:183], v154 offset:18432
	ds_read_b128 v[184:187], v154 offset:19456
	ds_read_b128 v[188:191], v154 offset:20480
	ds_read_b128 v[192:195], v154 offset:21504
	ds_read_b128 v[196:199], v154 offset:22528
	ds_read_b128 v[200:203], v154 offset:23552
	global_load_lds_dwordx4 v[224:225], off
	v_lshl_add_u64 v[226:227], s[30:31], 0, v[130:131]
	s_mov_b32 m0, s38
	s_nop 0
	global_load_lds_dwordx4 v[226:227], off
	s_waitcnt lgkmcnt(0)
	s_setprio 1
	s_barrier
	v_mfma_f32_16x16x32_bf16 v[60:63], v[144:147], v[170:173], v[60:63]
	v_mfma_f32_16x16x32_bf16 v[56:59], v[162:165], v[170:173], v[56:59]
	v_mfma_f32_16x16x32_bf16 v[44:47], v[144:147], v[180:183], v[44:47]
	v_mfma_f32_16x16x32_bf16 v[40:43], v[162:165], v[180:183], v[40:43]
	v_mfma_f32_16x16x32_bf16 v[28:31], v[144:147], v[188:191], v[28:31]
	v_mfma_f32_16x16x32_bf16 v[24:27], v[162:165], v[188:191], v[24:27]
	v_mfma_f32_16x16x32_bf16 v[12:15], v[144:147], v[196:199], v[12:15]
	v_mfma_f32_16x16x32_bf16 v[8:11], v[162:165], v[196:199], v[8:11]
	v_mfma_f32_16x16x32_bf16 v[60:63], v[158:161], v[176:179], v[60:63]
	v_mfma_f32_16x16x32_bf16 v[56:59], v[166:169], v[176:179], v[56:59]
	v_mfma_f32_16x16x32_bf16 v[44:47], v[158:161], v[184:187], v[44:47]
	v_mfma_f32_16x16x32_bf16 v[40:43], v[166:169], v[184:187], v[40:43]
	v_mfma_f32_16x16x32_bf16 v[28:31], v[158:161], v[192:195], v[28:31]
	v_mfma_f32_16x16x32_bf16 v[24:27], v[166:169], v[192:195], v[24:27]
	v_mfma_f32_16x16x32_bf16 v[12:15], v[158:161], v[200:203], v[12:15]
	v_mfma_f32_16x16x32_bf16 v[8:11], v[166:169], v[200:203], v[8:11]
	s_setprio 0
	s_barrier
	s_add_u32 s60, s28, 0x40000
	s_addc_u32 s61, s29, 0
	s_add_i32 s59, s51, s34
	v_lshl_add_u64 v[144:145], s[60:61], 0, v[132:133]
	s_mov_b32 m0, s59
	s_nop 0
	global_load_lds_dwordx4 v[144:145], off
	v_lshl_add_u64 v[144:145], s[60:61], 0, v[128:129]
	s_add_i32 m0, s59, 0x2000
	s_nop 0
	global_load_lds_dwordx4 v[144:145], off
	s_waitcnt vmcnt(6)
	s_setprio 1
	s_barrier
	v_mfma_f32_16x16x32_bf16 v[52:55], v[204:207], v[170:173], v[52:55]
	v_mfma_f32_16x16x32_bf16 v[48:51], v[216:219], v[170:173], v[48:51]
	v_mfma_f32_16x16x32_bf16 v[36:39], v[204:207], v[180:183], v[36:39]
	v_mfma_f32_16x16x32_bf16 v[32:35], v[216:219], v[180:183], v[32:35]
	v_mfma_f32_16x16x32_bf16 v[20:23], v[204:207], v[188:191], v[20:23]
	v_mfma_f32_16x16x32_bf16 v[16:19], v[216:219], v[188:191], v[16:19]
	v_mfma_f32_16x16x32_bf16 v[4:7], v[204:207], v[196:199], v[4:7]
	v_mfma_f32_16x16x32_bf16 v[0:3], v[216:219], v[196:199], v[0:3]
	v_mfma_f32_16x16x32_bf16 v[52:55], v[212:215], v[176:179], v[52:55]
	v_mfma_f32_16x16x32_bf16 v[48:51], v[220:223], v[176:179], v[48:51]
	v_mfma_f32_16x16x32_bf16 v[36:39], v[212:215], v[184:187], v[36:39]
	v_mfma_f32_16x16x32_bf16 v[32:35], v[220:223], v[184:187], v[32:35]
	v_mfma_f32_16x16x32_bf16 v[20:23], v[212:215], v[192:195], v[20:23]
	v_mfma_f32_16x16x32_bf16 v[16:19], v[220:223], v[192:195], v[16:19]
	v_mfma_f32_16x16x32_bf16 v[4:7], v[212:215], v[200:203], v[4:7]
	v_mfma_f32_16x16x32_bf16 v[0:3], v[220:223], v[200:203], v[0:3]
	s_setprio 0
	s_add_i32 s59, 0, 0x18000
	v_add_u32_e32 v157, s59, v151
	s_barrier
	ds_read_b128 v[144:147], v157
	ds_read_b128 v[158:161], v157 offset:1024
	ds_read_b128 v[162:165], v157 offset:2048
	ds_read_b128 v[166:169], v157 offset:3072
	s_add_u32 s30, s30, 0x40000
	s_addc_u32 s31, s31, 0
	s_mov_b32 m0, s39
	v_lshl_add_u64 v[204:205], s[30:31], 0, v[134:135]
	ds_read_b128 v[170:173], v154 offset:32768
	ds_read_b128 v[176:179], v154 offset:33792
	ds_read_b128 v[180:183], v154 offset:34816
	ds_read_b128 v[184:187], v154 offset:35840
	ds_read_b128 v[188:191], v154 offset:36864
	ds_read_b128 v[192:195], v154 offset:37888
	ds_read_b128 v[196:199], v154 offset:38912
	ds_read_b128 v[200:203], v154 offset:39936
	global_load_lds_dwordx4 v[204:205], off
	v_lshl_add_u64 v[204:205], s[30:31], 0, v[130:131]
	s_mov_b32 m0, s40
	s_nop 0
	global_load_lds_dwordx4 v[204:205], off
	s_waitcnt lgkmcnt(8)
	s_waitcnt lgkmcnt(0)
	s_setprio 1
	s_barrier
	v_mfma_f32_16x16x32_bf16 v[124:127], v[144:147], v[170:173], v[124:127]
	v_mfma_f32_16x16x32_bf16 v[120:123], v[162:165], v[170:173], v[120:123]
	v_mfma_f32_16x16x32_bf16 v[116:119], v[144:147], v[180:183], v[116:119]
	v_mfma_f32_16x16x32_bf16 v[112:115], v[162:165], v[180:183], v[112:115]
	v_mfma_f32_16x16x32_bf16 v[104:107], v[144:147], v[188:191], v[104:107]
	v_mfma_f32_16x16x32_bf16 v[96:99], v[162:165], v[188:191], v[96:99]
	v_mfma_f32_16x16x32_bf16 v[76:79], v[144:147], v[196:199], v[76:79]
	v_mfma_f32_16x16x32_bf16 v[72:75], v[162:165], v[196:199], v[72:75]
	v_mfma_f32_16x16x32_bf16 v[124:127], v[158:161], v[176:179], v[124:127]
	v_mfma_f32_16x16x32_bf16 v[120:123], v[166:169], v[176:179], v[120:123]
	v_mfma_f32_16x16x32_bf16 v[116:119], v[158:161], v[184:187], v[116:119]
	v_mfma_f32_16x16x32_bf16 v[112:115], v[166:169], v[184:187], v[112:115]
	v_mfma_f32_16x16x32_bf16 v[104:107], v[158:161], v[192:195], v[104:107]
	v_mfma_f32_16x16x32_bf16 v[96:99], v[166:169], v[192:195], v[96:99]
	v_mfma_f32_16x16x32_bf16 v[76:79], v[158:161], v[200:203], v[76:79]
	v_mfma_f32_16x16x32_bf16 v[72:75], v[166:169], v[200:203], v[72:75]
	s_setprio 0
	s_barrier
	s_add_i32 s30, 0, 0x1c000
	s_add_i32 s31, s59, s34
	v_add_u32_e32 v157, s30, v151
	v_lshl_add_u64 v[148:149], v[148:149], 0, s[8:9]
	s_mov_b32 m0, s31
	ds_read_b128 v[204:207], v157
	ds_read_b128 v[212:215], v157 offset:1024
	ds_read_b128 v[216:219], v157 offset:2048
	ds_read_b128 v[220:223], v157 offset:3072
	global_load_lds_dwordx4 v[148:149], off
	v_lshl_add_u64 v[148:149], v[208:209], 0, s[8:9]
	s_add_i32 m0, s31, 0x2000
	s_nop 0
	global_load_lds_dwordx4 v[148:149], off
	s_waitcnt lgkmcnt(0)
	s_setprio 1
	s_barrier
	v_mfma_f32_16x16x32_bf16 v[108:111], v[204:207], v[170:173], v[108:111]
	v_mfma_f32_16x16x32_bf16 v[100:103], v[216:219], v[170:173], v[100:103]
	v_mfma_f32_16x16x32_bf16 v[92:95], v[204:207], v[180:183], v[92:95]
	v_mfma_f32_16x16x32_bf16 v[88:91], v[216:219], v[180:183], v[88:91]
	v_mfma_f32_16x16x32_bf16 v[84:87], v[204:207], v[188:191], v[84:87]
	v_mfma_f32_16x16x32_bf16 v[80:83], v[216:219], v[188:191], v[80:83]
	v_mfma_f32_16x16x32_bf16 v[68:71], v[204:207], v[196:199], v[68:71]
	v_mfma_f32_16x16x32_bf16 v[64:67], v[216:219], v[196:199], v[64:67]
	v_mfma_f32_16x16x32_bf16 v[108:111], v[212:215], v[176:179], v[108:111]
	v_mfma_f32_16x16x32_bf16 v[100:103], v[220:223], v[176:179], v[100:103]
	v_mfma_f32_16x16x32_bf16 v[92:95], v[212:215], v[184:187], v[92:95]
	v_mfma_f32_16x16x32_bf16 v[88:91], v[220:223], v[184:187], v[88:91]
	v_mfma_f32_16x16x32_bf16 v[84:87], v[212:215], v[192:195], v[84:87]
	v_mfma_f32_16x16x32_bf16 v[80:83], v[220:223], v[192:195], v[80:83]
	v_mfma_f32_16x16x32_bf16 v[68:71], v[212:215], v[200:203], v[68:71]
	v_mfma_f32_16x16x32_bf16 v[64:67], v[220:223], v[200:203], v[64:67]
	s_setprio 0
	s_mov_b32 m0, s42
	v_lshl_add_u64 v[148:149], v[224:225], 0, s[8:9]
	s_barrier
	ds_read_b128 v[170:173], v154 offset:49152
	ds_read_b128 v[176:179], v154 offset:50176
	ds_read_b128 v[180:183], v154 offset:51200
	ds_read_b128 v[184:187], v154 offset:52224
	ds_read_b128 v[188:191], v154 offset:53248
	ds_read_b128 v[192:195], v154 offset:54272
	ds_read_b128 v[196:199], v154 offset:55296
	ds_read_b128 v[200:203], v154 offset:56320
	global_load_lds_dwordx4 v[148:149], off
	v_lshl_add_u64 v[148:149], v[226:227], 0, s[8:9]
	s_mov_b32 m0, s43
	s_nop 0
	global_load_lds_dwordx4 v[148:149], off
	s_waitcnt lgkmcnt(0)
	s_setprio 1
	s_barrier
	v_mfma_f32_16x16x32_bf16 v[60:63], v[144:147], v[170:173], v[60:63]
	v_mfma_f32_16x16x32_bf16 v[56:59], v[162:165], v[170:173], v[56:59]
	v_mfma_f32_16x16x32_bf16 v[44:47], v[144:147], v[180:183], v[44:47]
	v_mfma_f32_16x16x32_bf16 v[40:43], v[162:165], v[180:183], v[40:43]
	v_mfma_f32_16x16x32_bf16 v[28:31], v[144:147], v[188:191], v[28:31]
	v_mfma_f32_16x16x32_bf16 v[24:27], v[162:165], v[188:191], v[24:27]
	v_mfma_f32_16x16x32_bf16 v[12:15], v[144:147], v[196:199], v[12:15]
	v_mfma_f32_16x16x32_bf16 v[8:11], v[162:165], v[196:199], v[8:11]
	v_mfma_f32_16x16x32_bf16 v[60:63], v[158:161], v[176:179], v[60:63]
	v_mfma_f32_16x16x32_bf16 v[56:59], v[166:169], v[176:179], v[56:59]
	v_mfma_f32_16x16x32_bf16 v[44:47], v[158:161], v[184:187], v[44:47]
	v_mfma_f32_16x16x32_bf16 v[40:43], v[166:169], v[184:187], v[40:43]
	v_mfma_f32_16x16x32_bf16 v[28:31], v[158:161], v[192:195], v[28:31]
	v_mfma_f32_16x16x32_bf16 v[24:27], v[166:169], v[192:195], v[24:27]
	v_mfma_f32_16x16x32_bf16 v[12:15], v[158:161], v[200:203], v[12:15]
	v_mfma_f32_16x16x32_bf16 v[8:11], v[166:169], v[200:203], v[8:11]
	s_setprio 0
	s_barrier
	s_add_u32 s28, s28, 0x40080
	s_addc_u32 s29, s29, 0
	s_add_i32 s30, s30, s34
	v_lshl_add_u64 v[144:145], s[28:29], 0, v[132:133]
	s_mov_b32 m0, s30
	s_nop 0
	global_load_lds_dwordx4 v[144:145], off
	v_lshl_add_u64 v[144:145], s[28:29], 0, v[128:129]
	s_add_i32 m0, s30, 0x2000
	s_nop 0
	global_load_lds_dwordx4 v[144:145], off
	s_waitcnt vmcnt(6)
	s_setprio 1
	s_barrier
	v_mfma_f32_16x16x32_bf16 v[52:55], v[204:207], v[170:173], v[52:55]
	v_mfma_f32_16x16x32_bf16 v[48:51], v[216:219], v[170:173], v[48:51]
	v_mfma_f32_16x16x32_bf16 v[36:39], v[204:207], v[180:183], v[36:39]
	v_mfma_f32_16x16x32_bf16 v[32:35], v[216:219], v[180:183], v[32:35]
	v_mfma_f32_16x16x32_bf16 v[20:23], v[204:207], v[188:191], v[20:23]
	v_mfma_f32_16x16x32_bf16 v[16:19], v[216:219], v[188:191], v[16:19]
	v_mfma_f32_16x16x32_bf16 v[4:7], v[204:207], v[196:199], v[4:7]
	v_mfma_f32_16x16x32_bf16 v[0:3], v[216:219], v[196:199], v[0:3]
	v_mfma_f32_16x16x32_bf16 v[52:55], v[212:215], v[176:179], v[52:55]
	v_mfma_f32_16x16x32_bf16 v[48:51], v[220:223], v[176:179], v[48:51]
	v_mfma_f32_16x16x32_bf16 v[36:39], v[212:215], v[184:187], v[36:39]
	v_mfma_f32_16x16x32_bf16 v[32:35], v[220:223], v[184:187], v[32:35]
	v_mfma_f32_16x16x32_bf16 v[20:23], v[212:215], v[192:195], v[20:23]
	v_mfma_f32_16x16x32_bf16 v[16:19], v[220:223], v[192:195], v[16:19]
	v_mfma_f32_16x16x32_bf16 v[4:7], v[212:215], v[200:203], v[4:7]
	v_mfma_f32_16x16x32_bf16 v[0:3], v[220:223], v[200:203], v[0:3]
	s_setprio 0
	s_add_i32 s58, s58, 2
	s_add_u32 s2, s2, 0x100
	s_addc_u32 s3, s3, 0
	s_add_u32 s56, s56, 0x100
	s_addc_u32 s57, s57, 0
	s_cmp_gt_u32 s58, 13
	s_barrier
	s_cbranch_scc0 .LBB0_946
	v_lshl_add_u32 v144, s0, 8, v150
	v_ashrrev_i32_e32 v145, 31, v144
	v_lshl_add_u64 v[146:147], v[144:145], 2, s[18:19]
	global_load_dword v145, v[146:147], off
	global_load_dword v157, v[146:147], off offset:64
	global_load_dword v164, v[146:147], off offset:128
	global_load_dword v165, v[146:147], off offset:192
	global_load_dword v166, v[146:147], off offset:512
	global_load_dword v167, v[146:147], off offset:576
	global_load_dword v168, v[146:147], off offset:640
	global_load_dword v169, v[146:147], off offset:704
	v_mov_b64_e32 v[146:147], s[92:93]
	v_or_b32_e32 v160, 16, v144
	v_or_b32_e32 v162, 32, v144
	v_lshl_or_b32 v148, s1, 8, v152
	v_mad_i64_i32 v[158:159], s[0:1], v144, s52, v[146:147]
	v_mad_i64_i32 v[160:161], s[0:1], v160, s52, v[146:147]
	v_mad_i64_i32 v[162:163], s[0:1], v162, s52, v[146:147]
	v_ashrrev_i32_e32 v149, 31, v148
	v_lshlrev_b64 v[148:149], 1, v[148:149]
	v_lshl_add_u64 v[158:159], v[158:159], 0, v[148:149]
	v_lshl_add_u64 v[160:161], v[160:161], 0, v[148:149]
	v_lshl_add_u64 v[162:163], v[162:163], 0, v[148:149]
	v_add_u32_e32 v170, 0x80, v144
	s_mov_b64 s[28:29], s[26:27]
	s_waitcnt vmcnt(0)
	v_fmamk_f32 v145, v145, 0x3a800000, v156
	v_fmamk_f32 v157, v157, 0x3a800000, v156
	v_fmamk_f32 v164, v164, 0x3a800000, v156
	v_fmamk_f32 v171, v165, 0x3a800000, v156
	v_fmamk_f32 v172, v166, 0x3a800000, v156
	v_mul_f32_e32 v165, 0x4b800000, v145
	v_mul_f32_e32 v166, 0x4b800000, v157
	v_cmp_gt_f32_e32 vcc, s53, v145
	v_cmp_gt_f32_e64 s[0:1], s53, v157
	v_fmamk_f32 v173, v167, 0x3a800000, v156
	v_mul_f32_e32 v167, 0x4b800000, v164
	v_cndmask_b32_e32 v145, v145, v165, vcc
	v_cndmask_b32_e64 v157, v157, v166, s[0:1]
	v_cmp_gt_f32_e64 s[2:3], s53, v164
	v_rsq_f32_e32 v145, v145
	v_rsq_f32_e32 v157, v157
	v_cndmask_b32_e64 v164, v164, v167, s[2:3]
	v_rsq_f32_e32 v165, v164
	v_mul_f32_e32 v164, 0x45800000, v145
	v_mul_f32_e32 v166, 0x45800000, v157
	v_cndmask_b32_e32 v164, v145, v164, vcc
	v_mul_f32_e32 v167, 0x45800000, v165
	v_cndmask_b32_e64 v166, v157, v166, s[0:1]
	v_fmamk_f32 v175, v168, 0x3a800000, v156
	v_cndmask_b32_e64 v168, v165, v167, s[2:3]
	v_pk_mul_f32 v[126:127], v[126:127], v[164:165] op_sel_hi:[1,0]
	v_pk_mul_f32 v[124:125], v[124:125], v[164:165] op_sel_hi:[1,0]
	v_pk_mul_f32 v[122:123], v[122:123], v[164:165] op_sel_hi:[1,0]
	v_pk_mul_f32 v[120:121], v[120:121], v[164:165] op_sel_hi:[1,0]
	v_pk_mul_f32 v[110:111], v[110:111], v[164:165] op_sel_hi:[1,0]
	v_pk_mul_f32 v[108:109], v[108:109], v[164:165] op_sel_hi:[1,0]
	v_pk_mul_f32 v[102:103], v[102:103], v[164:165] op_sel_hi:[1,0]
	v_pk_mul_f32 v[100:101], v[100:101], v[164:165] op_sel_hi:[1,0]
	v_pk_mul_f32 v[118:119], v[118:119], v[166:167] op_sel_hi:[1,0]
	v_pk_mul_f32 v[116:117], v[116:117], v[166:167] op_sel_hi:[1,0]
	v_pk_mul_f32 v[114:115], v[114:115], v[166:167] op_sel_hi:[1,0]
	v_pk_mul_f32 v[112:113], v[112:113], v[166:167] op_sel_hi:[1,0]
	v_pk_mul_f32 v[94:95], v[94:95], v[166:167] op_sel_hi:[1,0]
	v_pk_mul_f32 v[92:93], v[92:93], v[166:167] op_sel_hi:[1,0]
	v_pk_mul_f32 v[164:165], v[90:91], v[166:167] op_sel_hi:[1,0]
	v_pk_mul_f32 v[166:167], v[88:89], v[166:167] op_sel_hi:[1,0]
	v_cvt_pk_bf16_f32 v88, v124, v125
	v_cvt_pk_bf16_f32 v89, v126, v127
	v_cvt_pk_bf16_f32 v90, v120, v121
	v_cvt_pk_bf16_f32 v91, v122, v123
	global_store_dwordx4 v[158:159], v[88:91], off nt
	v_fmamk_f32 v169, v169, 0x3a800000, v156
	v_pk_mul_f32 v[106:107], v[106:107], v[168:169] op_sel_hi:[1,0]
	v_cvt_pk_bf16_f32 v88, v108, v109
	v_cvt_pk_bf16_f32 v89, v110, v111
	v_cvt_pk_bf16_f32 v90, v100, v101
	v_cvt_pk_bf16_f32 v91, v102, v103
	global_store_dwordx4 v[158:159], v[88:91], off offset:256 nt
	v_pk_mul_f32 v[104:105], v[104:105], v[168:169] op_sel_hi:[1,0]
	v_pk_mul_f32 v[98:99], v[98:99], v[168:169] op_sel_hi:[1,0]
	v_cvt_pk_bf16_f32 v88, v116, v117
	v_cvt_pk_bf16_f32 v89, v118, v119
	v_cvt_pk_bf16_f32 v90, v112, v113
	v_cvt_pk_bf16_f32 v91, v114, v115
	global_store_dwordx4 v[160:161], v[88:91], off nt
	v_pk_mul_f32 v[96:97], v[96:97], v[168:169] op_sel_hi:[1,0]
	v_pk_mul_f32 v[86:87], v[86:87], v[168:169] op_sel_hi:[1,0]
	v_cvt_pk_bf16_f32 v88, v92, v93
	v_cvt_pk_bf16_f32 v89, v94, v95
	v_cvt_pk_bf16_f32 v90, v166, v167
	v_cvt_pk_bf16_f32 v91, v164, v165
	global_store_dwordx4 v[160:161], v[88:91], off offset:256 nt
	v_pk_mul_f32 v[84:85], v[84:85], v[168:169] op_sel_hi:[1,0]
	v_cmp_gt_f32_e32 vcc, s53, v171
	v_cvt_pk_bf16_f32 v88, v104, v105
	v_cvt_pk_bf16_f32 v89, v106, v107
	v_cvt_pk_bf16_f32 v90, v96, v97
	v_cvt_pk_bf16_f32 v91, v98, v99
	global_store_dwordx4 v[162:163], v[88:91], off nt
	s_mov_b64 s[2:3], s[24:25]
	s_nop 0
	v_pk_mul_f32 v[88:89], v[82:83], v[168:169] op_sel_hi:[1,0]
	v_pk_mul_f32 v[82:83], v[80:81], v[168:169] op_sel_hi:[1,0]
	v_cvt_pk_bf16_f32 v80, v84, v85
	v_cvt_pk_bf16_f32 v81, v86, v87
	s_nop 0
	v_cvt_pk_bf16_f32 v82, v82, v83
	v_cvt_pk_bf16_f32 v83, v88, v89
	global_store_dwordx4 v[162:163], v[80:83], off offset:256 nt
	s_nop 1
	v_mul_f32_e32 v81, 0x4b800000, v171
	v_cndmask_b32_e32 v81, v171, v81, vcc
	v_rsq_f32_e32 v82, v81
	v_or_b32_e32 v80, 48, v144
	v_mad_i64_i32 v[80:81], s[0:1], v80, s52, v[146:147]
	v_mul_f32_e32 v83, 0x45800000, v82
	v_cndmask_b32_e32 v82, v82, v83, vcc
	v_lshl_add_u64 v[80:81], v[80:81], 0, v[148:149]
	v_pk_mul_f32 v[78:79], v[78:79], v[82:83] op_sel_hi:[1,0]
	v_pk_mul_f32 v[76:77], v[76:77], v[82:83] op_sel_hi:[1,0]
	v_pk_mul_f32 v[84:85], v[74:75], v[82:83] op_sel_hi:[1,0]
	v_pk_mul_f32 v[74:75], v[72:73], v[82:83] op_sel_hi:[1,0]
	v_cvt_pk_bf16_f32 v72, v76, v77
	v_cvt_pk_bf16_f32 v73, v78, v79
	v_pk_mul_f32 v[68:69], v[68:69], v[82:83] op_sel_hi:[1,0]
	v_cvt_pk_bf16_f32 v74, v74, v75
	v_cvt_pk_bf16_f32 v75, v84, v85
	global_store_dwordx4 v[80:81], v[72:75], off nt
	v_pk_mul_f32 v[70:71], v[70:71], v[82:83] op_sel_hi:[1,0]
	v_cmp_gt_f32_e32 vcc, s53, v172
	v_pk_mul_f32 v[72:73], v[66:67], v[82:83] op_sel_hi:[1,0]
	v_pk_mul_f32 v[66:67], v[64:65], v[82:83] op_sel_hi:[1,0]
	v_cvt_pk_bf16_f32 v64, v68, v69
	v_cvt_pk_bf16_f32 v65, v70, v71
	s_nop 0
	v_cvt_pk_bf16_f32 v66, v66, v67
	v_cvt_pk_bf16_f32 v67, v72, v73
	global_store_dwordx4 v[80:81], v[64:67], off offset:256 nt
	s_nop 1
	v_mul_f32_e32 v64, 0x4b800000, v172
	v_cndmask_b32_e32 v64, v172, v64, vcc
	v_rsq_f32_e32 v66, v64
	v_mad_i64_i32 v[64:65], s[0:1], v170, s52, v[146:147]
	v_lshl_add_u64 v[64:65], v[64:65], 0, v[148:149]
	v_mul_f32_e32 v67, 0x45800000, v66
	v_cndmask_b32_e32 v66, v66, v67, vcc
	v_pk_mul_f32 v[62:63], v[62:63], v[66:67] op_sel_hi:[1,0]
	v_pk_mul_f32 v[60:61], v[60:61], v[66:67] op_sel_hi:[1,0]
	v_pk_mul_f32 v[68:69], v[58:59], v[66:67] op_sel_hi:[1,0]
	v_pk_mul_f32 v[58:59], v[56:57], v[66:67] op_sel_hi:[1,0]
	v_cvt_pk_bf16_f32 v56, v60, v61
	v_cvt_pk_bf16_f32 v57, v62, v63
	v_pk_mul_f32 v[54:55], v[54:55], v[66:67] op_sel_hi:[1,0]
	v_cvt_pk_bf16_f32 v58, v58, v59
	v_cvt_pk_bf16_f32 v59, v68, v69
	global_store_dwordx4 v[64:65], v[56:59], off nt
	v_pk_mul_f32 v[52:53], v[52:53], v[66:67] op_sel_hi:[1,0]
	v_cmp_gt_f32_e32 vcc, s53, v173
	v_pk_mul_f32 v[56:57], v[50:51], v[66:67] op_sel_hi:[1,0]
	v_pk_mul_f32 v[50:51], v[48:49], v[66:67] op_sel_hi:[1,0]
	v_cvt_pk_bf16_f32 v48, v52, v53
	v_cvt_pk_bf16_f32 v49, v54, v55
	s_nop 0
	v_cvt_pk_bf16_f32 v50, v50, v51
	v_cvt_pk_bf16_f32 v51, v56, v57
	global_store_dwordx4 v[64:65], v[48:51], off offset:256 nt
	s_nop 1
	v_mul_f32_e32 v49, 0x4b800000, v173
	v_cndmask_b32_e32 v49, v173, v49, vcc
	v_rsq_f32_e32 v50, v49
	v_add_u32_e32 v48, 0x90, v144
	v_mad_i64_i32 v[48:49], s[0:1], v48, s52, v[146:147]
	v_mul_f32_e32 v51, 0x45800000, v50
	v_cndmask_b32_e32 v50, v50, v51, vcc
	v_lshl_add_u64 v[48:49], v[48:49], 0, v[148:149]
	v_pk_mul_f32 v[46:47], v[46:47], v[50:51] op_sel_hi:[1,0]
	v_pk_mul_f32 v[44:45], v[44:45], v[50:51] op_sel_hi:[1,0]
	v_pk_mul_f32 v[52:53], v[42:43], v[50:51] op_sel_hi:[1,0]
	v_pk_mul_f32 v[42:43], v[40:41], v[50:51] op_sel_hi:[1,0]
	v_cvt_pk_bf16_f32 v40, v44, v45
	v_cvt_pk_bf16_f32 v41, v46, v47
	v_pk_mul_f32 v[38:39], v[38:39], v[50:51] op_sel_hi:[1,0]
	v_cvt_pk_bf16_f32 v42, v42, v43
	v_cvt_pk_bf16_f32 v43, v52, v53
	global_store_dwordx4 v[48:49], v[40:43], off nt
	v_pk_mul_f32 v[36:37], v[36:37], v[50:51] op_sel_hi:[1,0]
	v_cmp_gt_f32_e32 vcc, s53, v175
	v_pk_mul_f32 v[40:41], v[34:35], v[50:51] op_sel_hi:[1,0]
	v_pk_mul_f32 v[34:35], v[32:33], v[50:51] op_sel_hi:[1,0]
	v_cvt_pk_bf16_f32 v32, v36, v37
	v_cvt_pk_bf16_f32 v33, v38, v39
	s_nop 0
	v_cvt_pk_bf16_f32 v34, v34, v35
	v_cvt_pk_bf16_f32 v35, v40, v41
	global_store_dwordx4 v[48:49], v[32:35], off offset:256 nt
	s_nop 1
	v_mul_f32_e32 v33, 0x4b800000, v175
	v_cndmask_b32_e32 v33, v175, v33, vcc
	v_rsq_f32_e32 v34, v33
	v_add_u32_e32 v32, 0xa0, v144
	v_mad_i64_i32 v[32:33], s[0:1], v32, s52, v[146:147]
	v_mul_f32_e32 v35, 0x45800000, v34
	v_cndmask_b32_e32 v34, v34, v35, vcc
	v_lshl_add_u64 v[32:33], v[32:33], 0, v[148:149]
	v_pk_mul_f32 v[30:31], v[30:31], v[34:35] op_sel_hi:[1,0]
	v_pk_mul_f32 v[28:29], v[28:29], v[34:35] op_sel_hi:[1,0]
	v_pk_mul_f32 v[36:37], v[26:27], v[34:35] op_sel_hi:[1,0]
	v_pk_mul_f32 v[26:27], v[24:25], v[34:35] op_sel_hi:[1,0]
	v_cvt_pk_bf16_f32 v24, v28, v29
	v_cvt_pk_bf16_f32 v25, v30, v31
	v_pk_mul_f32 v[22:23], v[22:23], v[34:35] op_sel_hi:[1,0]
	v_cvt_pk_bf16_f32 v26, v26, v27
	v_cvt_pk_bf16_f32 v27, v36, v37
	global_store_dwordx4 v[32:33], v[24:27], off nt
	v_pk_mul_f32 v[20:21], v[20:21], v[34:35] op_sel_hi:[1,0]
	v_cmp_gt_f32_e32 vcc, s53, v169
	v_pk_mul_f32 v[24:25], v[18:19], v[34:35] op_sel_hi:[1,0]
	v_pk_mul_f32 v[18:19], v[16:17], v[34:35] op_sel_hi:[1,0]
	v_cvt_pk_bf16_f32 v16, v20, v21
	v_cvt_pk_bf16_f32 v17, v22, v23
	s_nop 0
	v_cvt_pk_bf16_f32 v18, v18, v19
	v_cvt_pk_bf16_f32 v19, v24, v25
	global_store_dwordx4 v[32:33], v[16:19], off offset:256 nt
	s_nop 1
	v_mul_f32_e32 v17, 0x4b800000, v169
	v_cndmask_b32_e32 v17, v169, v17, vcc
	v_rsq_f32_e32 v18, v17
	v_add_u32_e32 v16, 0xb0, v144
	v_mad_i64_i32 v[16:17], s[0:1], v16, s52, v[146:147]
	v_mul_f32_e32 v19, 0x45800000, v18
	v_cndmask_b32_e32 v18, v18, v19, vcc
	v_lshl_add_u64 v[16:17], v[16:17], 0, v[148:149]
	v_pk_mul_f32 v[14:15], v[14:15], v[18:19] op_sel_hi:[1,0]
	v_pk_mul_f32 v[12:13], v[12:13], v[18:19] op_sel_hi:[1,0]
	v_pk_mul_f32 v[20:21], v[10:11], v[18:19] op_sel_hi:[1,0]
	v_pk_mul_f32 v[10:11], v[8:9], v[18:19] op_sel_hi:[1,0]
	v_cvt_pk_bf16_f32 v8, v12, v13
	v_cvt_pk_bf16_f32 v9, v14, v15
	s_and_b64 vcc, exec, s[6:7]
	v_cvt_pk_bf16_f32 v10, v10, v11
	v_cvt_pk_bf16_f32 v11, v20, v21
	global_store_dwordx4 v[16:17], v[8:11], off nt
	s_mov_b32 s1, s20
	s_mov_b32 s0, s22
	v_pk_mul_f32 v[8:9], v[2:3], v[18:19] op_sel_hi:[1,0]
	v_pk_mul_f32 v[2:3], v[0:1], v[18:19] op_sel_hi:[1,0]
	v_pk_mul_f32 v[6:7], v[6:7], v[18:19] op_sel_hi:[1,0]
	v_pk_mul_f32 v[4:5], v[4:5], v[18:19] op_sel_hi:[1,0]
	s_nop 0
	v_cvt_pk_bf16_f32 v0, v4, v5
	v_cvt_pk_bf16_f32 v1, v6, v7
	v_cvt_pk_bf16_f32 v2, v2, v3
	v_cvt_pk_bf16_f32 v3, v8, v9
	global_store_dwordx4 v[16:17], v[0:3], off offset:256 nt
	s_cbranch_vccz .LBB0_943
	s_waitcnt vmcnt(0)
	s_cmpk_gt_u32 s33, 0xff
	s_cbranch_scc1 .LBB0_950
	s_barrier

.LBB0_1022:
	ds_read_b128 v[144:147], v178
	ds_read_b128 v[148:151], v178 offset:1024
	ds_read_b128 v[152:155], v178 offset:2048
	ds_read_b128 v[156:159], v178 offset:3072
	s_add_u32 s42, s40, 0xfffc0080
	s_addc_u32 s43, s41, -1
	s_cmp_eq_u32 s64, 12
	s_cselect_b32 s49, s29, s43
	s_cselect_b32 s48, s37, s42
	s_cselect_b32 s43, s27, s63
	s_cselect_b32 s42, s61, s62
	v_lshl_add_u64 v[172:173], s[40:41], 0, v[136:137]
	s_add_i32 m0, s39, 0xc000
	ds_read_b128 v[160:163], v179
	ds_read_b128 v[164:167], v179 offset:1024
	ds_read_b128 v[168:171], v179 offset:2048
	ds_read_b128 v[182:185], v179 offset:3072
	ds_read_b128 v[186:189], v179 offset:4096
	ds_read_b128 v[190:193], v179 offset:5120
	ds_read_b128 v[194:197], v179 offset:6144
	ds_read_b128 v[198:201], v179 offset:7168
	global_load_lds_dwordx4 v[172:173], off
	v_lshl_add_u64 v[172:173], s[40:41], 0, v[138:139]
	s_add_i32 m0, s39, 0xe000
	s_nop 0
	global_load_lds_dwordx4 v[172:173], off
	s_waitcnt lgkmcnt(8)
	s_waitcnt lgkmcnt(0)
	s_setprio 1
	s_barrier
	v_mfma_f32_16x16x32_bf16 v[124:127], v[144:147], v[160:163], v[124:127]
	v_mfma_f32_16x16x32_bf16 v[120:123], v[152:155], v[160:163], v[120:123]
	v_mfma_f32_16x16x32_bf16 v[108:111], v[144:147], v[168:171], v[108:111]
	v_mfma_f32_16x16x32_bf16 v[104:107], v[152:155], v[168:171], v[104:107]
	v_mfma_f32_16x16x32_bf16 v[96:99], v[144:147], v[186:189], v[96:99]
	v_mfma_f32_16x16x32_bf16 v[88:91], v[152:155], v[186:189], v[88:91]
	v_mfma_f32_16x16x32_bf16 v[80:83], v[144:147], v[194:197], v[80:83]
	v_mfma_f32_16x16x32_bf16 v[72:75], v[152:155], v[194:197], v[72:75]
	v_mfma_f32_16x16x32_bf16 v[124:127], v[148:151], v[164:167], v[124:127]
	v_mfma_f32_16x16x32_bf16 v[120:123], v[156:159], v[164:167], v[120:123]
	v_mfma_f32_16x16x32_bf16 v[108:111], v[148:151], v[182:185], v[108:111]
	v_mfma_f32_16x16x32_bf16 v[104:107], v[156:159], v[182:185], v[104:107]
	v_mfma_f32_16x16x32_bf16 v[96:99], v[148:151], v[190:193], v[96:99]
	v_mfma_f32_16x16x32_bf16 v[88:91], v[156:159], v[190:193], v[88:91]
	v_mfma_f32_16x16x32_bf16 v[80:83], v[148:151], v[198:201], v[80:83]
	v_mfma_f32_16x16x32_bf16 v[72:75], v[156:159], v[198:201], v[72:75]
	s_setprio 0
	s_barrier
	s_add_i32 s65, s59, s50
	v_lshl_add_u64 v[172:173], s[42:43], 0, v[130:131]
	s_mov_b32 m0, s65
	ds_read_b128 v[202:205], v180
	ds_read_b128 v[206:209], v180 offset:1024
	ds_read_b128 v[212:215], v180 offset:2048
	ds_read_b128 v[216:219], v180 offset:3072
	global_load_lds_dwordx4 v[172:173], off
	v_lshl_add_u64 v[220:221], s[42:43], 0, v[134:135]
	s_add_i32 m0, s65, 0x2000
	s_nop 0
	global_load_lds_dwordx4 v[220:221], off
	s_waitcnt lgkmcnt(0)
	s_setprio 1
	s_barrier
	v_mfma_f32_16x16x32_bf16 v[116:119], v[202:205], v[160:163], v[116:119]
	v_mfma_f32_16x16x32_bf16 v[112:115], v[212:215], v[160:163], v[112:115]
	v_mfma_f32_16x16x32_bf16 v[100:103], v[202:205], v[168:171], v[100:103]
	v_mfma_f32_16x16x32_bf16 v[92:95], v[212:215], v[168:171], v[92:95]
	v_mfma_f32_16x16x32_bf16 v[84:87], v[202:205], v[186:189], v[84:87]
	v_mfma_f32_16x16x32_bf16 v[76:79], v[212:215], v[186:189], v[76:79]
	v_mfma_f32_16x16x32_bf16 v[68:71], v[202:205], v[194:197], v[68:71]
	v_mfma_f32_16x16x32_bf16 v[64:67], v[212:215], v[194:197], v[64:67]
	v_mfma_f32_16x16x32_bf16 v[116:119], v[206:209], v[164:167], v[116:119]
	v_mfma_f32_16x16x32_bf16 v[112:115], v[216:219], v[164:167], v[112:115]
	v_mfma_f32_16x16x32_bf16 v[100:103], v[206:209], v[182:185], v[100:103]
	v_mfma_f32_16x16x32_bf16 v[92:95], v[216:219], v[182:185], v[92:95]
	v_mfma_f32_16x16x32_bf16 v[84:87], v[206:209], v[190:193], v[84:87]
	v_mfma_f32_16x16x32_bf16 v[76:79], v[216:219], v[190:193], v[76:79]
	v_mfma_f32_16x16x32_bf16 v[68:71], v[206:209], v[198:201], v[68:71]
	v_mfma_f32_16x16x32_bf16 v[64:67], v[216:219], v[198:201], v[64:67]
	s_setprio 0
	s_mov_b32 m0, s39
	v_lshl_add_u64 v[222:223], s[48:49], 0, v[128:129]
	s_barrier
	ds_read_b128 v[160:163], v179 offset:16384
	ds_read_b128 v[164:167], v179 offset:17408
	ds_read_b128 v[168:171], v179 offset:18432
	ds_read_b128 v[182:185], v179 offset:19456
	ds_read_b128 v[186:189], v179 offset:20480
	ds_read_b128 v[190:193], v179 offset:21504
	ds_read_b128 v[194:197], v179 offset:22528
	ds_read_b128 v[198:201], v179 offset:23552
	global_load_lds_dwordx4 v[222:223], off
	v_lshl_add_u64 v[224:225], s[48:49], 0, v[132:133]
	s_mov_b32 m0, s51
	s_nop 0
	global_load_lds_dwordx4 v[224:225], off
	s_waitcnt lgkmcnt(0)
	s_setprio 1
	s_barrier
	v_mfma_f32_16x16x32_bf16 v[60:63], v[144:147], v[160:163], v[60:63]
	v_mfma_f32_16x16x32_bf16 v[56:59], v[152:155], v[160:163], v[56:59]
	v_mfma_f32_16x16x32_bf16 v[44:47], v[144:147], v[168:171], v[44:47]
	v_mfma_f32_16x16x32_bf16 v[40:43], v[152:155], v[168:171], v[40:43]
	v_mfma_f32_16x16x32_bf16 v[32:35], v[144:147], v[186:189], v[32:35]
	v_mfma_f32_16x16x32_bf16 v[24:27], v[152:155], v[186:189], v[24:27]
	v_mfma_f32_16x16x32_bf16 v[16:19], v[144:147], v[194:197], v[16:19]
	v_mfma_f32_16x16x32_bf16 v[8:11], v[152:155], v[194:197], v[8:11]
	v_mfma_f32_16x16x32_bf16 v[60:63], v[148:151], v[164:167], v[60:63]
	v_mfma_f32_16x16x32_bf16 v[56:59], v[156:159], v[164:167], v[56:59]
	v_mfma_f32_16x16x32_bf16 v[44:47], v[148:151], v[182:185], v[44:47]
	v_mfma_f32_16x16x32_bf16 v[40:43], v[156:159], v[182:185], v[40:43]
	v_mfma_f32_16x16x32_bf16 v[32:35], v[148:151], v[190:193], v[32:35]
	v_mfma_f32_16x16x32_bf16 v[24:27], v[156:159], v[190:193], v[24:27]
	v_mfma_f32_16x16x32_bf16 v[16:19], v[148:151], v[198:201], v[16:19]
	v_mfma_f32_16x16x32_bf16 v[8:11], v[156:159], v[198:201], v[8:11]
	s_setprio 0
	s_barrier
	s_add_u32 s66, s42, 0x40000
	s_addc_u32 s67, s43, 0
	s_add_i32 s65, s60, s50
	v_lshl_add_u64 v[144:145], s[66:67], 0, v[130:131]
	s_mov_b32 m0, s65
	s_nop 0
	global_load_lds_dwordx4 v[144:145], off
	v_lshl_add_u64 v[144:145], s[66:67], 0, v[134:135]
	s_add_i32 m0, s65, 0x2000
	s_nop 0
	global_load_lds_dwordx4 v[144:145], off
	s_waitcnt vmcnt(6)
	s_setprio 1
	s_barrier
	v_mfma_f32_16x16x32_bf16 v[52:55], v[202:205], v[160:163], v[52:55]
	v_mfma_f32_16x16x32_bf16 v[48:51], v[212:215], v[160:163], v[48:51]
	v_mfma_f32_16x16x32_bf16 v[36:39], v[202:205], v[168:171], v[36:39]
	v_mfma_f32_16x16x32_bf16 v[28:31], v[212:215], v[168:171], v[28:31]
	v_mfma_f32_16x16x32_bf16 v[20:23], v[202:205], v[186:189], v[20:23]
	v_mfma_f32_16x16x32_bf16 v[12:15], v[212:215], v[186:189], v[12:15]
	v_mfma_f32_16x16x32_bf16 v[4:7], v[202:205], v[194:197], v[4:7]
	v_mfma_f32_16x16x32_bf16 v[0:3], v[212:215], v[194:197], v[0:3]
	v_mfma_f32_16x16x32_bf16 v[52:55], v[206:209], v[164:167], v[52:55]
	v_mfma_f32_16x16x32_bf16 v[48:51], v[216:219], v[164:167], v[48:51]
	v_mfma_f32_16x16x32_bf16 v[36:39], v[206:209], v[182:185], v[36:39]
	v_mfma_f32_16x16x32_bf16 v[28:31], v[216:219], v[182:185], v[28:31]
	v_mfma_f32_16x16x32_bf16 v[20:23], v[206:209], v[190:193], v[20:23]
	v_mfma_f32_16x16x32_bf16 v[12:15], v[216:219], v[190:193], v[12:15]
	v_mfma_f32_16x16x32_bf16 v[4:7], v[206:209], v[198:201], v[4:7]
	v_mfma_f32_16x16x32_bf16 v[0:3], v[216:219], v[198:201], v[0:3]
	s_setprio 0
	s_add_i32 s65, 0, 0x18000
	v_add_u32_e32 v156, s65, v176
	s_barrier
	ds_read_b128 v[144:147], v156
	ds_read_b128 v[148:151], v156 offset:1024
	ds_read_b128 v[152:155], v156 offset:2048
	ds_read_b128 v[156:159], v156 offset:3072
	s_add_u32 s48, s48, 0x40000
	s_addc_u32 s49, s49, 0
	s_mov_b32 m0, s52
	v_lshl_add_u64 v[202:203], s[48:49], 0, v[128:129]
	ds_read_b128 v[160:163], v179 offset:32768
	ds_read_b128 v[164:167], v179 offset:33792
	ds_read_b128 v[168:171], v179 offset:34816
	ds_read_b128 v[182:185], v179 offset:35840
	ds_read_b128 v[186:189], v179 offset:36864
	ds_read_b128 v[190:193], v179 offset:37888
	ds_read_b128 v[194:197], v179 offset:38912
	ds_read_b128 v[198:201], v179 offset:39936
	global_load_lds_dwordx4 v[202:203], off
	v_lshl_add_u64 v[202:203], s[48:49], 0, v[132:133]
	s_mov_b32 m0, s53
	s_nop 0
	global_load_lds_dwordx4 v[202:203], off
	s_waitcnt lgkmcnt(8)
	s_waitcnt lgkmcnt(0)
	s_setprio 1
	s_barrier
	v_mfma_f32_16x16x32_bf16 v[124:127], v[144:147], v[160:163], v[124:127]
	v_mfma_f32_16x16x32_bf16 v[120:123], v[152:155], v[160:163], v[120:123]
	v_mfma_f32_16x16x32_bf16 v[108:111], v[144:147], v[168:171], v[108:111]
	v_mfma_f32_16x16x32_bf16 v[104:107], v[152:155], v[168:171], v[104:107]
	v_mfma_f32_16x16x32_bf16 v[96:99], v[144:147], v[186:189], v[96:99]
	v_mfma_f32_16x16x32_bf16 v[88:91], v[152:155], v[186:189], v[88:91]
	v_mfma_f32_16x16x32_bf16 v[80:83], v[144:147], v[194:197], v[80:83]
	v_mfma_f32_16x16x32_bf16 v[72:75], v[152:155], v[194:197], v[72:75]
	v_mfma_f32_16x16x32_bf16 v[124:127], v[148:151], v[164:167], v[124:127]
	v_mfma_f32_16x16x32_bf16 v[120:123], v[156:159], v[164:167], v[120:123]
	v_mfma_f32_16x16x32_bf16 v[108:111], v[148:151], v[182:185], v[108:111]
	v_mfma_f32_16x16x32_bf16 v[104:107], v[156:159], v[182:185], v[104:107]
	v_mfma_f32_16x16x32_bf16 v[96:99], v[148:151], v[190:193], v[96:99]
	v_mfma_f32_16x16x32_bf16 v[88:91], v[156:159], v[190:193], v[88:91]
	v_mfma_f32_16x16x32_bf16 v[80:83], v[148:151], v[198:201], v[80:83]
	v_mfma_f32_16x16x32_bf16 v[72:75], v[156:159], v[198:201], v[72:75]
	s_setprio 0
	s_barrier
	s_add_i32 s48, 0, 0x1c000
	s_add_i32 s49, s65, s50
	v_add_u32_e32 v181, s48, v176
	v_lshl_add_u64 v[172:173], v[172:173], 0, s[2:3]
	s_mov_b32 m0, s49
	ds_read_b128 v[202:205], v181
	ds_read_b128 v[206:209], v181 offset:1024
	ds_read_b128 v[212:215], v181 offset:2048
	ds_read_b128 v[216:219], v181 offset:3072
	global_load_lds_dwordx4 v[172:173], off
	v_lshl_add_u64 v[172:173], v[220:221], 0, s[2:3]
	s_add_i32 m0, s49, 0x2000
	s_nop 0
	global_load_lds_dwordx4 v[172:173], off
	s_waitcnt lgkmcnt(0)
	s_setprio 1
	s_barrier
	v_mfma_f32_16x16x32_bf16 v[116:119], v[202:205], v[160:163], v[116:119]
	v_mfma_f32_16x16x32_bf16 v[112:115], v[212:215], v[160:163], v[112:115]
	v_mfma_f32_16x16x32_bf16 v[100:103], v[202:205], v[168:171], v[100:103]
	v_mfma_f32_16x16x32_bf16 v[92:95], v[212:215], v[168:171], v[92:95]
	v_mfma_f32_16x16x32_bf16 v[84:87], v[202:205], v[186:189], v[84:87]
	v_mfma_f32_16x16x32_bf16 v[76:79], v[212:215], v[186:189], v[76:79]
	v_mfma_f32_16x16x32_bf16 v[68:71], v[202:205], v[194:197], v[68:71]
	v_mfma_f32_16x16x32_bf16 v[64:67], v[212:215], v[194:197], v[64:67]
	v_mfma_f32_16x16x32_bf16 v[116:119], v[206:209], v[164:167], v[116:119]
	v_mfma_f32_16x16x32_bf16 v[112:115], v[216:219], v[164:167], v[112:115]
	v_mfma_f32_16x16x32_bf16 v[100:103], v[206:209], v[182:185], v[100:103]
	v_mfma_f32_16x16x32_bf16 v[92:95], v[216:219], v[182:185], v[92:95]
	v_mfma_f32_16x16x32_bf16 v[84:87], v[206:209], v[190:193], v[84:87]
	v_mfma_f32_16x16x32_bf16 v[76:79], v[216:219], v[190:193], v[76:79]
	v_mfma_f32_16x16x32_bf16 v[68:71], v[206:209], v[198:201], v[68:71]
	v_mfma_f32_16x16x32_bf16 v[64:67], v[216:219], v[198:201], v[64:67]
	s_setprio 0
	s_mov_b32 m0, s55
	v_lshl_add_u64 v[172:173], v[222:223], 0, s[2:3]
	s_barrier
	ds_read_b128 v[160:163], v179 offset:49152
	ds_read_b128 v[164:167], v179 offset:50176
	ds_read_b128 v[168:171], v179 offset:51200
	ds_read_b128 v[182:185], v179 offset:52224
	ds_read_b128 v[186:189], v179 offset:53248
	ds_read_b128 v[190:193], v179 offset:54272
	ds_read_b128 v[194:197], v179 offset:55296
	ds_read_b128 v[198:201], v179 offset:56320
	global_load_lds_dwordx4 v[172:173], off
	v_lshl_add_u64 v[172:173], v[224:225], 0, s[2:3]
	s_mov_b32 m0, s56
	s_nop 0
	global_load_lds_dwordx4 v[172:173], off
	s_waitcnt lgkmcnt(0)
	s_setprio 1
	s_barrier
	v_mfma_f32_16x16x32_bf16 v[60:63], v[144:147], v[160:163], v[60:63]
	v_mfma_f32_16x16x32_bf16 v[56:59], v[152:155], v[160:163], v[56:59]
	v_mfma_f32_16x16x32_bf16 v[44:47], v[144:147], v[168:171], v[44:47]
	v_mfma_f32_16x16x32_bf16 v[40:43], v[152:155], v[168:171], v[40:43]
	v_mfma_f32_16x16x32_bf16 v[32:35], v[144:147], v[186:189], v[32:35]
	v_mfma_f32_16x16x32_bf16 v[24:27], v[152:155], v[186:189], v[24:27]
	v_mfma_f32_16x16x32_bf16 v[16:19], v[144:147], v[194:197], v[16:19]
	v_mfma_f32_16x16x32_bf16 v[8:11], v[152:155], v[194:197], v[8:11]
	v_mfma_f32_16x16x32_bf16 v[60:63], v[148:151], v[164:167], v[60:63]
	v_mfma_f32_16x16x32_bf16 v[56:59], v[156:159], v[164:167], v[56:59]
	v_mfma_f32_16x16x32_bf16 v[44:47], v[148:151], v[182:185], v[44:47]
	v_mfma_f32_16x16x32_bf16 v[40:43], v[156:159], v[182:185], v[40:43]
	v_mfma_f32_16x16x32_bf16 v[32:35], v[148:151], v[190:193], v[32:35]
	v_mfma_f32_16x16x32_bf16 v[24:27], v[156:159], v[190:193], v[24:27]
	v_mfma_f32_16x16x32_bf16 v[16:19], v[148:151], v[198:201], v[16:19]
	v_mfma_f32_16x16x32_bf16 v[8:11], v[156:159], v[198:201], v[8:11]
	s_setprio 0
	s_barrier
	s_add_u32 s42, s42, 0x40080
	s_addc_u32 s43, s43, 0
	s_add_i32 s48, s48, s50
	v_lshl_add_u64 v[144:145], s[42:43], 0, v[130:131]
	s_mov_b32 m0, s48
	s_nop 0
	global_load_lds_dwordx4 v[144:145], off
	v_lshl_add_u64 v[144:145], s[42:43], 0, v[134:135]
	s_add_i32 m0, s48, 0x2000
	s_nop 0
	global_load_lds_dwordx4 v[144:145], off
	s_waitcnt vmcnt(6)
	s_setprio 1
	s_barrier
	v_mfma_f32_16x16x32_bf16 v[52:55], v[202:205], v[160:163], v[52:55]
	v_mfma_f32_16x16x32_bf16 v[48:51], v[212:215], v[160:163], v[48:51]
	v_mfma_f32_16x16x32_bf16 v[36:39], v[202:205], v[168:171], v[36:39]
	v_mfma_f32_16x16x32_bf16 v[28:31], v[212:215], v[168:171], v[28:31]
	v_mfma_f32_16x16x32_bf16 v[20:23], v[202:205], v[186:189], v[20:23]
	v_mfma_f32_16x16x32_bf16 v[12:15], v[212:215], v[186:189], v[12:15]
	v_mfma_f32_16x16x32_bf16 v[4:7], v[202:205], v[194:197], v[4:7]
	v_mfma_f32_16x16x32_bf16 v[0:3], v[212:215], v[194:197], v[0:3]
	v_mfma_f32_16x16x32_bf16 v[52:55], v[206:209], v[164:167], v[52:55]
	v_mfma_f32_16x16x32_bf16 v[48:51], v[216:219], v[164:167], v[48:51]
	v_mfma_f32_16x16x32_bf16 v[36:39], v[206:209], v[182:185], v[36:39]
	v_mfma_f32_16x16x32_bf16 v[28:31], v[216:219], v[182:185], v[28:31]
	v_mfma_f32_16x16x32_bf16 v[20:23], v[206:209], v[190:193], v[20:23]
	v_mfma_f32_16x16x32_bf16 v[12:15], v[216:219], v[190:193], v[12:15]
	v_mfma_f32_16x16x32_bf16 v[4:7], v[206:209], v[198:201], v[4:7]
	v_mfma_f32_16x16x32_bf16 v[0:3], v[216:219], v[198:201], v[0:3]
	s_setprio 0
	s_add_i32 s64, s64, 2
	s_add_u32 s40, s40, 0x100
	s_addc_u32 s41, s41, 0
	s_add_u32 s62, s62, 0x100
	s_addc_u32 s63, s63, 0
	s_cmp_gt_u32 s64, 13
	s_barrier
	s_cbranch_scc0 .LBB0_1022
	v_lshl_or_b32 v144, s38, 8, v177
	v_lshl_add_u32 v150, s36, 8, v175
	v_ashrrev_i32_e32 v145, 31, v144
	v_ashrrev_i32_e32 v151, 31, v150
	v_lshlrev_b64 v[144:145], 1, v[144:145]
	v_lshl_add_u64 v[146:147], s[10:11], 0, v[144:145]
	v_lshlrev_b64 v[148:149], 11, v[150:151]
	v_lshl_add_u64 v[152:153], v[146:147], 0, v[148:149]
	global_load_dwordx4 v[156:159], v[152:153], off
	global_load_dwordx4 v[160:163], v[152:153], off offset:256
	v_or_b32_e32 v152, 16, v150
	v_ashrrev_i32_e32 v153, 31, v152
	v_lshlrev_b64 v[170:171], 11, v[152:153]
	v_lshl_add_u64 v[152:153], v[146:147], 0, v[170:171]
	global_load_dwordx4 v[164:167], v[152:153], off
	global_load_dwordx4 v[182:185], v[152:153], off offset:256
	v_or_b32_e32 v152, 32, v150
	v_ashrrev_i32_e32 v153, 31, v152
	v_lshlrev_b64 v[154:155], 11, v[152:153]
	v_lshl_add_u64 v[152:153], v[146:147], 0, v[154:155]
	global_load_dwordx4 v[186:189], v[152:153], off
	global_load_dwordx4 v[190:193], v[152:153], off offset:256
	v_or_b32_e32 v152, 48, v150
	v_ashrrev_i32_e32 v153, 31, v152
	v_lshlrev_b64 v[152:153], 11, v[152:153]
	v_lshl_add_u64 v[168:169], v[146:147], 0, v[152:153]
	global_load_dwordx4 v[194:197], v[168:169], off
	global_load_dwordx4 v[198:201], v[168:169], off offset:256
	s_waitcnt vmcnt(0)
	v_lshlrev_b32_e32 v202, 16, v156
	v_and_b32_e32 v203, 0xffff0000, v156
	v_lshlrev_b32_e32 v204, 16, v157
	v_and_b32_e32 v205, 0xffff0000, v157
	v_lshlrev_b32_e32 v206, 16, v158
	v_and_b32_e32 v207, 0xffff0000, v158
	v_lshlrev_b32_e32 v208, 16, v159
	v_and_b32_e32 v209, 0xffff0000, v159
	v_pk_add_f32 v[126:127], v[126:127], v[204:205]
	v_pk_add_f32 v[124:125], v[124:125], v[202:203]
	v_lshlrev_b32_e32 v224, 16, v166
	v_and_b32_e32 v225, 0xffff0000, v166
	v_lshlrev_b32_e32 v226, 16, v167
	v_and_b32_e32 v227, 0xffff0000, v167
	v_lshlrev_b32_e32 v212, 16, v160
	v_lshlrev_b32_e32 v166, 16, v194
	v_and_b32_e32 v167, 0xffff0000, v194
	v_lshlrev_b32_e32 v172, 16, v195
	v_and_b32_e32 v173, 0xffff0000, v195
	v_pk_add_f32 v[194:195], v[122:123], v[208:209]
	v_pk_add_f32 v[122:123], v[120:121], v[206:207]
	v_mul_f32_e32 v120, v125, v125
	v_mul_f32_e32 v121, v127, v127
	v_fmac_f32_e32 v120, v124, v124
	v_fmac_f32_e32 v121, v126, v126
	v_add_f32_e32 v120, v120, v121
	v_mul_f32_e32 v121, v123, v123
	v_fmac_f32_e32 v121, v122, v122
	v_add_f32_e32 v120, v121, v120
	v_mul_f32_e32 v121, v195, v195
	v_fmac_f32_e32 v121, v194, v194
	v_and_b32_e32 v213, 0xffff0000, v160
	v_lshlrev_b32_e32 v214, 16, v161
	v_and_b32_e32 v215, 0xffff0000, v161
	v_add_f32_e32 v181, v121, v120
	v_cvt_pk_bf16_f32 v120, v124, v125
	v_lshl_add_u64 v[124:125], s[10:11], 0, v[148:149]
	v_lshlrev_b32_e32 v216, 16, v162
	v_and_b32_e32 v217, 0xffff0000, v162
	v_lshlrev_b32_e32 v218, 16, v163
	v_and_b32_e32 v219, 0xffff0000, v163
	v_cvt_pk_bf16_f32 v121, v126, v127
	v_lshl_add_u64 v[124:125], v[124:125], 0, v[144:145]
	v_pk_add_f32 v[118:119], v[118:119], v[214:215]
	v_pk_add_f32 v[116:117], v[116:117], v[212:213]
	v_cvt_pk_bf16_f32 v122, v122, v123
	v_cvt_pk_bf16_f32 v123, v194, v195
	global_store_dwordx4 v[124:125], v[120:123], off
	v_lshlrev_b32_e32 v220, 16, v164
	v_and_b32_e32 v221, 0xffff0000, v164
	v_pk_add_f32 v[120:121], v[114:115], v[218:219]
	v_pk_add_f32 v[114:115], v[112:113], v[216:217]
	v_mul_f32_e32 v112, v117, v117
	v_mul_f32_e32 v113, v119, v119
	v_fmac_f32_e32 v112, v116, v116
	v_fmac_f32_e32 v113, v118, v118
	v_add_f32_e32 v112, v112, v113
	v_mul_f32_e32 v113, v115, v115
	v_fmac_f32_e32 v113, v114, v114
	v_add_f32_e32 v112, v113, v112
	v_mul_f32_e32 v113, v121, v121
	v_fmac_f32_e32 v113, v120, v120
	v_add_f32_e32 v112, v113, v112
	v_lshlrev_b32_e32 v222, 16, v165
	v_and_b32_e32 v223, 0xffff0000, v165
	v_add_f32_e32 v126, v181, v112
	v_cvt_pk_bf16_f32 v112, v116, v117
	v_cvt_pk_bf16_f32 v113, v118, v119
	v_lshl_add_u64 v[116:117], s[10:11], 0, v[170:171]
	v_lshlrev_b32_e32 v230, 16, v184
	v_and_b32_e32 v231, 0xffff0000, v184
	v_lshlrev_b32_e32 v232, 16, v186
	v_and_b32_e32 v233, 0xffff0000, v186
	v_lshlrev_b32_e32 v186, 16, v187
	v_and_b32_e32 v187, 0xffff0000, v187
	v_cvt_pk_bf16_f32 v114, v114, v115
	v_cvt_pk_bf16_f32 v115, v120, v121
	global_store_dwordx4 v[124:125], v[112:115], off offset:256
	v_pk_add_f32 v[110:111], v[110:111], v[222:223]
	v_pk_add_f32 v[108:109], v[108:109], v[220:221]
	v_lshl_add_u64 v[118:119], v[116:117], 0, v[144:145]
	v_cvt_pk_bf16_f32 v112, v108, v109
	v_cvt_pk_bf16_f32 v113, v110, v111
	v_lshlrev_b32_e32 v228, 16, v182
	v_and_b32_e32 v229, 0xffff0000, v182
	v_lshlrev_b32_e32 v182, 16, v183
	v_and_b32_e32 v183, 0xffff0000, v183
	v_lshlrev_b32_e32 v184, 16, v185
	v_and_b32_e32 v185, 0xffff0000, v185
	v_lshlrev_b32_e32 v238, 16, v192
	v_and_b32_e32 v239, 0xffff0000, v192
	v_pk_add_f32 v[106:107], v[106:107], v[226:227]
	v_pk_add_f32 v[104:105], v[104:105], v[224:225]
	v_lshlrev_b32_e32 v156, 16, v200
	v_cvt_pk_bf16_f32 v114, v104, v105
	v_cvt_pk_bf16_f32 v115, v106, v107
	global_store_dwordx4 v[118:119], v[112:115], off
	v_and_b32_e32 v157, 0xffff0000, v200
	v_pk_add_f32 v[102:103], v[102:103], v[182:183]
	v_pk_add_f32 v[112:113], v[92:93], v[230:231]
	v_pk_add_f32 v[92:93], v[98:99], v[186:187]
	v_lshl_add_u64 v[98:99], s[10:11], 0, v[154:155]
	v_pk_add_f32 v[100:101], v[100:101], v[228:229]
	v_pk_add_f32 v[94:95], v[94:95], v[184:185]
	v_cvt_pk_bf16_f32 v114, v100, v101
	v_cvt_pk_bf16_f32 v115, v102, v103
	v_cvt_pk_bf16_f32 v116, v112, v113
	v_lshlrev_b32_e32 v234, 16, v188
	v_cvt_pk_bf16_f32 v117, v94, v95
	global_store_dwordx4 v[118:119], v[114:117], off offset:256
	v_lshl_add_u64 v[118:119], v[98:99], 0, v[144:145]
	v_pk_add_f32 v[98:99], v[76:77], v[238:239]
	v_pk_add_f32 v[76:77], v[82:83], v[172:173]
	v_lshl_add_u64 v[82:83], s[10:11], 0, v[152:153]
	v_lshl_add_u64 v[122:123], v[82:83], 0, v[144:145]
	v_pk_add_f32 v[82:83], v[64:65], v[156:157]
	v_and_b32_e32 v65, 64, v174
	v_and_b32_e32 v235, 0xffff0000, v188
	v_lshlrev_b32_e32 v188, 16, v189
	v_and_b32_e32 v189, 0xffff0000, v189
	v_lshlrev_b32_e32 v236, 16, v190
	v_and_b32_e32 v237, 0xffff0000, v190
	v_pk_add_f32 v[96:97], v[96:97], v[232:233]
	v_xor_b32_e32 v64, 16, v174
	v_cvt_pk_bf16_f32 v114, v96, v97
	v_add_u32_e32 v65, 64, v65
	v_lshlrev_b32_e32 v190, 16, v191
	v_and_b32_e32 v191, 0xffff0000, v191
	v_lshlrev_b32_e32 v192, 16, v193
	v_and_b32_e32 v193, 0xffff0000, v193
	v_pk_add_f32 v[90:91], v[90:91], v[188:189]
	v_pk_add_f32 v[88:89], v[88:89], v[234:235]
	v_cvt_pk_bf16_f32 v115, v92, v93
	v_pk_add_f32 v[84:85], v[84:85], v[236:237]
	v_cvt_pk_bf16_f32 v116, v88, v89
	v_cvt_pk_bf16_f32 v117, v90, v91
	global_store_dwordx4 v[118:119], v[114:117], off
	v_cmp_lt_i32_e32 vcc, v64, v65
	v_lshlrev_b32_e32 v164, 16, v196
	v_cvt_pk_bf16_f32 v114, v84, v85
	v_and_b32_e32 v165, 0xffff0000, v196
	v_lshlrev_b32_e32 v168, 16, v197
	v_and_b32_e32 v169, 0xffff0000, v197
	v_pk_add_f32 v[86:87], v[86:87], v[190:191]
	v_pk_add_f32 v[78:79], v[78:79], v[192:193]
	v_cvt_pk_bf16_f32 v115, v86, v87
	v_cvt_pk_bf16_f32 v116, v98, v99
	v_pk_add_f32 v[80:81], v[80:81], v[166:167]
	v_cvt_pk_bf16_f32 v117, v78, v79
	global_store_dwordx4 v[118:119], v[114:117], off offset:256
	v_cndmask_b32_e32 v64, v174, v64, vcc
	v_pk_add_f32 v[74:75], v[74:75], v[168:169]
	v_cvt_pk_bf16_f32 v114, v80, v81
	v_pk_add_f32 v[72:73], v[72:73], v[164:165]
	v_cvt_pk_bf16_f32 v115, v76, v77
	v_lshlrev_b32_e32 v158, 16, v198
	v_cvt_pk_bf16_f32 v116, v72, v73
	v_cvt_pk_bf16_f32 v117, v74, v75
	global_store_dwordx4 v[122:123], v[114:117], off
	v_and_b32_e32 v159, 0xffff0000, v198
	v_lshlrev_b32_e32 v162, 16, v199
	v_lshlrev_b32_e32 v114, 2, v64
	ds_bpermute_b32 v64, v114, v126
	v_xor_b32_e32 v115, 32, v174
	v_cmp_lt_i32_e32 vcc, v115, v65
	v_and_b32_e32 v163, 0xffff0000, v199
	v_lshlrev_b32_e32 v160, 16, v201
	v_cndmask_b32_e32 v65, v174, v115, vcc
	v_lshlrev_b32_e32 v115, 2, v65
	s_waitcnt lgkmcnt(0)
	v_add_f32_e32 v116, v126, v64
	ds_bpermute_b32 v117, v115, v116
	v_and_b32_e32 v161, 0xffff0000, v201
	v_pk_add_f32 v[70:71], v[70:71], v[162:163]
	v_pk_add_f32 v[68:69], v[68:69], v[158:159]
	v_pk_add_f32 v[66:67], v[66:67], v[160:161]
	v_lshl_add_u64 v[64:65], v[150:151], 2, s[18:19]
	v_cvt_pk_bf16_f32 v118, v68, v69
	v_cvt_pk_bf16_f32 v119, v70, v71
	v_cvt_pk_bf16_f32 v120, v82, v83
	v_cvt_pk_bf16_f32 v121, v66, v67
	global_store_dwordx4 v[122:123], v[118:121], off offset:256
	s_and_saveexec_b64 s[36:37], s[6:7]
	s_cbranch_execz .LBB0_1025
	s_waitcnt lgkmcnt(0)
	v_add_f32_e32 v116, v116, v117
	global_atomic_add_f32 v[64:65], v116, off

.LBB0_1080:
	ds_read_b128 v[144:147], v151
	ds_read_b128 v[156:159], v151 offset:1024
	ds_read_b128 v[160:163], v151 offset:2048
	ds_read_b128 v[164:167], v151 offset:3072
	s_add_u32 s36, s2, 0xfffc0080
	s_addc_u32 s37, s3, -1
	s_cmp_eq_u32 s67, 12
	s_cselect_b32 s39, s29, s37
	s_cselect_b32 s38, s63, s36
	s_cselect_b32 s37, s27, s66
	s_cselect_b32 s36, s64, s65
	v_lshl_add_u64 v[172:173], s[2:3], 0, v[136:137]
	s_add_i32 m0, s48, 0xc000
	ds_read_b128 v[168:171], v152
	ds_read_b128 v[176:179], v152 offset:1024
	ds_read_b128 v[180:183], v152 offset:2048
	ds_read_b128 v[184:187], v152 offset:3072
	ds_read_b128 v[188:191], v152 offset:4096
	ds_read_b128 v[192:195], v152 offset:5120
	ds_read_b128 v[196:199], v152 offset:6144
	ds_read_b128 v[200:203], v152 offset:7168
	global_load_lds_dwordx4 v[172:173], off
	v_lshl_add_u64 v[172:173], s[2:3], 0, v[138:139]
	s_add_i32 m0, s48, 0xe000
	s_nop 0
	global_load_lds_dwordx4 v[172:173], off
	s_waitcnt lgkmcnt(8)
	s_waitcnt lgkmcnt(0)
	s_setprio 1
	s_barrier
	v_mfma_f32_16x16x32_bf16 v[124:127], v[144:147], v[168:171], v[124:127]
	v_mfma_f32_16x16x32_bf16 v[120:123], v[160:163], v[168:171], v[120:123]
	v_mfma_f32_16x16x32_bf16 v[116:119], v[144:147], v[180:183], v[116:119]
	v_mfma_f32_16x16x32_bf16 v[112:115], v[160:163], v[180:183], v[112:115]
	v_mfma_f32_16x16x32_bf16 v[104:107], v[144:147], v[188:191], v[104:107]
	v_mfma_f32_16x16x32_bf16 v[96:99], v[160:163], v[188:191], v[96:99]
	v_mfma_f32_16x16x32_bf16 v[76:79], v[144:147], v[196:199], v[76:79]
	v_mfma_f32_16x16x32_bf16 v[72:75], v[160:163], v[196:199], v[72:75]
	v_mfma_f32_16x16x32_bf16 v[124:127], v[156:159], v[176:179], v[124:127]
	v_mfma_f32_16x16x32_bf16 v[120:123], v[164:167], v[176:179], v[120:123]
	v_mfma_f32_16x16x32_bf16 v[116:119], v[156:159], v[184:187], v[116:119]
	v_mfma_f32_16x16x32_bf16 v[112:115], v[164:167], v[184:187], v[112:115]
	v_mfma_f32_16x16x32_bf16 v[104:107], v[156:159], v[192:195], v[104:107]
	v_mfma_f32_16x16x32_bf16 v[96:99], v[164:167], v[192:195], v[96:99]
	v_mfma_f32_16x16x32_bf16 v[76:79], v[156:159], v[200:203], v[76:79]
	v_mfma_f32_16x16x32_bf16 v[72:75], v[164:167], v[200:203], v[72:75]
	s_setprio 0
	s_barrier
	s_add_i32 s68, s56, s43
	v_lshl_add_u64 v[172:173], s[36:37], 0, v[130:131]
	s_mov_b32 m0, s68
	ds_read_b128 v[204:207], v153
	ds_read_b128 v[212:215], v153 offset:1024
	ds_read_b128 v[216:219], v153 offset:2048
	ds_read_b128 v[220:223], v153 offset:3072
	global_load_lds_dwordx4 v[172:173], off
	v_lshl_add_u64 v[208:209], s[36:37], 0, v[134:135]
	s_add_i32 m0, s68, 0x2000
	s_nop 0
	global_load_lds_dwordx4 v[208:209], off
	s_waitcnt lgkmcnt(0)
	s_setprio 1
	s_barrier
	v_mfma_f32_16x16x32_bf16 v[108:111], v[204:207], v[168:171], v[108:111]
	v_mfma_f32_16x16x32_bf16 v[100:103], v[216:219], v[168:171], v[100:103]
	v_mfma_f32_16x16x32_bf16 v[92:95], v[204:207], v[180:183], v[92:95]
	v_mfma_f32_16x16x32_bf16 v[88:91], v[216:219], v[180:183], v[88:91]
	v_mfma_f32_16x16x32_bf16 v[84:87], v[204:207], v[188:191], v[84:87]
	v_mfma_f32_16x16x32_bf16 v[80:83], v[216:219], v[188:191], v[80:83]
	v_mfma_f32_16x16x32_bf16 v[68:71], v[204:207], v[196:199], v[68:71]
	v_mfma_f32_16x16x32_bf16 v[64:67], v[216:219], v[196:199], v[64:67]
	v_mfma_f32_16x16x32_bf16 v[108:111], v[212:215], v[176:179], v[108:111]
	v_mfma_f32_16x16x32_bf16 v[100:103], v[220:223], v[176:179], v[100:103]
	v_mfma_f32_16x16x32_bf16 v[92:95], v[212:215], v[184:187], v[92:95]
	v_mfma_f32_16x16x32_bf16 v[88:91], v[220:223], v[184:187], v[88:91]
	v_mfma_f32_16x16x32_bf16 v[84:87], v[212:215], v[192:195], v[84:87]
	v_mfma_f32_16x16x32_bf16 v[80:83], v[220:223], v[192:195], v[80:83]
	v_mfma_f32_16x16x32_bf16 v[68:71], v[212:215], v[200:203], v[68:71]
	v_mfma_f32_16x16x32_bf16 v[64:67], v[220:223], v[200:203], v[64:67]
	s_setprio 0
	s_mov_b32 m0, s48
	v_lshl_add_u64 v[224:225], s[38:39], 0, v[128:129]
	s_barrier
	ds_read_b128 v[168:171], v152 offset:16384
	ds_read_b128 v[176:179], v152 offset:17408
	ds_read_b128 v[180:183], v152 offset:18432
	ds_read_b128 v[184:187], v152 offset:19456
	ds_read_b128 v[188:191], v152 offset:20480
	ds_read_b128 v[192:195], v152 offset:21504
	ds_read_b128 v[196:199], v152 offset:22528
	ds_read_b128 v[200:203], v152 offset:23552
	global_load_lds_dwordx4 v[224:225], off
	v_lshl_add_u64 v[226:227], s[38:39], 0, v[132:133]
	s_mov_b32 m0, s49
	s_nop 0
	global_load_lds_dwordx4 v[226:227], off
	s_waitcnt lgkmcnt(0)
	s_setprio 1
	s_barrier
	v_mfma_f32_16x16x32_bf16 v[60:63], v[144:147], v[168:171], v[60:63]
	v_mfma_f32_16x16x32_bf16 v[56:59], v[160:163], v[168:171], v[56:59]
	v_mfma_f32_16x16x32_bf16 v[44:47], v[144:147], v[180:183], v[44:47]
	v_mfma_f32_16x16x32_bf16 v[40:43], v[160:163], v[180:183], v[40:43]
	v_mfma_f32_16x16x32_bf16 v[28:31], v[144:147], v[188:191], v[28:31]
	v_mfma_f32_16x16x32_bf16 v[24:27], v[160:163], v[188:191], v[24:27]
	v_mfma_f32_16x16x32_bf16 v[12:15], v[144:147], v[196:199], v[12:15]
	v_mfma_f32_16x16x32_bf16 v[8:11], v[160:163], v[196:199], v[8:11]
	v_mfma_f32_16x16x32_bf16 v[60:63], v[156:159], v[176:179], v[60:63]
	v_mfma_f32_16x16x32_bf16 v[56:59], v[164:167], v[176:179], v[56:59]
	v_mfma_f32_16x16x32_bf16 v[44:47], v[156:159], v[184:187], v[44:47]
	v_mfma_f32_16x16x32_bf16 v[40:43], v[164:167], v[184:187], v[40:43]
	v_mfma_f32_16x16x32_bf16 v[28:31], v[156:159], v[192:195], v[28:31]
	v_mfma_f32_16x16x32_bf16 v[24:27], v[164:167], v[192:195], v[24:27]
	v_mfma_f32_16x16x32_bf16 v[12:15], v[156:159], v[200:203], v[12:15]
	v_mfma_f32_16x16x32_bf16 v[8:11], v[164:167], v[200:203], v[8:11]
	s_setprio 0
	s_barrier
	s_add_u32 s68, s36, 0x40000
	s_addc_u32 s69, s37, 0
	s_add_i32 s70, s57, s43
	v_lshl_add_u64 v[144:145], s[68:69], 0, v[130:131]
	s_mov_b32 m0, s70
	s_nop 0
	global_load_lds_dwordx4 v[144:145], off
	v_lshl_add_u64 v[144:145], s[68:69], 0, v[134:135]
	s_add_i32 m0, s70, 0x2000
	s_nop 0
	global_load_lds_dwordx4 v[144:145], off
	s_waitcnt vmcnt(6)
	s_setprio 1
	s_barrier
	v_mfma_f32_16x16x32_bf16 v[52:55], v[204:207], v[168:171], v[52:55]
	v_mfma_f32_16x16x32_bf16 v[48:51], v[216:219], v[168:171], v[48:51]
	v_mfma_f32_16x16x32_bf16 v[36:39], v[204:207], v[180:183], v[36:39]
	v_mfma_f32_16x16x32_bf16 v[32:35], v[216:219], v[180:183], v[32:35]
	v_mfma_f32_16x16x32_bf16 v[20:23], v[204:207], v[188:191], v[20:23]
	v_mfma_f32_16x16x32_bf16 v[16:19], v[216:219], v[188:191], v[16:19]
	v_mfma_f32_16x16x32_bf16 v[4:7], v[204:207], v[196:199], v[4:7]
	v_mfma_f32_16x16x32_bf16 v[0:3], v[216:219], v[196:199], v[0:3]
	v_mfma_f32_16x16x32_bf16 v[52:55], v[212:215], v[176:179], v[52:55]
	v_mfma_f32_16x16x32_bf16 v[48:51], v[220:223], v[176:179], v[48:51]
	v_mfma_f32_16x16x32_bf16 v[36:39], v[212:215], v[184:187], v[36:39]
	v_mfma_f32_16x16x32_bf16 v[32:35], v[220:223], v[184:187], v[32:35]
	v_mfma_f32_16x16x32_bf16 v[20:23], v[212:215], v[192:195], v[20:23]
	v_mfma_f32_16x16x32_bf16 v[16:19], v[220:223], v[192:195], v[16:19]
	v_mfma_f32_16x16x32_bf16 v[4:7], v[212:215], v[200:203], v[4:7]
	v_mfma_f32_16x16x32_bf16 v[0:3], v[220:223], v[200:203], v[0:3]
	s_setprio 0
	s_add_i32 s68, 0, 0x18000
	v_add_u32_e32 v155, s68, v149
	s_barrier
	ds_read_b128 v[144:147], v155
	ds_read_b128 v[156:159], v155 offset:1024
	ds_read_b128 v[160:163], v155 offset:2048
	ds_read_b128 v[164:167], v155 offset:3072
	s_add_u32 s38, s38, 0x40000
	s_addc_u32 s39, s39, 0
	s_mov_b32 m0, s50
	v_lshl_add_u64 v[204:205], s[38:39], 0, v[128:129]
	ds_read_b128 v[168:171], v152 offset:32768
	ds_read_b128 v[176:179], v152 offset:33792
	ds_read_b128 v[180:183], v152 offset:34816
	ds_read_b128 v[184:187], v152 offset:35840
	ds_read_b128 v[188:191], v152 offset:36864
	ds_read_b128 v[192:195], v152 offset:37888
	ds_read_b128 v[196:199], v152 offset:38912
	ds_read_b128 v[200:203], v152 offset:39936
	global_load_lds_dwordx4 v[204:205], off
	v_lshl_add_u64 v[204:205], s[38:39], 0, v[132:133]
	s_mov_b32 m0, s51
	s_nop 0
	global_load_lds_dwordx4 v[204:205], off
	s_waitcnt lgkmcnt(8)
	s_waitcnt lgkmcnt(0)
	s_setprio 1
	s_barrier
	v_mfma_f32_16x16x32_bf16 v[124:127], v[144:147], v[168:171], v[124:127]
	v_mfma_f32_16x16x32_bf16 v[120:123], v[160:163], v[168:171], v[120:123]
	v_mfma_f32_16x16x32_bf16 v[116:119], v[144:147], v[180:183], v[116:119]
	v_mfma_f32_16x16x32_bf16 v[112:115], v[160:163], v[180:183], v[112:115]
	v_mfma_f32_16x16x32_bf16 v[104:107], v[144:147], v[188:191], v[104:107]
	v_mfma_f32_16x16x32_bf16 v[96:99], v[160:163], v[188:191], v[96:99]
	v_mfma_f32_16x16x32_bf16 v[76:79], v[144:147], v[196:199], v[76:79]
	v_mfma_f32_16x16x32_bf16 v[72:75], v[160:163], v[196:199], v[72:75]
	v_mfma_f32_16x16x32_bf16 v[124:127], v[156:159], v[176:179], v[124:127]
	v_mfma_f32_16x16x32_bf16 v[120:123], v[164:167], v[176:179], v[120:123]
	v_mfma_f32_16x16x32_bf16 v[116:119], v[156:159], v[184:187], v[116:119]
	v_mfma_f32_16x16x32_bf16 v[112:115], v[164:167], v[184:187], v[112:115]
	v_mfma_f32_16x16x32_bf16 v[104:107], v[156:159], v[192:195], v[104:107]
	v_mfma_f32_16x16x32_bf16 v[96:99], v[164:167], v[192:195], v[96:99]
	v_mfma_f32_16x16x32_bf16 v[76:79], v[156:159], v[200:203], v[76:79]
	v_mfma_f32_16x16x32_bf16 v[72:75], v[164:167], v[200:203], v[72:75]
	s_setprio 0
	s_barrier
	s_add_i32 s38, 0, 0x1c000
	s_add_i32 s39, s68, s43
	v_add_u32_e32 v155, s38, v149
	v_lshl_add_u64 v[172:173], v[172:173], 0, s[8:9]
	s_mov_b32 m0, s39
	ds_read_b128 v[204:207], v155
	ds_read_b128 v[212:215], v155 offset:1024
	ds_read_b128 v[216:219], v155 offset:2048
	ds_read_b128 v[220:223], v155 offset:3072
	global_load_lds_dwordx4 v[172:173], off
	v_lshl_add_u64 v[172:173], v[208:209], 0, s[8:9]
	s_add_i32 m0, s39, 0x2000
	s_nop 0
	global_load_lds_dwordx4 v[172:173], off
	s_waitcnt lgkmcnt(0)
	s_setprio 1
	s_barrier
	v_mfma_f32_16x16x32_bf16 v[108:111], v[204:207], v[168:171], v[108:111]
	v_mfma_f32_16x16x32_bf16 v[100:103], v[216:219], v[168:171], v[100:103]
	v_mfma_f32_16x16x32_bf16 v[92:95], v[204:207], v[180:183], v[92:95]
	v_mfma_f32_16x16x32_bf16 v[88:91], v[216:219], v[180:183], v[88:91]
	v_mfma_f32_16x16x32_bf16 v[84:87], v[204:207], v[188:191], v[84:87]
	v_mfma_f32_16x16x32_bf16 v[80:83], v[216:219], v[188:191], v[80:83]
	v_mfma_f32_16x16x32_bf16 v[68:71], v[204:207], v[196:199], v[68:71]
	v_mfma_f32_16x16x32_bf16 v[64:67], v[216:219], v[196:199], v[64:67]
	v_mfma_f32_16x16x32_bf16 v[108:111], v[212:215], v[176:179], v[108:111]
	v_mfma_f32_16x16x32_bf16 v[100:103], v[220:223], v[176:179], v[100:103]
	v_mfma_f32_16x16x32_bf16 v[92:95], v[212:215], v[184:187], v[92:95]
	v_mfma_f32_16x16x32_bf16 v[88:91], v[220:223], v[184:187], v[88:91]
	v_mfma_f32_16x16x32_bf16 v[84:87], v[212:215], v[192:195], v[84:87]
	v_mfma_f32_16x16x32_bf16 v[80:83], v[220:223], v[192:195], v[80:83]
	v_mfma_f32_16x16x32_bf16 v[68:71], v[212:215], v[200:203], v[68:71]
	v_mfma_f32_16x16x32_bf16 v[64:67], v[220:223], v[200:203], v[64:67]
	s_setprio 0
	s_mov_b32 m0, s53
	v_lshl_add_u64 v[172:173], v[224:225], 0, s[8:9]
	s_barrier
	ds_read_b128 v[168:171], v152 offset:49152
	ds_read_b128 v[176:179], v152 offset:50176
	ds_read_b128 v[180:183], v152 offset:51200
	ds_read_b128 v[184:187], v152 offset:52224
	ds_read_b128 v[188:191], v152 offset:53248
	ds_read_b128 v[192:195], v152 offset:54272
	ds_read_b128 v[196:199], v152 offset:55296
	ds_read_b128 v[200:203], v152 offset:56320
	global_load_lds_dwordx4 v[172:173], off
	v_lshl_add_u64 v[172:173], v[226:227], 0, s[8:9]
	s_mov_b32 m0, s54
	s_nop 0
	global_load_lds_dwordx4 v[172:173], off
	s_waitcnt lgkmcnt(0)
	s_setprio 1
	s_barrier
	v_mfma_f32_16x16x32_bf16 v[60:63], v[144:147], v[168:171], v[60:63]
	v_mfma_f32_16x16x32_bf16 v[56:59], v[160:163], v[168:171], v[56:59]
	v_mfma_f32_16x16x32_bf16 v[44:47], v[144:147], v[180:183], v[44:47]
	v_mfma_f32_16x16x32_bf16 v[40:43], v[160:163], v[180:183], v[40:43]
	v_mfma_f32_16x16x32_bf16 v[28:31], v[144:147], v[188:191], v[28:31]
	v_mfma_f32_16x16x32_bf16 v[24:27], v[160:163], v[188:191], v[24:27]
	v_mfma_f32_16x16x32_bf16 v[12:15], v[144:147], v[196:199], v[12:15]
	v_mfma_f32_16x16x32_bf16 v[8:11], v[160:163], v[196:199], v[8:11]
	v_mfma_f32_16x16x32_bf16 v[60:63], v[156:159], v[176:179], v[60:63]
	v_mfma_f32_16x16x32_bf16 v[56:59], v[164:167], v[176:179], v[56:59]
	v_mfma_f32_16x16x32_bf16 v[44:47], v[156:159], v[184:187], v[44:47]
	v_mfma_f32_16x16x32_bf16 v[40:43], v[164:167], v[184:187], v[40:43]
	v_mfma_f32_16x16x32_bf16 v[28:31], v[156:159], v[192:195], v[28:31]
	v_mfma_f32_16x16x32_bf16 v[24:27], v[164:167], v[192:195], v[24:27]
	v_mfma_f32_16x16x32_bf16 v[12:15], v[156:159], v[200:203], v[12:15]
	v_mfma_f32_16x16x32_bf16 v[8:11], v[164:167], v[200:203], v[8:11]
	s_setprio 0
	s_barrier
	s_add_u32 s36, s36, 0x40080
	s_addc_u32 s37, s37, 0
	s_add_i32 s38, s38, s43
	v_lshl_add_u64 v[144:145], s[36:37], 0, v[130:131]
	s_mov_b32 m0, s38
	s_nop 0
	global_load_lds_dwordx4 v[144:145], off
	v_lshl_add_u64 v[144:145], s[36:37], 0, v[134:135]
	s_add_i32 m0, s38, 0x2000
	s_nop 0
	global_load_lds_dwordx4 v[144:145], off
	s_waitcnt vmcnt(6)
	s_setprio 1
	s_barrier
	v_mfma_f32_16x16x32_bf16 v[52:55], v[204:207], v[168:171], v[52:55]
	v_mfma_f32_16x16x32_bf16 v[48:51], v[216:219], v[168:171], v[48:51]
	v_mfma_f32_16x16x32_bf16 v[36:39], v[204:207], v[180:183], v[36:39]
	v_mfma_f32_16x16x32_bf16 v[32:35], v[216:219], v[180:183], v[32:35]
	v_mfma_f32_16x16x32_bf16 v[20:23], v[204:207], v[188:191], v[20:23]
	v_mfma_f32_16x16x32_bf16 v[16:19], v[216:219], v[188:191], v[16:19]
	v_mfma_f32_16x16x32_bf16 v[4:7], v[204:207], v[196:199], v[4:7]
	v_mfma_f32_16x16x32_bf16 v[0:3], v[216:219], v[196:199], v[0:3]
	v_mfma_f32_16x16x32_bf16 v[52:55], v[212:215], v[176:179], v[52:55]
	v_mfma_f32_16x16x32_bf16 v[48:51], v[220:223], v[176:179], v[48:51]
	v_mfma_f32_16x16x32_bf16 v[36:39], v[212:215], v[184:187], v[36:39]
	v_mfma_f32_16x16x32_bf16 v[32:35], v[220:223], v[184:187], v[32:35]
	v_mfma_f32_16x16x32_bf16 v[20:23], v[212:215], v[192:195], v[20:23]
	v_mfma_f32_16x16x32_bf16 v[16:19], v[220:223], v[192:195], v[16:19]
	v_mfma_f32_16x16x32_bf16 v[4:7], v[212:215], v[200:203], v[4:7]
	v_mfma_f32_16x16x32_bf16 v[0:3], v[220:223], v[200:203], v[0:3]
	s_setprio 0
	s_add_i32 s67, s67, 2
	s_add_u32 s2, s2, 0x100
	s_addc_u32 s3, s3, 0
	s_add_u32 s65, s65, 0x100
	s_addc_u32 s66, s66, 0
	s_cmp_gt_u32 s67, 13
	s_barrier
	s_cbranch_scc0 .LBB0_1080
	v_lshl_add_u32 v146, s0, 8, v148
	v_ashrrev_i32_e32 v147, 31, v146
	v_lshl_add_u64 v[144:145], v[146:147], 2, s[18:19]
	global_load_dword v155, v[144:145], off
	global_load_dword v164, v[144:145], off offset:64
	global_load_dword v165, v[144:145], off offset:128
	global_load_dword v166, v[144:145], off offset:192
	global_load_dword v167, v[144:145], off offset:512
	global_load_dword v168, v[144:145], off offset:576
	global_load_dword v169, v[144:145], off offset:640
	global_load_dword v170, v[144:145], off offset:704
	v_lshl_or_b32 v144, s1, 8, v150
	v_ashrrev_i32_e32 v145, 31, v144
	v_lshlrev_b64 v[160:161], 10, v[146:147]
	v_lshlrev_b64 v[162:163], 1, v[144:145]
	v_lshl_add_u64 v[144:145], s[92:93], 0, v[160:161]
	v_or_b32_e32 v156, 16, v146
	v_ashrrev_i32_e32 v157, 31, v156
	v_or_b32_e32 v158, 32, v146
	v_lshlrev_b64 v[156:157], 10, v[156:157]
	v_lshl_add_u64 v[144:145], v[144:145], 0, v[162:163]
	v_ashrrev_i32_e32 v159, 31, v158
	v_lshl_add_u64 v[156:157], s[92:93], 0, v[156:157]
	v_lshlrev_b64 v[158:159], 10, v[158:159]
	v_lshl_add_u64 v[156:157], v[156:157], 0, v[162:163]
	v_lshl_add_u64 v[158:159], s[92:93], 0, v[158:159]
	v_lshl_add_u64 v[158:159], v[158:159], 0, v[162:163]
	s_mov_b64 s[36:37], s[34:35]
	s_waitcnt vmcnt(0)
	v_fmamk_f32 v147, v155, 0x3a800000, v154
	v_fmamk_f32 v155, v164, 0x3a800000, v154
	v_fmamk_f32 v160, v165, 0x3a800000, v154
	v_mul_f32_e32 v161, 0x4b800000, v147
	v_mul_f32_e32 v164, 0x4b800000, v155
	v_cmp_gt_f32_e32 vcc, s58, v147
	v_cmp_gt_f32_e64 s[0:1], s58, v155
	v_mul_f32_e32 v165, 0x4b800000, v160
	v_cndmask_b32_e32 v147, v147, v161, vcc
	v_cndmask_b32_e64 v155, v155, v164, s[0:1]
	v_cmp_gt_f32_e64 s[2:3], s58, v160
	v_rsq_f32_e32 v147, v147
	v_rsq_f32_e32 v155, v155
	v_cndmask_b32_e64 v160, v160, v165, s[2:3]
	v_rsq_f32_e32 v160, v160
	v_mul_f32_e32 v161, 0x45800000, v147
	v_mul_f32_e32 v164, 0x45800000, v155
	v_cndmask_b32_e32 v147, v147, v161, vcc
	v_mul_f32_e32 v165, 0x45800000, v160
	v_cndmask_b32_e64 v155, v155, v164, s[0:1]
	v_cndmask_b32_e64 v161, v160, v165, s[2:3]
	v_mul_f32_e32 v160, 0x3e0293ee, v147
	v_mul_f32_e32 v164, 0x3e0293ee, v155
	v_fmamk_f32 v171, v166, 0x3a800000, v154
	v_mul_f32_e32 v166, 0x3e0293ee, v161
	v_pk_mul_f32 v[126:127], v[126:127], v[160:161] op_sel_hi:[1,0]
	v_pk_mul_f32 v[124:125], v[124:125], v[160:161] op_sel_hi:[1,0]
	v_pk_mul_f32 v[122:123], v[122:123], v[160:161] op_sel_hi:[1,0]
	v_pk_mul_f32 v[120:121], v[120:121], v[160:161] op_sel_hi:[1,0]
	v_pk_mul_f32 v[110:111], v[110:111], v[160:161] op_sel_hi:[1,0]
	v_pk_mul_f32 v[108:109], v[108:109], v[160:161] op_sel_hi:[1,0]
	v_pk_mul_f32 v[102:103], v[102:103], v[160:161] op_sel_hi:[1,0]
	v_pk_mul_f32 v[100:101], v[100:101], v[160:161] op_sel_hi:[1,0]
	v_pk_mul_f32 v[118:119], v[118:119], v[164:165] op_sel_hi:[1,0]
	v_pk_mul_f32 v[116:117], v[116:117], v[164:165] op_sel_hi:[1,0]
	v_pk_mul_f32 v[114:115], v[114:115], v[164:165] op_sel_hi:[1,0]
	v_pk_mul_f32 v[112:113], v[112:113], v[164:165] op_sel_hi:[1,0]
	v_pk_mul_f32 v[94:95], v[94:95], v[164:165] op_sel_hi:[1,0]
	v_pk_mul_f32 v[92:93], v[92:93], v[164:165] op_sel_hi:[1,0]
	v_pk_mul_f32 v[160:161], v[90:91], v[164:165] op_sel_hi:[1,0]
	v_pk_mul_f32 v[164:165], v[88:89], v[164:165] op_sel_hi:[1,0]
	v_cvt_pk_bf16_f32 v88, v124, v125
	v_cvt_pk_bf16_f32 v89, v126, v127
	v_cvt_pk_bf16_f32 v90, v120, v121
	v_cvt_pk_bf16_f32 v91, v122, v123
	global_store_dwordx4 v[144:145], v[88:91], off
	v_fmamk_f32 v167, v167, 0x3a800000, v154
	v_pk_mul_f32 v[106:107], v[106:107], v[166:167] op_sel_hi:[1,0]
	v_cvt_pk_bf16_f32 v88, v108, v109
	v_cvt_pk_bf16_f32 v89, v110, v111
	v_cvt_pk_bf16_f32 v90, v100, v101
	v_cvt_pk_bf16_f32 v91, v102, v103
	global_store_dwordx4 v[144:145], v[88:91], off offset:256
	v_pk_mul_f32 v[104:105], v[104:105], v[166:167] op_sel_hi:[1,0]
	v_pk_mul_f32 v[98:99], v[98:99], v[166:167] op_sel_hi:[1,0]
	v_cvt_pk_bf16_f32 v88, v116, v117
	v_cvt_pk_bf16_f32 v89, v118, v119
	v_cvt_pk_bf16_f32 v90, v112, v113
	v_cvt_pk_bf16_f32 v91, v114, v115
	global_store_dwordx4 v[156:157], v[88:91], off
	v_pk_mul_f32 v[96:97], v[96:97], v[166:167] op_sel_hi:[1,0]
	v_pk_mul_f32 v[86:87], v[86:87], v[166:167] op_sel_hi:[1,0]
	v_cvt_pk_bf16_f32 v88, v92, v93
	v_cvt_pk_bf16_f32 v89, v94, v95
	v_cvt_pk_bf16_f32 v90, v164, v165
	v_cvt_pk_bf16_f32 v91, v160, v161
	global_store_dwordx4 v[156:157], v[88:91], off offset:256
	v_pk_mul_f32 v[84:85], v[84:85], v[166:167] op_sel_hi:[1,0]
	v_cmp_gt_f32_e32 vcc, s58, v171
	v_cvt_pk_bf16_f32 v88, v104, v105
	v_cvt_pk_bf16_f32 v89, v106, v107
	v_cvt_pk_bf16_f32 v90, v96, v97
	v_cvt_pk_bf16_f32 v91, v98, v99
	global_store_dwordx4 v[158:159], v[88:91], off
	v_fmamk_f32 v168, v168, 0x3a800000, v154
	v_fmamk_f32 v169, v169, 0x3a800000, v154
	v_pk_mul_f32 v[88:89], v[82:83], v[166:167] op_sel_hi:[1,0]
	v_pk_mul_f32 v[82:83], v[80:81], v[166:167] op_sel_hi:[1,0]
	v_cvt_pk_bf16_f32 v80, v84, v85
	v_cvt_pk_bf16_f32 v81, v86, v87
	v_fmamk_f32 v170, v170, 0x3a800000, v154
	v_cvt_pk_bf16_f32 v82, v82, v83
	v_cvt_pk_bf16_f32 v83, v88, v89
	global_store_dwordx4 v[158:159], v[80:83], off offset:256
	s_mov_b32 s1, s26
	s_mov_b32 s0, s28
	v_mul_f32_e32 v82, 0x4b800000, v171
	v_cndmask_b32_e32 v82, v171, v82, vcc
	v_rsq_f32_e32 v82, v82
	v_or_b32_e32 v80, 48, v146
	v_ashrrev_i32_e32 v81, 31, v80
	v_lshlrev_b64 v[80:81], 10, v[80:81]
	v_mul_f32_e32 v83, 0x45800000, v82
	v_cndmask_b32_e32 v82, v82, v83, vcc
	v_lshl_add_u64 v[80:81], s[92:93], 0, v[80:81]
	v_mul_f32_e32 v82, 0x3e0293ee, v82
	v_lshl_add_u64 v[80:81], v[80:81], 0, v[162:163]
	v_pk_mul_f32 v[78:79], v[78:79], v[82:83] op_sel_hi:[1,0]
	v_pk_mul_f32 v[76:77], v[76:77], v[82:83] op_sel_hi:[1,0]
	v_pk_mul_f32 v[84:85], v[74:75], v[82:83] op_sel_hi:[1,0]
	v_pk_mul_f32 v[74:75], v[72:73], v[82:83] op_sel_hi:[1,0]
	v_cvt_pk_bf16_f32 v72, v76, v77
	v_cvt_pk_bf16_f32 v73, v78, v79
	v_pk_mul_f32 v[70:71], v[70:71], v[82:83] op_sel_hi:[1,0]
	v_cvt_pk_bf16_f32 v74, v74, v75
	v_cvt_pk_bf16_f32 v75, v84, v85
	global_store_dwordx4 v[80:81], v[72:75], off
	v_pk_mul_f32 v[68:69], v[68:69], v[82:83] op_sel_hi:[1,0]
	v_cmp_gt_f32_e32 vcc, s58, v167
	v_pk_mul_f32 v[72:73], v[66:67], v[82:83] op_sel_hi:[1,0]
	v_pk_mul_f32 v[66:67], v[64:65], v[82:83] op_sel_hi:[1,0]
	v_cvt_pk_bf16_f32 v64, v68, v69
	v_cvt_pk_bf16_f32 v65, v70, v71
	s_mov_b64 s[2:3], s[30:31]
	v_cvt_pk_bf16_f32 v66, v66, v67
	v_mul_f32_e32 v67, 0x4b800000, v167
	v_cndmask_b32_e32 v67, v167, v67, vcc
	v_rsq_f32_e32 v68, v67
	v_cvt_pk_bf16_f32 v67, v72, v73
	global_store_dwordx4 v[80:81], v[64:67], off offset:256
	s_nop 1
	v_mul_f32_e32 v66, 0x45800000, v68
	v_cndmask_b32_e32 v66, v68, v66, vcc
	v_mul_f32_e32 v66, 0x3e0293ee, v66
	v_pk_mul_f32 v[60:61], v[60:61], v[66:67] op_sel_hi:[1,0]
	v_pk_mul_f32 v[68:69], v[58:59], v[66:67] op_sel_hi:[1,0]
	v_pk_mul_f32 v[58:59], v[56:57], v[66:67] op_sel_hi:[1,0]
	v_cvt_pk_bf16_f32 v56, v60, v61
	v_add_co_u32_e32 v60, vcc, s59, v144
	v_pk_mul_f32 v[62:63], v[62:63], v[66:67] op_sel_hi:[1,0]
	s_nop 0
	v_addc_co_u32_e32 v61, vcc, 0, v145, vcc
	v_cvt_pk_bf16_f32 v57, v62, v63
	v_cvt_pk_bf16_f32 v58, v58, v59
	v_cvt_pk_bf16_f32 v59, v68, v69
	global_store_dwordx4 v[60:61], v[56:59], off
	v_pk_mul_f32 v[54:55], v[54:55], v[66:67] op_sel_hi:[1,0]
	v_pk_mul_f32 v[52:53], v[52:53], v[66:67] op_sel_hi:[1,0]
	v_pk_mul_f32 v[56:57], v[50:51], v[66:67] op_sel_hi:[1,0]
	v_pk_mul_f32 v[50:51], v[48:49], v[66:67] op_sel_hi:[1,0]
	v_cvt_pk_bf16_f32 v48, v52, v53
	v_cvt_pk_bf16_f32 v49, v54, v55
	v_cmp_gt_f32_e32 vcc, s58, v168
	v_cvt_pk_bf16_f32 v50, v50, v51
	v_mul_f32_e32 v51, 0x4b800000, v168
	v_lshl_add_u64 v[64:65], v[144:145], 0, s[14:15]
	v_cndmask_b32_e32 v51, v168, v51, vcc
	v_rsq_f32_e32 v52, v51
	v_cvt_pk_bf16_f32 v51, v56, v57
	global_store_dwordx4 v[64:65], v[48:51], off offset:256
	s_nop 1
	v_mul_f32_e32 v50, 0x45800000, v52
	v_cndmask_b32_e32 v50, v52, v50, vcc
	v_mul_f32_e32 v50, 0x3e0293ee, v50
	v_pk_mul_f32 v[44:45], v[44:45], v[50:51] op_sel_hi:[1,0]
	v_pk_mul_f32 v[52:53], v[42:43], v[50:51] op_sel_hi:[1,0]
	v_pk_mul_f32 v[42:43], v[40:41], v[50:51] op_sel_hi:[1,0]
	v_cvt_pk_bf16_f32 v40, v44, v45
	v_add_co_u32_e32 v44, vcc, s60, v144
	v_pk_mul_f32 v[46:47], v[46:47], v[50:51] op_sel_hi:[1,0]
	s_nop 0
	v_addc_co_u32_e32 v45, vcc, 0, v145, vcc
	v_cvt_pk_bf16_f32 v41, v46, v47
	v_cvt_pk_bf16_f32 v42, v42, v43
	v_cvt_pk_bf16_f32 v43, v52, v53
	global_store_dwordx4 v[44:45], v[40:43], off
	v_pk_mul_f32 v[38:39], v[38:39], v[50:51] op_sel_hi:[1,0]
	v_pk_mul_f32 v[36:37], v[36:37], v[50:51] op_sel_hi:[1,0]
	v_pk_mul_f32 v[40:41], v[34:35], v[50:51] op_sel_hi:[1,0]
	v_pk_mul_f32 v[34:35], v[32:33], v[50:51] op_sel_hi:[1,0]
	v_cvt_pk_bf16_f32 v32, v36, v37
	v_cvt_pk_bf16_f32 v33, v38, v39
	v_cmp_gt_f32_e32 vcc, s58, v169
	v_cvt_pk_bf16_f32 v34, v34, v35
	v_mul_f32_e32 v35, 0x4b800000, v169
	v_lshl_add_u64 v[48:49], v[144:145], 0, s[20:21]
	v_cndmask_b32_e32 v35, v169, v35, vcc
	v_rsq_f32_e32 v36, v35
	v_cvt_pk_bf16_f32 v35, v40, v41
	global_store_dwordx4 v[48:49], v[32:35], off offset:256
	s_nop 1
	v_mul_f32_e32 v34, 0x45800000, v36
	v_cndmask_b32_e32 v34, v36, v34, vcc
	v_mul_f32_e32 v34, 0x3e0293ee, v34
	v_pk_mul_f32 v[28:29], v[28:29], v[34:35] op_sel_hi:[1,0]
	v_pk_mul_f32 v[36:37], v[26:27], v[34:35] op_sel_hi:[1,0]
	v_pk_mul_f32 v[26:27], v[24:25], v[34:35] op_sel_hi:[1,0]
	v_cvt_pk_bf16_f32 v24, v28, v29
	v_add_co_u32_e32 v28, vcc, s61, v144
	v_pk_mul_f32 v[30:31], v[30:31], v[34:35] op_sel_hi:[1,0]
	s_nop 0
	v_addc_co_u32_e32 v29, vcc, 0, v145, vcc
	v_cvt_pk_bf16_f32 v25, v30, v31
	v_cvt_pk_bf16_f32 v26, v26, v27
	v_cvt_pk_bf16_f32 v27, v36, v37
	global_store_dwordx4 v[28:29], v[24:27], off
	v_pk_mul_f32 v[22:23], v[22:23], v[34:35] op_sel_hi:[1,0]
	v_pk_mul_f32 v[20:21], v[20:21], v[34:35] op_sel_hi:[1,0]
	v_pk_mul_f32 v[24:25], v[18:19], v[34:35] op_sel_hi:[1,0]
	v_pk_mul_f32 v[18:19], v[16:17], v[34:35] op_sel_hi:[1,0]
	v_cvt_pk_bf16_f32 v16, v20, v21
	v_cvt_pk_bf16_f32 v17, v22, v23
	v_cmp_gt_f32_e32 vcc, s58, v170
	v_cvt_pk_bf16_f32 v18, v18, v19
	v_mul_f32_e32 v19, 0x4b800000, v170
	v_lshl_add_u64 v[32:33], v[144:145], 0, s[22:23]
	v_cndmask_b32_e32 v19, v170, v19, vcc
	v_rsq_f32_e32 v20, v19
	v_cvt_pk_bf16_f32 v19, v24, v25
	global_store_dwordx4 v[32:33], v[16:19], off offset:256
	s_nop 1
	v_mul_f32_e32 v18, 0x45800000, v20
	v_cndmask_b32_e32 v18, v20, v18, vcc
	v_mul_f32_e32 v18, 0x3e0293ee, v18
	v_pk_mul_f32 v[12:13], v[12:13], v[18:19] op_sel_hi:[1,0]
	v_pk_mul_f32 v[20:21], v[10:11], v[18:19] op_sel_hi:[1,0]
	v_pk_mul_f32 v[10:11], v[8:9], v[18:19] op_sel_hi:[1,0]
	v_cvt_pk_bf16_f32 v8, v12, v13
	v_add_co_u32_e32 v12, vcc, s62, v144
	v_pk_mul_f32 v[14:15], v[14:15], v[18:19] op_sel_hi:[1,0]
	s_nop 0
	v_addc_co_u32_e32 v13, vcc, 0, v145, vcc
	v_cvt_pk_bf16_f32 v9, v14, v15
	v_lshl_add_u64 v[16:17], v[144:145], 0, s[24:25]
	v_cvt_pk_bf16_f32 v10, v10, v11
	v_cvt_pk_bf16_f32 v11, v20, v21
	global_store_dwordx4 v[12:13], v[8:11], off
	s_and_b64 vcc, exec, s[6:7]
	v_pk_mul_f32 v[6:7], v[6:7], v[18:19] op_sel_hi:[1,0]
	v_pk_mul_f32 v[8:9], v[2:3], v[18:19] op_sel_hi:[1,0]
	v_pk_mul_f32 v[2:3], v[0:1], v[18:19] op_sel_hi:[1,0]
	v_pk_mul_f32 v[4:5], v[4:5], v[18:19] op_sel_hi:[1,0]
	s_nop 0
	v_cvt_pk_bf16_f32 v0, v4, v5
	v_cvt_pk_bf16_f32 v1, v6, v7
	v_cvt_pk_bf16_f32 v2, v2, v3
	v_cvt_pk_bf16_f32 v3, v8, v9
	global_store_dwordx4 v[16:17], v[0:3], off offset:256
	s_cbranch_vccz .LBB0_1073
	s_waitcnt vmcnt(0)
	s_cmpk_gt_u32 s33, 0xff
	s_cbranch_scc1 .LBB0_1084
	s_barrier

.LBB0_1160:
	ds_read_b128 v[144:147], v178
	ds_read_b128 v[148:151], v178 offset:1024
	ds_read_b128 v[152:155], v178 offset:2048
	ds_read_b128 v[156:159], v178 offset:3072
	s_add_u32 s38, s36, 0xfffe0080
	s_addc_u32 s39, s37, -1
	s_cmp_eq_u32 s62, 4
	s_cselect_b32 s41, s25, s39
	s_cselect_b32 s40, s31, s38
	s_cselect_b32 s39, s23, s61
	s_cselect_b32 s38, s59, s60
	v_lshl_add_u64 v[172:173], s[36:37], 0, v[136:137]
	s_add_i32 m0, s35, 0xc000
	ds_read_b128 v[160:163], v179
	ds_read_b128 v[164:167], v179 offset:1024
	ds_read_b128 v[168:171], v179 offset:2048
	ds_read_b128 v[182:185], v179 offset:3072
	ds_read_b128 v[186:189], v179 offset:4096
	ds_read_b128 v[190:193], v179 offset:5120
	ds_read_b128 v[194:197], v179 offset:6144
	ds_read_b128 v[198:201], v179 offset:7168
	global_load_lds_dwordx4 v[172:173], off
	v_lshl_add_u64 v[172:173], s[36:37], 0, v[138:139]
	s_add_i32 m0, s35, 0xe000
	s_nop 0
	global_load_lds_dwordx4 v[172:173], off
	s_waitcnt lgkmcnt(8)
	s_waitcnt lgkmcnt(0)
	s_setprio 1
	s_barrier
	v_mfma_f32_16x16x32_bf16 v[124:127], v[144:147], v[160:163], v[124:127]
	v_mfma_f32_16x16x32_bf16 v[120:123], v[152:155], v[160:163], v[120:123]
	v_mfma_f32_16x16x32_bf16 v[108:111], v[144:147], v[168:171], v[108:111]
	v_mfma_f32_16x16x32_bf16 v[104:107], v[152:155], v[168:171], v[104:107]
	v_mfma_f32_16x16x32_bf16 v[96:99], v[144:147], v[186:189], v[96:99]
	v_mfma_f32_16x16x32_bf16 v[88:91], v[152:155], v[186:189], v[88:91]
	v_mfma_f32_16x16x32_bf16 v[80:83], v[144:147], v[194:197], v[80:83]
	v_mfma_f32_16x16x32_bf16 v[72:75], v[152:155], v[194:197], v[72:75]
	v_mfma_f32_16x16x32_bf16 v[124:127], v[148:151], v[164:167], v[124:127]
	v_mfma_f32_16x16x32_bf16 v[120:123], v[156:159], v[164:167], v[120:123]
	v_mfma_f32_16x16x32_bf16 v[108:111], v[148:151], v[182:185], v[108:111]
	v_mfma_f32_16x16x32_bf16 v[104:107], v[156:159], v[182:185], v[104:107]
	v_mfma_f32_16x16x32_bf16 v[96:99], v[148:151], v[190:193], v[96:99]
	v_mfma_f32_16x16x32_bf16 v[88:91], v[156:159], v[190:193], v[88:91]
	v_mfma_f32_16x16x32_bf16 v[80:83], v[148:151], v[198:201], v[80:83]
	v_mfma_f32_16x16x32_bf16 v[72:75], v[156:159], v[198:201], v[72:75]
	s_setprio 0
	s_barrier
	s_add_i32 s63, s57, s48
	v_lshl_add_u64 v[172:173], s[38:39], 0, v[130:131]
	s_mov_b32 m0, s63
	ds_read_b128 v[202:205], v180
	ds_read_b128 v[206:209], v180 offset:1024
	ds_read_b128 v[212:215], v180 offset:2048
	ds_read_b128 v[216:219], v180 offset:3072
	global_load_lds_dwordx4 v[172:173], off
	v_lshl_add_u64 v[220:221], s[38:39], 0, v[134:135]
	s_add_i32 m0, s63, 0x2000
	s_nop 0
	global_load_lds_dwordx4 v[220:221], off
	s_waitcnt lgkmcnt(0)
	s_setprio 1
	s_barrier
	v_mfma_f32_16x16x32_bf16 v[116:119], v[202:205], v[160:163], v[116:119]
	v_mfma_f32_16x16x32_bf16 v[112:115], v[212:215], v[160:163], v[112:115]
	v_mfma_f32_16x16x32_bf16 v[100:103], v[202:205], v[168:171], v[100:103]
	v_mfma_f32_16x16x32_bf16 v[92:95], v[212:215], v[168:171], v[92:95]
	v_mfma_f32_16x16x32_bf16 v[84:87], v[202:205], v[186:189], v[84:87]
	v_mfma_f32_16x16x32_bf16 v[76:79], v[212:215], v[186:189], v[76:79]
	v_mfma_f32_16x16x32_bf16 v[68:71], v[202:205], v[194:197], v[68:71]
	v_mfma_f32_16x16x32_bf16 v[64:67], v[212:215], v[194:197], v[64:67]
	v_mfma_f32_16x16x32_bf16 v[116:119], v[206:209], v[164:167], v[116:119]
	v_mfma_f32_16x16x32_bf16 v[112:115], v[216:219], v[164:167], v[112:115]
	v_mfma_f32_16x16x32_bf16 v[100:103], v[206:209], v[182:185], v[100:103]
	v_mfma_f32_16x16x32_bf16 v[92:95], v[216:219], v[182:185], v[92:95]
	v_mfma_f32_16x16x32_bf16 v[84:87], v[206:209], v[190:193], v[84:87]
	v_mfma_f32_16x16x32_bf16 v[76:79], v[216:219], v[190:193], v[76:79]
	v_mfma_f32_16x16x32_bf16 v[68:71], v[206:209], v[198:201], v[68:71]
	v_mfma_f32_16x16x32_bf16 v[64:67], v[216:219], v[198:201], v[64:67]
	s_setprio 0
	s_mov_b32 m0, s35
	v_lshl_add_u64 v[222:223], s[40:41], 0, v[128:129]
	s_barrier
	ds_read_b128 v[160:163], v179 offset:16384
	ds_read_b128 v[164:167], v179 offset:17408
	ds_read_b128 v[168:171], v179 offset:18432
	ds_read_b128 v[182:185], v179 offset:19456
	ds_read_b128 v[186:189], v179 offset:20480
	ds_read_b128 v[190:193], v179 offset:21504
	ds_read_b128 v[194:197], v179 offset:22528
	ds_read_b128 v[198:201], v179 offset:23552
	global_load_lds_dwordx4 v[222:223], off
	v_lshl_add_u64 v[224:225], s[40:41], 0, v[132:133]
	s_mov_b32 m0, s49
	s_nop 0
	global_load_lds_dwordx4 v[224:225], off
	s_waitcnt lgkmcnt(0)
	s_setprio 1
	s_barrier
	v_mfma_f32_16x16x32_bf16 v[60:63], v[144:147], v[160:163], v[60:63]
	v_mfma_f32_16x16x32_bf16 v[56:59], v[152:155], v[160:163], v[56:59]
	v_mfma_f32_16x16x32_bf16 v[44:47], v[144:147], v[168:171], v[44:47]
	v_mfma_f32_16x16x32_bf16 v[40:43], v[152:155], v[168:171], v[40:43]
	v_mfma_f32_16x16x32_bf16 v[32:35], v[144:147], v[186:189], v[32:35]
	v_mfma_f32_16x16x32_bf16 v[24:27], v[152:155], v[186:189], v[24:27]
	v_mfma_f32_16x16x32_bf16 v[16:19], v[144:147], v[194:197], v[16:19]
	v_mfma_f32_16x16x32_bf16 v[8:11], v[152:155], v[194:197], v[8:11]
	v_mfma_f32_16x16x32_bf16 v[60:63], v[148:151], v[164:167], v[60:63]
	v_mfma_f32_16x16x32_bf16 v[56:59], v[156:159], v[164:167], v[56:59]
	v_mfma_f32_16x16x32_bf16 v[44:47], v[148:151], v[182:185], v[44:47]
	v_mfma_f32_16x16x32_bf16 v[40:43], v[156:159], v[182:185], v[40:43]
	v_mfma_f32_16x16x32_bf16 v[32:35], v[148:151], v[190:193], v[32:35]
	v_mfma_f32_16x16x32_bf16 v[24:27], v[156:159], v[190:193], v[24:27]
	v_mfma_f32_16x16x32_bf16 v[16:19], v[148:151], v[198:201], v[16:19]
	v_mfma_f32_16x16x32_bf16 v[8:11], v[156:159], v[198:201], v[8:11]
	s_setprio 0
	s_barrier
	s_add_u32 s64, s38, 0x20000
	s_addc_u32 s65, s39, 0
	s_add_i32 s63, s58, s48
	v_lshl_add_u64 v[144:145], s[64:65], 0, v[130:131]
	s_mov_b32 m0, s63
	s_nop 0
	global_load_lds_dwordx4 v[144:145], off
	v_lshl_add_u64 v[144:145], s[64:65], 0, v[134:135]
	s_add_i32 m0, s63, 0x2000
	s_nop 0
	global_load_lds_dwordx4 v[144:145], off
	s_waitcnt vmcnt(6)
	s_setprio 1
	s_barrier
	v_mfma_f32_16x16x32_bf16 v[52:55], v[202:205], v[160:163], v[52:55]
	v_mfma_f32_16x16x32_bf16 v[48:51], v[212:215], v[160:163], v[48:51]
	v_mfma_f32_16x16x32_bf16 v[36:39], v[202:205], v[168:171], v[36:39]
	v_mfma_f32_16x16x32_bf16 v[28:31], v[212:215], v[168:171], v[28:31]
	v_mfma_f32_16x16x32_bf16 v[20:23], v[202:205], v[186:189], v[20:23]
	v_mfma_f32_16x16x32_bf16 v[12:15], v[212:215], v[186:189], v[12:15]
	v_mfma_f32_16x16x32_bf16 v[4:7], v[202:205], v[194:197], v[4:7]
	v_mfma_f32_16x16x32_bf16 v[0:3], v[212:215], v[194:197], v[0:3]
	v_mfma_f32_16x16x32_bf16 v[52:55], v[206:209], v[164:167], v[52:55]
	v_mfma_f32_16x16x32_bf16 v[48:51], v[216:219], v[164:167], v[48:51]
	v_mfma_f32_16x16x32_bf16 v[36:39], v[206:209], v[182:185], v[36:39]
	v_mfma_f32_16x16x32_bf16 v[28:31], v[216:219], v[182:185], v[28:31]
	v_mfma_f32_16x16x32_bf16 v[20:23], v[206:209], v[190:193], v[20:23]
	v_mfma_f32_16x16x32_bf16 v[12:15], v[216:219], v[190:193], v[12:15]
	v_mfma_f32_16x16x32_bf16 v[4:7], v[206:209], v[198:201], v[4:7]
	v_mfma_f32_16x16x32_bf16 v[0:3], v[216:219], v[198:201], v[0:3]
	s_setprio 0
	s_add_i32 s63, 0, 0x18000
	v_add_u32_e32 v156, s63, v176
	s_barrier
	ds_read_b128 v[144:147], v156
	ds_read_b128 v[148:151], v156 offset:1024
	ds_read_b128 v[152:155], v156 offset:2048
	ds_read_b128 v[156:159], v156 offset:3072
	s_add_u32 s40, s40, 0x20000
	s_addc_u32 s41, s41, 0
	s_mov_b32 m0, s50
	v_lshl_add_u64 v[202:203], s[40:41], 0, v[128:129]
	ds_read_b128 v[160:163], v179 offset:32768
	ds_read_b128 v[164:167], v179 offset:33792
	ds_read_b128 v[168:171], v179 offset:34816
	ds_read_b128 v[182:185], v179 offset:35840
	ds_read_b128 v[186:189], v179 offset:36864
	ds_read_b128 v[190:193], v179 offset:37888
	ds_read_b128 v[194:197], v179 offset:38912
	ds_read_b128 v[198:201], v179 offset:39936
	global_load_lds_dwordx4 v[202:203], off
	v_lshl_add_u64 v[202:203], s[40:41], 0, v[132:133]
	s_mov_b32 m0, s51
	s_nop 0
	global_load_lds_dwordx4 v[202:203], off
	s_waitcnt lgkmcnt(8)
	s_waitcnt lgkmcnt(0)
	s_setprio 1
	s_barrier
	v_mfma_f32_16x16x32_bf16 v[124:127], v[144:147], v[160:163], v[124:127]
	v_mfma_f32_16x16x32_bf16 v[120:123], v[152:155], v[160:163], v[120:123]
	v_mfma_f32_16x16x32_bf16 v[108:111], v[144:147], v[168:171], v[108:111]
	v_mfma_f32_16x16x32_bf16 v[104:107], v[152:155], v[168:171], v[104:107]
	v_mfma_f32_16x16x32_bf16 v[96:99], v[144:147], v[186:189], v[96:99]
	v_mfma_f32_16x16x32_bf16 v[88:91], v[152:155], v[186:189], v[88:91]
	v_mfma_f32_16x16x32_bf16 v[80:83], v[144:147], v[194:197], v[80:83]
	v_mfma_f32_16x16x32_bf16 v[72:75], v[152:155], v[194:197], v[72:75]
	v_mfma_f32_16x16x32_bf16 v[124:127], v[148:151], v[164:167], v[124:127]
	v_mfma_f32_16x16x32_bf16 v[120:123], v[156:159], v[164:167], v[120:123]
	v_mfma_f32_16x16x32_bf16 v[108:111], v[148:151], v[182:185], v[108:111]
	v_mfma_f32_16x16x32_bf16 v[104:107], v[156:159], v[182:185], v[104:107]
	v_mfma_f32_16x16x32_bf16 v[96:99], v[148:151], v[190:193], v[96:99]
	v_mfma_f32_16x16x32_bf16 v[88:91], v[156:159], v[190:193], v[88:91]
	v_mfma_f32_16x16x32_bf16 v[80:83], v[148:151], v[198:201], v[80:83]
	v_mfma_f32_16x16x32_bf16 v[72:75], v[156:159], v[198:201], v[72:75]
	s_setprio 0
	s_barrier
	s_add_i32 s40, 0, 0x1c000
	s_add_i32 s41, s63, s48
	v_add_u32_e32 v181, s40, v176
	v_lshl_add_u64 v[172:173], v[172:173], 0, s[0:1]
	s_mov_b32 m0, s41
	ds_read_b128 v[202:205], v181
	ds_read_b128 v[206:209], v181 offset:1024
	ds_read_b128 v[212:215], v181 offset:2048
	ds_read_b128 v[216:219], v181 offset:3072
	global_load_lds_dwordx4 v[172:173], off
	v_lshl_add_u64 v[172:173], v[220:221], 0, s[0:1]
	s_add_i32 m0, s41, 0x2000
	s_nop 0
	global_load_lds_dwordx4 v[172:173], off
	s_waitcnt lgkmcnt(0)
	s_setprio 1
	s_barrier
	v_mfma_f32_16x16x32_bf16 v[116:119], v[202:205], v[160:163], v[116:119]
	v_mfma_f32_16x16x32_bf16 v[112:115], v[212:215], v[160:163], v[112:115]
	v_mfma_f32_16x16x32_bf16 v[100:103], v[202:205], v[168:171], v[100:103]
	v_mfma_f32_16x16x32_bf16 v[92:95], v[212:215], v[168:171], v[92:95]
	v_mfma_f32_16x16x32_bf16 v[84:87], v[202:205], v[186:189], v[84:87]
	v_mfma_f32_16x16x32_bf16 v[76:79], v[212:215], v[186:189], v[76:79]
	v_mfma_f32_16x16x32_bf16 v[68:71], v[202:205], v[194:197], v[68:71]
	v_mfma_f32_16x16x32_bf16 v[64:67], v[212:215], v[194:197], v[64:67]
	v_mfma_f32_16x16x32_bf16 v[116:119], v[206:209], v[164:167], v[116:119]
	v_mfma_f32_16x16x32_bf16 v[112:115], v[216:219], v[164:167], v[112:115]
	v_mfma_f32_16x16x32_bf16 v[100:103], v[206:209], v[182:185], v[100:103]
	v_mfma_f32_16x16x32_bf16 v[92:95], v[216:219], v[182:185], v[92:95]
	v_mfma_f32_16x16x32_bf16 v[84:87], v[206:209], v[190:193], v[84:87]
	v_mfma_f32_16x16x32_bf16 v[76:79], v[216:219], v[190:193], v[76:79]
	v_mfma_f32_16x16x32_bf16 v[68:71], v[206:209], v[198:201], v[68:71]
	v_mfma_f32_16x16x32_bf16 v[64:67], v[216:219], v[198:201], v[64:67]
	s_setprio 0
	s_mov_b32 m0, s53
	v_lshl_add_u64 v[172:173], v[222:223], 0, s[0:1]
	s_barrier
	ds_read_b128 v[160:163], v179 offset:49152
	ds_read_b128 v[164:167], v179 offset:50176
	ds_read_b128 v[168:171], v179 offset:51200
	ds_read_b128 v[182:185], v179 offset:52224
	ds_read_b128 v[186:189], v179 offset:53248
	ds_read_b128 v[190:193], v179 offset:54272
	ds_read_b128 v[194:197], v179 offset:55296
	ds_read_b128 v[198:201], v179 offset:56320
	global_load_lds_dwordx4 v[172:173], off
	v_lshl_add_u64 v[172:173], v[224:225], 0, s[0:1]
	s_mov_b32 m0, s54
	s_nop 0
	global_load_lds_dwordx4 v[172:173], off
	s_waitcnt lgkmcnt(0)
	s_setprio 1
	s_barrier
	v_mfma_f32_16x16x32_bf16 v[60:63], v[144:147], v[160:163], v[60:63]
	v_mfma_f32_16x16x32_bf16 v[56:59], v[152:155], v[160:163], v[56:59]
	v_mfma_f32_16x16x32_bf16 v[44:47], v[144:147], v[168:171], v[44:47]
	v_mfma_f32_16x16x32_bf16 v[40:43], v[152:155], v[168:171], v[40:43]
	v_mfma_f32_16x16x32_bf16 v[32:35], v[144:147], v[186:189], v[32:35]
	v_mfma_f32_16x16x32_bf16 v[24:27], v[152:155], v[186:189], v[24:27]
	v_mfma_f32_16x16x32_bf16 v[16:19], v[144:147], v[194:197], v[16:19]
	v_mfma_f32_16x16x32_bf16 v[8:11], v[152:155], v[194:197], v[8:11]
	v_mfma_f32_16x16x32_bf16 v[60:63], v[148:151], v[164:167], v[60:63]
	v_mfma_f32_16x16x32_bf16 v[56:59], v[156:159], v[164:167], v[56:59]
	v_mfma_f32_16x16x32_bf16 v[44:47], v[148:151], v[182:185], v[44:47]
	v_mfma_f32_16x16x32_bf16 v[40:43], v[156:159], v[182:185], v[40:43]
	v_mfma_f32_16x16x32_bf16 v[32:35], v[148:151], v[190:193], v[32:35]
	v_mfma_f32_16x16x32_bf16 v[24:27], v[156:159], v[190:193], v[24:27]
	v_mfma_f32_16x16x32_bf16 v[16:19], v[148:151], v[198:201], v[16:19]
	v_mfma_f32_16x16x32_bf16 v[8:11], v[156:159], v[198:201], v[8:11]
	s_setprio 0
	s_barrier
	s_add_u32 s38, s38, 0x20080
	s_addc_u32 s39, s39, 0
	s_add_i32 s40, s40, s48
	v_lshl_add_u64 v[144:145], s[38:39], 0, v[130:131]
	s_mov_b32 m0, s40
	s_nop 0
	global_load_lds_dwordx4 v[144:145], off
	v_lshl_add_u64 v[144:145], s[38:39], 0, v[134:135]
	s_add_i32 m0, s40, 0x2000
	s_nop 0
	global_load_lds_dwordx4 v[144:145], off
	s_waitcnt vmcnt(6)
	s_setprio 1
	s_barrier
	v_mfma_f32_16x16x32_bf16 v[52:55], v[202:205], v[160:163], v[52:55]
	v_mfma_f32_16x16x32_bf16 v[48:51], v[212:215], v[160:163], v[48:51]
	v_mfma_f32_16x16x32_bf16 v[36:39], v[202:205], v[168:171], v[36:39]
	v_mfma_f32_16x16x32_bf16 v[28:31], v[212:215], v[168:171], v[28:31]
	v_mfma_f32_16x16x32_bf16 v[20:23], v[202:205], v[186:189], v[20:23]
	v_mfma_f32_16x16x32_bf16 v[12:15], v[212:215], v[186:189], v[12:15]
	v_mfma_f32_16x16x32_bf16 v[4:7], v[202:205], v[194:197], v[4:7]
	v_mfma_f32_16x16x32_bf16 v[0:3], v[212:215], v[194:197], v[0:3]
	v_mfma_f32_16x16x32_bf16 v[52:55], v[206:209], v[164:167], v[52:55]
	v_mfma_f32_16x16x32_bf16 v[48:51], v[216:219], v[164:167], v[48:51]
	v_mfma_f32_16x16x32_bf16 v[36:39], v[206:209], v[182:185], v[36:39]
	v_mfma_f32_16x16x32_bf16 v[28:31], v[216:219], v[182:185], v[28:31]
	v_mfma_f32_16x16x32_bf16 v[20:23], v[206:209], v[190:193], v[20:23]
	v_mfma_f32_16x16x32_bf16 v[12:15], v[216:219], v[190:193], v[12:15]
	v_mfma_f32_16x16x32_bf16 v[4:7], v[206:209], v[198:201], v[4:7]
	v_mfma_f32_16x16x32_bf16 v[0:3], v[216:219], v[198:201], v[0:3]
	s_setprio 0
	s_add_i32 s62, s62, 2
	s_add_u32 s36, s36, 0x100
	s_addc_u32 s37, s37, 0
	s_add_u32 s60, s60, 0x100
	s_addc_u32 s61, s61, 0
	s_cmp_gt_u32 s62, 5
	s_barrier
	s_cbranch_scc0 .LBB0_1160
	v_lshl_or_b32 v144, s34, 8, v177
	v_lshl_add_u32 v150, s30, 8, v175
	v_ashrrev_i32_e32 v145, 31, v144
	v_ashrrev_i32_e32 v151, 31, v150
	v_lshlrev_b64 v[144:145], 1, v[144:145]
	v_lshl_add_u64 v[146:147], s[10:11], 0, v[144:145]
	v_lshlrev_b64 v[148:149], 11, v[150:151]
	v_lshl_add_u64 v[152:153], v[146:147], 0, v[148:149]
	global_load_dwordx4 v[156:159], v[152:153], off
	global_load_dwordx4 v[160:163], v[152:153], off offset:256
	v_or_b32_e32 v152, 16, v150
	v_ashrrev_i32_e32 v153, 31, v152
	v_lshlrev_b64 v[170:171], 11, v[152:153]
	v_lshl_add_u64 v[152:153], v[146:147], 0, v[170:171]
	global_load_dwordx4 v[164:167], v[152:153], off
	global_load_dwordx4 v[182:185], v[152:153], off offset:256
	v_or_b32_e32 v152, 32, v150
	v_ashrrev_i32_e32 v153, 31, v152
	v_lshlrev_b64 v[154:155], 11, v[152:153]
	v_lshl_add_u64 v[152:153], v[146:147], 0, v[154:155]
	global_load_dwordx4 v[186:189], v[152:153], off
	global_load_dwordx4 v[190:193], v[152:153], off offset:256
	v_or_b32_e32 v152, 48, v150
	v_ashrrev_i32_e32 v153, 31, v152
	v_lshlrev_b64 v[152:153], 11, v[152:153]
	v_lshl_add_u64 v[168:169], v[146:147], 0, v[152:153]
	global_load_dwordx4 v[194:197], v[168:169], off
	global_load_dwordx4 v[198:201], v[168:169], off offset:256
	s_waitcnt vmcnt(0)
	v_lshlrev_b32_e32 v202, 16, v156
	v_and_b32_e32 v203, 0xffff0000, v156
	v_lshlrev_b32_e32 v204, 16, v157
	v_and_b32_e32 v205, 0xffff0000, v157
	v_lshlrev_b32_e32 v206, 16, v158
	v_and_b32_e32 v207, 0xffff0000, v158
	v_lshlrev_b32_e32 v208, 16, v159
	v_and_b32_e32 v209, 0xffff0000, v159
	v_pk_add_f32 v[126:127], v[126:127], v[204:205]
	v_pk_add_f32 v[124:125], v[124:125], v[202:203]
	v_lshlrev_b32_e32 v224, 16, v166
	v_and_b32_e32 v225, 0xffff0000, v166
	v_lshlrev_b32_e32 v226, 16, v167
	v_and_b32_e32 v227, 0xffff0000, v167
	v_lshlrev_b32_e32 v212, 16, v160
	v_lshlrev_b32_e32 v166, 16, v194
	v_and_b32_e32 v167, 0xffff0000, v194
	v_lshlrev_b32_e32 v172, 16, v195
	v_and_b32_e32 v173, 0xffff0000, v195
	v_pk_add_f32 v[194:195], v[122:123], v[208:209]
	v_pk_add_f32 v[122:123], v[120:121], v[206:207]
	v_mul_f32_e32 v120, v125, v125
	v_mul_f32_e32 v121, v127, v127
	v_fmac_f32_e32 v120, v124, v124
	v_fmac_f32_e32 v121, v126, v126
	v_add_f32_e32 v120, v120, v121
	v_mul_f32_e32 v121, v123, v123
	v_fmac_f32_e32 v121, v122, v122
	v_add_f32_e32 v120, v121, v120
	v_mul_f32_e32 v121, v195, v195
	v_fmac_f32_e32 v121, v194, v194
	v_and_b32_e32 v213, 0xffff0000, v160
	v_lshlrev_b32_e32 v214, 16, v161
	v_and_b32_e32 v215, 0xffff0000, v161
	v_add_f32_e32 v181, v121, v120
	v_cvt_pk_bf16_f32 v120, v124, v125
	v_lshl_add_u64 v[124:125], s[90:91], 0, v[148:149]
	v_lshlrev_b32_e32 v216, 16, v162
	v_and_b32_e32 v217, 0xffff0000, v162
	v_lshlrev_b32_e32 v218, 16, v163
	v_and_b32_e32 v219, 0xffff0000, v163
	v_cvt_pk_bf16_f32 v121, v126, v127
	v_lshl_add_u64 v[124:125], v[124:125], 0, v[144:145]
	v_pk_add_f32 v[118:119], v[118:119], v[214:215]
	v_pk_add_f32 v[116:117], v[116:117], v[212:213]
	v_cvt_pk_bf16_f32 v122, v122, v123
	v_cvt_pk_bf16_f32 v123, v194, v195
	global_store_dwordx4 v[124:125], v[120:123], off
	v_lshlrev_b32_e32 v220, 16, v164
	v_and_b32_e32 v221, 0xffff0000, v164
	v_pk_add_f32 v[120:121], v[114:115], v[218:219]
	v_pk_add_f32 v[114:115], v[112:113], v[216:217]
	v_mul_f32_e32 v112, v117, v117
	v_mul_f32_e32 v113, v119, v119
	v_fmac_f32_e32 v112, v116, v116
	v_fmac_f32_e32 v113, v118, v118
	v_add_f32_e32 v112, v112, v113
	v_mul_f32_e32 v113, v115, v115
	v_fmac_f32_e32 v113, v114, v114
	v_add_f32_e32 v112, v113, v112
	v_mul_f32_e32 v113, v121, v121
	v_fmac_f32_e32 v113, v120, v120
	v_add_f32_e32 v112, v113, v112
	v_lshlrev_b32_e32 v222, 16, v165
	v_and_b32_e32 v223, 0xffff0000, v165
	v_add_f32_e32 v126, v181, v112
	v_cvt_pk_bf16_f32 v112, v116, v117
	v_cvt_pk_bf16_f32 v113, v118, v119
	v_lshl_add_u64 v[116:117], s[90:91], 0, v[170:171]
	v_lshlrev_b32_e32 v230, 16, v184
	v_and_b32_e32 v231, 0xffff0000, v184
	v_lshlrev_b32_e32 v232, 16, v186
	v_and_b32_e32 v233, 0xffff0000, v186
	v_lshlrev_b32_e32 v186, 16, v187
	v_and_b32_e32 v187, 0xffff0000, v187
	v_cvt_pk_bf16_f32 v114, v114, v115
	v_cvt_pk_bf16_f32 v115, v120, v121
	global_store_dwordx4 v[124:125], v[112:115], off offset:256
	v_pk_add_f32 v[110:111], v[110:111], v[222:223]
	v_pk_add_f32 v[108:109], v[108:109], v[220:221]
	v_lshl_add_u64 v[118:119], v[116:117], 0, v[144:145]
	v_cvt_pk_bf16_f32 v112, v108, v109
	v_cvt_pk_bf16_f32 v113, v110, v111
	v_lshlrev_b32_e32 v228, 16, v182
	v_and_b32_e32 v229, 0xffff0000, v182
	v_lshlrev_b32_e32 v182, 16, v183
	v_and_b32_e32 v183, 0xffff0000, v183
	v_lshlrev_b32_e32 v184, 16, v185
	v_and_b32_e32 v185, 0xffff0000, v185
	v_lshlrev_b32_e32 v238, 16, v192
	v_and_b32_e32 v239, 0xffff0000, v192
	v_pk_add_f32 v[106:107], v[106:107], v[226:227]
	v_pk_add_f32 v[104:105], v[104:105], v[224:225]
	v_lshlrev_b32_e32 v156, 16, v200
	v_cvt_pk_bf16_f32 v114, v104, v105
	v_cvt_pk_bf16_f32 v115, v106, v107
	global_store_dwordx4 v[118:119], v[112:115], off
	v_and_b32_e32 v157, 0xffff0000, v200
	v_pk_add_f32 v[102:103], v[102:103], v[182:183]
	v_pk_add_f32 v[112:113], v[92:93], v[230:231]
	v_pk_add_f32 v[92:93], v[98:99], v[186:187]
	v_lshl_add_u64 v[98:99], s[90:91], 0, v[154:155]
	v_pk_add_f32 v[100:101], v[100:101], v[228:229]
	v_pk_add_f32 v[94:95], v[94:95], v[184:185]
	v_cvt_pk_bf16_f32 v114, v100, v101
	v_cvt_pk_bf16_f32 v115, v102, v103
	v_cvt_pk_bf16_f32 v116, v112, v113
	v_lshlrev_b32_e32 v234, 16, v188
	v_cvt_pk_bf16_f32 v117, v94, v95
	global_store_dwordx4 v[118:119], v[114:117], off offset:256
	v_lshl_add_u64 v[118:119], v[98:99], 0, v[144:145]
	v_pk_add_f32 v[98:99], v[76:77], v[238:239]
	v_pk_add_f32 v[76:77], v[82:83], v[172:173]
	v_lshl_add_u64 v[82:83], s[90:91], 0, v[152:153]
	v_lshl_add_u64 v[122:123], v[82:83], 0, v[144:145]
	v_pk_add_f32 v[82:83], v[64:65], v[156:157]
	v_and_b32_e32 v65, 64, v174
	v_and_b32_e32 v235, 0xffff0000, v188
	v_lshlrev_b32_e32 v188, 16, v189
	v_and_b32_e32 v189, 0xffff0000, v189
	v_lshlrev_b32_e32 v236, 16, v190
	v_and_b32_e32 v237, 0xffff0000, v190
	v_pk_add_f32 v[96:97], v[96:97], v[232:233]
	v_xor_b32_e32 v64, 16, v174
	v_cvt_pk_bf16_f32 v114, v96, v97
	v_add_u32_e32 v65, 64, v65
	v_lshlrev_b32_e32 v190, 16, v191
	v_and_b32_e32 v191, 0xffff0000, v191
	v_lshlrev_b32_e32 v192, 16, v193
	v_and_b32_e32 v193, 0xffff0000, v193
	v_pk_add_f32 v[90:91], v[90:91], v[188:189]
	v_pk_add_f32 v[88:89], v[88:89], v[234:235]
	v_cvt_pk_bf16_f32 v115, v92, v93
	v_pk_add_f32 v[84:85], v[84:85], v[236:237]
	v_cvt_pk_bf16_f32 v116, v88, v89
	v_cvt_pk_bf16_f32 v117, v90, v91
	global_store_dwordx4 v[118:119], v[114:117], off
	v_cmp_lt_i32_e32 vcc, v64, v65
	v_lshlrev_b32_e32 v164, 16, v196
	v_cvt_pk_bf16_f32 v114, v84, v85
	v_and_b32_e32 v165, 0xffff0000, v196
	v_lshlrev_b32_e32 v168, 16, v197
	v_and_b32_e32 v169, 0xffff0000, v197
	v_pk_add_f32 v[86:87], v[86:87], v[190:191]
	v_pk_add_f32 v[78:79], v[78:79], v[192:193]
	v_cvt_pk_bf16_f32 v115, v86, v87
	v_cvt_pk_bf16_f32 v116, v98, v99
	v_pk_add_f32 v[80:81], v[80:81], v[166:167]
	v_cvt_pk_bf16_f32 v117, v78, v79
	global_store_dwordx4 v[118:119], v[114:117], off offset:256
	v_cndmask_b32_e32 v64, v174, v64, vcc
	v_pk_add_f32 v[74:75], v[74:75], v[168:169]
	v_cvt_pk_bf16_f32 v114, v80, v81
	v_pk_add_f32 v[72:73], v[72:73], v[164:165]
	v_cvt_pk_bf16_f32 v115, v76, v77
	v_lshlrev_b32_e32 v158, 16, v198
	v_cvt_pk_bf16_f32 v116, v72, v73
	v_cvt_pk_bf16_f32 v117, v74, v75
	global_store_dwordx4 v[122:123], v[114:117], off
	v_and_b32_e32 v159, 0xffff0000, v198
	v_lshlrev_b32_e32 v162, 16, v199
	v_lshlrev_b32_e32 v114, 2, v64
	ds_bpermute_b32 v64, v114, v126
	v_xor_b32_e32 v115, 32, v174
	v_cmp_lt_i32_e32 vcc, v115, v65
	v_and_b32_e32 v163, 0xffff0000, v199
	v_lshlrev_b32_e32 v160, 16, v201
	v_cndmask_b32_e32 v65, v174, v115, vcc
	v_lshlrev_b32_e32 v115, 2, v65
	s_waitcnt lgkmcnt(0)
	v_add_f32_e32 v116, v126, v64
	ds_bpermute_b32 v117, v115, v116
	v_and_b32_e32 v161, 0xffff0000, v201
	v_pk_add_f32 v[70:71], v[70:71], v[162:163]
	v_pk_add_f32 v[68:69], v[68:69], v[158:159]
	v_pk_add_f32 v[66:67], v[66:67], v[160:161]
	v_lshl_add_u64 v[64:65], v[150:151], 2, s[8:9]
	v_cvt_pk_bf16_f32 v118, v68, v69
	v_cvt_pk_bf16_f32 v119, v70, v71
	v_cvt_pk_bf16_f32 v120, v82, v83
	v_cvt_pk_bf16_f32 v121, v66, v67
	global_store_dwordx4 v[122:123], v[118:121], off offset:256
	s_and_saveexec_b64 s[30:31], s[2:3]
	s_cbranch_execz .LBB0_1163
	s_waitcnt lgkmcnt(0)
	v_add_f32_e32 v116, v116, v117
	global_atomic_add_f32 v[64:65], v116, off

.LBB0_1218:
	ds_read_b128 v[144:147], v151
	ds_read_b128 v[156:159], v151 offset:1024
	ds_read_b128 v[160:163], v151 offset:2048
	ds_read_b128 v[164:167], v151 offset:3072
	s_add_u32 s30, s28, 0xfffc0080
	s_addc_u32 s31, s29, -1
	s_cmp_eq_u32 s63, 12
	s_cselect_b32 s35, s23, s31
	s_cselect_b32 s34, s59, s30
	s_cselect_b32 s31, s21, s62
	s_cselect_b32 s30, s60, s61
	v_lshl_add_u64 v[172:173], s[28:29], 0, v[136:137]
	s_add_i32 m0, s40, 0xc000
	ds_read_b128 v[168:171], v152
	ds_read_b128 v[176:179], v152 offset:1024
	ds_read_b128 v[180:183], v152 offset:2048
	ds_read_b128 v[184:187], v152 offset:3072
	ds_read_b128 v[188:191], v152 offset:4096
	ds_read_b128 v[192:195], v152 offset:5120
	ds_read_b128 v[196:199], v152 offset:6144
	ds_read_b128 v[200:203], v152 offset:7168
	global_load_lds_dwordx4 v[172:173], off
	v_lshl_add_u64 v[172:173], s[28:29], 0, v[138:139]
	s_add_i32 m0, s40, 0xe000
	s_nop 0
	global_load_lds_dwordx4 v[172:173], off
	s_waitcnt lgkmcnt(8)
	s_waitcnt lgkmcnt(0)
	s_setprio 1
	s_barrier
	v_mfma_f32_16x16x32_bf16 v[124:127], v[144:147], v[168:171], v[124:127]
	v_mfma_f32_16x16x32_bf16 v[120:123], v[160:163], v[168:171], v[120:123]
	v_mfma_f32_16x16x32_bf16 v[116:119], v[144:147], v[180:183], v[116:119]
	v_mfma_f32_16x16x32_bf16 v[112:115], v[160:163], v[180:183], v[112:115]
	v_mfma_f32_16x16x32_bf16 v[92:95], v[144:147], v[188:191], v[92:95]
	v_mfma_f32_16x16x32_bf16 v[88:91], v[160:163], v[188:191], v[88:91]
	v_mfma_f32_16x16x32_bf16 v[76:79], v[144:147], v[196:199], v[76:79]
	v_mfma_f32_16x16x32_bf16 v[72:75], v[160:163], v[196:199], v[72:75]
	v_mfma_f32_16x16x32_bf16 v[124:127], v[156:159], v[176:179], v[124:127]
	v_mfma_f32_16x16x32_bf16 v[120:123], v[164:167], v[176:179], v[120:123]
	v_mfma_f32_16x16x32_bf16 v[116:119], v[156:159], v[184:187], v[116:119]
	v_mfma_f32_16x16x32_bf16 v[112:115], v[164:167], v[184:187], v[112:115]
	v_mfma_f32_16x16x32_bf16 v[92:95], v[156:159], v[192:195], v[92:95]
	v_mfma_f32_16x16x32_bf16 v[88:91], v[164:167], v[192:195], v[88:91]
	v_mfma_f32_16x16x32_bf16 v[76:79], v[156:159], v[200:203], v[76:79]
	v_mfma_f32_16x16x32_bf16 v[72:75], v[164:167], v[200:203], v[72:75]
	s_setprio 0
	s_barrier
	s_add_i32 s64, s52, s39
	v_lshl_add_u64 v[172:173], s[30:31], 0, v[130:131]
	s_mov_b32 m0, s64
	ds_read_b128 v[204:207], v153
	ds_read_b128 v[212:215], v153 offset:1024
	ds_read_b128 v[216:219], v153 offset:2048
	ds_read_b128 v[220:223], v153 offset:3072
	global_load_lds_dwordx4 v[172:173], off
	v_lshl_add_u64 v[208:209], s[30:31], 0, v[134:135]
	s_add_i32 m0, s64, 0x2000
	s_nop 0
	global_load_lds_dwordx4 v[208:209], off
	s_waitcnt lgkmcnt(0)
	s_setprio 1
	s_barrier
	v_mfma_f32_16x16x32_bf16 v[108:111], v[204:207], v[168:171], v[108:111]
	v_mfma_f32_16x16x32_bf16 v[104:107], v[216:219], v[168:171], v[104:107]
	v_mfma_f32_16x16x32_bf16 v[100:103], v[204:207], v[180:183], v[100:103]
	v_mfma_f32_16x16x32_bf16 v[96:99], v[216:219], v[180:183], v[96:99]
	v_mfma_f32_16x16x32_bf16 v[84:87], v[204:207], v[188:191], v[84:87]
	v_mfma_f32_16x16x32_bf16 v[80:83], v[216:219], v[188:191], v[80:83]
	v_mfma_f32_16x16x32_bf16 v[68:71], v[204:207], v[196:199], v[68:71]
	v_mfma_f32_16x16x32_bf16 v[64:67], v[216:219], v[196:199], v[64:67]
	v_mfma_f32_16x16x32_bf16 v[108:111], v[212:215], v[176:179], v[108:111]
	v_mfma_f32_16x16x32_bf16 v[104:107], v[220:223], v[176:179], v[104:107]
	v_mfma_f32_16x16x32_bf16 v[100:103], v[212:215], v[184:187], v[100:103]
	v_mfma_f32_16x16x32_bf16 v[96:99], v[220:223], v[184:187], v[96:99]
	v_mfma_f32_16x16x32_bf16 v[84:87], v[212:215], v[192:195], v[84:87]
	v_mfma_f32_16x16x32_bf16 v[80:83], v[220:223], v[192:195], v[80:83]
	v_mfma_f32_16x16x32_bf16 v[68:71], v[212:215], v[200:203], v[68:71]
	v_mfma_f32_16x16x32_bf16 v[64:67], v[220:223], v[200:203], v[64:67]
	s_setprio 0
	s_mov_b32 m0, s40
	v_lshl_add_u64 v[224:225], s[34:35], 0, v[128:129]
	s_barrier
	ds_read_b128 v[168:171], v152 offset:16384
	ds_read_b128 v[176:179], v152 offset:17408
	ds_read_b128 v[180:183], v152 offset:18432
	ds_read_b128 v[184:187], v152 offset:19456
	ds_read_b128 v[188:191], v152 offset:20480
	ds_read_b128 v[192:195], v152 offset:21504
	ds_read_b128 v[196:199], v152 offset:22528
	ds_read_b128 v[200:203], v152 offset:23552
	global_load_lds_dwordx4 v[224:225], off
	v_lshl_add_u64 v[226:227], s[34:35], 0, v[132:133]
	s_mov_b32 m0, s41
	s_nop 0
	global_load_lds_dwordx4 v[226:227], off
	s_waitcnt lgkmcnt(0)
	s_setprio 1
	s_barrier
	v_mfma_f32_16x16x32_bf16 v[60:63], v[144:147], v[168:171], v[60:63]
	v_mfma_f32_16x16x32_bf16 v[56:59], v[160:163], v[168:171], v[56:59]
	v_mfma_f32_16x16x32_bf16 v[44:47], v[144:147], v[180:183], v[44:47]
	v_mfma_f32_16x16x32_bf16 v[40:43], v[160:163], v[180:183], v[40:43]
	v_mfma_f32_16x16x32_bf16 v[28:31], v[144:147], v[188:191], v[28:31]
	v_mfma_f32_16x16x32_bf16 v[24:27], v[160:163], v[188:191], v[24:27]
	v_mfma_f32_16x16x32_bf16 v[12:15], v[144:147], v[196:199], v[12:15]
	v_mfma_f32_16x16x32_bf16 v[8:11], v[160:163], v[196:199], v[8:11]
	v_mfma_f32_16x16x32_bf16 v[60:63], v[156:159], v[176:179], v[60:63]
	v_mfma_f32_16x16x32_bf16 v[56:59], v[164:167], v[176:179], v[56:59]
	v_mfma_f32_16x16x32_bf16 v[44:47], v[156:159], v[184:187], v[44:47]
	v_mfma_f32_16x16x32_bf16 v[40:43], v[164:167], v[184:187], v[40:43]
	v_mfma_f32_16x16x32_bf16 v[28:31], v[156:159], v[192:195], v[28:31]
	v_mfma_f32_16x16x32_bf16 v[24:27], v[164:167], v[192:195], v[24:27]
	v_mfma_f32_16x16x32_bf16 v[12:15], v[156:159], v[200:203], v[12:15]
	v_mfma_f32_16x16x32_bf16 v[8:11], v[164:167], v[200:203], v[8:11]
	s_setprio 0
	s_barrier
	s_add_u32 s64, s30, 0x40000
	s_addc_u32 s65, s31, 0
	s_add_i32 s66, s53, s39
	v_lshl_add_u64 v[144:145], s[64:65], 0, v[130:131]
	s_mov_b32 m0, s66
	s_nop 0
	global_load_lds_dwordx4 v[144:145], off
	v_lshl_add_u64 v[144:145], s[64:65], 0, v[134:135]
	s_add_i32 m0, s66, 0x2000
	s_nop 0
	global_load_lds_dwordx4 v[144:145], off
	s_waitcnt vmcnt(6)
	s_setprio 1
	s_barrier
	v_mfma_f32_16x16x32_bf16 v[52:55], v[204:207], v[168:171], v[52:55]
	v_mfma_f32_16x16x32_bf16 v[48:51], v[216:219], v[168:171], v[48:51]
	v_mfma_f32_16x16x32_bf16 v[36:39], v[204:207], v[180:183], v[36:39]
	v_mfma_f32_16x16x32_bf16 v[32:35], v[216:219], v[180:183], v[32:35]
	v_mfma_f32_16x16x32_bf16 v[20:23], v[204:207], v[188:191], v[20:23]
	v_mfma_f32_16x16x32_bf16 v[16:19], v[216:219], v[188:191], v[16:19]
	v_mfma_f32_16x16x32_bf16 v[4:7], v[204:207], v[196:199], v[4:7]
	v_mfma_f32_16x16x32_bf16 v[0:3], v[216:219], v[196:199], v[0:3]
	v_mfma_f32_16x16x32_bf16 v[52:55], v[212:215], v[176:179], v[52:55]
	v_mfma_f32_16x16x32_bf16 v[48:51], v[220:223], v[176:179], v[48:51]
	v_mfma_f32_16x16x32_bf16 v[36:39], v[212:215], v[184:187], v[36:39]
	v_mfma_f32_16x16x32_bf16 v[32:35], v[220:223], v[184:187], v[32:35]
	v_mfma_f32_16x16x32_bf16 v[20:23], v[212:215], v[192:195], v[20:23]
	v_mfma_f32_16x16x32_bf16 v[16:19], v[220:223], v[192:195], v[16:19]
	v_mfma_f32_16x16x32_bf16 v[4:7], v[212:215], v[200:203], v[4:7]
	v_mfma_f32_16x16x32_bf16 v[0:3], v[220:223], v[200:203], v[0:3]
	s_setprio 0
	s_add_i32 s64, 0, 0x18000
	v_add_u32_e32 v155, s64, v149
	s_barrier
	ds_read_b128 v[144:147], v155
	ds_read_b128 v[156:159], v155 offset:1024
	ds_read_b128 v[160:163], v155 offset:2048
	ds_read_b128 v[164:167], v155 offset:3072
	s_add_u32 s34, s34, 0x40000
	s_addc_u32 s35, s35, 0
	s_mov_b32 m0, s42
	v_lshl_add_u64 v[204:205], s[34:35], 0, v[128:129]
	ds_read_b128 v[168:171], v152 offset:32768
	ds_read_b128 v[176:179], v152 offset:33792
	ds_read_b128 v[180:183], v152 offset:34816
	ds_read_b128 v[184:187], v152 offset:35840
	ds_read_b128 v[188:191], v152 offset:36864
	ds_read_b128 v[192:195], v152 offset:37888
	ds_read_b128 v[196:199], v152 offset:38912
	ds_read_b128 v[200:203], v152 offset:39936
	global_load_lds_dwordx4 v[204:205], off
	v_lshl_add_u64 v[204:205], s[34:35], 0, v[132:133]
	s_mov_b32 m0, s43
	s_nop 0
	global_load_lds_dwordx4 v[204:205], off
	s_waitcnt lgkmcnt(8)
	s_waitcnt lgkmcnt(0)
	s_setprio 1
	s_barrier
	v_mfma_f32_16x16x32_bf16 v[124:127], v[144:147], v[168:171], v[124:127]
	v_mfma_f32_16x16x32_bf16 v[120:123], v[160:163], v[168:171], v[120:123]
	v_mfma_f32_16x16x32_bf16 v[116:119], v[144:147], v[180:183], v[116:119]
	v_mfma_f32_16x16x32_bf16 v[112:115], v[160:163], v[180:183], v[112:115]
	v_mfma_f32_16x16x32_bf16 v[92:95], v[144:147], v[188:191], v[92:95]
	v_mfma_f32_16x16x32_bf16 v[88:91], v[160:163], v[188:191], v[88:91]
	v_mfma_f32_16x16x32_bf16 v[76:79], v[144:147], v[196:199], v[76:79]
	v_mfma_f32_16x16x32_bf16 v[72:75], v[160:163], v[196:199], v[72:75]
	v_mfma_f32_16x16x32_bf16 v[124:127], v[156:159], v[176:179], v[124:127]
	v_mfma_f32_16x16x32_bf16 v[120:123], v[164:167], v[176:179], v[120:123]
	v_mfma_f32_16x16x32_bf16 v[116:119], v[156:159], v[184:187], v[116:119]
	v_mfma_f32_16x16x32_bf16 v[112:115], v[164:167], v[184:187], v[112:115]
	v_mfma_f32_16x16x32_bf16 v[92:95], v[156:159], v[192:195], v[92:95]
	v_mfma_f32_16x16x32_bf16 v[88:91], v[164:167], v[192:195], v[88:91]
	v_mfma_f32_16x16x32_bf16 v[76:79], v[156:159], v[200:203], v[76:79]
	v_mfma_f32_16x16x32_bf16 v[72:75], v[164:167], v[200:203], v[72:75]
	s_setprio 0
	s_barrier
	s_add_i32 s34, 0, 0x1c000
	s_add_i32 s35, s64, s39
	v_add_u32_e32 v155, s34, v149
	v_lshl_add_u64 v[172:173], v[172:173], 0, s[6:7]
	s_mov_b32 m0, s35
	ds_read_b128 v[204:207], v155
	ds_read_b128 v[212:215], v155 offset:1024
	ds_read_b128 v[216:219], v155 offset:2048
	ds_read_b128 v[220:223], v155 offset:3072
	global_load_lds_dwordx4 v[172:173], off
	v_lshl_add_u64 v[172:173], v[208:209], 0, s[6:7]
	s_add_i32 m0, s35, 0x2000
	s_nop 0
	global_load_lds_dwordx4 v[172:173], off
	s_waitcnt lgkmcnt(0)
	s_setprio 1
	s_barrier
	v_mfma_f32_16x16x32_bf16 v[108:111], v[204:207], v[168:171], v[108:111]
	v_mfma_f32_16x16x32_bf16 v[104:107], v[216:219], v[168:171], v[104:107]
	v_mfma_f32_16x16x32_bf16 v[100:103], v[204:207], v[180:183], v[100:103]
	v_mfma_f32_16x16x32_bf16 v[96:99], v[216:219], v[180:183], v[96:99]
	v_mfma_f32_16x16x32_bf16 v[84:87], v[204:207], v[188:191], v[84:87]
	v_mfma_f32_16x16x32_bf16 v[80:83], v[216:219], v[188:191], v[80:83]
	v_mfma_f32_16x16x32_bf16 v[68:71], v[204:207], v[196:199], v[68:71]
	v_mfma_f32_16x16x32_bf16 v[64:67], v[216:219], v[196:199], v[64:67]
	v_mfma_f32_16x16x32_bf16 v[108:111], v[212:215], v[176:179], v[108:111]
	v_mfma_f32_16x16x32_bf16 v[104:107], v[220:223], v[176:179], v[104:107]
	v_mfma_f32_16x16x32_bf16 v[100:103], v[212:215], v[184:187], v[100:103]
	v_mfma_f32_16x16x32_bf16 v[96:99], v[220:223], v[184:187], v[96:99]
	v_mfma_f32_16x16x32_bf16 v[84:87], v[212:215], v[192:195], v[84:87]
	v_mfma_f32_16x16x32_bf16 v[80:83], v[220:223], v[192:195], v[80:83]
	v_mfma_f32_16x16x32_bf16 v[68:71], v[212:215], v[200:203], v[68:71]
	v_mfma_f32_16x16x32_bf16 v[64:67], v[220:223], v[200:203], v[64:67]
	s_setprio 0
	s_mov_b32 m0, s49
	v_lshl_add_u64 v[172:173], v[224:225], 0, s[6:7]
	s_barrier
	ds_read_b128 v[168:171], v152 offset:49152
	ds_read_b128 v[176:179], v152 offset:50176
	ds_read_b128 v[180:183], v152 offset:51200
	ds_read_b128 v[184:187], v152 offset:52224
	ds_read_b128 v[188:191], v152 offset:53248
	ds_read_b128 v[192:195], v152 offset:54272
	ds_read_b128 v[196:199], v152 offset:55296
	ds_read_b128 v[200:203], v152 offset:56320
	global_load_lds_dwordx4 v[172:173], off
	v_lshl_add_u64 v[172:173], v[226:227], 0, s[6:7]
	s_mov_b32 m0, s50
	s_nop 0
	global_load_lds_dwordx4 v[172:173], off
	s_waitcnt lgkmcnt(0)
	s_setprio 1
	s_barrier
	v_mfma_f32_16x16x32_bf16 v[60:63], v[144:147], v[168:171], v[60:63]
	v_mfma_f32_16x16x32_bf16 v[56:59], v[160:163], v[168:171], v[56:59]
	v_mfma_f32_16x16x32_bf16 v[44:47], v[144:147], v[180:183], v[44:47]
	v_mfma_f32_16x16x32_bf16 v[40:43], v[160:163], v[180:183], v[40:43]
	v_mfma_f32_16x16x32_bf16 v[28:31], v[144:147], v[188:191], v[28:31]
	v_mfma_f32_16x16x32_bf16 v[24:27], v[160:163], v[188:191], v[24:27]
	v_mfma_f32_16x16x32_bf16 v[12:15], v[144:147], v[196:199], v[12:15]
	v_mfma_f32_16x16x32_bf16 v[8:11], v[160:163], v[196:199], v[8:11]
	v_mfma_f32_16x16x32_bf16 v[60:63], v[156:159], v[176:179], v[60:63]
	v_mfma_f32_16x16x32_bf16 v[56:59], v[164:167], v[176:179], v[56:59]
	v_mfma_f32_16x16x32_bf16 v[44:47], v[156:159], v[184:187], v[44:47]
	v_mfma_f32_16x16x32_bf16 v[40:43], v[164:167], v[184:187], v[40:43]
	v_mfma_f32_16x16x32_bf16 v[28:31], v[156:159], v[192:195], v[28:31]
	v_mfma_f32_16x16x32_bf16 v[24:27], v[164:167], v[192:195], v[24:27]
	v_mfma_f32_16x16x32_bf16 v[12:15], v[156:159], v[200:203], v[12:15]
	v_mfma_f32_16x16x32_bf16 v[8:11], v[164:167], v[200:203], v[8:11]
	s_setprio 0
	s_barrier
	s_add_u32 s30, s30, 0x40080
	s_addc_u32 s31, s31, 0
	s_add_i32 s34, s34, s39
	v_lshl_add_u64 v[144:145], s[30:31], 0, v[130:131]
	s_mov_b32 m0, s34
	s_nop 0
	global_load_lds_dwordx4 v[144:145], off
	v_lshl_add_u64 v[144:145], s[30:31], 0, v[134:135]
	s_add_i32 m0, s34, 0x2000
	s_nop 0
	global_load_lds_dwordx4 v[144:145], off
	s_waitcnt vmcnt(6)
	s_setprio 1
	s_barrier
	v_mfma_f32_16x16x32_bf16 v[52:55], v[204:207], v[168:171], v[52:55]
	v_mfma_f32_16x16x32_bf16 v[48:51], v[216:219], v[168:171], v[48:51]
	v_mfma_f32_16x16x32_bf16 v[36:39], v[204:207], v[180:183], v[36:39]
	v_mfma_f32_16x16x32_bf16 v[32:35], v[216:219], v[180:183], v[32:35]
	v_mfma_f32_16x16x32_bf16 v[20:23], v[204:207], v[188:191], v[20:23]
	v_mfma_f32_16x16x32_bf16 v[16:19], v[216:219], v[188:191], v[16:19]
	v_mfma_f32_16x16x32_bf16 v[4:7], v[204:207], v[196:199], v[4:7]
	v_mfma_f32_16x16x32_bf16 v[0:3], v[216:219], v[196:199], v[0:3]
	v_mfma_f32_16x16x32_bf16 v[52:55], v[212:215], v[176:179], v[52:55]
	v_mfma_f32_16x16x32_bf16 v[48:51], v[220:223], v[176:179], v[48:51]
	v_mfma_f32_16x16x32_bf16 v[36:39], v[212:215], v[184:187], v[36:39]
	v_mfma_f32_16x16x32_bf16 v[32:35], v[220:223], v[184:187], v[32:35]
	v_mfma_f32_16x16x32_bf16 v[20:23], v[212:215], v[192:195], v[20:23]
	v_mfma_f32_16x16x32_bf16 v[16:19], v[220:223], v[192:195], v[16:19]
	v_mfma_f32_16x16x32_bf16 v[4:7], v[212:215], v[200:203], v[4:7]
	v_mfma_f32_16x16x32_bf16 v[0:3], v[220:223], v[200:203], v[0:3]
	s_setprio 0
	s_add_i32 s63, s63, 2
	s_add_u32 s28, s28, 0x100
	s_addc_u32 s29, s29, 0
	s_add_u32 s61, s61, 0x100
	s_addc_u32 s62, s62, 0
	s_cmp_gt_u32 s63, 13
	s_barrier
	s_cbranch_scc0 .LBB0_1218
	v_lshl_add_u32 v146, s0, 8, v148
	v_ashrrev_i32_e32 v147, 31, v146
	v_lshl_add_u64 v[144:145], v[146:147], 2, s[8:9]
	global_load_dword v155, v[144:145], off
	global_load_dword v162, v[144:145], off offset:64
	global_load_dword v163, v[144:145], off offset:128
	global_load_dword v164, v[144:145], off offset:192
	global_load_dword v165, v[144:145], off offset:512
	global_load_dword v166, v[144:145], off offset:576
	global_load_dword v167, v[144:145], off offset:640
	global_load_dword v168, v[144:145], off offset:704
	v_lshl_or_b32 v144, s1, 8, v150
	v_ashrrev_i32_e32 v145, 31, v144
	v_lshlrev_b64 v[158:159], 13, v[146:147]
	v_lshlrev_b64 v[160:161], 1, v[144:145]
	v_lshl_add_u64 v[144:145], s[92:93], 0, v[158:159]
	v_lshl_add_u64 v[144:145], v[144:145], 0, v[160:161]
	v_or_b32_e32 v156, 16, v146
	v_ashrrev_i32_e32 v157, 31, v156
	v_lshlrev_b64 v[156:157], 13, v[156:157]
	v_lshl_add_u64 v[156:157], s[92:93], 0, v[156:157]
	v_lshl_add_u64 v[156:157], v[156:157], 0, v[160:161]
	s_mov_b64 s[30:31], s[26:27]
	s_mov_b64 s[28:29], s[24:25]
	s_waitcnt vmcnt(0)
	v_fmamk_f32 v147, v155, 0x3a800000, v154
	v_mul_f32_e32 v158, 0x4b800000, v147
	v_cmp_gt_f32_e32 vcc, s54, v147
	v_fmamk_f32 v155, v162, 0x3a800000, v154
	v_mul_f32_e32 v162, 0x4b800000, v155
	v_cndmask_b32_e32 v147, v147, v158, vcc
	v_rsq_f32_e32 v158, v147
	v_cmp_gt_f32_e64 s[0:1], s54, v155
	v_fmamk_f32 v159, v163, 0x3a800000, v154
	v_fmamk_f32 v163, v164, 0x3a800000, v154
	v_cndmask_b32_e64 v155, v155, v162, s[0:1]
	v_rsq_f32_e32 v155, v155
	v_mul_f32_e32 v162, 0x45800000, v158
	v_cndmask_b32_e32 v158, v158, v162, vcc
	v_pk_mul_f32 v[124:125], v[124:125], v[158:159] op_sel_hi:[1,0]
	v_pk_mul_f32 v[104:105], v[104:105], v[158:159] op_sel_hi:[1,0]
	v_fmamk_f32 v164, v165, 0x3a800000, v154
	v_fmamk_f32 v165, v166, 0x3a800000, v154
	v_fmamk_f32 v166, v167, 0x3a800000, v154
	v_mul_f32_e32 v167, 0x45800000, v155
	v_pk_mul_f32 v[126:127], v[126:127], v[158:159] op_sel_hi:[1,0]
	v_pk_mul_f32 v[122:123], v[122:123], v[158:159] op_sel_hi:[1,0]
	v_pk_mul_f32 v[120:121], v[120:121], v[158:159] op_sel_hi:[1,0]
	v_pk_mul_f32 v[108:109], v[108:109], v[158:159] op_sel_hi:[1,0]
	v_pk_mul_f32 v[106:107], v[106:107], v[158:159] op_sel_hi:[1,0]
	v_max_f32_e32 v124, 0, v124
	v_max_f32_e32 v125, 0, v125
	v_max_f32_e32 v104, 0, v104
	v_cndmask_b32_e64 v162, v155, v167, s[0:1]
	v_pk_mul_f32 v[110:111], v[110:111], v[158:159] op_sel_hi:[1,0]
	v_max_f32_e32 v120, 0, v120
	v_max_f32_e32 v121, 0, v121
	v_max_f32_e32 v126, 0, v126
	v_max_f32_e32 v122, 0, v122
	v_max_f32_e32 v127, 0, v127
	v_max_f32_e32 v123, 0, v123
	v_max_f32_e32 v108, 0, v108
	v_max_f32_e32 v109, 0, v109
	v_max_f32_e32 v105, 0, v105
	v_max_f32_e32 v106, 0, v106
	v_max_f32_e32 v107, 0, v107
	v_mul_f32_e32 v124, v124, v124
	v_mul_f32_e32 v125, v125, v125
	v_mul_f32_e32 v155, v104, v104
	v_cvt_pk_bf16_f32 v104, v124, v125
	v_fmamk_f32 v147, v168, 0x3a800000, v154
	v_pk_mul_f32 v[112:113], v[112:113], v[162:163] op_sel_hi:[1,0]
	v_max_f32_e32 v110, 0, v110
	v_max_f32_e32 v111, 0, v111
	v_mul_f32_e32 v120, v120, v120
	v_mul_f32_e32 v121, v121, v121
	v_mul_f32_e32 v126, v126, v126
	v_mul_f32_e32 v122, v122, v122
	v_mul_f32_e32 v127, v127, v127
	v_mul_f32_e32 v123, v123, v123
	v_mul_f32_e32 v108, v108, v108
	v_mul_f32_e32 v109, v109, v109
	v_mul_f32_e32 v158, v105, v105
	v_mul_f32_e32 v167, v106, v106
	v_mul_f32_e32 v168, v107, v107
	v_cvt_pk_bf16_f32 v105, v126, v127
	v_cvt_pk_bf16_f32 v106, v120, v121
	v_cvt_pk_bf16_f32 v107, v122, v123
	global_store_dwordx4 v[144:145], v[104:107], off nt
	v_pk_mul_f32 v[116:117], v[116:117], v[162:163] op_sel_hi:[1,0]
	v_mul_f32_e32 v110, v110, v110
	v_cvt_pk_bf16_f32 v104, v108, v109
	v_mul_f32_e32 v111, v111, v111
	v_cvt_pk_bf16_f32 v105, v110, v111
	v_cvt_pk_bf16_f32 v106, v155, v158
	v_cvt_pk_bf16_f32 v107, v167, v168
	global_store_dwordx4 v[144:145], v[104:107], off offset:256 nt
	v_pk_mul_f32 v[118:119], v[118:119], v[162:163] op_sel_hi:[1,0]
	v_pk_mul_f32 v[114:115], v[114:115], v[162:163] op_sel_hi:[1,0]
	v_max_f32_e32 v104, 0, v112
	v_mul_f32_e32 v106, v104, v104
	v_max_f32_e32 v104, 0, v117
	v_max_f32_e32 v116, 0, v116
	v_max_f32_e32 v107, 0, v113
	v_mul_f32_e32 v104, v104, v104
	v_pk_mul_f32 v[98:99], v[98:99], v[162:163] op_sel_hi:[1,0]
	v_pk_mul_f32 v[96:97], v[96:97], v[162:163] op_sel_hi:[1,0]
	v_mul_f32_e32 v105, v116, v116
	v_mul_f32_e32 v107, v107, v107
	v_max_f32_e32 v108, 0, v118
	v_max_f32_e32 v109, 0, v114
	v_max_f32_e32 v110, 0, v119
	v_max_f32_e32 v111, 0, v115
	v_cvt_pk_bf16_f32 v104, v105, v104
	v_pk_mul_f32 v[102:103], v[102:103], v[162:163] op_sel_hi:[1,0]
	v_pk_mul_f32 v[100:101], v[100:101], v[162:163] op_sel_hi:[1,0]
	v_max_f32_e32 v96, 0, v96
	v_max_f32_e32 v97, 0, v97
	v_max_f32_e32 v98, 0, v98
	v_mul_f32_e32 v108, v108, v108
	v_mul_f32_e32 v109, v109, v109
	v_mul_f32_e32 v110, v110, v110
	v_mul_f32_e32 v111, v111, v111
	v_cvt_pk_bf16_f32 v105, v108, v110
	v_cvt_pk_bf16_f32 v106, v106, v107
	v_cvt_pk_bf16_f32 v107, v109, v111
	global_store_dwordx4 v[156:157], v[104:107], off nt
	v_max_f32_e32 v100, 0, v100
	v_max_f32_e32 v99, 0, v99
	v_mul_f32_e32 v104, v96, v96
	v_max_f32_e32 v96, 0, v101
	v_mul_f32_e32 v101, v97, v97
	v_max_f32_e32 v97, 0, v102
	v_mul_f32_e32 v102, v98, v98
	v_max_f32_e32 v98, 0, v103
	v_mul_f32_e32 v96, v96, v96
	v_mul_f32_e32 v97, v97, v97
	v_mul_f32_e32 v98, v98, v98
	v_mul_f32_e32 v100, v100, v100
	v_mul_f32_e32 v99, v99, v99
	v_cvt_pk_bf16_f32 v96, v100, v96
	v_cvt_pk_bf16_f32 v97, v97, v98
	v_cvt_pk_bf16_f32 v98, v104, v101
	v_cvt_pk_bf16_f32 v99, v102, v99
	global_store_dwordx4 v[156:157], v[96:99], off offset:256 nt
	v_cmp_gt_f32_e32 vcc, s54, v159
	s_mov_b32 s1, s20
	v_mul_f32_e32 v98, 0x4b800000, v159
	v_cndmask_b32_e32 v98, v159, v98, vcc
	v_rsq_f32_e32 v98, v98
	v_or_b32_e32 v96, 32, v146
	v_ashrrev_i32_e32 v97, 31, v96
	v_lshlrev_b64 v[96:97], 13, v[96:97]
	v_mul_f32_e32 v99, 0x45800000, v98
	v_cndmask_b32_e32 v98, v98, v99, vcc
	v_pk_mul_f32 v[88:89], v[88:89], v[98:99] op_sel_hi:[1,0]
	v_pk_mul_f32 v[92:93], v[92:93], v[98:99] op_sel_hi:[1,0]
	v_pk_mul_f32 v[90:91], v[90:91], v[98:99] op_sel_hi:[1,0]
	v_max_f32_e32 v88, 0, v88
	v_pk_mul_f32 v[94:95], v[94:95], v[98:99] op_sel_hi:[1,0]
	v_mul_f32_e32 v99, v88, v88
	v_max_f32_e32 v88, 0, v93
	v_max_f32_e32 v89, 0, v89
	v_max_f32_e32 v90, 0, v90
	v_lshl_add_u64 v[96:97], s[92:93], 0, v[96:97]
	v_max_f32_e32 v92, 0, v92
	v_mul_f32_e32 v88, v88, v88
	v_mul_f32_e32 v93, v89, v89
	v_max_f32_e32 v89, 0, v94
	v_mul_f32_e32 v94, v90, v90
	v_max_f32_e32 v90, 0, v95
	v_max_f32_e32 v91, 0, v91
	v_pk_mul_f32 v[82:83], v[82:83], v[98:99] op_sel_hi:[1,0]
	v_pk_mul_f32 v[80:81], v[80:81], v[98:99] op_sel_hi:[1,0]
	v_lshl_add_u64 v[96:97], v[96:97], 0, v[160:161]
	v_mul_f32_e32 v92, v92, v92
	v_mul_f32_e32 v89, v89, v89
	v_mul_f32_e32 v90, v90, v90
	v_mul_f32_e32 v91, v91, v91
	v_cvt_pk_bf16_f32 v88, v92, v88
	v_pk_mul_f32 v[86:87], v[86:87], v[98:99] op_sel_hi:[1,0]
	v_pk_mul_f32 v[84:85], v[84:85], v[98:99] op_sel_hi:[1,0]
	v_max_f32_e32 v80, 0, v80
	v_max_f32_e32 v81, 0, v81
	v_max_f32_e32 v82, 0, v82
	v_cvt_pk_bf16_f32 v89, v89, v90
	v_cvt_pk_bf16_f32 v90, v99, v93
	v_cvt_pk_bf16_f32 v91, v94, v91
	global_store_dwordx4 v[96:97], v[88:91], off nt
	v_max_f32_e32 v84, 0, v84
	v_max_f32_e32 v83, 0, v83
	v_mul_f32_e32 v88, v80, v80
	v_max_f32_e32 v80, 0, v85
	v_mul_f32_e32 v85, v81, v81
	v_max_f32_e32 v81, 0, v86
	v_mul_f32_e32 v86, v82, v82
	v_max_f32_e32 v82, 0, v87
	v_mul_f32_e32 v80, v80, v80
	v_mul_f32_e32 v81, v81, v81
	v_mul_f32_e32 v82, v82, v82
	v_mul_f32_e32 v84, v84, v84
	v_mul_f32_e32 v83, v83, v83
	v_cvt_pk_bf16_f32 v80, v84, v80
	v_cvt_pk_bf16_f32 v81, v81, v82
	v_cvt_pk_bf16_f32 v82, v88, v85
	v_cvt_pk_bf16_f32 v83, v86, v83
	global_store_dwordx4 v[96:97], v[80:83], off offset:256 nt
	v_cmp_gt_f32_e32 vcc, s54, v163
	s_mov_b32 s0, s22
	v_mul_f32_e32 v82, 0x4b800000, v163
	v_cndmask_b32_e32 v82, v163, v82, vcc
	v_rsq_f32_e32 v82, v82
	v_or_b32_e32 v80, 48, v146
	v_ashrrev_i32_e32 v81, 31, v80
	v_lshlrev_b64 v[80:81], 13, v[80:81]
	v_mul_f32_e32 v83, 0x45800000, v82
	v_cndmask_b32_e32 v82, v82, v83, vcc
	v_pk_mul_f32 v[72:73], v[72:73], v[82:83] op_sel_hi:[1,0]
	v_pk_mul_f32 v[76:77], v[76:77], v[82:83] op_sel_hi:[1,0]
	v_pk_mul_f32 v[74:75], v[74:75], v[82:83] op_sel_hi:[1,0]
	v_max_f32_e32 v72, 0, v72
	v_pk_mul_f32 v[78:79], v[78:79], v[82:83] op_sel_hi:[1,0]
	v_mul_f32_e32 v83, v72, v72
	v_max_f32_e32 v72, 0, v77
	v_max_f32_e32 v73, 0, v73
	v_max_f32_e32 v74, 0, v74
	v_lshl_add_u64 v[80:81], s[92:93], 0, v[80:81]
	v_max_f32_e32 v76, 0, v76
	v_mul_f32_e32 v72, v72, v72
	v_mul_f32_e32 v77, v73, v73
	v_max_f32_e32 v73, 0, v78
	v_mul_f32_e32 v78, v74, v74
	v_max_f32_e32 v74, 0, v79
	v_max_f32_e32 v75, 0, v75
	v_pk_mul_f32 v[64:65], v[64:65], v[82:83] op_sel_hi:[1,0]
	v_lshl_add_u64 v[80:81], v[80:81], 0, v[160:161]
	v_mul_f32_e32 v76, v76, v76
	v_mul_f32_e32 v73, v73, v73
	v_mul_f32_e32 v74, v74, v74
	v_mul_f32_e32 v75, v75, v75
	v_cvt_pk_bf16_f32 v72, v76, v72
	v_pk_mul_f32 v[68:69], v[68:69], v[82:83] op_sel_hi:[1,0]
	v_max_f32_e32 v64, 0, v64
	v_cvt_pk_bf16_f32 v73, v73, v74
	v_cvt_pk_bf16_f32 v74, v83, v77
	v_cvt_pk_bf16_f32 v75, v78, v75
	global_store_dwordx4 v[80:81], v[72:75], off nt
	v_max_f32_e32 v68, 0, v68
	v_mul_f32_e32 v68, v68, v68
	v_mul_f32_e32 v72, v64, v64
	v_max_f32_e32 v64, 0, v69
	v_mul_f32_e32 v64, v64, v64
	v_cvt_pk_bf16_f32 v64, v68, v64
	v_mul_f32_e32 v68, 0x4b800000, v164
	v_cmp_gt_f32_e32 vcc, s54, v164
	v_pk_mul_f32 v[66:67], v[66:67], v[82:83] op_sel_hi:[1,0]
	v_pk_mul_f32 v[70:71], v[70:71], v[82:83] op_sel_hi:[1,0]
	v_cndmask_b32_e32 v68, v164, v68, vcc
	v_max_f32_e32 v65, 0, v65
	v_max_f32_e32 v66, 0, v66
	v_rsq_f32_e32 v68, v68
	v_mul_f32_e32 v69, v65, v65
	v_max_f32_e32 v65, 0, v70
	v_mul_f32_e32 v70, v66, v66
	v_max_f32_e32 v66, 0, v71
	v_mul_f32_e32 v65, v65, v65
	v_max_f32_e32 v67, 0, v67
	v_mul_f32_e32 v66, v66, v66
	v_mul_f32_e32 v67, v67, v67
	v_cvt_pk_bf16_f32 v65, v65, v66
	v_cvt_pk_bf16_f32 v66, v72, v69
	v_cvt_pk_bf16_f32 v67, v70, v67
	global_store_dwordx4 v[80:81], v[64:67], off offset:256 nt
	s_nop 1
	v_mul_f32_e32 v66, 0x45800000, v68
	v_cndmask_b32_e32 v66, v68, v66, vcc
	v_pk_mul_f32 v[56:57], v[56:57], v[66:67] op_sel_hi:[1,0]
	v_pk_mul_f32 v[60:61], v[60:61], v[66:67] op_sel_hi:[1,0]
	v_pk_mul_f32 v[58:59], v[58:59], v[66:67] op_sel_hi:[1,0]
	v_max_f32_e32 v56, 0, v56
	v_pk_mul_f32 v[62:63], v[62:63], v[66:67] op_sel_hi:[1,0]
	v_max_f32_e32 v60, 0, v60
	v_mul_f32_e32 v67, v56, v56
	v_max_f32_e32 v56, 0, v61
	v_max_f32_e32 v57, 0, v57
	v_max_f32_e32 v58, 0, v58
	v_mul_f32_e32 v60, v60, v60
	v_mul_f32_e32 v56, v56, v56
	v_mul_f32_e32 v61, v57, v57
	v_max_f32_e32 v57, 0, v62
	v_mul_f32_e32 v62, v58, v58
	v_max_f32_e32 v58, 0, v63
	v_mul_f32_e32 v57, v57, v57
	v_max_f32_e32 v59, 0, v59
	v_mul_f32_e32 v58, v58, v58
	v_cvt_pk_bf16_f32 v56, v60, v56
	v_add_co_u32_e32 v60, vcc, s55, v144
	v_pk_mul_f32 v[48:49], v[48:49], v[66:67] op_sel_hi:[1,0]
	v_mul_f32_e32 v59, v59, v59
	v_cvt_pk_bf16_f32 v57, v57, v58
	v_cvt_pk_bf16_f32 v58, v67, v61
	v_addc_co_u32_e32 v61, vcc, 0, v145, vcc
	v_pk_mul_f32 v[52:53], v[52:53], v[66:67] op_sel_hi:[1,0]
	v_max_f32_e32 v48, 0, v48
	v_cvt_pk_bf16_f32 v59, v62, v59
	global_store_dwordx4 v[60:61], v[56:59], off nt
	v_max_f32_e32 v52, 0, v52
	v_mul_f32_e32 v52, v52, v52
	v_mul_f32_e32 v56, v48, v48
	v_max_f32_e32 v48, 0, v53
	v_mul_f32_e32 v48, v48, v48
	v_cvt_pk_bf16_f32 v48, v52, v48
	v_mul_f32_e32 v52, 0x4b800000, v165
	v_cmp_gt_f32_e32 vcc, s54, v165
	v_pk_mul_f32 v[50:51], v[50:51], v[66:67] op_sel_hi:[1,0]
	v_pk_mul_f32 v[54:55], v[54:55], v[66:67] op_sel_hi:[1,0]
	v_cndmask_b32_e32 v52, v165, v52, vcc
	v_max_f32_e32 v49, 0, v49
	v_max_f32_e32 v50, 0, v50
	v_rsq_f32_e32 v52, v52
	v_mul_f32_e32 v53, v49, v49
	v_max_f32_e32 v49, 0, v54
	v_mul_f32_e32 v54, v50, v50
	v_max_f32_e32 v50, 0, v55
	v_mul_f32_e32 v49, v49, v49
	v_max_f32_e32 v51, 0, v51
	v_mul_f32_e32 v50, v50, v50
	v_lshl_add_u64 v[64:65], v[144:145], 0, s[12:13]
	v_mul_f32_e32 v51, v51, v51
	v_cvt_pk_bf16_f32 v49, v49, v50
	v_cvt_pk_bf16_f32 v50, v56, v53
	v_cvt_pk_bf16_f32 v51, v54, v51
	global_store_dwordx4 v[64:65], v[48:51], off offset:256 nt
	s_nop 1
	v_mul_f32_e32 v50, 0x45800000, v52
	v_cndmask_b32_e32 v50, v52, v50, vcc
	v_pk_mul_f32 v[40:41], v[40:41], v[50:51] op_sel_hi:[1,0]
	v_pk_mul_f32 v[44:45], v[44:45], v[50:51] op_sel_hi:[1,0]
	v_pk_mul_f32 v[42:43], v[42:43], v[50:51] op_sel_hi:[1,0]
	v_max_f32_e32 v40, 0, v40
	v_pk_mul_f32 v[46:47], v[46:47], v[50:51] op_sel_hi:[1,0]
	v_max_f32_e32 v44, 0, v44
	v_mul_f32_e32 v51, v40, v40
	v_max_f32_e32 v40, 0, v45
	v_max_f32_e32 v41, 0, v41
	v_max_f32_e32 v42, 0, v42
	v_mul_f32_e32 v44, v44, v44
	v_mul_f32_e32 v40, v40, v40
	v_mul_f32_e32 v45, v41, v41
	v_max_f32_e32 v41, 0, v46
	v_mul_f32_e32 v46, v42, v42
	v_max_f32_e32 v42, 0, v47
	v_mul_f32_e32 v41, v41, v41
	v_max_f32_e32 v43, 0, v43
	v_mul_f32_e32 v42, v42, v42
	v_cvt_pk_bf16_f32 v40, v44, v40
	v_add_co_u32_e32 v44, vcc, s56, v144
	v_pk_mul_f32 v[32:33], v[32:33], v[50:51] op_sel_hi:[1,0]
	v_mul_f32_e32 v43, v43, v43
	v_cvt_pk_bf16_f32 v41, v41, v42
	v_cvt_pk_bf16_f32 v42, v51, v45
	v_addc_co_u32_e32 v45, vcc, 0, v145, vcc
	v_pk_mul_f32 v[36:37], v[36:37], v[50:51] op_sel_hi:[1,0]
	v_max_f32_e32 v32, 0, v32
	v_cvt_pk_bf16_f32 v43, v46, v43
	global_store_dwordx4 v[44:45], v[40:43], off nt
	v_max_f32_e32 v36, 0, v36
	v_mul_f32_e32 v36, v36, v36
	v_mul_f32_e32 v40, v32, v32
	v_max_f32_e32 v32, 0, v37
	v_mul_f32_e32 v32, v32, v32
	v_cvt_pk_bf16_f32 v32, v36, v32
	v_mul_f32_e32 v36, 0x4b800000, v166
	v_cmp_gt_f32_e32 vcc, s54, v166
	v_pk_mul_f32 v[34:35], v[34:35], v[50:51] op_sel_hi:[1,0]
	v_pk_mul_f32 v[38:39], v[38:39], v[50:51] op_sel_hi:[1,0]
	v_cndmask_b32_e32 v36, v166, v36, vcc
	v_max_f32_e32 v33, 0, v33
	v_max_f32_e32 v34, 0, v34
	v_rsq_f32_e32 v36, v36
	v_mul_f32_e32 v37, v33, v33
	v_max_f32_e32 v33, 0, v38
	v_mul_f32_e32 v38, v34, v34
	v_max_f32_e32 v34, 0, v39
	v_mul_f32_e32 v33, v33, v33
	v_max_f32_e32 v35, 0, v35
	v_mul_f32_e32 v34, v34, v34
	v_lshl_add_u64 v[48:49], v[144:145], 0, s[14:15]
	v_mul_f32_e32 v35, v35, v35
	v_cvt_pk_bf16_f32 v33, v33, v34
	v_cvt_pk_bf16_f32 v34, v40, v37
	v_cvt_pk_bf16_f32 v35, v38, v35
	global_store_dwordx4 v[48:49], v[32:35], off offset:256 nt
	s_nop 1
	v_mul_f32_e32 v34, 0x45800000, v36
	v_cndmask_b32_e32 v34, v36, v34, vcc
	v_pk_mul_f32 v[24:25], v[24:25], v[34:35] op_sel_hi:[1,0]
	v_pk_mul_f32 v[28:29], v[28:29], v[34:35] op_sel_hi:[1,0]
	v_pk_mul_f32 v[26:27], v[26:27], v[34:35] op_sel_hi:[1,0]
	v_max_f32_e32 v24, 0, v24
	v_pk_mul_f32 v[30:31], v[30:31], v[34:35] op_sel_hi:[1,0]
	v_max_f32_e32 v28, 0, v28
	v_mul_f32_e32 v35, v24, v24
	v_max_f32_e32 v24, 0, v29
	v_max_f32_e32 v25, 0, v25
	v_max_f32_e32 v26, 0, v26
	v_mul_f32_e32 v28, v28, v28
	v_mul_f32_e32 v24, v24, v24
	v_mul_f32_e32 v29, v25, v25
	v_max_f32_e32 v25, 0, v30
	v_mul_f32_e32 v30, v26, v26
	v_max_f32_e32 v26, 0, v31
	v_mul_f32_e32 v25, v25, v25
	v_max_f32_e32 v27, 0, v27
	v_mul_f32_e32 v26, v26, v26
	v_cvt_pk_bf16_f32 v24, v28, v24
	v_add_co_u32_e32 v28, vcc, s57, v144
	v_pk_mul_f32 v[16:17], v[16:17], v[34:35] op_sel_hi:[1,0]
	v_mul_f32_e32 v27, v27, v27
	v_cvt_pk_bf16_f32 v25, v25, v26
	v_cvt_pk_bf16_f32 v26, v35, v29
	v_addc_co_u32_e32 v29, vcc, 0, v145, vcc
	v_pk_mul_f32 v[20:21], v[20:21], v[34:35] op_sel_hi:[1,0]
	v_max_f32_e32 v16, 0, v16
	v_cvt_pk_bf16_f32 v27, v30, v27
	global_store_dwordx4 v[28:29], v[24:27], off nt
	v_max_f32_e32 v20, 0, v20
	v_mul_f32_e32 v20, v20, v20
	v_mul_f32_e32 v24, v16, v16
	v_max_f32_e32 v16, 0, v21
	v_mul_f32_e32 v16, v16, v16
	v_cvt_pk_bf16_f32 v16, v20, v16
	v_mul_f32_e32 v20, 0x4b800000, v147
	v_cmp_gt_f32_e32 vcc, s54, v147
	v_pk_mul_f32 v[18:19], v[18:19], v[34:35] op_sel_hi:[1,0]
	v_pk_mul_f32 v[22:23], v[22:23], v[34:35] op_sel_hi:[1,0]
	v_cndmask_b32_e32 v20, v147, v20, vcc
	v_max_f32_e32 v17, 0, v17
	v_max_f32_e32 v18, 0, v18
	v_rsq_f32_e32 v20, v20
	v_mul_f32_e32 v21, v17, v17
	v_max_f32_e32 v17, 0, v22
	v_mul_f32_e32 v22, v18, v18
	v_max_f32_e32 v18, 0, v23
	v_mul_f32_e32 v17, v17, v17
	v_max_f32_e32 v19, 0, v19
	v_mul_f32_e32 v18, v18, v18
	v_lshl_add_u64 v[32:33], v[144:145], 0, s[16:17]
	v_mul_f32_e32 v19, v19, v19
	v_cvt_pk_bf16_f32 v17, v17, v18
	v_cvt_pk_bf16_f32 v18, v24, v21
	v_cvt_pk_bf16_f32 v19, v22, v19
	global_store_dwordx4 v[32:33], v[16:19], off offset:256 nt
	s_nop 1
	v_mul_f32_e32 v18, 0x45800000, v20
	v_cndmask_b32_e32 v18, v20, v18, vcc
	v_pk_mul_f32 v[8:9], v[8:9], v[18:19] op_sel_hi:[1,0]
	v_pk_mul_f32 v[12:13], v[12:13], v[18:19] op_sel_hi:[1,0]
	v_pk_mul_f32 v[10:11], v[10:11], v[18:19] op_sel_hi:[1,0]
	v_max_f32_e32 v8, 0, v8
	v_pk_mul_f32 v[14:15], v[14:15], v[18:19] op_sel_hi:[1,0]
	v_max_f32_e32 v12, 0, v12
	v_mul_f32_e32 v19, v8, v8
	v_max_f32_e32 v8, 0, v13
	v_max_f32_e32 v9, 0, v9
	v_max_f32_e32 v10, 0, v10
	v_mul_f32_e32 v12, v12, v12
	v_mul_f32_e32 v8, v8, v8
	v_mul_f32_e32 v13, v9, v9
	v_max_f32_e32 v9, 0, v14
	v_mul_f32_e32 v14, v10, v10
	v_max_f32_e32 v10, 0, v15
	v_mul_f32_e32 v9, v9, v9
	v_max_f32_e32 v11, 0, v11
	v_mul_f32_e32 v10, v10, v10
	v_cvt_pk_bf16_f32 v8, v12, v8
	v_add_co_u32_e32 v12, vcc, s58, v144
	v_pk_mul_f32 v[2:3], v[2:3], v[18:19] op_sel_hi:[1,0]
	v_pk_mul_f32 v[0:1], v[0:1], v[18:19] op_sel_hi:[1,0]
	v_mul_f32_e32 v11, v11, v11
	v_cvt_pk_bf16_f32 v9, v9, v10
	v_cvt_pk_bf16_f32 v10, v19, v13
	v_addc_co_u32_e32 v13, vcc, 0, v145, vcc
	v_pk_mul_f32 v[6:7], v[6:7], v[18:19] op_sel_hi:[1,0]
	v_pk_mul_f32 v[4:5], v[4:5], v[18:19] op_sel_hi:[1,0]
	v_max_f32_e32 v0, 0, v0
	v_max_f32_e32 v1, 0, v1
	v_max_f32_e32 v2, 0, v2
	v_cvt_pk_bf16_f32 v11, v14, v11
	global_store_dwordx4 v[12:13], v[8:11], off nt
	v_max_f32_e32 v3, 0, v3
	v_lshl_add_u64 v[16:17], v[144:145], 0, s[18:19]
	v_mul_f32_e32 v8, v0, v0
	v_max_f32_e32 v0, 0, v5
	v_mul_f32_e32 v5, v1, v1
	v_max_f32_e32 v1, 0, v6
	v_mul_f32_e32 v6, v2, v2
	v_max_f32_e32 v2, 0, v7
	v_max_f32_e32 v4, 0, v4
	v_mul_f32_e32 v0, v0, v0
	v_mul_f32_e32 v1, v1, v1
	v_mul_f32_e32 v2, v2, v2
	v_mul_f32_e32 v3, v3, v3
	s_and_b64 vcc, exec, s[2:3]
	v_mul_f32_e32 v4, v4, v4
	v_cvt_pk_bf16_f32 v0, v4, v0
	v_cvt_pk_bf16_f32 v1, v1, v2
	v_cvt_pk_bf16_f32 v2, v8, v5
	v_cvt_pk_bf16_f32 v3, v6, v3
	global_store_dwordx4 v[16:17], v[0:3], off offset:256 nt
	s_cbranch_vccz .LBB0_1211
	s_waitcnt vmcnt(0)
	s_cmpk_gt_u32 s33, 0xff
	s_cbranch_scc1 .LBB0_1222
	s_barrier

.LBB0_1264:
	ds_read_b128 v[144:147], v178
	ds_read_b128 v[148:151], v178 offset:1024
	ds_read_b128 v[152:155], v178 offset:2048
	ds_read_b128 v[156:159], v178 offset:3072
	s_add_u32 s34, s30, 0xfff00080
	s_addc_u32 s35, s31, -1
	s_cmp_eq_u32 s58, 60
	s_cselect_b32 s37, s21, s35
	s_cselect_b32 s36, s27, s34
	s_cselect_b32 s35, s19, s57
	s_cselect_b32 s34, s55, s56
	v_lshl_add_u64 v[172:173], s[30:31], 0, v[136:137]
	s_add_i32 m0, s29, 0xc000
	ds_read_b128 v[160:163], v179
	ds_read_b128 v[164:167], v179 offset:1024
	ds_read_b128 v[168:171], v179 offset:2048
	ds_read_b128 v[182:185], v179 offset:3072
	ds_read_b128 v[186:189], v179 offset:4096
	ds_read_b128 v[190:193], v179 offset:5120
	ds_read_b128 v[194:197], v179 offset:6144
	ds_read_b128 v[198:201], v179 offset:7168
	global_load_lds_dwordx4 v[172:173], off
	v_lshl_add_u64 v[172:173], s[30:31], 0, v[138:139]
	s_add_i32 m0, s29, 0xe000
	s_nop 0
	global_load_lds_dwordx4 v[172:173], off
	s_waitcnt lgkmcnt(8)
	s_waitcnt lgkmcnt(0)
	s_setprio 1
	s_barrier
	v_mfma_f32_16x16x32_bf16 v[124:127], v[144:147], v[160:163], v[124:127]
	v_mfma_f32_16x16x32_bf16 v[120:123], v[152:155], v[160:163], v[120:123]
	v_mfma_f32_16x16x32_bf16 v[108:111], v[144:147], v[168:171], v[108:111]
	v_mfma_f32_16x16x32_bf16 v[104:107], v[152:155], v[168:171], v[104:107]
	v_mfma_f32_16x16x32_bf16 v[96:99], v[144:147], v[186:189], v[96:99]
	v_mfma_f32_16x16x32_bf16 v[88:91], v[152:155], v[186:189], v[88:91]
	v_mfma_f32_16x16x32_bf16 v[80:83], v[144:147], v[194:197], v[80:83]
	v_mfma_f32_16x16x32_bf16 v[72:75], v[152:155], v[194:197], v[72:75]
	v_mfma_f32_16x16x32_bf16 v[124:127], v[148:151], v[164:167], v[124:127]
	v_mfma_f32_16x16x32_bf16 v[120:123], v[156:159], v[164:167], v[120:123]
	v_mfma_f32_16x16x32_bf16 v[108:111], v[148:151], v[182:185], v[108:111]
	v_mfma_f32_16x16x32_bf16 v[104:107], v[156:159], v[182:185], v[104:107]
	v_mfma_f32_16x16x32_bf16 v[96:99], v[148:151], v[190:193], v[96:99]
	v_mfma_f32_16x16x32_bf16 v[88:91], v[156:159], v[190:193], v[88:91]
	v_mfma_f32_16x16x32_bf16 v[80:83], v[148:151], v[198:201], v[80:83]
	v_mfma_f32_16x16x32_bf16 v[72:75], v[156:159], v[198:201], v[72:75]
	s_setprio 0
	s_barrier
	s_add_i32 s59, s53, s40
	v_lshl_add_u64 v[172:173], s[34:35], 0, v[130:131]
	s_mov_b32 m0, s59
	ds_read_b128 v[202:205], v180
	ds_read_b128 v[206:209], v180 offset:1024
	ds_read_b128 v[212:215], v180 offset:2048
	ds_read_b128 v[216:219], v180 offset:3072
	global_load_lds_dwordx4 v[172:173], off
	v_lshl_add_u64 v[220:221], s[34:35], 0, v[134:135]
	s_add_i32 m0, s59, 0x2000
	s_nop 0
	global_load_lds_dwordx4 v[220:221], off
	s_waitcnt lgkmcnt(0)
	s_setprio 1
	s_barrier
	v_mfma_f32_16x16x32_bf16 v[116:119], v[202:205], v[160:163], v[116:119]
	v_mfma_f32_16x16x32_bf16 v[112:115], v[212:215], v[160:163], v[112:115]
	v_mfma_f32_16x16x32_bf16 v[100:103], v[202:205], v[168:171], v[100:103]
	v_mfma_f32_16x16x32_bf16 v[92:95], v[212:215], v[168:171], v[92:95]
	v_mfma_f32_16x16x32_bf16 v[84:87], v[202:205], v[186:189], v[84:87]
	v_mfma_f32_16x16x32_bf16 v[76:79], v[212:215], v[186:189], v[76:79]
	v_mfma_f32_16x16x32_bf16 v[68:71], v[202:205], v[194:197], v[68:71]
	v_mfma_f32_16x16x32_bf16 v[64:67], v[212:215], v[194:197], v[64:67]
	v_mfma_f32_16x16x32_bf16 v[116:119], v[206:209], v[164:167], v[116:119]
	v_mfma_f32_16x16x32_bf16 v[112:115], v[216:219], v[164:167], v[112:115]
	v_mfma_f32_16x16x32_bf16 v[100:103], v[206:209], v[182:185], v[100:103]
	v_mfma_f32_16x16x32_bf16 v[92:95], v[216:219], v[182:185], v[92:95]
	v_mfma_f32_16x16x32_bf16 v[84:87], v[206:209], v[190:193], v[84:87]
	v_mfma_f32_16x16x32_bf16 v[76:79], v[216:219], v[190:193], v[76:79]
	v_mfma_f32_16x16x32_bf16 v[68:71], v[206:209], v[198:201], v[68:71]
	v_mfma_f32_16x16x32_bf16 v[64:67], v[216:219], v[198:201], v[64:67]
	s_setprio 0
	s_mov_b32 m0, s29
	v_lshl_add_u64 v[222:223], s[36:37], 0, v[128:129]
	s_barrier
	ds_read_b128 v[160:163], v179 offset:16384
	ds_read_b128 v[164:167], v179 offset:17408
	ds_read_b128 v[168:171], v179 offset:18432
	ds_read_b128 v[182:185], v179 offset:19456
	ds_read_b128 v[186:189], v179 offset:20480
	ds_read_b128 v[190:193], v179 offset:21504
	ds_read_b128 v[194:197], v179 offset:22528
	ds_read_b128 v[198:201], v179 offset:23552
	global_load_lds_dwordx4 v[222:223], off
	v_lshl_add_u64 v[224:225], s[36:37], 0, v[132:133]
	s_mov_b32 m0, s41
	s_nop 0
	global_load_lds_dwordx4 v[224:225], off
	s_waitcnt lgkmcnt(0)
	s_setprio 1
	s_barrier
	v_mfma_f32_16x16x32_bf16 v[60:63], v[144:147], v[160:163], v[60:63]
	v_mfma_f32_16x16x32_bf16 v[56:59], v[152:155], v[160:163], v[56:59]
	v_mfma_f32_16x16x32_bf16 v[44:47], v[144:147], v[168:171], v[44:47]
	v_mfma_f32_16x16x32_bf16 v[40:43], v[152:155], v[168:171], v[40:43]
	v_mfma_f32_16x16x32_bf16 v[32:35], v[144:147], v[186:189], v[32:35]
	v_mfma_f32_16x16x32_bf16 v[24:27], v[152:155], v[186:189], v[24:27]
	v_mfma_f32_16x16x32_bf16 v[16:19], v[144:147], v[194:197], v[16:19]
	v_mfma_f32_16x16x32_bf16 v[8:11], v[152:155], v[194:197], v[8:11]
	v_mfma_f32_16x16x32_bf16 v[60:63], v[148:151], v[164:167], v[60:63]
	v_mfma_f32_16x16x32_bf16 v[56:59], v[156:159], v[164:167], v[56:59]
	v_mfma_f32_16x16x32_bf16 v[44:47], v[148:151], v[182:185], v[44:47]
	v_mfma_f32_16x16x32_bf16 v[40:43], v[156:159], v[182:185], v[40:43]
	v_mfma_f32_16x16x32_bf16 v[32:35], v[148:151], v[190:193], v[32:35]
	v_mfma_f32_16x16x32_bf16 v[24:27], v[156:159], v[190:193], v[24:27]
	v_mfma_f32_16x16x32_bf16 v[16:19], v[148:151], v[198:201], v[16:19]
	v_mfma_f32_16x16x32_bf16 v[8:11], v[156:159], v[198:201], v[8:11]
	s_setprio 0
	s_barrier
	s_add_u32 s60, s34, 0x100000
	s_addc_u32 s61, s35, 0
	s_add_i32 s59, s54, s40
	v_lshl_add_u64 v[144:145], s[60:61], 0, v[130:131]
	s_mov_b32 m0, s59
	s_nop 0
	global_load_lds_dwordx4 v[144:145], off
	v_lshl_add_u64 v[144:145], s[60:61], 0, v[134:135]
	s_add_i32 m0, s59, 0x2000
	s_nop 0
	global_load_lds_dwordx4 v[144:145], off
	s_waitcnt vmcnt(6)
	s_setprio 1
	s_barrier
	v_mfma_f32_16x16x32_bf16 v[52:55], v[202:205], v[160:163], v[52:55]
	v_mfma_f32_16x16x32_bf16 v[48:51], v[212:215], v[160:163], v[48:51]
	v_mfma_f32_16x16x32_bf16 v[36:39], v[202:205], v[168:171], v[36:39]
	v_mfma_f32_16x16x32_bf16 v[28:31], v[212:215], v[168:171], v[28:31]
	v_mfma_f32_16x16x32_bf16 v[20:23], v[202:205], v[186:189], v[20:23]
	v_mfma_f32_16x16x32_bf16 v[12:15], v[212:215], v[186:189], v[12:15]
	v_mfma_f32_16x16x32_bf16 v[4:7], v[202:205], v[194:197], v[4:7]
	v_mfma_f32_16x16x32_bf16 v[0:3], v[212:215], v[194:197], v[0:3]
	v_mfma_f32_16x16x32_bf16 v[52:55], v[206:209], v[164:167], v[52:55]
	v_mfma_f32_16x16x32_bf16 v[48:51], v[216:219], v[164:167], v[48:51]
	v_mfma_f32_16x16x32_bf16 v[36:39], v[206:209], v[182:185], v[36:39]
	v_mfma_f32_16x16x32_bf16 v[28:31], v[216:219], v[182:185], v[28:31]
	v_mfma_f32_16x16x32_bf16 v[20:23], v[206:209], v[190:193], v[20:23]
	v_mfma_f32_16x16x32_bf16 v[12:15], v[216:219], v[190:193], v[12:15]
	v_mfma_f32_16x16x32_bf16 v[4:7], v[206:209], v[198:201], v[4:7]
	v_mfma_f32_16x16x32_bf16 v[0:3], v[216:219], v[198:201], v[0:3]
	s_setprio 0
	s_add_i32 s59, 0, 0x18000
	v_add_u32_e32 v156, s59, v176
	s_barrier
	ds_read_b128 v[144:147], v156
	ds_read_b128 v[148:151], v156 offset:1024
	ds_read_b128 v[152:155], v156 offset:2048
	ds_read_b128 v[156:159], v156 offset:3072
	s_add_u32 s36, s36, 0x100000
	s_addc_u32 s37, s37, 0
	s_mov_b32 m0, s42
	v_lshl_add_u64 v[202:203], s[36:37], 0, v[128:129]
	ds_read_b128 v[160:163], v179 offset:32768
	ds_read_b128 v[164:167], v179 offset:33792
	ds_read_b128 v[168:171], v179 offset:34816
	ds_read_b128 v[182:185], v179 offset:35840
	ds_read_b128 v[186:189], v179 offset:36864
	ds_read_b128 v[190:193], v179 offset:37888
	ds_read_b128 v[194:197], v179 offset:38912
	ds_read_b128 v[198:201], v179 offset:39936
	global_load_lds_dwordx4 v[202:203], off
	v_lshl_add_u64 v[202:203], s[36:37], 0, v[132:133]
	s_mov_b32 m0, s43
	s_nop 0
	global_load_lds_dwordx4 v[202:203], off
	s_waitcnt lgkmcnt(8)
	s_waitcnt lgkmcnt(0)
	s_setprio 1
	s_barrier
	v_mfma_f32_16x16x32_bf16 v[124:127], v[144:147], v[160:163], v[124:127]
	v_mfma_f32_16x16x32_bf16 v[120:123], v[152:155], v[160:163], v[120:123]
	v_mfma_f32_16x16x32_bf16 v[108:111], v[144:147], v[168:171], v[108:111]
	v_mfma_f32_16x16x32_bf16 v[104:107], v[152:155], v[168:171], v[104:107]
	v_mfma_f32_16x16x32_bf16 v[96:99], v[144:147], v[186:189], v[96:99]
	v_mfma_f32_16x16x32_bf16 v[88:91], v[152:155], v[186:189], v[88:91]
	v_mfma_f32_16x16x32_bf16 v[80:83], v[144:147], v[194:197], v[80:83]
	v_mfma_f32_16x16x32_bf16 v[72:75], v[152:155], v[194:197], v[72:75]
	v_mfma_f32_16x16x32_bf16 v[124:127], v[148:151], v[164:167], v[124:127]
	v_mfma_f32_16x16x32_bf16 v[120:123], v[156:159], v[164:167], v[120:123]
	v_mfma_f32_16x16x32_bf16 v[108:111], v[148:151], v[182:185], v[108:111]
	v_mfma_f32_16x16x32_bf16 v[104:107], v[156:159], v[182:185], v[104:107]
	v_mfma_f32_16x16x32_bf16 v[96:99], v[148:151], v[190:193], v[96:99]
	v_mfma_f32_16x16x32_bf16 v[88:91], v[156:159], v[190:193], v[88:91]
	v_mfma_f32_16x16x32_bf16 v[80:83], v[148:151], v[198:201], v[80:83]
	v_mfma_f32_16x16x32_bf16 v[72:75], v[156:159], v[198:201], v[72:75]
	s_setprio 0
	s_barrier
	s_add_i32 s36, 0, 0x1c000
	s_add_i32 s37, s59, s40
	v_add_u32_e32 v181, s36, v176
	v_lshl_add_u64 v[172:173], v[172:173], 0, s[0:1]
	s_mov_b32 m0, s37
	ds_read_b128 v[202:205], v181
	ds_read_b128 v[206:209], v181 offset:1024
	ds_read_b128 v[212:215], v181 offset:2048
	ds_read_b128 v[216:219], v181 offset:3072
	global_load_lds_dwordx4 v[172:173], off
	v_lshl_add_u64 v[172:173], v[220:221], 0, s[0:1]
	s_add_i32 m0, s37, 0x2000
	s_nop 0
	global_load_lds_dwordx4 v[172:173], off
	s_waitcnt lgkmcnt(0)
	s_setprio 1
	s_barrier
	v_mfma_f32_16x16x32_bf16 v[116:119], v[202:205], v[160:163], v[116:119]
	v_mfma_f32_16x16x32_bf16 v[112:115], v[212:215], v[160:163], v[112:115]
	v_mfma_f32_16x16x32_bf16 v[100:103], v[202:205], v[168:171], v[100:103]
	v_mfma_f32_16x16x32_bf16 v[92:95], v[212:215], v[168:171], v[92:95]
	v_mfma_f32_16x16x32_bf16 v[84:87], v[202:205], v[186:189], v[84:87]
	v_mfma_f32_16x16x32_bf16 v[76:79], v[212:215], v[186:189], v[76:79]
	v_mfma_f32_16x16x32_bf16 v[68:71], v[202:205], v[194:197], v[68:71]
	v_mfma_f32_16x16x32_bf16 v[64:67], v[212:215], v[194:197], v[64:67]
	v_mfma_f32_16x16x32_bf16 v[116:119], v[206:209], v[164:167], v[116:119]
	v_mfma_f32_16x16x32_bf16 v[112:115], v[216:219], v[164:167], v[112:115]
	v_mfma_f32_16x16x32_bf16 v[100:103], v[206:209], v[182:185], v[100:103]
	v_mfma_f32_16x16x32_bf16 v[92:95], v[216:219], v[182:185], v[92:95]
	v_mfma_f32_16x16x32_bf16 v[84:87], v[206:209], v[190:193], v[84:87]
	v_mfma_f32_16x16x32_bf16 v[76:79], v[216:219], v[190:193], v[76:79]
	v_mfma_f32_16x16x32_bf16 v[68:71], v[206:209], v[198:201], v[68:71]
	v_mfma_f32_16x16x32_bf16 v[64:67], v[216:219], v[198:201], v[64:67]
	s_setprio 0
	s_mov_b32 m0, s49
	v_lshl_add_u64 v[172:173], v[222:223], 0, s[0:1]
	s_barrier
	ds_read_b128 v[160:163], v179 offset:49152
	ds_read_b128 v[164:167], v179 offset:50176
	ds_read_b128 v[168:171], v179 offset:51200
	ds_read_b128 v[182:185], v179 offset:52224
	ds_read_b128 v[186:189], v179 offset:53248
	ds_read_b128 v[190:193], v179 offset:54272
	ds_read_b128 v[194:197], v179 offset:55296
	ds_read_b128 v[198:201], v179 offset:56320
	global_load_lds_dwordx4 v[172:173], off
	v_lshl_add_u64 v[172:173], v[224:225], 0, s[0:1]
	s_mov_b32 m0, s50
	s_nop 0
	global_load_lds_dwordx4 v[172:173], off
	s_waitcnt lgkmcnt(0)
	s_setprio 1
	s_barrier
	v_mfma_f32_16x16x32_bf16 v[60:63], v[144:147], v[160:163], v[60:63]
	v_mfma_f32_16x16x32_bf16 v[56:59], v[152:155], v[160:163], v[56:59]
	v_mfma_f32_16x16x32_bf16 v[44:47], v[144:147], v[168:171], v[44:47]
	v_mfma_f32_16x16x32_bf16 v[40:43], v[152:155], v[168:171], v[40:43]
	v_mfma_f32_16x16x32_bf16 v[32:35], v[144:147], v[186:189], v[32:35]
	v_mfma_f32_16x16x32_bf16 v[24:27], v[152:155], v[186:189], v[24:27]
	v_mfma_f32_16x16x32_bf16 v[16:19], v[144:147], v[194:197], v[16:19]
	v_mfma_f32_16x16x32_bf16 v[8:11], v[152:155], v[194:197], v[8:11]
	v_mfma_f32_16x16x32_bf16 v[60:63], v[148:151], v[164:167], v[60:63]
	v_mfma_f32_16x16x32_bf16 v[56:59], v[156:159], v[164:167], v[56:59]
	v_mfma_f32_16x16x32_bf16 v[44:47], v[148:151], v[182:185], v[44:47]
	v_mfma_f32_16x16x32_bf16 v[40:43], v[156:159], v[182:185], v[40:43]
	v_mfma_f32_16x16x32_bf16 v[32:35], v[148:151], v[190:193], v[32:35]
	v_mfma_f32_16x16x32_bf16 v[24:27], v[156:159], v[190:193], v[24:27]
	v_mfma_f32_16x16x32_bf16 v[16:19], v[148:151], v[198:201], v[16:19]
	v_mfma_f32_16x16x32_bf16 v[8:11], v[156:159], v[198:201], v[8:11]
	s_setprio 0
	s_barrier
	s_add_u32 s34, s34, 0x100080
	s_addc_u32 s35, s35, 0
	s_add_i32 s36, s36, s40
	v_lshl_add_u64 v[144:145], s[34:35], 0, v[130:131]
	s_mov_b32 m0, s36
	s_nop 0
	global_load_lds_dwordx4 v[144:145], off
	v_lshl_add_u64 v[144:145], s[34:35], 0, v[134:135]
	s_add_i32 m0, s36, 0x2000
	s_nop 0
	global_load_lds_dwordx4 v[144:145], off
	s_waitcnt vmcnt(6)
	s_setprio 1
	s_barrier
	v_mfma_f32_16x16x32_bf16 v[52:55], v[202:205], v[160:163], v[52:55]
	v_mfma_f32_16x16x32_bf16 v[48:51], v[212:215], v[160:163], v[48:51]
	v_mfma_f32_16x16x32_bf16 v[36:39], v[202:205], v[168:171], v[36:39]
	v_mfma_f32_16x16x32_bf16 v[28:31], v[212:215], v[168:171], v[28:31]
	v_mfma_f32_16x16x32_bf16 v[20:23], v[202:205], v[186:189], v[20:23]
	v_mfma_f32_16x16x32_bf16 v[12:15], v[212:215], v[186:189], v[12:15]
	v_mfma_f32_16x16x32_bf16 v[4:7], v[202:205], v[194:197], v[4:7]
	v_mfma_f32_16x16x32_bf16 v[0:3], v[212:215], v[194:197], v[0:3]
	v_mfma_f32_16x16x32_bf16 v[52:55], v[206:209], v[164:167], v[52:55]
	v_mfma_f32_16x16x32_bf16 v[48:51], v[216:219], v[164:167], v[48:51]
	v_mfma_f32_16x16x32_bf16 v[36:39], v[206:209], v[182:185], v[36:39]
	v_mfma_f32_16x16x32_bf16 v[28:31], v[216:219], v[182:185], v[28:31]
	v_mfma_f32_16x16x32_bf16 v[20:23], v[206:209], v[190:193], v[20:23]
	v_mfma_f32_16x16x32_bf16 v[12:15], v[216:219], v[190:193], v[12:15]
	v_mfma_f32_16x16x32_bf16 v[4:7], v[206:209], v[198:201], v[4:7]
	v_mfma_f32_16x16x32_bf16 v[0:3], v[216:219], v[198:201], v[0:3]
	s_setprio 0
	s_add_i32 s58, s58, 2
	s_add_u32 s30, s30, 0x100
	s_addc_u32 s31, s31, 0
	s_add_u32 s56, s56, 0x100
	s_addc_u32 s57, s57, 0
	s_cmp_gt_u32 s58, 61
	s_barrier
	s_cbranch_scc0 .LBB0_1264
	v_lshl_or_b32 v144, s28, 8, v177
	v_lshl_add_u32 v150, s26, 8, v175
	v_ashrrev_i32_e32 v145, 31, v144
	v_ashrrev_i32_e32 v151, 31, v150
	v_lshlrev_b64 v[144:145], 1, v[144:145]
	v_lshl_add_u64 v[146:147], s[90:91], 0, v[144:145]
	v_lshlrev_b64 v[148:149], 11, v[150:151]
	v_lshl_add_u64 v[152:153], v[146:147], 0, v[148:149]
	global_load_dwordx4 v[156:159], v[152:153], off
	global_load_dwordx4 v[160:163], v[152:153], off offset:256
	v_or_b32_e32 v152, 16, v150
	v_ashrrev_i32_e32 v153, 31, v152
	v_lshlrev_b64 v[170:171], 11, v[152:153]
	v_lshl_add_u64 v[152:153], v[146:147], 0, v[170:171]
	global_load_dwordx4 v[164:167], v[152:153], off
	global_load_dwordx4 v[182:185], v[152:153], off offset:256
	v_or_b32_e32 v152, 32, v150
	v_ashrrev_i32_e32 v153, 31, v152
	v_lshlrev_b64 v[154:155], 11, v[152:153]
	v_lshl_add_u64 v[152:153], v[146:147], 0, v[154:155]
	global_load_dwordx4 v[186:189], v[152:153], off
	global_load_dwordx4 v[190:193], v[152:153], off offset:256
	v_or_b32_e32 v152, 48, v150
	v_ashrrev_i32_e32 v153, 31, v152
	v_lshlrev_b64 v[152:153], 11, v[152:153]
	v_lshl_add_u64 v[168:169], v[146:147], 0, v[152:153]
	global_load_dwordx4 v[194:197], v[168:169], off
	global_load_dwordx4 v[198:201], v[168:169], off offset:256
	s_waitcnt vmcnt(0)
	v_lshlrev_b32_e32 v202, 16, v156
	v_and_b32_e32 v203, 0xffff0000, v156
	v_lshlrev_b32_e32 v204, 16, v157
	v_and_b32_e32 v205, 0xffff0000, v157
	v_lshlrev_b32_e32 v206, 16, v158
	v_and_b32_e32 v207, 0xffff0000, v158
	v_lshlrev_b32_e32 v208, 16, v159
	v_and_b32_e32 v209, 0xffff0000, v159
	v_pk_add_f32 v[126:127], v[126:127], v[204:205]
	v_pk_add_f32 v[124:125], v[124:125], v[202:203]
	v_lshlrev_b32_e32 v224, 16, v166
	v_and_b32_e32 v225, 0xffff0000, v166
	v_lshlrev_b32_e32 v226, 16, v167
	v_and_b32_e32 v227, 0xffff0000, v167
	v_lshlrev_b32_e32 v212, 16, v160
	v_lshlrev_b32_e32 v166, 16, v194
	v_and_b32_e32 v167, 0xffff0000, v194
	v_lshlrev_b32_e32 v172, 16, v195
	v_and_b32_e32 v173, 0xffff0000, v195
	v_pk_add_f32 v[194:195], v[122:123], v[208:209]
	v_pk_add_f32 v[122:123], v[120:121], v[206:207]
	v_mul_f32_e32 v120, v125, v125
	v_mul_f32_e32 v121, v127, v127
	v_fmac_f32_e32 v120, v124, v124
	v_fmac_f32_e32 v121, v126, v126
	v_add_f32_e32 v120, v120, v121
	v_mul_f32_e32 v121, v123, v123
	v_fmac_f32_e32 v121, v122, v122
	v_add_f32_e32 v120, v121, v120
	v_mul_f32_e32 v121, v195, v195
	v_fmac_f32_e32 v121, v194, v194
	v_and_b32_e32 v213, 0xffff0000, v160
	v_lshlrev_b32_e32 v214, 16, v161
	v_and_b32_e32 v215, 0xffff0000, v161
	v_add_f32_e32 v181, v121, v120
	v_cvt_pk_bf16_f32 v120, v124, v125
	v_lshl_add_u64 v[124:125], s[10:11], 0, v[148:149]
	v_lshlrev_b32_e32 v216, 16, v162
	v_and_b32_e32 v217, 0xffff0000, v162
	v_lshlrev_b32_e32 v218, 16, v163
	v_and_b32_e32 v219, 0xffff0000, v163
	v_cvt_pk_bf16_f32 v121, v126, v127
	v_lshl_add_u64 v[124:125], v[124:125], 0, v[144:145]
	v_pk_add_f32 v[118:119], v[118:119], v[214:215]
	v_pk_add_f32 v[116:117], v[116:117], v[212:213]
	v_cvt_pk_bf16_f32 v122, v122, v123
	v_cvt_pk_bf16_f32 v123, v194, v195
	global_store_dwordx4 v[124:125], v[120:123], off
	v_lshlrev_b32_e32 v220, 16, v164
	v_and_b32_e32 v221, 0xffff0000, v164
	v_pk_add_f32 v[120:121], v[114:115], v[218:219]
	v_pk_add_f32 v[114:115], v[112:113], v[216:217]
	v_mul_f32_e32 v112, v117, v117
	v_mul_f32_e32 v113, v119, v119
	v_fmac_f32_e32 v112, v116, v116
	v_fmac_f32_e32 v113, v118, v118
	v_add_f32_e32 v112, v112, v113
	v_mul_f32_e32 v113, v115, v115
	v_fmac_f32_e32 v113, v114, v114
	v_add_f32_e32 v112, v113, v112
	v_mul_f32_e32 v113, v121, v121
	v_fmac_f32_e32 v113, v120, v120
	v_add_f32_e32 v112, v113, v112
	v_lshlrev_b32_e32 v222, 16, v165
	v_and_b32_e32 v223, 0xffff0000, v165
	v_add_f32_e32 v126, v181, v112
	v_cvt_pk_bf16_f32 v112, v116, v117
	v_cvt_pk_bf16_f32 v113, v118, v119
	v_lshl_add_u64 v[116:117], s[10:11], 0, v[170:171]
	v_lshlrev_b32_e32 v230, 16, v184
	v_and_b32_e32 v231, 0xffff0000, v184
	v_lshlrev_b32_e32 v232, 16, v186
	v_and_b32_e32 v233, 0xffff0000, v186
	v_lshlrev_b32_e32 v186, 16, v187
	v_and_b32_e32 v187, 0xffff0000, v187
	v_cvt_pk_bf16_f32 v114, v114, v115
	v_cvt_pk_bf16_f32 v115, v120, v121
	global_store_dwordx4 v[124:125], v[112:115], off offset:256
	v_pk_add_f32 v[110:111], v[110:111], v[222:223]
	v_pk_add_f32 v[108:109], v[108:109], v[220:221]
	v_lshl_add_u64 v[118:119], v[116:117], 0, v[144:145]
	v_cvt_pk_bf16_f32 v112, v108, v109
	v_cvt_pk_bf16_f32 v113, v110, v111
	v_lshlrev_b32_e32 v228, 16, v182
	v_and_b32_e32 v229, 0xffff0000, v182
	v_lshlrev_b32_e32 v182, 16, v183
	v_and_b32_e32 v183, 0xffff0000, v183
	v_lshlrev_b32_e32 v184, 16, v185
	v_and_b32_e32 v185, 0xffff0000, v185
	v_lshlrev_b32_e32 v238, 16, v192
	v_and_b32_e32 v239, 0xffff0000, v192
	v_pk_add_f32 v[106:107], v[106:107], v[226:227]
	v_pk_add_f32 v[104:105], v[104:105], v[224:225]
	v_lshlrev_b32_e32 v156, 16, v200
	v_cvt_pk_bf16_f32 v114, v104, v105
	v_cvt_pk_bf16_f32 v115, v106, v107
	global_store_dwordx4 v[118:119], v[112:115], off
	v_and_b32_e32 v157, 0xffff0000, v200
	v_pk_add_f32 v[102:103], v[102:103], v[182:183]
	v_pk_add_f32 v[112:113], v[92:93], v[230:231]
	v_pk_add_f32 v[92:93], v[98:99], v[186:187]
	v_lshl_add_u64 v[98:99], s[10:11], 0, v[154:155]
	v_pk_add_f32 v[100:101], v[100:101], v[228:229]
	v_pk_add_f32 v[94:95], v[94:95], v[184:185]
	v_cvt_pk_bf16_f32 v114, v100, v101
	v_cvt_pk_bf16_f32 v115, v102, v103
	v_cvt_pk_bf16_f32 v116, v112, v113
	v_lshlrev_b32_e32 v234, 16, v188
	v_cvt_pk_bf16_f32 v117, v94, v95
	global_store_dwordx4 v[118:119], v[114:117], off offset:256
	v_lshl_add_u64 v[118:119], v[98:99], 0, v[144:145]
	v_pk_add_f32 v[98:99], v[76:77], v[238:239]
	v_pk_add_f32 v[76:77], v[82:83], v[172:173]
	v_lshl_add_u64 v[82:83], s[10:11], 0, v[152:153]
	v_lshl_add_u64 v[122:123], v[82:83], 0, v[144:145]
	v_pk_add_f32 v[82:83], v[64:65], v[156:157]
	v_and_b32_e32 v65, 64, v174
	v_and_b32_e32 v235, 0xffff0000, v188
	v_lshlrev_b32_e32 v188, 16, v189
	v_and_b32_e32 v189, 0xffff0000, v189
	v_lshlrev_b32_e32 v236, 16, v190
	v_and_b32_e32 v237, 0xffff0000, v190
	v_pk_add_f32 v[96:97], v[96:97], v[232:233]
	v_xor_b32_e32 v64, 16, v174
	v_cvt_pk_bf16_f32 v114, v96, v97
	v_add_u32_e32 v65, 64, v65
	v_lshlrev_b32_e32 v190, 16, v191
	v_and_b32_e32 v191, 0xffff0000, v191
	v_lshlrev_b32_e32 v192, 16, v193
	v_and_b32_e32 v193, 0xffff0000, v193
	v_pk_add_f32 v[90:91], v[90:91], v[188:189]
	v_pk_add_f32 v[88:89], v[88:89], v[234:235]
	v_cvt_pk_bf16_f32 v115, v92, v93
	v_pk_add_f32 v[84:85], v[84:85], v[236:237]
	v_cvt_pk_bf16_f32 v116, v88, v89
	v_cvt_pk_bf16_f32 v117, v90, v91
	global_store_dwordx4 v[118:119], v[114:117], off
	v_cmp_lt_i32_e32 vcc, v64, v65
	v_lshlrev_b32_e32 v164, 16, v196
	v_cvt_pk_bf16_f32 v114, v84, v85
	v_and_b32_e32 v165, 0xffff0000, v196
	v_lshlrev_b32_e32 v168, 16, v197
	v_and_b32_e32 v169, 0xffff0000, v197
	v_pk_add_f32 v[86:87], v[86:87], v[190:191]
	v_pk_add_f32 v[78:79], v[78:79], v[192:193]
	v_cvt_pk_bf16_f32 v115, v86, v87
	v_cvt_pk_bf16_f32 v116, v98, v99
	v_pk_add_f32 v[80:81], v[80:81], v[166:167]
	v_cvt_pk_bf16_f32 v117, v78, v79
	global_store_dwordx4 v[118:119], v[114:117], off offset:256
	v_cndmask_b32_e32 v64, v174, v64, vcc
	v_pk_add_f32 v[74:75], v[74:75], v[168:169]
	v_cvt_pk_bf16_f32 v114, v80, v81
	v_pk_add_f32 v[72:73], v[72:73], v[164:165]
	v_cvt_pk_bf16_f32 v115, v76, v77
	v_lshlrev_b32_e32 v158, 16, v198
	v_cvt_pk_bf16_f32 v116, v72, v73
	v_cvt_pk_bf16_f32 v117, v74, v75
	global_store_dwordx4 v[122:123], v[114:117], off
	v_and_b32_e32 v159, 0xffff0000, v198
	v_lshlrev_b32_e32 v162, 16, v199
	v_lshlrev_b32_e32 v114, 2, v64
	ds_bpermute_b32 v64, v114, v126
	v_xor_b32_e32 v115, 32, v174
	v_cmp_lt_i32_e32 vcc, v115, v65
	v_and_b32_e32 v163, 0xffff0000, v199
	v_lshlrev_b32_e32 v160, 16, v201
	v_cndmask_b32_e32 v65, v174, v115, vcc
	v_lshlrev_b32_e32 v115, 2, v65
	s_waitcnt lgkmcnt(0)
	v_add_f32_e32 v116, v126, v64
	ds_bpermute_b32 v117, v115, v116
	v_and_b32_e32 v161, 0xffff0000, v201
	v_pk_add_f32 v[70:71], v[70:71], v[162:163]
	v_pk_add_f32 v[68:69], v[68:69], v[158:159]
	v_pk_add_f32 v[66:67], v[66:67], v[160:161]
	v_lshl_add_u64 v[64:65], v[150:151], 2, s[6:7]
	v_cvt_pk_bf16_f32 v118, v68, v69
	v_cvt_pk_bf16_f32 v119, v70, v71
	v_cvt_pk_bf16_f32 v120, v82, v83
	v_cvt_pk_bf16_f32 v121, v66, v67
	global_store_dwordx4 v[122:123], v[118:121], off offset:256
	s_and_saveexec_b64 s[26:27], s[2:3]
	s_cbranch_execz .LBB0_1267
	s_waitcnt lgkmcnt(0)
	v_add_f32_e32 v116, v116, v117
	global_atomic_add_f32 v[64:65], v116, off
